# plus: ds_bpermute row reductions in GEMM epilogues replaced by v_permlane16/32_swap (no LDS round trip); compiler's vmcnt(0) drain before each GEMM K-loop removed (counted waits stay conservative)
# speedup vs baseline: 1.0580x; 1.0067x over previous
; #define PG8_STAGE(bufoff, gbase, voff) do { _Pragma("unroll") for (int _i = 0; _i < 2; ++_i) \
;         __builtin_amdgcn_global_load_lds((const unsigned*)((const char*)(gbase) + (voff)[_i]), (LAS unsigned*)(lds + (bufoff) + ldsw + _i * 8192), 16, 0, 0); } while (0)
; #define PG8_LDA(dst, b, h) do { _Pragma("unroll") for (int m = 0; m < 4; ++m) _Pragma("unroll") for (int k = 0; k < 2; ++k) dst[m][k] = *(const LAS bf16x8*)(lds + PG8_SA(b, h) + aoff + m * 2048 + k * 1024); } while (0)
; #define PG8_LDB(dst, b, h) do { _Pragma("unroll") for (int n = 0; n < 2; ++n) _Pragma("unroll") for (int k = 0; k < 2; ++k) dst[n][k] = *(const LAS bf16x8*)(lds + PG8_SB(b, h) + boff + n * 2048 + k * 1024); } while (0)
; #define PG8_WAIT_L(n) asm volatile("s_waitcnt lgkmcnt(" #n ")" ::: "memory")
; #define PG8_BAR __builtin_amdgcn_s_barrier()
; #define PG8_SCHED __builtin_amdgcn_sched_barrier(0)
; template <class Epi, int KK, int LDA, int LDB, int NN, bool AGRP>
; __device__ __forceinline__ void gemm_phase(LAS unsigned char* lds, const bf16_t* gA, const bf16_t* gBt, int G_, int bid_, int tid) {
;     ...
;     for (;;) {
;         const bool has_next = S.next(ui + 1, nxt);
;         const char* nA = has_next ? (const char*)g.A + (size_t)nxt.pm * tstepA + PG8_ACOL(nxt.pn) : cA; const char* nB = has_next ? (const char*)g.Bt + (size_t)nxt.pn * tstepB : cB;
; #pragma nounroll
;         for (int t = 0; t < nt; t += 2) {
;             const bool last = (t == nt - 2);
;             const char* a1 = cA + (size_t)(t + 1) * kstep;
;             const char* a2 = last ? nA : cA + (size_t)(t + 2) * kstep; const char* b2 = last ? nB : cB + (size_t)(t + 2) * kstep;
;             const char* a3 = a2 + kstep; const char* b3 = b2 + kstep;
;             PG8_LDB(B0, 0, 0); PG8_SCHED; PG8_LDA(At, 0, 0); PG8_STAGE(PG8_SA(1, 1), a1 + hstepA, voffA);
;             PG8_WAIT_L(8); PG8_BAR; PG8_WAIT_L(0); PG8_MMA(0, 0, At, B0); PG8_BAR; PG8_SCHED;
;     ...
; #pragma unroll
;         for (int a = 0; a < 2; ++a)
; #pragma unroll
;             for (int b = 0; b < 2; ++b)
; #pragma unroll
;                 for (int m = 0; m < 4; ++m)
; #pragma unroll
;                     for (int n = 0; n < 2; ++n) acc[a][b][m][n] = (f32x4){zr, zr, zr, zr};
;         cur = nxt; cA = nA; cB = nB; ++ui;
.LBB1_22:
	s_ashr_i32 s1, s0, 31
	s_lshl_b64 s[12:13], s[0:1], 19
	s_add_u32 s12, s96, s12
	s_addc_u32 s13, s97, s13
	s_and_b64 s[14:15], s[22:23], exec
	s_cselect_b32 s1, s13, s21
	s_cselect_b32 s19, s12, s20
	s_ashr_i32 s9, s8, 31
	s_lshl_b64 s[14:15], s[8:9], 19
	s_add_u32 s14, s27, s14
	s_addc_u32 s15, s28, s15
	s_and_b64 s[22:23], s[22:23], exec
	s_cselect_b32 s9, s15, s17
	s_cselect_b32 s24, s14, s16
	s_add_u32 s25, s16, 0x100
	s_addc_u32 s65, s17, 0
	s_add_u32 s16, s20, 0x40080
	s_addc_u32 s17, s21, 0
	s_mov_b32 s70, -2
	v_mov_b32_e32 v0, v150
	s_waitcnt lgkmcnt(0)
	v_mov_b32_e32 v1, v150
	v_mov_b32_e32 v2, v150
	v_mov_b32_e32 v3, v150
	v_mov_b32_e32 v6, v150
	v_mov_b32_e32 v7, v150
	v_mov_b32_e32 v8, v150
	v_mov_b32_e32 v9, v150
	v_mov_b32_e32 v18, v150
	v_mov_b32_e32 v19, v150
	v_mov_b32_e32 v20, v150
	v_mov_b32_e32 v21, v150
	v_mov_b32_e32 v22, v150
	v_mov_b32_e32 v23, v150
	v_mov_b32_e32 v24, v150
	v_mov_b32_e32 v25, v150
	v_mov_b32_e32 v34, v150
	v_mov_b32_e32 v35, v150
	v_mov_b32_e32 v36, v150
	v_mov_b32_e32 v37, v150
	v_mov_b32_e32 v38, v150
	v_mov_b32_e32 v39, v150
	v_mov_b32_e32 v40, v150
	v_mov_b32_e32 v41, v150
	v_mov_b32_e32 v50, v150
	v_mov_b32_e32 v51, v150
	v_mov_b32_e32 v52, v150
	v_mov_b32_e32 v53, v150
	v_mov_b32_e32 v54, v150
	v_mov_b32_e32 v55, v150
	v_mov_b32_e32 v56, v150
	v_mov_b32_e32 v57, v150
	v_mov_b32_e32 v10, v150
	v_mov_b32_e32 v11, v150
	v_mov_b32_e32 v12, v150
	v_mov_b32_e32 v13, v150
	v_mov_b32_e32 v14, v150
	v_mov_b32_e32 v15, v150
	v_mov_b32_e32 v16, v150
	v_mov_b32_e32 v17, v150
	v_mov_b32_e32 v26, v150
	v_mov_b32_e32 v27, v150
	v_mov_b32_e32 v28, v150
	v_mov_b32_e32 v29, v150
	v_mov_b32_e32 v30, v150
	v_mov_b32_e32 v31, v150
	v_mov_b32_e32 v32, v150
	v_mov_b32_e32 v33, v150
	v_mov_b32_e32 v42, v150
	v_mov_b32_e32 v43, v150
	v_mov_b32_e32 v44, v150
	v_mov_b32_e32 v45, v150
	v_mov_b32_e32 v46, v150
	v_mov_b32_e32 v47, v150
	v_mov_b32_e32 v48, v150
	v_mov_b32_e32 v49, v150
	v_mov_b32_e32 v58, v150
	v_mov_b32_e32 v59, v150
	v_mov_b32_e32 v60, v150
	v_mov_b32_e32 v61, v150
	v_mov_b32_e32 v62, v150
	v_mov_b32_e32 v63, v150
	v_mov_b32_e32 v64, v150
	v_mov_b32_e32 v65, v150
	v_mov_b32_e32 v66, v150
	v_mov_b32_e32 v67, v150
	v_mov_b32_e32 v68, v150
	v_mov_b32_e32 v69, v150
	v_mov_b32_e32 v70, v150
	v_mov_b32_e32 v71, v150
	v_mov_b32_e32 v72, v150
	v_mov_b32_e32 v73, v150
	s_nop 0
	v_mov_b32_e32 v82, v150
	v_mov_b32_e32 v83, v150
	v_mov_b32_e32 v84, v150
	v_mov_b32_e32 v85, v150
	v_mov_b32_e32 v86, v150
	v_mov_b32_e32 v87, v150
	v_mov_b32_e32 v88, v150
	v_mov_b32_e32 v89, v150
	v_mov_b32_e32 v98, v150
	v_mov_b32_e32 v99, v150
	v_mov_b32_e32 v100, v150
	v_mov_b32_e32 v101, v150
	v_mov_b32_e32 v102, v150
	v_mov_b32_e32 v103, v150
	v_mov_b32_e32 v104, v150
	v_mov_b32_e32 v105, v150
	v_mov_b32_e32 v114, v150
	v_mov_b32_e32 v115, v150
	v_mov_b32_e32 v116, v150
	v_mov_b32_e32 v117, v150
	v_mov_b32_e32 v118, v150
	v_mov_b32_e32 v119, v150
	v_mov_b32_e32 v120, v150
	v_mov_b32_e32 v121, v150
	v_mov_b32_e32 v74, v150
	v_mov_b32_e32 v75, v150
	v_mov_b32_e32 v76, v150
	v_mov_b32_e32 v77, v150
	v_mov_b32_e32 v78, v150
	v_mov_b32_e32 v79, v150
	v_mov_b32_e32 v80, v150
	v_mov_b32_e32 v81, v150
	v_mov_b32_e32 v90, v150
	v_mov_b32_e32 v91, v150
	v_mov_b32_e32 v92, v150
	v_mov_b32_e32 v93, v150
	v_mov_b32_e32 v94, v150
	v_mov_b32_e32 v95, v150
	v_mov_b32_e32 v96, v150
	v_mov_b32_e32 v97, v150
	v_mov_b32_e32 v106, v150
	v_mov_b32_e32 v107, v150
	v_mov_b32_e32 v108, v150
	v_mov_b32_e32 v109, v150
	v_mov_b32_e32 v110, v150
	v_mov_b32_e32 v111, v150
	v_mov_b32_e32 v112, v150
	v_mov_b32_e32 v113, v150
	v_mov_b32_e32 v122, v150
	v_mov_b32_e32 v123, v150
	v_mov_b32_e32 v124, v150
	v_mov_b32_e32 v125, v150
	v_mov_b32_e32 v126, v150
	v_mov_b32_e32 v127, v150
	v_mov_b32_e32 v128, v150
	v_mov_b32_e32 v129, v150
.LBB1_23:
	ds_read_b128 v[142:145], v153
	ds_read_b128 v[146:149], v153 offset:1024
	ds_read_b128 v[158:161], v153 offset:2048
	ds_read_b128 v[162:165], v153 offset:3072
	s_add_u32 s20, s16, 0xfffc0080
	s_addc_u32 s21, s17, -1
	s_cmp_eq_u32 s70, 12
	s_cselect_b32 s23, s1, s21
	s_cselect_b32 s22, s19, s20
	s_cselect_b32 s21, s9, s65
	s_cselect_b32 s20, s24, s25
	v_lshl_add_u64 v[208:209], s[16:17], 0, v[140:141]
	s_add_i32 m0, s31, 0xc000
	ds_read_b128 v[166:169], v154
	ds_read_b128 v[176:179], v154 offset:1024
	ds_read_b128 v[180:183], v154 offset:2048
	ds_read_b128 v[184:187], v154 offset:3072
	ds_read_b128 v[188:191], v154 offset:4096
	ds_read_b128 v[194:197], v154 offset:5120
	ds_read_b128 v[200:203], v154 offset:6144
	ds_read_b128 v[204:207], v154 offset:7168
	global_load_lds_dwordx4 v[208:209], off
	v_lshl_add_u64 v[208:209], s[16:17], 0, v[138:139]
	s_add_i32 m0, s31, 0xe000
	s_nop 0
	global_load_lds_dwordx4 v[208:209], off
	s_waitcnt lgkmcnt(8)
	s_barrier
	s_waitcnt lgkmcnt(0)
	s_setprio 1
	s_waitcnt lgkmcnt(0)
	v_mfma_f32_16x16x32_bf16 v[126:129], v[142:145], v[166:169], v[126:129]
	v_mfma_f32_16x16x32_bf16 v[122:125], v[158:161], v[166:169], v[122:125]
	v_mfma_f32_16x16x32_bf16 v[110:113], v[142:145], v[180:183], v[110:113]
	v_mfma_f32_16x16x32_bf16 v[106:109], v[158:161], v[180:183], v[106:109]
	v_mfma_f32_16x16x32_bf16 v[94:97], v[142:145], v[188:191], v[94:97]
	v_mfma_f32_16x16x32_bf16 v[90:93], v[158:161], v[188:191], v[90:93]
	v_mfma_f32_16x16x32_bf16 v[78:81], v[142:145], v[200:203], v[78:81]
	v_mfma_f32_16x16x32_bf16 v[74:77], v[158:161], v[200:203], v[74:77]
	v_mfma_f32_16x16x32_bf16 v[126:129], v[146:149], v[176:179], v[126:129]
	v_mfma_f32_16x16x32_bf16 v[122:125], v[162:165], v[176:179], v[122:125]
	v_mfma_f32_16x16x32_bf16 v[110:113], v[146:149], v[184:187], v[110:113]
	v_mfma_f32_16x16x32_bf16 v[106:109], v[162:165], v[184:187], v[106:109]
	v_mfma_f32_16x16x32_bf16 v[94:97], v[146:149], v[194:197], v[94:97]
	v_mfma_f32_16x16x32_bf16 v[90:93], v[162:165], v[194:197], v[90:93]
	v_mfma_f32_16x16x32_bf16 v[78:81], v[146:149], v[204:207], v[78:81]
	v_mfma_f32_16x16x32_bf16 v[74:77], v[162:165], v[204:207], v[74:77]
	s_setprio 0
	s_barrier
; #define PG8_STAGE(bufoff, gbase, voff) do { _Pragma("unroll") for (int _i = 0; _i < 2; ++_i) \
;         __builtin_amdgcn_global_load_lds((const unsigned*)((const char*)(gbase) + (voff)[_i]), (LAS unsigned*)(lds + (bufoff) + ldsw + _i * 8192), 16, 0, 0); } while (0)
; #define PG8_LDA(dst, b, h) do { _Pragma("unroll") for (int m = 0; m < 4; ++m) _Pragma("unroll") for (int k = 0; k < 2; ++k) dst[m][k] = *(const LAS bf16x8*)(lds + PG8_SA(b, h) + aoff + m * 2048 + k * 1024); } while (0)
; #define PG8_LDB(dst, b, h) do { _Pragma("unroll") for (int n = 0; n < 2; ++n) _Pragma("unroll") for (int k = 0; k < 2; ++k) dst[n][k] = *(const LAS bf16x8*)(lds + PG8_SB(b, h) + boff + n * 2048 + k * 1024); } while (0)
; #define PG8_WAIT_V(n) asm volatile("s_waitcnt vmcnt(" #n ")" ::: "memory")
; #define PG8_WAIT_L(n) asm volatile("s_waitcnt lgkmcnt(" #n ")" ::: "memory")
; #define PG8_BAR __builtin_amdgcn_s_barrier()
; template <class Epi, int KK, int LDA, int LDB, int NN, bool AGRP>
; __device__ __forceinline__ void gemm_phase(LAS unsigned char* lds, const bf16_t* gA, const bf16_t* gBt, int G_, int bid_, int tid) {
;     ...
;             PG8_LDB(B0, 0, 0); PG8_SCHED; PG8_LDA(At, 0, 0); PG8_STAGE(PG8_SA(1, 1), a1 + hstepA, voffA);
;             PG8_WAIT_L(8); PG8_BAR; PG8_WAIT_L(0); PG8_MMA(0, 0, At, B0); PG8_BAR; PG8_SCHED;
;             PG8_LDB(B1, 0, 1); PG8_STAGE(PG8_SB(0, 0), b2, voffB);
;             PG8_BAR; PG8_WAIT_L(0); PG8_MMA(0, 1, At, B1); PG8_BAR;
;             PG8_LDA(At, 0, 1); PG8_STAGE(PG8_SA(0, 0), a2, voffA);
;             PG8_BAR; PG8_WAIT_L(0); PG8_MMA(1, 0, At, B0); PG8_BAR; PG8_SCHED;
;             PG8_STAGE(PG8_SB(0, 1), b2 + hstepB, voffB);
;             PG8_WAIT_V(6); PG8_BAR; PG8_MMA(1, 1, At, B1); PG8_BAR;
;             PG8_LDB(B0, 1, 0); PG8_SCHED; PG8_LDA(At, 1, 0); PG8_STAGE(PG8_SA(0, 1), a2 + hstepA, voffA);
;             PG8_WAIT_L(8); PG8_BAR; PG8_WAIT_L(0); PG8_MMA(0, 0, At, B0); PG8_BAR; PG8_SCHED;
;             PG8_LDB(B1, 1, 1); PG8_STAGE(PG8_SB(1, 0), b3, voffB);
;             PG8_BAR; PG8_WAIT_L(0); PG8_MMA(0, 1, At, B1); PG8_BAR;
;             PG8_LDA(At, 1, 1); PG8_STAGE(PG8_SA(1, 0), a3, voffA);
;             PG8_BAR; PG8_WAIT_L(0); PG8_MMA(1, 0, At, B0); PG8_BAR; PG8_SCHED;
;             PG8_STAGE(PG8_SB(1, 1), b3 + hstepB, voffB);
;             PG8_WAIT_V(6); PG8_BAR; PG8_MMA(1, 1, At, B1); PG8_BAR;
	s_mov_b32 m0, s29
	v_lshl_add_u64 v[224:225], s[20:21], 0, v[134:135]
	ds_read_b128 v[208:211], v155
	ds_read_b128 v[212:215], v155 offset:1024
	ds_read_b128 v[216:219], v155 offset:2048
	ds_read_b128 v[220:223], v155 offset:3072
	global_load_lds_dwordx4 v[224:225], off
	v_lshl_add_u64 v[226:227], s[20:21], 0, v[130:131]
	s_mov_b32 m0, s30
	s_nop 0
	global_load_lds_dwordx4 v[226:227], off
	s_barrier
	s_waitcnt lgkmcnt(0)
	s_setprio 1
	s_waitcnt lgkmcnt(0)
	v_mfma_f32_16x16x32_bf16 v[118:121], v[208:211], v[166:169], v[118:121]
	v_mfma_f32_16x16x32_bf16 v[114:117], v[216:219], v[166:169], v[114:117]
	v_mfma_f32_16x16x32_bf16 v[102:105], v[208:211], v[180:183], v[102:105]
	v_mfma_f32_16x16x32_bf16 v[98:101], v[216:219], v[180:183], v[98:101]
	v_mfma_f32_16x16x32_bf16 v[86:89], v[208:211], v[188:191], v[86:89]
	v_mfma_f32_16x16x32_bf16 v[82:85], v[216:219], v[188:191], v[82:85]
	v_mfma_f32_16x16x32_bf16 v[70:73], v[208:211], v[200:203], v[70:73]
	v_mfma_f32_16x16x32_bf16 v[66:69], v[216:219], v[200:203], v[66:69]
	v_mfma_f32_16x16x32_bf16 v[118:121], v[212:215], v[176:179], v[118:121]
	v_mfma_f32_16x16x32_bf16 v[114:117], v[220:223], v[176:179], v[114:117]
	v_mfma_f32_16x16x32_bf16 v[102:105], v[212:215], v[184:187], v[102:105]
	v_mfma_f32_16x16x32_bf16 v[98:101], v[220:223], v[184:187], v[98:101]
	v_mfma_f32_16x16x32_bf16 v[86:89], v[212:215], v[194:197], v[86:89]
	v_mfma_f32_16x16x32_bf16 v[82:85], v[220:223], v[194:197], v[82:85]
	v_mfma_f32_16x16x32_bf16 v[70:73], v[212:215], v[204:207], v[70:73]
	v_mfma_f32_16x16x32_bf16 v[66:69], v[220:223], v[204:207], v[66:69]
	s_setprio 0
	s_mov_b32 m0, s31
	v_lshl_add_u64 v[228:229], s[22:23], 0, v[136:137]
	s_barrier
	ds_read_b128 v[166:169], v154 offset:16384
	ds_read_b128 v[176:179], v154 offset:17408
	ds_read_b128 v[180:183], v154 offset:18432
	ds_read_b128 v[184:187], v154 offset:19456
	ds_read_b128 v[188:191], v154 offset:20480
	ds_read_b128 v[194:197], v154 offset:21504
	ds_read_b128 v[200:203], v154 offset:22528
	ds_read_b128 v[204:207], v154 offset:23552
	global_load_lds_dwordx4 v[228:229], off
	v_lshl_add_u64 v[230:231], s[22:23], 0, v[132:133]
	s_mov_b32 m0, s34
	s_nop 0
	global_load_lds_dwordx4 v[230:231], off
	s_barrier
	s_waitcnt lgkmcnt(0)
	s_setprio 1
	s_waitcnt lgkmcnt(0)
	v_mfma_f32_16x16x32_bf16 v[62:65], v[142:145], v[166:169], v[62:65]
	v_mfma_f32_16x16x32_bf16 v[58:61], v[158:161], v[166:169], v[58:61]
	v_mfma_f32_16x16x32_bf16 v[46:49], v[142:145], v[180:183], v[46:49]
	v_mfma_f32_16x16x32_bf16 v[42:45], v[158:161], v[180:183], v[42:45]
	v_mfma_f32_16x16x32_bf16 v[30:33], v[142:145], v[188:191], v[30:33]
	v_mfma_f32_16x16x32_bf16 v[26:29], v[158:161], v[188:191], v[26:29]
	v_mfma_f32_16x16x32_bf16 v[14:17], v[142:145], v[200:203], v[14:17]
	v_mfma_f32_16x16x32_bf16 v[10:13], v[158:161], v[200:203], v[10:13]
	v_mfma_f32_16x16x32_bf16 v[62:65], v[146:149], v[176:179], v[62:65]
	v_mfma_f32_16x16x32_bf16 v[58:61], v[162:165], v[176:179], v[58:61]
	v_mfma_f32_16x16x32_bf16 v[46:49], v[146:149], v[184:187], v[46:49]
	v_mfma_f32_16x16x32_bf16 v[42:45], v[162:165], v[184:187], v[42:45]
	v_mfma_f32_16x16x32_bf16 v[30:33], v[146:149], v[194:197], v[30:33]
	v_mfma_f32_16x16x32_bf16 v[26:29], v[162:165], v[194:197], v[26:29]
	v_mfma_f32_16x16x32_bf16 v[14:17], v[146:149], v[204:207], v[14:17]
	v_mfma_f32_16x16x32_bf16 v[10:13], v[162:165], v[204:207], v[10:13]
	s_setprio 0
	s_barrier
	s_add_u32 s66, s20, 0x40000
	s_addc_u32 s67, s21, 0
	s_mov_b32 m0, s35
	v_lshl_add_u64 v[142:143], s[66:67], 0, v[134:135]
	global_load_lds_dwordx4 v[142:143], off
	v_lshl_add_u64 v[142:143], s[66:67], 0, v[130:131]
	s_mov_b32 m0, s36
	s_nop 0
	global_load_lds_dwordx4 v[142:143], off
	s_waitcnt vmcnt(6)
	s_barrier
	s_setprio 1
	v_mfma_f32_16x16x32_bf16 v[54:57], v[208:211], v[166:169], v[54:57]
	v_mfma_f32_16x16x32_bf16 v[50:53], v[216:219], v[166:169], v[50:53]
	v_mfma_f32_16x16x32_bf16 v[38:41], v[208:211], v[180:183], v[38:41]
	v_mfma_f32_16x16x32_bf16 v[34:37], v[216:219], v[180:183], v[34:37]
	v_mfma_f32_16x16x32_bf16 v[22:25], v[208:211], v[188:191], v[22:25]
	v_mfma_f32_16x16x32_bf16 v[18:21], v[216:219], v[188:191], v[18:21]
	v_mfma_f32_16x16x32_bf16 v[6:9], v[208:211], v[200:203], v[6:9]
	v_mfma_f32_16x16x32_bf16 v[0:3], v[216:219], v[200:203], v[0:3]
	v_mfma_f32_16x16x32_bf16 v[54:57], v[212:215], v[176:179], v[54:57]
	v_mfma_f32_16x16x32_bf16 v[50:53], v[220:223], v[176:179], v[50:53]
	v_mfma_f32_16x16x32_bf16 v[38:41], v[212:215], v[184:187], v[38:41]
	v_mfma_f32_16x16x32_bf16 v[34:37], v[220:223], v[184:187], v[34:37]
	v_mfma_f32_16x16x32_bf16 v[22:25], v[212:215], v[194:197], v[22:25]
	v_mfma_f32_16x16x32_bf16 v[18:21], v[220:223], v[194:197], v[18:21]
	v_mfma_f32_16x16x32_bf16 v[6:9], v[212:215], v[204:207], v[6:9]
	v_mfma_f32_16x16x32_bf16 v[0:3], v[220:223], v[204:207], v[0:3]
	s_setprio 0
	s_barrier
	ds_read_b128 v[142:145], v156
	ds_read_b128 v[146:149], v156 offset:1024
	ds_read_b128 v[158:161], v156 offset:2048
	ds_read_b128 v[162:165], v156 offset:3072
	s_add_u32 s22, s22, 0x40000
	s_addc_u32 s23, s23, 0
	s_mov_b32 m0, s37
	v_lshl_add_u64 v[208:209], s[22:23], 0, v[136:137]
	ds_read_b128 v[166:169], v154 offset:32768
	ds_read_b128 v[176:179], v154 offset:33792
	ds_read_b128 v[180:183], v154 offset:34816
	ds_read_b128 v[184:187], v154 offset:35840
	ds_read_b128 v[188:191], v154 offset:36864
	ds_read_b128 v[194:197], v154 offset:37888
	ds_read_b128 v[200:203], v154 offset:38912
	ds_read_b128 v[204:207], v154 offset:39936
	global_load_lds_dwordx4 v[208:209], off
	v_lshl_add_u64 v[208:209], s[22:23], 0, v[132:133]
	s_mov_b32 m0, s39
	s_nop 0
	global_load_lds_dwordx4 v[208:209], off
	s_waitcnt lgkmcnt(8)
	s_barrier
; #define PG8_STAGE(bufoff, gbase, voff) do { _Pragma("unroll") for (int _i = 0; _i < 2; ++_i) \
;         __builtin_amdgcn_global_load_lds((const unsigned*)((const char*)(gbase) + (voff)[_i]), (LAS unsigned*)(lds + (bufoff) + ldsw + _i * 8192), 16, 0, 0); } while (0)
; #define PG8_LDA(dst, b, h) do { _Pragma("unroll") for (int m = 0; m < 4; ++m) _Pragma("unroll") for (int k = 0; k < 2; ++k) dst[m][k] = *(const LAS bf16x8*)(lds + PG8_SA(b, h) + aoff + m * 2048 + k * 1024); } while (0)
; #define PG8_LDB(dst, b, h) do { _Pragma("unroll") for (int n = 0; n < 2; ++n) _Pragma("unroll") for (int k = 0; k < 2; ++k) dst[n][k] = *(const LAS bf16x8*)(lds + PG8_SB(b, h) + boff + n * 2048 + k * 1024); } while (0)
; #define PG8_WAIT_V(n) asm volatile("s_waitcnt vmcnt(" #n ")" ::: "memory")
; #define PG8_WAIT_L(n) asm volatile("s_waitcnt lgkmcnt(" #n ")" ::: "memory")
; #define PG8_BAR __builtin_amdgcn_s_barrier()
; template <class Epi, int KK, int LDA, int LDB, int NN, bool AGRP>
; __device__ __forceinline__ void gemm_phase(LAS unsigned char* lds, const bf16_t* gA, const bf16_t* gBt, int G_, int bid_, int tid) {
;     ...
;             PG8_LDB(B0, 0, 0); PG8_SCHED; PG8_LDA(At, 0, 0); PG8_STAGE(PG8_SA(1, 1), a1 + hstepA, voffA);
;             PG8_WAIT_L(8); PG8_BAR; PG8_WAIT_L(0); PG8_MMA(0, 0, At, B0); PG8_BAR; PG8_SCHED;
;             PG8_LDB(B1, 0, 1); PG8_STAGE(PG8_SB(0, 0), b2, voffB);
;             PG8_BAR; PG8_WAIT_L(0); PG8_MMA(0, 1, At, B1); PG8_BAR;
;             PG8_LDA(At, 0, 1); PG8_STAGE(PG8_SA(0, 0), a2, voffA);
;             PG8_BAR; PG8_WAIT_L(0); PG8_MMA(1, 0, At, B0); PG8_BAR; PG8_SCHED;
;             PG8_STAGE(PG8_SB(0, 1), b2 + hstepB, voffB);
;             PG8_WAIT_V(6); PG8_BAR; PG8_MMA(1, 1, At, B1); PG8_BAR;
;             PG8_LDB(B0, 1, 0); PG8_SCHED; PG8_LDA(At, 1, 0); PG8_STAGE(PG8_SA(0, 1), a2 + hstepA, voffA);
;             PG8_WAIT_L(8); PG8_BAR; PG8_WAIT_L(0); PG8_MMA(0, 0, At, B0); PG8_BAR; PG8_SCHED;
;             PG8_LDB(B1, 1, 1); PG8_STAGE(PG8_SB(1, 0), b3, voffB);
;             PG8_BAR; PG8_WAIT_L(0); PG8_MMA(0, 1, At, B1); PG8_BAR;
;             PG8_LDA(At, 1, 1); PG8_STAGE(PG8_SA(1, 0), a3, voffA);
;             PG8_BAR; PG8_WAIT_L(0); PG8_MMA(1, 0, At, B0); PG8_BAR; PG8_SCHED;
;             PG8_STAGE(PG8_SB(1, 1), b3 + hstepB, voffB);
;             PG8_WAIT_V(6); PG8_BAR; PG8_MMA(1, 1, At, B1); PG8_BAR;
	s_waitcnt lgkmcnt(0)
	s_setprio 1
	s_waitcnt lgkmcnt(0)
	v_mfma_f32_16x16x32_bf16 v[126:129], v[142:145], v[166:169], v[126:129]
	v_mfma_f32_16x16x32_bf16 v[122:125], v[158:161], v[166:169], v[122:125]
	v_mfma_f32_16x16x32_bf16 v[110:113], v[142:145], v[180:183], v[110:113]
	v_mfma_f32_16x16x32_bf16 v[106:109], v[158:161], v[180:183], v[106:109]
	v_mfma_f32_16x16x32_bf16 v[94:97], v[142:145], v[188:191], v[94:97]
	v_mfma_f32_16x16x32_bf16 v[90:93], v[158:161], v[188:191], v[90:93]
	v_mfma_f32_16x16x32_bf16 v[78:81], v[142:145], v[200:203], v[78:81]
	v_mfma_f32_16x16x32_bf16 v[74:77], v[158:161], v[200:203], v[74:77]
	v_mfma_f32_16x16x32_bf16 v[126:129], v[146:149], v[176:179], v[126:129]
	v_mfma_f32_16x16x32_bf16 v[122:125], v[162:165], v[176:179], v[122:125]
	v_mfma_f32_16x16x32_bf16 v[110:113], v[146:149], v[184:187], v[110:113]
	v_mfma_f32_16x16x32_bf16 v[106:109], v[162:165], v[184:187], v[106:109]
	v_mfma_f32_16x16x32_bf16 v[94:97], v[146:149], v[194:197], v[94:97]
	v_mfma_f32_16x16x32_bf16 v[90:93], v[162:165], v[194:197], v[90:93]
	v_mfma_f32_16x16x32_bf16 v[78:81], v[146:149], v[204:207], v[78:81]
	v_mfma_f32_16x16x32_bf16 v[74:77], v[162:165], v[204:207], v[74:77]
	s_setprio 0
	s_barrier
	s_mov_b32 m0, s43
	v_lshl_add_u64 v[224:225], v[224:225], 0, s[76:77]
	ds_read_b128 v[208:211], v157
	ds_read_b128 v[212:215], v157 offset:1024
	ds_read_b128 v[216:219], v157 offset:2048
	ds_read_b128 v[220:223], v157 offset:3072
	global_load_lds_dwordx4 v[224:225], off
	v_lshl_add_u64 v[224:225], v[226:227], 0, s[76:77]
	s_mov_b32 m0, s44
	s_nop 0
	global_load_lds_dwordx4 v[224:225], off
	s_barrier
	s_waitcnt lgkmcnt(0)
	s_setprio 1
	s_waitcnt lgkmcnt(0)
	v_mfma_f32_16x16x32_bf16 v[118:121], v[208:211], v[166:169], v[118:121]
	v_mfma_f32_16x16x32_bf16 v[114:117], v[216:219], v[166:169], v[114:117]
	v_mfma_f32_16x16x32_bf16 v[102:105], v[208:211], v[180:183], v[102:105]
	v_mfma_f32_16x16x32_bf16 v[98:101], v[216:219], v[180:183], v[98:101]
	v_mfma_f32_16x16x32_bf16 v[86:89], v[208:211], v[188:191], v[86:89]
	v_mfma_f32_16x16x32_bf16 v[82:85], v[216:219], v[188:191], v[82:85]
	v_mfma_f32_16x16x32_bf16 v[70:73], v[208:211], v[200:203], v[70:73]
	v_mfma_f32_16x16x32_bf16 v[66:69], v[216:219], v[200:203], v[66:69]
	v_mfma_f32_16x16x32_bf16 v[118:121], v[212:215], v[176:179], v[118:121]
	v_mfma_f32_16x16x32_bf16 v[114:117], v[220:223], v[176:179], v[114:117]
	v_mfma_f32_16x16x32_bf16 v[102:105], v[212:215], v[184:187], v[102:105]
	v_mfma_f32_16x16x32_bf16 v[98:101], v[220:223], v[184:187], v[98:101]
	v_mfma_f32_16x16x32_bf16 v[86:89], v[212:215], v[194:197], v[86:89]
	v_mfma_f32_16x16x32_bf16 v[82:85], v[220:223], v[194:197], v[82:85]
	v_mfma_f32_16x16x32_bf16 v[70:73], v[212:215], v[204:207], v[70:73]
	v_mfma_f32_16x16x32_bf16 v[66:69], v[220:223], v[204:207], v[66:69]
	s_setprio 0
	s_mov_b32 m0, s45
	v_lshl_add_u64 v[224:225], v[228:229], 0, s[76:77]
	s_barrier
	ds_read_b128 v[166:169], v154 offset:49152
	ds_read_b128 v[176:179], v154 offset:50176
	ds_read_b128 v[180:183], v154 offset:51200
	ds_read_b128 v[184:187], v154 offset:52224
	ds_read_b128 v[188:191], v154 offset:53248
	ds_read_b128 v[194:197], v154 offset:54272
	ds_read_b128 v[200:203], v154 offset:55296
	ds_read_b128 v[204:207], v154 offset:56320
	global_load_lds_dwordx4 v[224:225], off
	v_lshl_add_u64 v[224:225], v[230:231], 0, s[76:77]
	s_mov_b32 m0, s46
	s_nop 0
	global_load_lds_dwordx4 v[224:225], off
	s_barrier
	s_waitcnt lgkmcnt(0)
	s_setprio 1
	s_waitcnt lgkmcnt(0)
	v_mfma_f32_16x16x32_bf16 v[62:65], v[142:145], v[166:169], v[62:65]
	v_mfma_f32_16x16x32_bf16 v[58:61], v[158:161], v[166:169], v[58:61]
	v_mfma_f32_16x16x32_bf16 v[46:49], v[142:145], v[180:183], v[46:49]
	v_mfma_f32_16x16x32_bf16 v[42:45], v[158:161], v[180:183], v[42:45]
	v_mfma_f32_16x16x32_bf16 v[30:33], v[142:145], v[188:191], v[30:33]
	v_mfma_f32_16x16x32_bf16 v[26:29], v[158:161], v[188:191], v[26:29]
	v_mfma_f32_16x16x32_bf16 v[14:17], v[142:145], v[200:203], v[14:17]
	v_mfma_f32_16x16x32_bf16 v[10:13], v[158:161], v[200:203], v[10:13]
	v_mfma_f32_16x16x32_bf16 v[62:65], v[146:149], v[176:179], v[62:65]
	v_mfma_f32_16x16x32_bf16 v[58:61], v[162:165], v[176:179], v[58:61]
	v_mfma_f32_16x16x32_bf16 v[46:49], v[146:149], v[184:187], v[46:49]
	v_mfma_f32_16x16x32_bf16 v[42:45], v[162:165], v[184:187], v[42:45]
	v_mfma_f32_16x16x32_bf16 v[30:33], v[146:149], v[194:197], v[30:33]
	v_mfma_f32_16x16x32_bf16 v[26:29], v[162:165], v[194:197], v[26:29]
	v_mfma_f32_16x16x32_bf16 v[14:17], v[146:149], v[204:207], v[14:17]
	v_mfma_f32_16x16x32_bf16 v[10:13], v[162:165], v[204:207], v[10:13]
	s_setprio 0
	s_barrier
	s_add_u32 s20, s20, 0x40080
	s_addc_u32 s21, s21, 0
	s_mov_b32 m0, s47
	v_lshl_add_u64 v[142:143], s[20:21], 0, v[134:135]
	global_load_lds_dwordx4 v[142:143], off
	v_lshl_add_u64 v[142:143], s[20:21], 0, v[130:131]
	s_mov_b32 m0, s48
	s_nop 0
	global_load_lds_dwordx4 v[142:143], off
	s_waitcnt vmcnt(6)
	s_barrier
	s_setprio 1
	v_mfma_f32_16x16x32_bf16 v[54:57], v[208:211], v[166:169], v[54:57]
	v_mfma_f32_16x16x32_bf16 v[50:53], v[216:219], v[166:169], v[50:53]
	v_mfma_f32_16x16x32_bf16 v[38:41], v[208:211], v[180:183], v[38:41]
	v_mfma_f32_16x16x32_bf16 v[34:37], v[216:219], v[180:183], v[34:37]
	v_mfma_f32_16x16x32_bf16 v[22:25], v[208:211], v[188:191], v[22:25]
	v_mfma_f32_16x16x32_bf16 v[18:21], v[216:219], v[188:191], v[18:21]
	v_mfma_f32_16x16x32_bf16 v[6:9], v[208:211], v[200:203], v[6:9]
	v_mfma_f32_16x16x32_bf16 v[0:3], v[216:219], v[200:203], v[0:3]
	v_mfma_f32_16x16x32_bf16 v[54:57], v[212:215], v[176:179], v[54:57]
	v_mfma_f32_16x16x32_bf16 v[50:53], v[220:223], v[176:179], v[50:53]
	v_mfma_f32_16x16x32_bf16 v[38:41], v[212:215], v[184:187], v[38:41]
	v_mfma_f32_16x16x32_bf16 v[34:37], v[220:223], v[184:187], v[34:37]
	v_mfma_f32_16x16x32_bf16 v[22:25], v[212:215], v[194:197], v[22:25]
	v_mfma_f32_16x16x32_bf16 v[18:21], v[220:223], v[194:197], v[18:21]
	v_mfma_f32_16x16x32_bf16 v[6:9], v[212:215], v[204:207], v[6:9]
	v_mfma_f32_16x16x32_bf16 v[0:3], v[220:223], v[204:207], v[0:3]
	s_setprio 0
	s_add_i32 s70, s70, 2
	s_add_u32 s25, s25, 0x100
	s_addc_u32 s65, s65, 0
	s_add_u32 s16, s16, 0x100
	s_addc_u32 s17, s17, 0
	s_cmp_gt_u32 s70, 13
	s_barrier
;     __device__ __forceinline__ void operator()(const f32x4 (&acc)[2][2][4][2], const Unit& u, int wr, int wc, int fr, int fq, LAS unsigned char* lds) const {
;         const float* rss_in = EPP(const float*, 1); const float* bias = EPP(const float*, 2);
;         const bf16_t* base = EPP(const bf16_t*, 3);
;         bf16_t* hb = EPP(bf16_t*, 5); float* rss_out = EPP(float*, 6); const bf16_t* pp = EPP(const bf16_t*, 7); const float scale = __uint_as_float((unsigned)ep64(lds, 8));
;         const int row0 = u.pm * BM + wr * 64 + fr, col0 = u.pn * BM + wc * 32 + 8 * fq;
;         f32x4 bv[2][2];
; #pragma unroll
;         for (int bj = 0; bj < 2; ++bj)
; #pragma unroll
;             for (int n = 0; n < 2; ++n) bv[bj][n] = (MODE == 0 && bias) ? *(const f32x4*)(bias + col0 + bj * HALF + 4 * n) : (f32x4){0.f, 0.f, 0.f, 0.f};
; #pragma unroll
;         for (int ai = 0; ai < 2; ++ai)
; #pragma unroll
;             for (int m = 0; m < 4; ++m) { const int row = row0 + ai * HALF + m * 16; const size_t off = (size_t)row * D + col0;
;                 float rs = 1.0f; if (MODE == 1) rs = rstd_of4(rss_in, row, fq);
;                 float ss = 0.f;
; #pragma unroll
;                 for (int bj = 0; bj < 2; ++bj) { const size_t o = off + bj * HALF; const u32x4 bw = *(const u32x4*)(base + o);
;                     const float bs[8] = {bflo(bw.x), bfhi(bw.x), bflo(bw.y), bfhi(bw.y), bflo(bw.z), bfhi(bw.z), bflo(bw.w), bfhi(bw.w)};
;                     float hn[8];
;                     if (MODE == 0) {
; #pragma unroll
;                         for (int n = 0; n < 2; ++n)
; #pragma unroll
;                             for (int e = 0; e < 4; ++e) hn[4 * n + e] = bs[4 * n + e] + (acc[ai][bj][m][n][e] + bv[bj][n][e]) * scale;
;                     } else { const u32x4 pw = *(const u32x4*)(pp + o);
;                         const float pv[8] = {bflo(pw.x), bfhi(pw.x), bflo(pw.y), bfhi(pw.y), bflo(pw.z), bfhi(pw.z), bflo(pw.w), bfhi(pw.w)};
; #pragma unroll
;                         for (int n = 0; n < 2; ++n)
; #pragma unroll
;                             for (int e = 0; e < 4; ++e) hn[4 * n + e] = bs[4 * n + e] + fast_sigmoid(acc[ai][bj][m][n][e] * rs) * pv[4 * n + e]; }
;                     u32x4 w; w.x = cvt_pk_bf16(hn[0], hn[1]); w.y = cvt_pk_bf16(hn[2], hn[3]); w.z = cvt_pk_bf16(hn[4], hn[5]); w.w = cvt_pk_bf16(hn[6], hn[7]); *(u32x4*)(hb + o) = w;
	s_cbranch_scc0 .LBB1_23
	v_mov_b32_e32 v142, s49
	ds_read_b32 v142, v142
	v_mov_b32_e32 v143, s50
	ds_read_b32 v148, v143
	v_mov_b32_e32 v143, s51
	ds_read_b32 v143, v143
	s_waitcnt lgkmcnt(0)
	v_mov_b32_e32 v143, s52
	ds_read_b32 v143, v143
	s_waitcnt lgkmcnt(0)
	v_mov_b32_e32 v143, s53
	v_mov_b32_e32 v144, s54
	v_readfirstlane_b32 s20, v142
	v_mov_b32_e32 v142, s55
	ds_read_b32 v143, v143
	ds_read_b32 v144, v144
	ds_read_b32 v175, v142
	v_mov_b32_e32 v142, s56
	ds_read_b32 v184, v142
	v_mov_b32_e32 v142, s57
	ds_read_b32 v185, v142
	v_mov_b32_e32 v142, s58
	ds_read_b32 v186, v142
	v_mov_b32_e32 v142, s59
	ds_read_b32 v176, v142
	v_mov_b32_e32 v142, s60
	ds_read_b32 v177, v142
	v_mov_b32_e32 v142, s61
	ds_read_b32 v142, v142
	s_waitcnt lgkmcnt(0)
	v_mov_b32_e32 v142, s62
	v_readfirstlane_b32 s17, v144
	ds_read_b32 v142, v142
	v_lshl_add_u32 v144, s18, 8, v151
	s_waitcnt lgkmcnt(0)
	v_lshl_or_b32 v142, s41, 8, v152
	v_ashrrev_i32_e32 v145, 31, v144
	v_readfirstlane_b32 s16, v143
	v_ashrrev_i32_e32 v143, 31, v142
	v_lshlrev_b64 v[146:147], 10, v[144:145]
	v_lshl_add_u64 v[146:147], v[146:147], 0, v[142:143]
	v_readfirstlane_b32 s21, v148
	v_lshlrev_b64 v[168:169], 1, v[146:147]
	v_lshlrev_b64 v[148:149], 6, v[144:145]
	v_lshl_add_u64 v[146:147], s[20:21], 0, v[4:5]
	v_lshl_add_u64 v[180:181], s[16:17], 0, v[168:169]
	v_lshl_add_u64 v[158:159], v[146:147], 0, v[148:149]
	global_load_dwordx4 v[160:163], v[180:181], off
	global_load_dwordx4 v[164:167], v[158:159], off
	v_readfirstlane_b32 s22, v176
	v_readfirstlane_b32 s23, v177
	v_and_b32_e32 v158, 64, v171
	v_xor_b32_e32 v145, 16, v171
	v_lshl_add_u64 v[182:183], s[22:23], 0, v[168:169]
	global_load_dwordx4 v[176:179], v[182:183], off
	global_load_dwordx4 v[200:203], v[180:181], off offset:256
	global_load_dwordx4 v[204:207], v[182:183], off offset:256
	v_add_u32_e32 v158, 64, v158
	v_xor_b32_e32 v159, 32, v171
	v_cmp_lt_i32_e32 vcc, v145, v158
	v_readfirstlane_b32 s18, v175
	v_readfirstlane_b32 s19, v184
	v_cndmask_b32_e32 v145, v171, v145, vcc
	v_cmp_lt_i32_e32 vcc, v159, v158
	v_lshlrev_b32_e32 v158, 2, v145
	v_readfirstlane_b32 s20, v185
	v_cndmask_b32_e32 v159, v171, v159, vcc
	v_lshlrev_b32_e32 v145, 2, v159
	v_readfirstlane_b32 s21, v186
	s_waitcnt vmcnt(0)
	v_lshlrev_b32_e32 v159, 16, v160
	v_and_b32_e32 v175, 0xffff0000, v160
	v_lshlrev_b32_e32 v184, 16, v161
	v_and_b32_e32 v187, 0xffff0000, v161
	v_mov_b32_e32 v160, v165
	v_mov_b32_e32 v161, v166
	v_mov_b32_e32 v165, v167
	v_pk_add_f32 v[160:161], v[160:161], v[164:165]
	v_lshlrev_b32_e32 v164, 16, v163
	v_add_f32_e32 v160, v160, v161
	v_mov_b32_e32 v161, v160
	s_nop 1
	v_permlane16_swap_b32 v161, v160
	v_lshlrev_b32_e32 v165, 16, v176
	v_and_b32_e32 v166, 0xffff0000, v176
	v_lshlrev_b32_e32 v167, 16, v177
	v_and_b32_e32 v176, 0xffff0000, v177
	s_waitcnt lgkmcnt(0)
	v_add_f32_e32 v160, v160, v161
	v_mov_b32_e32 v161, v160
	s_nop 1
	v_permlane32_swap_b32 v161, v160
	v_lshlrev_b32_e32 v177, 16, v178
	v_lshlrev_b32_e32 v188, 16, v162
	v_and_b32_e32 v162, 0xffff0000, v162
	v_and_b32_e32 v163, 0xffff0000, v163
	s_waitcnt lgkmcnt(0)
	v_add_f32_e32 v160, v160, v161
	v_fmamk_f32 v160, v160, 0x3a800000, v173
	v_mul_f32_e32 v161, 0x4b800000, v160
	v_cmp_gt_f32_e32 vcc, s64, v160
	s_nop 1
	v_cndmask_b32_e32 v160, v160, v161, vcc
	v_rsq_f32_e32 v160, v160
	v_and_b32_e32 v161, 0xffff0000, v178
	v_lshlrev_b32_e32 v178, 16, v179
	v_and_b32_e32 v179, 0xffff0000, v179
	v_mul_f32_e32 v189, 0x45800000, v160
	v_cndmask_b32_e32 v189, v160, v189, vcc
	v_mul_f32_e32 v124, v124, v189
	v_mul_f32_e32 v126, v126, v189
	v_mul_f32_e32 v127, v127, v189
	v_mul_f32_e32 v128, v128, v189
	v_mul_f32_e32 v129, v129, v189
	v_mul_f32_e32 v122, v122, v189
	v_mul_f32_e32 v123, v123, v189
	v_mul_f32_e32 v124, 0xbfb8aa3b, v124
	v_mul_f32_e32 v125, v125, v189
	v_mul_f32_e32 v126, 0xbfb8aa3b, v126
	v_mul_f32_e32 v127, 0xbfb8aa3b, v127
	v_mul_f32_e32 v128, 0xbfb8aa3b, v128
	v_mul_f32_e32 v129, 0xbfb8aa3b, v129
	v_mul_f32_e32 v122, 0xbfb8aa3b, v122
	v_mul_f32_e32 v123, 0xbfb8aa3b, v123
	v_exp_f32_e32 v124, v124
	v_mul_f32_e32 v125, 0xbfb8aa3b, v125
	v_exp_f32_e32 v126, v126
	v_exp_f32_e32 v127, v127
	v_exp_f32_e32 v128, v128
	v_exp_f32_e32 v129, v129
	v_exp_f32_e32 v122, v122
	v_exp_f32_e32 v123, v123
	v_exp_f32_e32 v125, v125
	v_add_f32_e32 v124, 1.0, v124
	v_add_f32_e32 v126, 1.0, v126
	v_add_f32_e32 v127, 1.0, v127
	v_add_f32_e32 v128, 1.0, v128
	v_add_f32_e32 v129, 1.0, v129
	v_add_f32_e32 v122, 1.0, v122
	v_add_f32_e32 v123, 1.0, v123
	v_rcp_f32_e32 v124, v124
	v_add_f32_e32 v125, 1.0, v125
	v_rcp_f32_e32 v126, v126
	v_rcp_f32_e32 v127, v127
	v_rcp_f32_e32 v128, v128
	v_rcp_f32_e32 v129, v129
	v_rcp_f32_e32 v122, v122
	v_rcp_f32_e32 v123, v123
	v_rcp_f32_e32 v125, v125
	v_fmac_f32_e32 v164, v124, v178
	v_fmac_f32_e32 v159, v126, v165
	v_fmac_f32_e32 v175, v127, v166
	v_fmac_f32_e32 v184, v128, v167
	v_fmac_f32_e32 v187, v129, v176
	v_fmac_f32_e32 v188, v122, v177
	v_fmac_f32_e32 v162, v123, v161
	v_fmac_f32_e32 v163, v125, v179
	v_cvt_pk_bf16_f32 v122, v159, v175
	v_cvt_pk_bf16_f32 v123, v184, v187
	v_cvt_pk_bf16_f32 v124, v188, v162
	v_cvt_pk_bf16_f32 v125, v164, v163
	v_lshl_add_u64 v[164:165], s[18:19], 0, v[168:169]
	global_store_dwordx4 v[164:165], v[122:125], off
	v_mov_b32_e32 v126, v200
	v_mov_b32_e32 v127, v201
	v_mov_b32_e32 v128, v202
	v_mov_b32_e32 v129, v203
	v_mov_b32_e32 v160, v204
	v_mov_b32_e32 v161, v205
	v_mov_b32_e32 v162, v206
	v_mov_b32_e32 v163, v207
	v_mul_f32_e32 v118, v118, v189
	v_mul_f32_e32 v119, v119, v189
	v_mul_f32_e32 v115, v115, v189
	v_mul_f32_e32 v116, v116, v189
	v_mul_f32_e32 v120, v120, v189
	v_mul_f32_e32 v121, v121, v189
; __device__ __forceinline__ unsigned cvt_pk_bf16(float lo, float hi) { unsigned r; asm volatile("v_cvt_pk_bf16_f32 %0, %1, %2" : "=v"(r) : "v"(lo), "v"(hi)); return r; }
; __device__ __forceinline__ float bflo(unsigned w) { return __uint_as_float(w << 16); }
;     __device__ __forceinline__ void operator()(const f32x4 (&acc)[2][2][4][2], const Unit& u, int wr, int wc, int fr, int fq, LAS unsigned char* lds) const {
;     ...
;             for (int m = 0; m < 4; ++m) { const int row = row0 + ai * HALF + m * 16; const size_t off = (size_t)row * D + col0;
;                 float rs = 1.0f; if (MODE == 1) rs = rstd_of4(rss_in, row, fq);
;                 float ss = 0.f;
; #pragma unroll
;                 for (int bj = 0; bj < 2; ++bj) { const size_t o = off + bj * HALF; const u32x4 bw = *(const u32x4*)(base + o);
;                     const float bs[8] = {bflo(bw.x), bfhi(bw.x), bflo(bw.y), bfhi(bw.y), bflo(bw.z), bfhi(bw.z), bflo(bw.w), bfhi(bw.w)};
;                     float hn[8];
;                     if (MODE == 0) {
; #pragma unroll
;                         for (int n = 0; n < 2; ++n)
; #pragma unroll
;                             for (int e = 0; e < 4; ++e) hn[4 * n + e] = bs[4 * n + e] + (acc[ai][bj][m][n][e] + bv[bj][n][e]) * scale;
;                     } else { const u32x4 pw = *(const u32x4*)(pp + o);
;                         const float pv[8] = {bflo(pw.x), bfhi(pw.x), bflo(pw.y), bfhi(pw.y), bflo(pw.z), bfhi(pw.z), bflo(pw.w), bfhi(pw.w)};
; #pragma unroll
;                         for (int n = 0; n < 2; ++n)
; #pragma unroll
;                             for (int e = 0; e < 4; ++e) hn[4 * n + e] = bs[4 * n + e] + fast_sigmoid(acc[ai][bj][m][n][e] * rs) * pv[4 * n + e]; }
;                     u32x4 w; w.x = cvt_pk_bf16(hn[0], hn[1]); w.y = cvt_pk_bf16(hn[2], hn[3]); w.z = cvt_pk_bf16(hn[4], hn[5]); w.w = cvt_pk_bf16(hn[6], hn[7]); *(u32x4*)(hb + o) = w;
;                     const float hr[8] = {bflo(w.x), bfhi(w.x), bflo(w.y), bfhi(w.y), bflo(w.z), bfhi(w.z), bflo(w.w), bfhi(w.w)};
;                     ss += ((hr[0] * hr[0] + hr[1] * hr[1]) + (hr[2] * hr[2] + hr[3] * hr[3])) + ((hr[4] * hr[4] + hr[5] * hr[5]) + (hr[6] * hr[6] + hr[7] * hr[7])); }
;                 ss += __shfl_xor(ss, 16); ss += __shfl_xor(ss, 32);
;                 if (fq == 0) rss_out[(size_t)row * 16 + u.pn * 4 + wc] = ss; }
	v_mul_f32_e32 v114, v114, v189
	v_mul_f32_e32 v118, 0xbfb8aa3b, v118
	v_mul_f32_e32 v119, 0xbfb8aa3b, v119
	v_mul_f32_e32 v115, 0xbfb8aa3b, v115
	v_mul_f32_e32 v116, 0xbfb8aa3b, v116
	v_mul_f32_e32 v117, v117, v189
	v_mul_f32_e32 v120, 0xbfb8aa3b, v120
	v_mul_f32_e32 v121, 0xbfb8aa3b, v121
	v_mul_f32_e32 v114, 0xbfb8aa3b, v114
	v_exp_f32_e32 v118, v118
	v_exp_f32_e32 v119, v119
	v_exp_f32_e32 v115, v115
	v_exp_f32_e32 v116, v116
	v_mul_f32_e32 v117, 0xbfb8aa3b, v117
	v_exp_f32_e32 v120, v120
	v_exp_f32_e32 v121, v121
	v_exp_f32_e32 v114, v114
	v_exp_f32_e32 v117, v117
	v_add_f32_e32 v118, 1.0, v118
	v_add_f32_e32 v119, 1.0, v119
	v_lshlrev_b32_e32 v159, 16, v122
	v_and_b32_e32 v122, 0xffff0000, v122
	v_lshlrev_b32_e32 v166, 16, v123
	v_and_b32_e32 v123, 0xffff0000, v123
	v_lshlrev_b32_e32 v167, 16, v124
	v_and_b32_e32 v124, 0xffff0000, v124
	v_lshlrev_b32_e32 v168, 16, v125
	v_and_b32_e32 v125, 0xffff0000, v125
	v_add_f32_e32 v115, 1.0, v115
	v_add_f32_e32 v116, 1.0, v116
	v_add_f32_e32 v120, 1.0, v120
	v_add_f32_e32 v121, 1.0, v121
	v_rcp_f32_e32 v118, v118
	v_rcp_f32_e32 v119, v119
	v_mul_f32_e32 v122, v122, v122
	v_mul_f32_e32 v123, v123, v123
	v_mul_f32_e32 v124, v124, v124
	v_mul_f32_e32 v125, v125, v125
	v_add_f32_e32 v114, 1.0, v114
	v_rcp_f32_e32 v115, v115
	v_rcp_f32_e32 v116, v116
	v_add_f32_e32 v117, 1.0, v117
	v_rcp_f32_e32 v120, v120
	v_rcp_f32_e32 v121, v121
	v_fmac_f32_e32 v122, v159, v159
	v_fmac_f32_e32 v123, v166, v166
	v_fmac_f32_e32 v124, v167, v167
	v_fmac_f32_e32 v125, v168, v168
	v_rcp_f32_e32 v114, v114
	v_rcp_f32_e32 v117, v117
	v_add_f32_e32 v122, v122, v123
	v_add_f32_e32 v123, v124, v125
	v_add_f32_e32 v122, v122, v123
	s_nop 0
	v_lshlrev_b32_e32 v123, 16, v126
	v_and_b32_e32 v124, 0xffff0000, v126
	v_lshlrev_b32_e32 v125, 16, v127
	v_and_b32_e32 v126, 0xffff0000, v127
	v_lshlrev_b32_e32 v127, 16, v128
	v_and_b32_e32 v128, 0xffff0000, v128
	v_lshlrev_b32_e32 v159, 16, v129
	s_nop 0
	v_lshlrev_b32_e32 v166, 16, v160
	v_and_b32_e32 v160, 0xffff0000, v160
	v_lshlrev_b32_e32 v168, 16, v162
	v_and_b32_e32 v162, 0xffff0000, v162
	v_lshlrev_b32_e32 v169, 16, v163
	v_and_b32_e32 v129, 0xffff0000, v129
	v_lshlrev_b32_e32 v167, 16, v161
	v_and_b32_e32 v161, 0xffff0000, v161
	v_and_b32_e32 v163, 0xffff0000, v163
	v_fmac_f32_e32 v123, v118, v166
	v_fmac_f32_e32 v124, v119, v160
	v_fmac_f32_e32 v128, v115, v162
	v_fmac_f32_e32 v159, v116, v169
	v_cvt_pk_bf16_f32 v116, v123, v124
	v_fmac_f32_e32 v125, v120, v167
	v_and_b32_e32 v115, 0xffff0000, v116
	v_fmac_f32_e32 v126, v121, v161
	v_fmac_f32_e32 v127, v114, v168
	v_fmac_f32_e32 v129, v117, v163
	v_cvt_pk_bf16_f32 v117, v125, v126
	v_lshlrev_b32_e32 v114, 16, v116
	v_and_b32_e32 v121, 0xffff0000, v117
	v_mul_f32_e32 v115, v115, v115
	v_lshlrev_b32_e32 v120, 16, v117
	v_fmac_f32_e32 v115, v114, v114
	v_mul_f32_e32 v114, v121, v121
	v_cvt_pk_bf16_f32 v118, v127, v128
	v_cvt_pk_bf16_f32 v119, v159, v129
	v_fmac_f32_e32 v114, v120, v120
	v_and_b32_e32 v124, 0xffff0000, v118
	v_and_b32_e32 v126, 0xffff0000, v119
	v_lshlrev_b32_e32 v123, 16, v118
	v_lshlrev_b32_e32 v125, 16, v119
	v_add_f32_e32 v114, v115, v114
	v_mul_f32_e32 v115, v124, v124
	v_mul_f32_e32 v120, v126, v126
	v_fmac_f32_e32 v115, v123, v123
	v_fmac_f32_e32 v120, v125, v125
	v_add_f32_e32 v115, v115, v120
	v_add_f32_e32 v114, v114, v115
	v_add_f32_e32 v114, v122, v114
	v_mov_b32_e32 v115, v114
	s_nop 1
	v_permlane16_swap_b32 v115, v114
	global_store_dwordx4 v[164:165], v[116:119], off offset:256
	s_waitcnt lgkmcnt(0)
	v_add_f32_e32 v114, v114, v115
	v_mov_b32_e32 v115, v114
	s_nop 1
	v_permlane32_swap_b32 v115, v114
	s_and_saveexec_b64 s[24:25], s[6:7]
	s_cbranch_execz .LBB1_26
	s_lshl_b32 s66, s41, 2
	v_lshl_add_u64 v[116:117], s[20:21], 0, v[148:149]
	s_ashr_i32 s67, s66, 31
	v_lshl_add_u64 v[116:117], s[66:67], 2, v[116:117]
	s_lshl_b32 s74, s40, 2
	v_lshl_add_u64 v[116:117], v[116:117], 0, s[74:75]
	s_waitcnt lgkmcnt(0)
	v_add_f32_e32 v114, v114, v115
	global_store_dword v[116:117], v114, off
.LBB1_26:
	s_or_b64 exec, exec, s[24:25]
	v_or_b32_e32 v114, 16, v144
	s_waitcnt lgkmcnt(0)
	v_ashrrev_i32_e32 v115, 31, v114
	v_lshlrev_b64 v[116:117], 10, v[114:115]
	v_lshlrev_b64 v[114:115], 6, v[114:115]
	v_lshl_add_u64 v[120:121], v[116:117], 0, v[142:143]
	v_lshl_add_u64 v[116:117], v[146:147], 0, v[114:115]
	global_load_dwordx4 v[116:119], v[116:117], off
	v_lshlrev_b64 v[120:121], 1, v[120:121]
	v_lshl_add_u64 v[216:217], s[16:17], 0, v[120:121]
	v_lshl_add_u64 v[218:219], s[22:23], 0, v[120:121]
	global_load_dwordx4 v[200:203], v[216:217], off
	global_load_dwordx4 v[204:207], v[218:219], off
	global_load_dwordx4 v[208:211], v[216:217], off offset:256
	global_load_dwordx4 v[212:215], v[218:219], off offset:256
	s_waitcnt vmcnt(0)
	v_mov_b32_e32 v122, v117
	v_mov_b32_e32 v123, v118
	v_mov_b32_e32 v117, v119
	v_pk_add_f32 v[116:117], v[122:123], v[116:117]
	v_lshl_add_u64 v[118:119], s[22:23], 0, v[120:121]
	v_add_f32_e32 v116, v116, v117
	v_mov_b32_e32 v117, v116
	s_nop 1
	v_permlane16_swap_b32 v117, v116
	s_waitcnt lgkmcnt(0)
	v_add_f32_e32 v116, v116, v117
	v_mov_b32_e32 v117, v116
	s_nop 1
	v_permlane32_swap_b32 v117, v116
	s_waitcnt lgkmcnt(0)
; __device__ __forceinline__ float rstd_of4(const float* rss, int row, int fq) {
;     const f32x4 a = *(const f32x4*)(rss + (size_t)row * 16 + 4 * fq); float s = (a[0] + a[1]) + (a[2] + a[3]);
;     s += __shfl_xor(s, 16); s += __shfl_xor(s, 32);
;     return rsqrtf(s * (1.0f / 1024.0f) + EPS); }
;     __device__ __forceinline__ void operator()(const f32x4 (&acc)[2][2][4][2], const Unit& u, int wr, int wc, int fr, int fq, LAS unsigned char* lds) const {
;     ...
;             for (int m = 0; m < 4; ++m) { const int row = row0 + ai * HALF + m * 16; const size_t off = (size_t)row * D + col0;
;                 float rs = 1.0f; if (MODE == 1) rs = rstd_of4(rss_in, row, fq);
;                 float ss = 0.f;
; #pragma unroll
;                 for (int bj = 0; bj < 2; ++bj) { const size_t o = off + bj * HALF; const u32x4 bw = *(const u32x4*)(base + o);
;                     const float bs[8] = {bflo(bw.x), bfhi(bw.x), bflo(bw.y), bfhi(bw.y), bflo(bw.z), bfhi(bw.z), bflo(bw.w), bfhi(bw.w)};
;                     float hn[8];
;                     if (MODE == 0) {
; #pragma unroll
;                         for (int n = 0; n < 2; ++n)
; #pragma unroll
;                             for (int e = 0; e < 4; ++e) hn[4 * n + e] = bs[4 * n + e] + (acc[ai][bj][m][n][e] + bv[bj][n][e]) * scale;
;                     } else { const u32x4 pw = *(const u32x4*)(pp + o);
;                         const float pv[8] = {bflo(pw.x), bfhi(pw.x), bflo(pw.y), bfhi(pw.y), bflo(pw.z), bfhi(pw.z), bflo(pw.w), bfhi(pw.w)};
; #pragma unroll
;                         for (int n = 0; n < 2; ++n)
; #pragma unroll
;                             for (int e = 0; e < 4; ++e) hn[4 * n + e] = bs[4 * n + e] + fast_sigmoid(acc[ai][bj][m][n][e] * rs) * pv[4 * n + e]; }
;                     u32x4 w; w.x = cvt_pk_bf16(hn[0], hn[1]); w.y = cvt_pk_bf16(hn[2], hn[3]); w.z = cvt_pk_bf16(hn[4], hn[5]); w.w = cvt_pk_bf16(hn[6], hn[7]); *(u32x4*)(hb + o) = w;
;                     const float hr[8] = {bflo(w.x), bfhi(w.x), bflo(w.y), bfhi(w.y), bflo(w.z), bfhi(w.z), bflo(w.w), bfhi(w.w)};
;                     ss += ((hr[0] * hr[0] + hr[1] * hr[1]) + (hr[2] * hr[2] + hr[3] * hr[3])) + ((hr[4] * hr[4] + hr[5] * hr[5]) + (hr[6] * hr[6] + hr[7] * hr[7])); }
;                 ss += __shfl_xor(ss, 16); ss += __shfl_xor(ss, 32);
;                 if (fq == 0) rss_out[(size_t)row * 16 + u.pn * 4 + wc] = ss; }
	v_add_f32_e32 v116, v116, v117
	v_fmamk_f32 v116, v116, 0x3a800000, v173
	v_cmp_gt_f32_e32 vcc, s64, v116
	v_mul_f32_e32 v117, 0x4b800000, v116
	s_nop 0
	v_cndmask_b32_e32 v116, v116, v117, vcc
	v_rsq_f32_e32 v116, v116
	s_nop 0
	v_mul_f32_e32 v117, 0x45800000, v116
	v_cndmask_b32_e32 v122, v116, v117, vcc
	v_lshl_add_u64 v[116:117], s[16:17], 0, v[120:121]
	v_mov_b32_e32 v124, v200
	v_mov_b32_e32 v125, v201
	v_mov_b32_e32 v126, v202
	v_mov_b32_e32 v127, v203
	v_mul_f32_e32 v110, v110, v122
	v_mul_f32_e32 v110, 0xbfb8aa3b, v110
	v_mul_f32_e32 v106, v106, v122
	v_exp_f32_e32 v110, v110
	v_mul_f32_e32 v106, 0xbfb8aa3b, v106
	v_exp_f32_e32 v106, v106
	v_mul_f32_e32 v102, v102, v122
	v_add_f32_e32 v110, 1.0, v110
	v_rcp_f32_e32 v110, v110
	v_add_f32_e32 v106, 1.0, v106
	v_rcp_f32_e32 v106, v106
	v_mul_f32_e32 v98, v98, v122
	v_mul_f32_e32 v102, 0xbfb8aa3b, v102
	v_mul_f32_e32 v98, 0xbfb8aa3b, v98
	v_exp_f32_e32 v102, v102
	v_exp_f32_e32 v98, v98
	v_add_f32_e32 v102, 1.0, v102
	v_add_f32_e32 v98, 1.0, v98
	v_rcp_f32_e32 v102, v102
	v_rcp_f32_e32 v98, v98
	s_nop 0
	v_lshlrev_b32_e32 v123, 16, v124
	v_and_b32_e32 v128, 0xffff0000, v124
	v_lshlrev_b32_e32 v129, 16, v125
	v_and_b32_e32 v148, 0xffff0000, v125
	v_lshlrev_b32_e32 v149, 16, v126
	v_and_b32_e32 v159, 0xffff0000, v126
	v_lshlrev_b32_e32 v160, 16, v127
	v_and_b32_e32 v161, 0xffff0000, v127
	v_mov_b32_e32 v124, v204
	v_mov_b32_e32 v125, v205
	v_mov_b32_e32 v126, v206
	v_mov_b32_e32 v127, v207
	s_nop 0
	v_lshlrev_b32_e32 v162, 16, v124
	v_lshlrev_b32_e32 v164, 16, v126
	v_fmac_f32_e32 v123, v110, v162
	v_mul_f32_e32 v110, v111, v122
	v_mul_f32_e32 v110, 0xbfb8aa3b, v110
	v_fmac_f32_e32 v149, v106, v164
	v_mul_f32_e32 v106, v107, v122
	v_exp_f32_e32 v110, v110
	v_mul_f32_e32 v106, 0xbfb8aa3b, v106
	v_exp_f32_e32 v106, v106
	v_and_b32_e32 v124, 0xffff0000, v124
	v_add_f32_e32 v110, 1.0, v110
	v_rcp_f32_e32 v110, v110
	v_add_f32_e32 v106, 1.0, v106
	v_rcp_f32_e32 v106, v106
	v_and_b32_e32 v126, 0xffff0000, v126
	v_fmac_f32_e32 v128, v110, v124
	v_mul_f32_e32 v110, v112, v122
	v_mul_f32_e32 v110, 0xbfb8aa3b, v110
	v_fmac_f32_e32 v159, v106, v126
	v_mul_f32_e32 v106, v108, v122
	v_exp_f32_e32 v110, v110
	v_mul_f32_e32 v106, 0xbfb8aa3b, v106
	v_exp_f32_e32 v106, v106
	v_lshlrev_b32_e32 v163, 16, v125
	v_add_f32_e32 v110, 1.0, v110
	v_rcp_f32_e32 v110, v110
	v_add_f32_e32 v106, 1.0, v106
	v_rcp_f32_e32 v106, v106
	v_lshlrev_b32_e32 v165, 16, v127
	v_fmac_f32_e32 v129, v110, v163
	v_mul_f32_e32 v110, v113, v122
	v_mul_f32_e32 v110, 0xbfb8aa3b, v110
	v_fmac_f32_e32 v160, v106, v165
	v_mul_f32_e32 v106, v109, v122
	v_exp_f32_e32 v110, v110
	v_mul_f32_e32 v106, 0xbfb8aa3b, v106
	v_exp_f32_e32 v106, v106
	v_and_b32_e32 v125, 0xffff0000, v125
	v_add_f32_e32 v110, 1.0, v110
	v_rcp_f32_e32 v110, v110
	v_add_f32_e32 v106, 1.0, v106
	v_rcp_f32_e32 v106, v106
	v_and_b32_e32 v127, 0xffff0000, v127
	v_fmac_f32_e32 v148, v110, v125
	v_lshl_add_u64 v[110:111], s[18:19], 0, v[120:121]
	v_fmac_f32_e32 v161, v106, v127
	v_cvt_pk_bf16_f32 v106, v123, v128
	v_cvt_pk_bf16_f32 v107, v129, v148
	v_cvt_pk_bf16_f32 v108, v149, v159
	v_cvt_pk_bf16_f32 v109, v160, v161
	global_store_dwordx4 v[110:111], v[106:109], off
	v_mov_b32_e32 v124, v208
	v_mov_b32_e32 v125, v209
	v_mov_b32_e32 v126, v210
	v_mov_b32_e32 v127, v211
	v_lshlrev_b32_e32 v112, 16, v106
	v_and_b32_e32 v106, 0xffff0000, v106
	v_lshlrev_b32_e32 v113, 16, v107
	v_and_b32_e32 v107, 0xffff0000, v107
	v_mul_f32_e32 v106, v106, v106
	v_mul_f32_e32 v107, v107, v107
	v_lshlrev_b32_e32 v120, 16, v108
	v_and_b32_e32 v108, 0xffff0000, v108
	v_lshlrev_b32_e32 v121, 16, v109
	v_and_b32_e32 v109, 0xffff0000, v109
	v_fmac_f32_e32 v106, v112, v112
	v_fmac_f32_e32 v107, v113, v113
	v_add_f32_e32 v106, v106, v107
	v_mul_f32_e32 v107, v108, v108
	v_mul_f32_e32 v108, v109, v109
	v_fmac_f32_e32 v107, v120, v120
	v_fmac_f32_e32 v108, v121, v121
	v_add_f32_e32 v107, v107, v108
	v_add_f32_e32 v106, v106, v107
	s_nop 0
	v_lshlrev_b32_e32 v107, 16, v124
	v_and_b32_e32 v108, 0xffff0000, v124
	v_lshlrev_b32_e32 v109, 16, v125
	v_and_b32_e32 v112, 0xffff0000, v125
	v_lshlrev_b32_e32 v113, 16, v126
	v_and_b32_e32 v116, 0xffff0000, v126
	v_lshlrev_b32_e32 v117, 16, v127
	v_and_b32_e32 v120, 0xffff0000, v127
	v_mov_b32_e32 v124, v212
	v_mov_b32_e32 v125, v213
	v_mov_b32_e32 v126, v214
	v_mov_b32_e32 v127, v215
	s_nop 0
	v_lshlrev_b32_e32 v118, 16, v124
	v_and_b32_e32 v119, 0xffff0000, v124
	v_lshlrev_b32_e32 v124, 16, v126
	v_fmac_f32_e32 v107, v102, v118
	v_mul_f32_e32 v102, v103, v122
	v_fmac_f32_e32 v113, v98, v124
	v_mul_f32_e32 v98, v99, v122
	v_mul_f32_e32 v102, 0xbfb8aa3b, v102
	v_mul_f32_e32 v98, 0xbfb8aa3b, v98
	v_exp_f32_e32 v102, v102
	v_exp_f32_e32 v98, v98
	v_lshlrev_b32_e32 v121, 16, v125
	v_and_b32_e32 v123, 0xffff0000, v125
	v_add_f32_e32 v102, 1.0, v102
	v_add_f32_e32 v98, 1.0, v98
	v_rcp_f32_e32 v102, v102
	v_rcp_f32_e32 v98, v98
	v_and_b32_e32 v125, 0xffff0000, v126
	v_lshlrev_b32_e32 v126, 16, v127
	v_fmac_f32_e32 v108, v102, v119
	v_mul_f32_e32 v102, v104, v122
	v_fmac_f32_e32 v116, v98, v125
	v_mul_f32_e32 v98, v100, v122
	v_mul_f32_e32 v102, 0xbfb8aa3b, v102
	v_mul_f32_e32 v98, 0xbfb8aa3b, v98
	v_exp_f32_e32 v102, v102
	v_exp_f32_e32 v98, v98
	v_and_b32_e32 v127, 0xffff0000, v127
	v_add_f32_e32 v102, 1.0, v102
	v_add_f32_e32 v98, 1.0, v98
	v_rcp_f32_e32 v102, v102
	v_rcp_f32_e32 v98, v98
	v_fmac_f32_e32 v109, v102, v121
	v_mul_f32_e32 v102, v105, v122
	v_fmac_f32_e32 v117, v98, v126
	v_mul_f32_e32 v98, v101, v122
	v_mul_f32_e32 v102, 0xbfb8aa3b, v102
	v_mul_f32_e32 v98, 0xbfb8aa3b, v98
	v_exp_f32_e32 v102, v102
	v_exp_f32_e32 v98, v98
	v_add_f32_e32 v102, 1.0, v102
	v_add_f32_e32 v98, 1.0, v98
	v_rcp_f32_e32 v102, v102
	v_rcp_f32_e32 v98, v98
	v_fmac_f32_e32 v112, v102, v123
	v_fmac_f32_e32 v120, v98, v127
	v_cvt_pk_bf16_f32 v98, v107, v108
	v_cvt_pk_bf16_f32 v99, v109, v112
	v_cvt_pk_bf16_f32 v100, v113, v116
	v_cvt_pk_bf16_f32 v101, v117, v120
	global_store_dwordx4 v[110:111], v[98:101], off offset:256
	v_lshlrev_b32_e32 v102, 16, v98
	v_lshlrev_b32_e32 v103, 16, v99
	v_and_b32_e32 v98, 0xffff0000, v98
	v_and_b32_e32 v99, 0xffff0000, v99
	v_mul_f32_e32 v98, v98, v98
	v_mul_f32_e32 v99, v99, v99
	v_lshlrev_b32_e32 v104, 16, v100
	v_and_b32_e32 v100, 0xffff0000, v100
	v_lshlrev_b32_e32 v105, 16, v101
	v_and_b32_e32 v101, 0xffff0000, v101
	v_fmac_f32_e32 v98, v102, v102
	v_fmac_f32_e32 v99, v103, v103
	v_add_f32_e32 v98, v98, v99
	v_mul_f32_e32 v99, v100, v100
	v_mul_f32_e32 v100, v101, v101
	v_fmac_f32_e32 v99, v104, v104
	v_fmac_f32_e32 v100, v105, v105
	v_add_f32_e32 v99, v99, v100
	v_add_f32_e32 v98, v98, v99
	v_add_f32_e32 v98, v106, v98
	v_mov_b32_e32 v99, v98
	s_nop 1
	v_permlane16_swap_b32 v99, v98
	s_waitcnt lgkmcnt(0)
	v_add_f32_e32 v98, v98, v99
	v_mov_b32_e32 v99, v98
	s_nop 1
	v_permlane32_swap_b32 v99, v98
	s_and_saveexec_b64 s[24:25], s[6:7]
	s_cbranch_execz .LBB1_28
; __device__ __forceinline__ float rstd_of4(const float* rss, int row, int fq) {
;     const f32x4 a = *(const f32x4*)(rss + (size_t)row * 16 + 4 * fq); float s = (a[0] + a[1]) + (a[2] + a[3]);
;     s += __shfl_xor(s, 16); s += __shfl_xor(s, 32);
;     return rsqrtf(s * (1.0f / 1024.0f) + EPS); }
;     __device__ __forceinline__ void operator()(const f32x4 (&acc)[2][2][4][2], const Unit& u, int wr, int wc, int fr, int fq, LAS unsigned char* lds) const {
;     ...
;             for (int m = 0; m < 4; ++m) { const int row = row0 + ai * HALF + m * 16; const size_t off = (size_t)row * D + col0;
;                 float rs = 1.0f; if (MODE == 1) rs = rstd_of4(rss_in, row, fq);
;                 float ss = 0.f;
; #pragma unroll
;                 for (int bj = 0; bj < 2; ++bj) { const size_t o = off + bj * HALF; const u32x4 bw = *(const u32x4*)(base + o);
;                     const float bs[8] = {bflo(bw.x), bfhi(bw.x), bflo(bw.y), bfhi(bw.y), bflo(bw.z), bfhi(bw.z), bflo(bw.w), bfhi(bw.w)};
;                     float hn[8];
;                     if (MODE == 0) {
; #pragma unroll
;                         for (int n = 0; n < 2; ++n)
; #pragma unroll
;                             for (int e = 0; e < 4; ++e) hn[4 * n + e] = bs[4 * n + e] + (acc[ai][bj][m][n][e] + bv[bj][n][e]) * scale;
;                     } else { const u32x4 pw = *(const u32x4*)(pp + o);
;                         const float pv[8] = {bflo(pw.x), bfhi(pw.x), bflo(pw.y), bfhi(pw.y), bflo(pw.z), bfhi(pw.z), bflo(pw.w), bfhi(pw.w)};
; #pragma unroll
;                         for (int n = 0; n < 2; ++n)
; #pragma unroll
;                             for (int e = 0; e < 4; ++e) hn[4 * n + e] = bs[4 * n + e] + fast_sigmoid(acc[ai][bj][m][n][e] * rs) * pv[4 * n + e]; }
;                     u32x4 w; w.x = cvt_pk_bf16(hn[0], hn[1]); w.y = cvt_pk_bf16(hn[2], hn[3]); w.z = cvt_pk_bf16(hn[4], hn[5]); w.w = cvt_pk_bf16(hn[6], hn[7]); *(u32x4*)(hb + o) = w;
;                     const float hr[8] = {bflo(w.x), bfhi(w.x), bflo(w.y), bfhi(w.y), bflo(w.z), bfhi(w.z), bflo(w.w), bfhi(w.w)};
;                     ss += ((hr[0] * hr[0] + hr[1] * hr[1]) + (hr[2] * hr[2] + hr[3] * hr[3])) + ((hr[4] * hr[4] + hr[5] * hr[5]) + (hr[6] * hr[6] + hr[7] * hr[7])); }
;                 ss += __shfl_xor(ss, 16); ss += __shfl_xor(ss, 32);
;                 if (fq == 0) rss_out[(size_t)row * 16 + u.pn * 4 + wc] = ss; }
	s_lshl_b32 s66, s41, 2
	v_lshl_add_u64 v[100:101], s[20:21], 0, v[114:115]
	s_ashr_i32 s67, s66, 31
	v_lshl_add_u64 v[100:101], s[66:67], 2, v[100:101]
	s_lshl_b32 s74, s40, 2
	v_lshl_add_u64 v[100:101], v[100:101], 0, s[74:75]
	s_waitcnt lgkmcnt(0)
	v_add_f32_e32 v98, v98, v99
	global_store_dword v[100:101], v98, off
.LBB1_28:
	s_or_b64 exec, exec, s[24:25]
	v_or_b32_e32 v98, 32, v144
	s_waitcnt lgkmcnt(0)
	v_ashrrev_i32_e32 v99, 31, v98
	v_lshlrev_b64 v[100:101], 10, v[98:99]
	v_lshlrev_b64 v[98:99], 6, v[98:99]
	v_lshl_add_u64 v[104:105], v[100:101], 0, v[142:143]
	v_lshl_add_u64 v[100:101], v[146:147], 0, v[98:99]
	global_load_dwordx4 v[100:103], v[100:101], off
	v_lshlrev_b64 v[104:105], 1, v[104:105]
	v_lshl_add_u64 v[216:217], s[16:17], 0, v[104:105]
	v_lshl_add_u64 v[218:219], s[22:23], 0, v[104:105]
	global_load_dwordx4 v[200:203], v[216:217], off
	global_load_dwordx4 v[204:207], v[218:219], off
	global_load_dwordx4 v[208:211], v[216:217], off offset:256
	global_load_dwordx4 v[212:215], v[218:219], off offset:256
	s_waitcnt vmcnt(0)
	v_mov_b32_e32 v106, v101
	v_mov_b32_e32 v107, v102
	v_mov_b32_e32 v101, v103
	v_pk_add_f32 v[100:101], v[106:107], v[100:101]
	v_lshl_add_u64 v[102:103], s[22:23], 0, v[104:105]
	v_add_f32_e32 v100, v100, v101
	v_mov_b32_e32 v101, v100
	s_nop 1
	v_permlane16_swap_b32 v101, v100
	s_waitcnt lgkmcnt(0)
	v_add_f32_e32 v100, v100, v101
	v_mov_b32_e32 v101, v100
	s_nop 1
	v_permlane32_swap_b32 v101, v100
	s_waitcnt lgkmcnt(0)
	v_add_f32_e32 v100, v100, v101
	v_fmamk_f32 v100, v100, 0x3a800000, v173
	v_cmp_gt_f32_e32 vcc, s64, v100
	v_mul_f32_e32 v101, 0x4b800000, v100
	s_nop 0
	v_cndmask_b32_e32 v100, v100, v101, vcc
	v_rsq_f32_e32 v100, v100
	s_nop 0
	v_mul_f32_e32 v101, 0x45800000, v100
	v_cndmask_b32_e32 v106, v100, v101, vcc
	v_lshl_add_u64 v[100:101], s[16:17], 0, v[104:105]
	v_mov_b32_e32 v108, v200
	v_mov_b32_e32 v109, v201
	v_mov_b32_e32 v110, v202
	v_mov_b32_e32 v111, v203
	v_mul_f32_e32 v94, v94, v106
	v_mul_f32_e32 v94, 0xbfb8aa3b, v94
	v_mul_f32_e32 v90, v90, v106
	v_exp_f32_e32 v94, v94
	v_mul_f32_e32 v90, 0xbfb8aa3b, v90
	v_exp_f32_e32 v90, v90
	v_mul_f32_e32 v86, v86, v106
	v_add_f32_e32 v94, 1.0, v94
	v_rcp_f32_e32 v94, v94
	v_add_f32_e32 v90, 1.0, v90
	v_rcp_f32_e32 v90, v90
	v_mul_f32_e32 v82, v82, v106
	v_mul_f32_e32 v86, 0xbfb8aa3b, v86
	v_mul_f32_e32 v82, 0xbfb8aa3b, v82
	v_exp_f32_e32 v86, v86
	v_exp_f32_e32 v82, v82
	v_add_f32_e32 v86, 1.0, v86
	v_add_f32_e32 v82, 1.0, v82
	v_rcp_f32_e32 v86, v86
	v_rcp_f32_e32 v82, v82
	s_nop 0
	v_lshlrev_b32_e32 v107, 16, v108
	v_and_b32_e32 v112, 0xffff0000, v108
	v_lshlrev_b32_e32 v113, 16, v109
	v_and_b32_e32 v114, 0xffff0000, v109
	v_lshlrev_b32_e32 v115, 16, v110
	v_and_b32_e32 v116, 0xffff0000, v110
	v_lshlrev_b32_e32 v117, 16, v111
	v_and_b32_e32 v118, 0xffff0000, v111
	v_mov_b32_e32 v108, v204
	v_mov_b32_e32 v109, v205
	v_mov_b32_e32 v110, v206
	v_mov_b32_e32 v111, v207
	s_nop 0
	v_lshlrev_b32_e32 v119, 16, v108
	v_lshlrev_b32_e32 v121, 16, v110
	v_fmac_f32_e32 v107, v94, v119
	v_mul_f32_e32 v94, v95, v106
	v_mul_f32_e32 v94, 0xbfb8aa3b, v94
	v_fmac_f32_e32 v115, v90, v121
	v_mul_f32_e32 v90, v91, v106
	v_exp_f32_e32 v94, v94
	v_mul_f32_e32 v90, 0xbfb8aa3b, v90
	v_exp_f32_e32 v90, v90
	v_and_b32_e32 v108, 0xffff0000, v108
	v_add_f32_e32 v94, 1.0, v94
	v_rcp_f32_e32 v94, v94
	v_add_f32_e32 v90, 1.0, v90
	v_rcp_f32_e32 v90, v90
	v_and_b32_e32 v110, 0xffff0000, v110
	v_fmac_f32_e32 v112, v94, v108
	v_mul_f32_e32 v94, v96, v106
	v_mul_f32_e32 v94, 0xbfb8aa3b, v94
	v_fmac_f32_e32 v116, v90, v110
	v_mul_f32_e32 v90, v92, v106
	v_exp_f32_e32 v94, v94
	v_mul_f32_e32 v90, 0xbfb8aa3b, v90
	v_exp_f32_e32 v90, v90
	v_lshlrev_b32_e32 v120, 16, v109
	v_add_f32_e32 v94, 1.0, v94
	v_rcp_f32_e32 v94, v94
	v_add_f32_e32 v90, 1.0, v90
	v_rcp_f32_e32 v90, v90
	v_lshlrev_b32_e32 v122, 16, v111
	v_fmac_f32_e32 v113, v94, v120
	v_mul_f32_e32 v94, v97, v106
	v_mul_f32_e32 v94, 0xbfb8aa3b, v94
	v_fmac_f32_e32 v117, v90, v122
	v_mul_f32_e32 v90, v93, v106
	v_exp_f32_e32 v94, v94
	v_mul_f32_e32 v90, 0xbfb8aa3b, v90
	v_exp_f32_e32 v90, v90
	v_and_b32_e32 v109, 0xffff0000, v109
	v_add_f32_e32 v94, 1.0, v94
	v_rcp_f32_e32 v94, v94
	v_add_f32_e32 v90, 1.0, v90
	v_rcp_f32_e32 v90, v90
	v_and_b32_e32 v111, 0xffff0000, v111
	v_fmac_f32_e32 v114, v94, v109
	v_lshl_add_u64 v[94:95], s[18:19], 0, v[104:105]
	v_fmac_f32_e32 v118, v90, v111
	v_cvt_pk_bf16_f32 v90, v107, v112
	v_cvt_pk_bf16_f32 v91, v113, v114
	v_cvt_pk_bf16_f32 v92, v115, v116
	v_cvt_pk_bf16_f32 v93, v117, v118
	global_store_dwordx4 v[94:95], v[90:93], off
	v_mov_b32_e32 v108, v208
	v_mov_b32_e32 v109, v209
	v_mov_b32_e32 v110, v210
	v_mov_b32_e32 v111, v211
	v_lshlrev_b32_e32 v96, 16, v90
	v_and_b32_e32 v90, 0xffff0000, v90
	v_lshlrev_b32_e32 v97, 16, v91
	v_and_b32_e32 v91, 0xffff0000, v91
	v_mul_f32_e32 v90, v90, v90
	v_mul_f32_e32 v91, v91, v91
	v_lshlrev_b32_e32 v104, 16, v92
	v_and_b32_e32 v92, 0xffff0000, v92
	v_lshlrev_b32_e32 v105, 16, v93
	v_and_b32_e32 v93, 0xffff0000, v93
	v_fmac_f32_e32 v90, v96, v96
	v_fmac_f32_e32 v91, v97, v97
	v_add_f32_e32 v90, v90, v91
	v_mul_f32_e32 v91, v92, v92
	v_mul_f32_e32 v92, v93, v93
	v_fmac_f32_e32 v91, v104, v104
	v_fmac_f32_e32 v92, v105, v105
	v_add_f32_e32 v91, v91, v92
	v_add_f32_e32 v90, v90, v91
	s_nop 0
	v_lshlrev_b32_e32 v91, 16, v108
	v_and_b32_e32 v92, 0xffff0000, v108
	v_lshlrev_b32_e32 v93, 16, v109
	v_and_b32_e32 v96, 0xffff0000, v109
	v_lshlrev_b32_e32 v97, 16, v110
	v_and_b32_e32 v100, 0xffff0000, v110
	v_lshlrev_b32_e32 v101, 16, v111
	v_and_b32_e32 v104, 0xffff0000, v111
	v_mov_b32_e32 v108, v212
	v_mov_b32_e32 v109, v213
	v_mov_b32_e32 v110, v214
; __device__ __forceinline__ float rstd_of4(const float* rss, int row, int fq) {
;     const f32x4 a = *(const f32x4*)(rss + (size_t)row * 16 + 4 * fq); float s = (a[0] + a[1]) + (a[2] + a[3]);
;     s += __shfl_xor(s, 16); s += __shfl_xor(s, 32);
;     return rsqrtf(s * (1.0f / 1024.0f) + EPS); }
;     __device__ __forceinline__ void operator()(const f32x4 (&acc)[2][2][4][2], const Unit& u, int wr, int wc, int fr, int fq, LAS unsigned char* lds) const {
;     ...
;             for (int m = 0; m < 4; ++m) { const int row = row0 + ai * HALF + m * 16; const size_t off = (size_t)row * D + col0;
;                 float rs = 1.0f; if (MODE == 1) rs = rstd_of4(rss_in, row, fq);
;                 float ss = 0.f;
; #pragma unroll
;                 for (int bj = 0; bj < 2; ++bj) { const size_t o = off + bj * HALF; const u32x4 bw = *(const u32x4*)(base + o);
;                     const float bs[8] = {bflo(bw.x), bfhi(bw.x), bflo(bw.y), bfhi(bw.y), bflo(bw.z), bfhi(bw.z), bflo(bw.w), bfhi(bw.w)};
;                     float hn[8];
;                     if (MODE == 0) {
; #pragma unroll
;                         for (int n = 0; n < 2; ++n)
; #pragma unroll
;                             for (int e = 0; e < 4; ++e) hn[4 * n + e] = bs[4 * n + e] + (acc[ai][bj][m][n][e] + bv[bj][n][e]) * scale;
;                     } else { const u32x4 pw = *(const u32x4*)(pp + o);
;                         const float pv[8] = {bflo(pw.x), bfhi(pw.x), bflo(pw.y), bfhi(pw.y), bflo(pw.z), bfhi(pw.z), bflo(pw.w), bfhi(pw.w)};
; #pragma unroll
;                         for (int n = 0; n < 2; ++n)
; #pragma unroll
;                             for (int e = 0; e < 4; ++e) hn[4 * n + e] = bs[4 * n + e] + fast_sigmoid(acc[ai][bj][m][n][e] * rs) * pv[4 * n + e]; }
;                     u32x4 w; w.x = cvt_pk_bf16(hn[0], hn[1]); w.y = cvt_pk_bf16(hn[2], hn[3]); w.z = cvt_pk_bf16(hn[4], hn[5]); w.w = cvt_pk_bf16(hn[6], hn[7]); *(u32x4*)(hb + o) = w;
;                     const float hr[8] = {bflo(w.x), bfhi(w.x), bflo(w.y), bfhi(w.y), bflo(w.z), bfhi(w.z), bflo(w.w), bfhi(w.w)};
;                     ss += ((hr[0] * hr[0] + hr[1] * hr[1]) + (hr[2] * hr[2] + hr[3] * hr[3])) + ((hr[4] * hr[4] + hr[5] * hr[5]) + (hr[6] * hr[6] + hr[7] * hr[7])); }
;                 ss += __shfl_xor(ss, 16); ss += __shfl_xor(ss, 32);
;                 if (fq == 0) rss_out[(size_t)row * 16 + u.pn * 4 + wc] = ss; }
	v_mov_b32_e32 v111, v215
	s_nop 0
	v_lshlrev_b32_e32 v102, 16, v108
	v_and_b32_e32 v103, 0xffff0000, v108
	v_lshlrev_b32_e32 v108, 16, v110
	v_fmac_f32_e32 v91, v86, v102
	v_mul_f32_e32 v86, v87, v106
	v_fmac_f32_e32 v97, v82, v108
	v_mul_f32_e32 v82, v83, v106
	v_mul_f32_e32 v86, 0xbfb8aa3b, v86
	v_mul_f32_e32 v82, 0xbfb8aa3b, v82
	v_exp_f32_e32 v86, v86
	v_exp_f32_e32 v82, v82
	v_lshlrev_b32_e32 v105, 16, v109
	v_and_b32_e32 v107, 0xffff0000, v109
	v_add_f32_e32 v86, 1.0, v86
	v_add_f32_e32 v82, 1.0, v82
	v_rcp_f32_e32 v86, v86
	v_rcp_f32_e32 v82, v82
	v_and_b32_e32 v109, 0xffff0000, v110
	v_lshlrev_b32_e32 v110, 16, v111
	v_fmac_f32_e32 v92, v86, v103
	v_mul_f32_e32 v86, v88, v106
	v_fmac_f32_e32 v100, v82, v109
	v_mul_f32_e32 v82, v84, v106
	v_mul_f32_e32 v86, 0xbfb8aa3b, v86
	v_mul_f32_e32 v82, 0xbfb8aa3b, v82
	v_exp_f32_e32 v86, v86
	v_exp_f32_e32 v82, v82
	v_and_b32_e32 v111, 0xffff0000, v111
	v_add_f32_e32 v86, 1.0, v86
	v_add_f32_e32 v82, 1.0, v82
	v_rcp_f32_e32 v86, v86
	v_rcp_f32_e32 v82, v82
	v_fmac_f32_e32 v93, v86, v105
	v_mul_f32_e32 v86, v89, v106
	v_fmac_f32_e32 v101, v82, v110
	v_mul_f32_e32 v82, v85, v106
	v_mul_f32_e32 v86, 0xbfb8aa3b, v86
	v_mul_f32_e32 v82, 0xbfb8aa3b, v82
	v_exp_f32_e32 v86, v86
	v_exp_f32_e32 v82, v82
	v_add_f32_e32 v86, 1.0, v86
	v_add_f32_e32 v82, 1.0, v82
	v_rcp_f32_e32 v86, v86
	v_rcp_f32_e32 v82, v82
	v_fmac_f32_e32 v96, v86, v107
	v_fmac_f32_e32 v104, v82, v111
	v_cvt_pk_bf16_f32 v82, v91, v92
	v_cvt_pk_bf16_f32 v83, v93, v96
	v_cvt_pk_bf16_f32 v84, v97, v100
	v_cvt_pk_bf16_f32 v85, v101, v104
	global_store_dwordx4 v[94:95], v[82:85], off offset:256
	v_lshlrev_b32_e32 v86, 16, v82
	v_lshlrev_b32_e32 v87, 16, v83
	v_and_b32_e32 v82, 0xffff0000, v82
	v_and_b32_e32 v83, 0xffff0000, v83
	v_mul_f32_e32 v82, v82, v82
	v_mul_f32_e32 v83, v83, v83
	v_lshlrev_b32_e32 v88, 16, v84
	v_and_b32_e32 v84, 0xffff0000, v84
	v_lshlrev_b32_e32 v89, 16, v85
	v_and_b32_e32 v85, 0xffff0000, v85
	v_fmac_f32_e32 v82, v86, v86
	v_fmac_f32_e32 v83, v87, v87
	v_add_f32_e32 v82, v82, v83
	v_mul_f32_e32 v83, v84, v84
	v_mul_f32_e32 v84, v85, v85
	v_fmac_f32_e32 v83, v88, v88
	v_fmac_f32_e32 v84, v89, v89
	v_add_f32_e32 v83, v83, v84
	v_add_f32_e32 v82, v82, v83
	v_add_f32_e32 v82, v90, v82
	v_mov_b32_e32 v83, v82
	s_nop 1
	v_permlane16_swap_b32 v83, v82
	s_waitcnt lgkmcnt(0)
	v_add_f32_e32 v82, v82, v83
	v_mov_b32_e32 v83, v82
	s_nop 1
	v_permlane32_swap_b32 v83, v82
	s_and_saveexec_b64 s[24:25], s[6:7]
	s_cbranch_execz .LBB1_30
	s_lshl_b32 s66, s41, 2
	v_lshl_add_u64 v[84:85], s[20:21], 0, v[98:99]
	s_ashr_i32 s67, s66, 31
	v_lshl_add_u64 v[84:85], s[66:67], 2, v[84:85]
	s_lshl_b32 s74, s40, 2
	v_lshl_add_u64 v[84:85], v[84:85], 0, s[74:75]
	s_waitcnt lgkmcnt(0)
	v_add_f32_e32 v82, v82, v83
	global_store_dword v[84:85], v82, off
.LBB1_30:
	s_or_b64 exec, exec, s[24:25]
	v_or_b32_e32 v82, 48, v144
	s_waitcnt lgkmcnt(0)
	v_ashrrev_i32_e32 v83, 31, v82
	v_lshlrev_b64 v[84:85], 10, v[82:83]
	v_lshlrev_b64 v[82:83], 6, v[82:83]
	v_lshl_add_u64 v[88:89], v[84:85], 0, v[142:143]
	v_lshl_add_u64 v[84:85], v[146:147], 0, v[82:83]
	global_load_dwordx4 v[84:87], v[84:85], off
	v_lshlrev_b64 v[88:89], 1, v[88:89]
	v_lshl_add_u64 v[216:217], s[16:17], 0, v[88:89]
	v_lshl_add_u64 v[218:219], s[22:23], 0, v[88:89]
	global_load_dwordx4 v[200:203], v[216:217], off
	global_load_dwordx4 v[204:207], v[218:219], off
	global_load_dwordx4 v[208:211], v[216:217], off offset:256
	global_load_dwordx4 v[212:215], v[218:219], off offset:256
	s_waitcnt vmcnt(0)
	v_mov_b32_e32 v90, v85
	v_mov_b32_e32 v91, v86
	v_mov_b32_e32 v85, v87
	v_pk_add_f32 v[84:85], v[90:91], v[84:85]
	v_lshl_add_u64 v[86:87], s[22:23], 0, v[88:89]
	v_add_f32_e32 v84, v84, v85
	v_mov_b32_e32 v85, v84
	s_nop 1
	v_permlane16_swap_b32 v85, v84
	s_waitcnt lgkmcnt(0)
	v_add_f32_e32 v84, v84, v85
	v_mov_b32_e32 v85, v84
	s_nop 1
	v_permlane32_swap_b32 v85, v84
	s_waitcnt lgkmcnt(0)
	v_add_f32_e32 v84, v84, v85
	v_fmamk_f32 v84, v84, 0x3a800000, v173
	v_cmp_gt_f32_e32 vcc, s64, v84
	v_mul_f32_e32 v85, 0x4b800000, v84
	s_nop 0
	v_cndmask_b32_e32 v84, v84, v85, vcc
	v_rsq_f32_e32 v84, v84
	s_nop 0
	v_mul_f32_e32 v85, 0x45800000, v84
	v_cndmask_b32_e32 v90, v84, v85, vcc
	v_lshl_add_u64 v[84:85], s[16:17], 0, v[88:89]
	v_mov_b32_e32 v92, v200
	v_mov_b32_e32 v93, v201
	v_mov_b32_e32 v94, v202
	v_mov_b32_e32 v95, v203
	v_mul_f32_e32 v78, v78, v90
	v_mul_f32_e32 v78, 0xbfb8aa3b, v78
	v_mul_f32_e32 v74, v74, v90
	v_exp_f32_e32 v78, v78
	v_mul_f32_e32 v74, 0xbfb8aa3b, v74
	v_exp_f32_e32 v74, v74
	v_mul_f32_e32 v70, v70, v90
	v_add_f32_e32 v78, 1.0, v78
	v_rcp_f32_e32 v78, v78
	v_add_f32_e32 v74, 1.0, v74
	v_rcp_f32_e32 v74, v74
	v_mul_f32_e32 v66, v66, v90
	v_mul_f32_e32 v70, 0xbfb8aa3b, v70
	v_mul_f32_e32 v66, 0xbfb8aa3b, v66
	v_exp_f32_e32 v70, v70
	v_exp_f32_e32 v66, v66
	v_add_f32_e32 v70, 1.0, v70
	v_add_f32_e32 v66, 1.0, v66
	v_rcp_f32_e32 v70, v70
	v_rcp_f32_e32 v66, v66
	s_nop 0
	v_lshlrev_b32_e32 v91, 16, v92
	v_and_b32_e32 v96, 0xffff0000, v92
	v_lshlrev_b32_e32 v97, 16, v93
	v_and_b32_e32 v98, 0xffff0000, v93
	v_lshlrev_b32_e32 v99, 16, v94
	v_and_b32_e32 v100, 0xffff0000, v94
	v_lshlrev_b32_e32 v101, 16, v95
	v_and_b32_e32 v102, 0xffff0000, v95
	v_mov_b32_e32 v92, v204
	v_mov_b32_e32 v93, v205
	v_mov_b32_e32 v94, v206
	v_mov_b32_e32 v95, v207
	s_nop 0
	v_lshlrev_b32_e32 v103, 16, v92
	v_lshlrev_b32_e32 v105, 16, v94
	v_fmac_f32_e32 v91, v78, v103
	v_mul_f32_e32 v78, v79, v90
	v_mul_f32_e32 v78, 0xbfb8aa3b, v78
	v_fmac_f32_e32 v99, v74, v105
	v_mul_f32_e32 v74, v75, v90
	v_exp_f32_e32 v78, v78
	v_mul_f32_e32 v74, 0xbfb8aa3b, v74
	v_exp_f32_e32 v74, v74
	v_and_b32_e32 v92, 0xffff0000, v92
; __device__ __forceinline__ unsigned cvt_pk_bf16(float lo, float hi) { unsigned r; asm volatile("v_cvt_pk_bf16_f32 %0, %1, %2" : "=v"(r) : "v"(lo), "v"(hi)); return r; }
; __device__ __forceinline__ float bflo(unsigned w) { return __uint_as_float(w << 16); }
; __device__ __forceinline__ float bfhi(unsigned w) { return __uint_as_float(w & 0xffff0000u); }
; __device__ __forceinline__ float fast_sigmoid(float x) { return __builtin_amdgcn_rcpf(1.0f + __builtin_amdgcn_exp2f(-1.44269504089f * x)); }
;     __device__ __forceinline__ void operator()(const f32x4 (&acc)[2][2][4][2], const Unit& u, int wr, int wc, int fr, int fq, LAS unsigned char* lds) const {
;     ...
;                 for (int bj = 0; bj < 2; ++bj) { const size_t o = off + bj * HALF; const u32x4 bw = *(const u32x4*)(base + o);
;                     const float bs[8] = {bflo(bw.x), bfhi(bw.x), bflo(bw.y), bfhi(bw.y), bflo(bw.z), bfhi(bw.z), bflo(bw.w), bfhi(bw.w)};
;                     float hn[8];
;                     if (MODE == 0) {
; #pragma unroll
;                         for (int n = 0; n < 2; ++n)
; #pragma unroll
;                             for (int e = 0; e < 4; ++e) hn[4 * n + e] = bs[4 * n + e] + (acc[ai][bj][m][n][e] + bv[bj][n][e]) * scale;
;                     } else { const u32x4 pw = *(const u32x4*)(pp + o);
;                         const float pv[8] = {bflo(pw.x), bfhi(pw.x), bflo(pw.y), bfhi(pw.y), bflo(pw.z), bfhi(pw.z), bflo(pw.w), bfhi(pw.w)};
; #pragma unroll
;                         for (int n = 0; n < 2; ++n)
; #pragma unroll
;                             for (int e = 0; e < 4; ++e) hn[4 * n + e] = bs[4 * n + e] + fast_sigmoid(acc[ai][bj][m][n][e] * rs) * pv[4 * n + e]; }
;                     u32x4 w; w.x = cvt_pk_bf16(hn[0], hn[1]); w.y = cvt_pk_bf16(hn[2], hn[3]); w.z = cvt_pk_bf16(hn[4], hn[5]); w.w = cvt_pk_bf16(hn[6], hn[7]); *(u32x4*)(hb + o) = w;
;                     const float hr[8] = {bflo(w.x), bfhi(w.x), bflo(w.y), bfhi(w.y), bflo(w.z), bfhi(w.z), bflo(w.w), bfhi(w.w)};
;                     ss += ((hr[0] * hr[0] + hr[1] * hr[1]) + (hr[2] * hr[2] + hr[3] * hr[3])) + ((hr[4] * hr[4] + hr[5] * hr[5]) + (hr[6] * hr[6] + hr[7] * hr[7])); }
;                 ss += __shfl_xor(ss, 16); ss += __shfl_xor(ss, 32);
;                 if (fq == 0) rss_out[(size_t)row * 16 + u.pn * 4 + wc] = ss; }
	v_add_f32_e32 v78, 1.0, v78
	v_rcp_f32_e32 v78, v78
	v_add_f32_e32 v74, 1.0, v74
	v_rcp_f32_e32 v74, v74
	v_and_b32_e32 v94, 0xffff0000, v94
	v_fmac_f32_e32 v96, v78, v92
	v_mul_f32_e32 v78, v80, v90
	v_mul_f32_e32 v78, 0xbfb8aa3b, v78
	v_fmac_f32_e32 v100, v74, v94
	v_mul_f32_e32 v74, v76, v90
	v_exp_f32_e32 v78, v78
	v_mul_f32_e32 v74, 0xbfb8aa3b, v74
	v_exp_f32_e32 v74, v74
	v_lshlrev_b32_e32 v104, 16, v93
	v_add_f32_e32 v78, 1.0, v78
	v_rcp_f32_e32 v78, v78
	v_add_f32_e32 v74, 1.0, v74
	v_rcp_f32_e32 v74, v74
	v_lshlrev_b32_e32 v106, 16, v95
	v_fmac_f32_e32 v97, v78, v104
	v_mul_f32_e32 v78, v81, v90
	v_mul_f32_e32 v78, 0xbfb8aa3b, v78
	v_fmac_f32_e32 v101, v74, v106
	v_mul_f32_e32 v74, v77, v90
	v_exp_f32_e32 v78, v78
	v_mul_f32_e32 v74, 0xbfb8aa3b, v74
	v_exp_f32_e32 v74, v74
	v_and_b32_e32 v93, 0xffff0000, v93
	v_add_f32_e32 v78, 1.0, v78
	v_rcp_f32_e32 v78, v78
	v_add_f32_e32 v74, 1.0, v74
	v_rcp_f32_e32 v74, v74
	v_and_b32_e32 v95, 0xffff0000, v95
	v_fmac_f32_e32 v98, v78, v93
	v_lshl_add_u64 v[78:79], s[18:19], 0, v[88:89]
	v_fmac_f32_e32 v102, v74, v95
	v_cvt_pk_bf16_f32 v74, v91, v96
	v_cvt_pk_bf16_f32 v75, v97, v98
	v_cvt_pk_bf16_f32 v76, v99, v100
	v_cvt_pk_bf16_f32 v77, v101, v102
	global_store_dwordx4 v[78:79], v[74:77], off
	v_mov_b32_e32 v92, v208
	v_mov_b32_e32 v93, v209
	v_mov_b32_e32 v94, v210
	v_mov_b32_e32 v95, v211
	v_lshlrev_b32_e32 v80, 16, v74
	v_and_b32_e32 v74, 0xffff0000, v74
	v_lshlrev_b32_e32 v81, 16, v75
	v_and_b32_e32 v75, 0xffff0000, v75
	v_mul_f32_e32 v74, v74, v74
	v_mul_f32_e32 v75, v75, v75
	v_lshlrev_b32_e32 v88, 16, v76
	v_and_b32_e32 v76, 0xffff0000, v76
	v_lshlrev_b32_e32 v89, 16, v77
	v_and_b32_e32 v77, 0xffff0000, v77
	v_fmac_f32_e32 v74, v80, v80
	v_fmac_f32_e32 v75, v81, v81
	v_add_f32_e32 v74, v74, v75
	v_mul_f32_e32 v75, v76, v76
	v_mul_f32_e32 v76, v77, v77
	v_fmac_f32_e32 v75, v88, v88
	v_fmac_f32_e32 v76, v89, v89
	v_add_f32_e32 v75, v75, v76
	v_add_f32_e32 v74, v74, v75
	s_nop 0
	v_lshlrev_b32_e32 v75, 16, v92
	v_and_b32_e32 v76, 0xffff0000, v92
	v_lshlrev_b32_e32 v77, 16, v93
	v_and_b32_e32 v80, 0xffff0000, v93
	v_lshlrev_b32_e32 v81, 16, v94
	v_and_b32_e32 v84, 0xffff0000, v94
	v_lshlrev_b32_e32 v85, 16, v95
	v_and_b32_e32 v88, 0xffff0000, v95
	v_mov_b32_e32 v92, v212
	v_mov_b32_e32 v93, v213
	v_mov_b32_e32 v94, v214
	v_mov_b32_e32 v95, v215
	s_nop 0
	v_lshlrev_b32_e32 v86, 16, v92
	v_and_b32_e32 v87, 0xffff0000, v92
	v_lshlrev_b32_e32 v92, 16, v94
	v_fmac_f32_e32 v75, v70, v86
	v_mul_f32_e32 v70, v71, v90
	v_fmac_f32_e32 v81, v66, v92
	v_mul_f32_e32 v66, v67, v90
	v_mul_f32_e32 v70, 0xbfb8aa3b, v70
	v_mul_f32_e32 v66, 0xbfb8aa3b, v66
	v_exp_f32_e32 v70, v70
	v_exp_f32_e32 v66, v66
	v_lshlrev_b32_e32 v89, 16, v93
	v_and_b32_e32 v91, 0xffff0000, v93
	v_add_f32_e32 v70, 1.0, v70
	v_add_f32_e32 v66, 1.0, v66
	v_rcp_f32_e32 v70, v70
	v_rcp_f32_e32 v66, v66
	v_and_b32_e32 v93, 0xffff0000, v94
	v_lshlrev_b32_e32 v94, 16, v95
	v_fmac_f32_e32 v76, v70, v87
	v_mul_f32_e32 v70, v72, v90
	v_fmac_f32_e32 v84, v66, v93
	v_mul_f32_e32 v66, v68, v90
	v_mul_f32_e32 v70, 0xbfb8aa3b, v70
	v_mul_f32_e32 v66, 0xbfb8aa3b, v66
	v_exp_f32_e32 v70, v70
	v_exp_f32_e32 v66, v66
	v_and_b32_e32 v95, 0xffff0000, v95
	v_add_f32_e32 v70, 1.0, v70
	v_add_f32_e32 v66, 1.0, v66
	v_rcp_f32_e32 v70, v70
	v_rcp_f32_e32 v66, v66
	v_fmac_f32_e32 v77, v70, v89
	v_mul_f32_e32 v70, v73, v90
	v_fmac_f32_e32 v85, v66, v94
	v_mul_f32_e32 v66, v69, v90
	v_mul_f32_e32 v70, 0xbfb8aa3b, v70
	v_mul_f32_e32 v66, 0xbfb8aa3b, v66
	v_exp_f32_e32 v70, v70
	v_exp_f32_e32 v66, v66
	v_add_f32_e32 v70, 1.0, v70
	v_add_f32_e32 v66, 1.0, v66
	v_rcp_f32_e32 v70, v70
	v_rcp_f32_e32 v66, v66
	v_fmac_f32_e32 v80, v70, v91
	v_fmac_f32_e32 v88, v66, v95
	v_cvt_pk_bf16_f32 v66, v75, v76
	v_cvt_pk_bf16_f32 v67, v77, v80
	v_cvt_pk_bf16_f32 v68, v81, v84
	v_cvt_pk_bf16_f32 v69, v85, v88
	global_store_dwordx4 v[78:79], v[66:69], off offset:256
	v_lshlrev_b32_e32 v70, 16, v66
	v_lshlrev_b32_e32 v71, 16, v67
	v_and_b32_e32 v66, 0xffff0000, v66
	v_and_b32_e32 v67, 0xffff0000, v67
	v_mul_f32_e32 v66, v66, v66
	v_mul_f32_e32 v67, v67, v67
	v_lshlrev_b32_e32 v72, 16, v68
	v_and_b32_e32 v68, 0xffff0000, v68
	v_lshlrev_b32_e32 v73, 16, v69
	v_and_b32_e32 v69, 0xffff0000, v69
	v_fmac_f32_e32 v66, v70, v70
	v_fmac_f32_e32 v67, v71, v71
	v_add_f32_e32 v66, v66, v67
	v_mul_f32_e32 v67, v68, v68
	v_mul_f32_e32 v68, v69, v69
	v_fmac_f32_e32 v67, v72, v72
	v_fmac_f32_e32 v68, v73, v73
	v_add_f32_e32 v67, v67, v68
	v_add_f32_e32 v66, v66, v67
	v_add_f32_e32 v66, v74, v66
	v_mov_b32_e32 v67, v66
	s_nop 1
	v_permlane16_swap_b32 v67, v66
	s_waitcnt lgkmcnt(0)
	v_add_f32_e32 v66, v66, v67
	v_mov_b32_e32 v67, v66
	s_nop 1
	v_permlane32_swap_b32 v67, v66
	s_and_saveexec_b64 s[24:25], s[6:7]
	s_cbranch_execz .LBB1_32
	s_lshl_b32 s66, s41, 2
	v_lshl_add_u64 v[68:69], s[20:21], 0, v[82:83]
	s_ashr_i32 s67, s66, 31
	v_lshl_add_u64 v[68:69], s[66:67], 2, v[68:69]
	s_lshl_b32 s74, s40, 2
	v_lshl_add_u64 v[68:69], v[68:69], 0, s[74:75]
	s_waitcnt lgkmcnt(0)
	v_add_f32_e32 v66, v66, v67
	global_store_dword v[68:69], v66, off
; __device__ __forceinline__ float rstd_of4(const float* rss, int row, int fq) {
;     const f32x4 a = *(const f32x4*)(rss + (size_t)row * 16 + 4 * fq); float s = (a[0] + a[1]) + (a[2] + a[3]);
;     s += __shfl_xor(s, 16); s += __shfl_xor(s, 32);
;     return rsqrtf(s * (1.0f / 1024.0f) + EPS); }
;     __device__ __forceinline__ void operator()(const f32x4 (&acc)[2][2][4][2], const Unit& u, int wr, int wc, int fr, int fq, LAS unsigned char* lds) const {
;     ...
;             for (int m = 0; m < 4; ++m) { const int row = row0 + ai * HALF + m * 16; const size_t off = (size_t)row * D + col0;
;                 float rs = 1.0f; if (MODE == 1) rs = rstd_of4(rss_in, row, fq);
;                 float ss = 0.f;
; #pragma unroll
;                 for (int bj = 0; bj < 2; ++bj) { const size_t o = off + bj * HALF; const u32x4 bw = *(const u32x4*)(base + o);
;                     const float bs[8] = {bflo(bw.x), bfhi(bw.x), bflo(bw.y), bfhi(bw.y), bflo(bw.z), bfhi(bw.z), bflo(bw.w), bfhi(bw.w)};
;                     float hn[8];
;                     if (MODE == 0) {
; #pragma unroll
;                         for (int n = 0; n < 2; ++n)
; #pragma unroll
;                             for (int e = 0; e < 4; ++e) hn[4 * n + e] = bs[4 * n + e] + (acc[ai][bj][m][n][e] + bv[bj][n][e]) * scale;
;                     } else { const u32x4 pw = *(const u32x4*)(pp + o);
;                         const float pv[8] = {bflo(pw.x), bfhi(pw.x), bflo(pw.y), bfhi(pw.y), bflo(pw.z), bfhi(pw.z), bflo(pw.w), bfhi(pw.w)};
; #pragma unroll
;                         for (int n = 0; n < 2; ++n)
; #pragma unroll
;                             for (int e = 0; e < 4; ++e) hn[4 * n + e] = bs[4 * n + e] + fast_sigmoid(acc[ai][bj][m][n][e] * rs) * pv[4 * n + e]; }
;                     u32x4 w; w.x = cvt_pk_bf16(hn[0], hn[1]); w.y = cvt_pk_bf16(hn[2], hn[3]); w.z = cvt_pk_bf16(hn[4], hn[5]); w.w = cvt_pk_bf16(hn[6], hn[7]); *(u32x4*)(hb + o) = w;
;                     const float hr[8] = {bflo(w.x), bfhi(w.x), bflo(w.y), bfhi(w.y), bflo(w.z), bfhi(w.z), bflo(w.w), bfhi(w.w)};
;                     ss += ((hr[0] * hr[0] + hr[1] * hr[1]) + (hr[2] * hr[2] + hr[3] * hr[3])) + ((hr[4] * hr[4] + hr[5] * hr[5]) + (hr[6] * hr[6] + hr[7] * hr[7])); }
;                 ss += __shfl_xor(ss, 16); ss += __shfl_xor(ss, 32);
;                 if (fq == 0) rss_out[(size_t)row * 16 + u.pn * 4 + wc] = ss; }
.LBB1_32:
	s_or_b64 exec, exec, s[24:25]
	v_add_u32_e32 v66, 0x80, v144
	s_waitcnt lgkmcnt(0)
	v_ashrrev_i32_e32 v67, 31, v66
	v_lshlrev_b64 v[68:69], 10, v[66:67]
	v_lshlrev_b64 v[66:67], 6, v[66:67]
	v_lshl_add_u64 v[72:73], v[68:69], 0, v[142:143]
	v_lshl_add_u64 v[68:69], v[146:147], 0, v[66:67]
	global_load_dwordx4 v[68:71], v[68:69], off
	v_lshlrev_b64 v[72:73], 1, v[72:73]
	v_lshl_add_u64 v[216:217], s[16:17], 0, v[72:73]
	v_lshl_add_u64 v[218:219], s[22:23], 0, v[72:73]
	global_load_dwordx4 v[200:203], v[216:217], off
	global_load_dwordx4 v[204:207], v[218:219], off
	global_load_dwordx4 v[208:211], v[216:217], off offset:256
	global_load_dwordx4 v[212:215], v[218:219], off offset:256
	s_waitcnt vmcnt(0)
	v_mov_b32_e32 v74, v69
	v_mov_b32_e32 v75, v70
	v_mov_b32_e32 v69, v71
	v_pk_add_f32 v[68:69], v[74:75], v[68:69]
	v_lshl_add_u64 v[70:71], s[22:23], 0, v[72:73]
	v_add_f32_e32 v68, v68, v69
	v_mov_b32_e32 v69, v68
	s_nop 1
	v_permlane16_swap_b32 v69, v68
	s_waitcnt lgkmcnt(0)
	v_add_f32_e32 v68, v68, v69
	v_mov_b32_e32 v69, v68
	s_nop 1
	v_permlane32_swap_b32 v69, v68
	s_waitcnt lgkmcnt(0)
	v_add_f32_e32 v68, v68, v69
	v_fmamk_f32 v68, v68, 0x3a800000, v173
	v_cmp_gt_f32_e32 vcc, s64, v68
	v_mul_f32_e32 v69, 0x4b800000, v68
	s_nop 0
	v_cndmask_b32_e32 v68, v68, v69, vcc
	v_rsq_f32_e32 v68, v68
	s_nop 0
	v_mul_f32_e32 v69, 0x45800000, v68
	v_cndmask_b32_e32 v74, v68, v69, vcc
	v_lshl_add_u64 v[68:69], s[16:17], 0, v[72:73]
	v_mov_b32_e32 v76, v200
	v_mov_b32_e32 v77, v201
	v_mov_b32_e32 v78, v202
	v_mov_b32_e32 v79, v203
	v_mul_f32_e32 v62, v62, v74
	v_mul_f32_e32 v62, 0xbfb8aa3b, v62
	v_mul_f32_e32 v58, v58, v74
	v_exp_f32_e32 v62, v62
	v_mul_f32_e32 v58, 0xbfb8aa3b, v58
	v_exp_f32_e32 v58, v58
	v_mul_f32_e32 v54, v54, v74
	v_add_f32_e32 v62, 1.0, v62
	v_rcp_f32_e32 v62, v62
	v_add_f32_e32 v58, 1.0, v58
	v_rcp_f32_e32 v58, v58
	v_mul_f32_e32 v50, v50, v74
	v_mul_f32_e32 v54, 0xbfb8aa3b, v54
	v_mul_f32_e32 v50, 0xbfb8aa3b, v50
	v_exp_f32_e32 v54, v54
	v_exp_f32_e32 v50, v50
	v_add_f32_e32 v54, 1.0, v54
	v_add_f32_e32 v50, 1.0, v50
	v_rcp_f32_e32 v54, v54
	v_rcp_f32_e32 v50, v50
	s_nop 0
	v_lshlrev_b32_e32 v75, 16, v76
	v_and_b32_e32 v80, 0xffff0000, v76
	v_lshlrev_b32_e32 v81, 16, v77
	v_and_b32_e32 v82, 0xffff0000, v77
	v_lshlrev_b32_e32 v83, 16, v78
	v_and_b32_e32 v84, 0xffff0000, v78
	v_lshlrev_b32_e32 v85, 16, v79
	v_and_b32_e32 v86, 0xffff0000, v79
	v_mov_b32_e32 v76, v204
	v_mov_b32_e32 v77, v205
	v_mov_b32_e32 v78, v206
	v_mov_b32_e32 v79, v207
	s_nop 0
	v_lshlrev_b32_e32 v87, 16, v76
	v_lshlrev_b32_e32 v89, 16, v78
	v_fmac_f32_e32 v75, v62, v87
	v_mul_f32_e32 v62, v63, v74
	v_mul_f32_e32 v62, 0xbfb8aa3b, v62
	v_fmac_f32_e32 v83, v58, v89
	v_mul_f32_e32 v58, v59, v74
	v_exp_f32_e32 v62, v62
	v_mul_f32_e32 v58, 0xbfb8aa3b, v58
	v_exp_f32_e32 v58, v58
	v_and_b32_e32 v76, 0xffff0000, v76
	v_add_f32_e32 v62, 1.0, v62
	v_rcp_f32_e32 v62, v62
	v_add_f32_e32 v58, 1.0, v58
	v_rcp_f32_e32 v58, v58
	v_and_b32_e32 v78, 0xffff0000, v78
	v_fmac_f32_e32 v80, v62, v76
	v_mul_f32_e32 v62, v64, v74
	v_mul_f32_e32 v62, 0xbfb8aa3b, v62
	v_fmac_f32_e32 v84, v58, v78
	v_mul_f32_e32 v58, v60, v74
	v_exp_f32_e32 v62, v62
	v_mul_f32_e32 v58, 0xbfb8aa3b, v58
	v_exp_f32_e32 v58, v58
	v_lshlrev_b32_e32 v88, 16, v77
	v_add_f32_e32 v62, 1.0, v62
	v_rcp_f32_e32 v62, v62
	v_add_f32_e32 v58, 1.0, v58
	v_rcp_f32_e32 v58, v58
	v_lshlrev_b32_e32 v90, 16, v79
	v_fmac_f32_e32 v81, v62, v88
	v_mul_f32_e32 v62, v65, v74
	v_mul_f32_e32 v62, 0xbfb8aa3b, v62
	v_fmac_f32_e32 v85, v58, v90
	v_mul_f32_e32 v58, v61, v74
	v_exp_f32_e32 v62, v62
	v_mul_f32_e32 v58, 0xbfb8aa3b, v58
	v_exp_f32_e32 v58, v58
	v_and_b32_e32 v77, 0xffff0000, v77
	v_add_f32_e32 v62, 1.0, v62
	v_rcp_f32_e32 v62, v62
	v_add_f32_e32 v58, 1.0, v58
	v_rcp_f32_e32 v58, v58
	v_and_b32_e32 v79, 0xffff0000, v79
	v_fmac_f32_e32 v82, v62, v77
	v_lshl_add_u64 v[62:63], s[18:19], 0, v[72:73]
	v_fmac_f32_e32 v86, v58, v79
	v_cvt_pk_bf16_f32 v58, v75, v80
	v_cvt_pk_bf16_f32 v59, v81, v82
	v_cvt_pk_bf16_f32 v60, v83, v84
	v_cvt_pk_bf16_f32 v61, v85, v86
	global_store_dwordx4 v[62:63], v[58:61], off
	v_mov_b32_e32 v76, v208
	v_mov_b32_e32 v77, v209
	v_mov_b32_e32 v78, v210
	v_mov_b32_e32 v79, v211
	v_lshlrev_b32_e32 v64, 16, v58
	v_and_b32_e32 v58, 0xffff0000, v58
	v_lshlrev_b32_e32 v65, 16, v59
	v_and_b32_e32 v59, 0xffff0000, v59
	v_mul_f32_e32 v58, v58, v58
	v_mul_f32_e32 v59, v59, v59
	v_lshlrev_b32_e32 v72, 16, v60
	v_and_b32_e32 v60, 0xffff0000, v60
	v_lshlrev_b32_e32 v73, 16, v61
	v_and_b32_e32 v61, 0xffff0000, v61
	v_fmac_f32_e32 v58, v64, v64
	v_fmac_f32_e32 v59, v65, v65
	v_add_f32_e32 v58, v58, v59
	v_mul_f32_e32 v59, v60, v60
	v_mul_f32_e32 v60, v61, v61
	v_fmac_f32_e32 v59, v72, v72
	v_fmac_f32_e32 v60, v73, v73
	v_add_f32_e32 v59, v59, v60
	v_add_f32_e32 v58, v58, v59
	s_nop 0
	v_lshlrev_b32_e32 v59, 16, v76
	v_and_b32_e32 v60, 0xffff0000, v76
	v_lshlrev_b32_e32 v61, 16, v77
	v_and_b32_e32 v64, 0xffff0000, v77
	v_lshlrev_b32_e32 v65, 16, v78
	v_and_b32_e32 v68, 0xffff0000, v78
	v_lshlrev_b32_e32 v69, 16, v79
	v_and_b32_e32 v72, 0xffff0000, v79
	v_mov_b32_e32 v76, v212
	v_mov_b32_e32 v77, v213
	v_mov_b32_e32 v78, v214
	v_mov_b32_e32 v79, v215
	s_nop 0
	v_lshlrev_b32_e32 v70, 16, v76
	v_and_b32_e32 v71, 0xffff0000, v76
	v_lshlrev_b32_e32 v76, 16, v78
	v_fmac_f32_e32 v59, v54, v70
	v_mul_f32_e32 v54, v55, v74
	v_fmac_f32_e32 v65, v50, v76
	v_mul_f32_e32 v50, v51, v74
	v_mul_f32_e32 v54, 0xbfb8aa3b, v54
	v_mul_f32_e32 v50, 0xbfb8aa3b, v50
	v_exp_f32_e32 v54, v54
	v_exp_f32_e32 v50, v50
	v_lshlrev_b32_e32 v73, 16, v77
	v_and_b32_e32 v75, 0xffff0000, v77
	v_add_f32_e32 v54, 1.0, v54
	v_add_f32_e32 v50, 1.0, v50
; __device__ __forceinline__ float rstd_of4(const float* rss, int row, int fq) {
;     const f32x4 a = *(const f32x4*)(rss + (size_t)row * 16 + 4 * fq); float s = (a[0] + a[1]) + (a[2] + a[3]);
;     s += __shfl_xor(s, 16); s += __shfl_xor(s, 32);
;     return rsqrtf(s * (1.0f / 1024.0f) + EPS); }
;     __device__ __forceinline__ void operator()(const f32x4 (&acc)[2][2][4][2], const Unit& u, int wr, int wc, int fr, int fq, LAS unsigned char* lds) const {
;     ...
;             for (int m = 0; m < 4; ++m) { const int row = row0 + ai * HALF + m * 16; const size_t off = (size_t)row * D + col0;
;                 float rs = 1.0f; if (MODE == 1) rs = rstd_of4(rss_in, row, fq);
;                 float ss = 0.f;
; #pragma unroll
;                 for (int bj = 0; bj < 2; ++bj) { const size_t o = off + bj * HALF; const u32x4 bw = *(const u32x4*)(base + o);
;                     const float bs[8] = {bflo(bw.x), bfhi(bw.x), bflo(bw.y), bfhi(bw.y), bflo(bw.z), bfhi(bw.z), bflo(bw.w), bfhi(bw.w)};
;                     float hn[8];
;                     if (MODE == 0) {
; #pragma unroll
;                         for (int n = 0; n < 2; ++n)
; #pragma unroll
;                             for (int e = 0; e < 4; ++e) hn[4 * n + e] = bs[4 * n + e] + (acc[ai][bj][m][n][e] + bv[bj][n][e]) * scale;
;                     } else { const u32x4 pw = *(const u32x4*)(pp + o);
;                         const float pv[8] = {bflo(pw.x), bfhi(pw.x), bflo(pw.y), bfhi(pw.y), bflo(pw.z), bfhi(pw.z), bflo(pw.w), bfhi(pw.w)};
; #pragma unroll
;                         for (int n = 0; n < 2; ++n)
; #pragma unroll
;                             for (int e = 0; e < 4; ++e) hn[4 * n + e] = bs[4 * n + e] + fast_sigmoid(acc[ai][bj][m][n][e] * rs) * pv[4 * n + e]; }
;                     u32x4 w; w.x = cvt_pk_bf16(hn[0], hn[1]); w.y = cvt_pk_bf16(hn[2], hn[3]); w.z = cvt_pk_bf16(hn[4], hn[5]); w.w = cvt_pk_bf16(hn[6], hn[7]); *(u32x4*)(hb + o) = w;
;                     const float hr[8] = {bflo(w.x), bfhi(w.x), bflo(w.y), bfhi(w.y), bflo(w.z), bfhi(w.z), bflo(w.w), bfhi(w.w)};
;                     ss += ((hr[0] * hr[0] + hr[1] * hr[1]) + (hr[2] * hr[2] + hr[3] * hr[3])) + ((hr[4] * hr[4] + hr[5] * hr[5]) + (hr[6] * hr[6] + hr[7] * hr[7])); }
;                 ss += __shfl_xor(ss, 16); ss += __shfl_xor(ss, 32);
;                 if (fq == 0) rss_out[(size_t)row * 16 + u.pn * 4 + wc] = ss; }
	v_rcp_f32_e32 v54, v54
	v_rcp_f32_e32 v50, v50
	v_and_b32_e32 v77, 0xffff0000, v78
	v_lshlrev_b32_e32 v78, 16, v79
	v_fmac_f32_e32 v60, v54, v71
	v_mul_f32_e32 v54, v56, v74
	v_fmac_f32_e32 v68, v50, v77
	v_mul_f32_e32 v50, v52, v74
	v_mul_f32_e32 v54, 0xbfb8aa3b, v54
	v_mul_f32_e32 v50, 0xbfb8aa3b, v50
	v_exp_f32_e32 v54, v54
	v_exp_f32_e32 v50, v50
	v_and_b32_e32 v79, 0xffff0000, v79
	v_add_f32_e32 v54, 1.0, v54
	v_add_f32_e32 v50, 1.0, v50
	v_rcp_f32_e32 v54, v54
	v_rcp_f32_e32 v50, v50
	v_fmac_f32_e32 v61, v54, v73
	v_mul_f32_e32 v54, v57, v74
	v_fmac_f32_e32 v69, v50, v78
	v_mul_f32_e32 v50, v53, v74
	v_mul_f32_e32 v54, 0xbfb8aa3b, v54
	v_mul_f32_e32 v50, 0xbfb8aa3b, v50
	v_exp_f32_e32 v54, v54
	v_exp_f32_e32 v50, v50
	v_add_f32_e32 v54, 1.0, v54
	v_add_f32_e32 v50, 1.0, v50
	v_rcp_f32_e32 v54, v54
	v_rcp_f32_e32 v50, v50
	v_fmac_f32_e32 v64, v54, v75
	v_fmac_f32_e32 v72, v50, v79
	v_cvt_pk_bf16_f32 v50, v59, v60
	v_cvt_pk_bf16_f32 v51, v61, v64
	v_cvt_pk_bf16_f32 v52, v65, v68
	v_cvt_pk_bf16_f32 v53, v69, v72
	global_store_dwordx4 v[62:63], v[50:53], off offset:256
	v_lshlrev_b32_e32 v54, 16, v50
	v_lshlrev_b32_e32 v55, 16, v51
	v_and_b32_e32 v50, 0xffff0000, v50
	v_and_b32_e32 v51, 0xffff0000, v51
	v_mul_f32_e32 v50, v50, v50
	v_mul_f32_e32 v51, v51, v51
	v_lshlrev_b32_e32 v56, 16, v52
	v_and_b32_e32 v52, 0xffff0000, v52
	v_lshlrev_b32_e32 v57, 16, v53
	v_and_b32_e32 v53, 0xffff0000, v53
	v_fmac_f32_e32 v50, v54, v54
	v_fmac_f32_e32 v51, v55, v55
	v_add_f32_e32 v50, v50, v51
	v_mul_f32_e32 v51, v52, v52
	v_mul_f32_e32 v52, v53, v53
	v_fmac_f32_e32 v51, v56, v56
	v_fmac_f32_e32 v52, v57, v57
	v_add_f32_e32 v51, v51, v52
	v_add_f32_e32 v50, v50, v51
	v_add_f32_e32 v50, v58, v50
	v_mov_b32_e32 v51, v50
	s_nop 1
	v_permlane16_swap_b32 v51, v50
	s_waitcnt lgkmcnt(0)
	v_add_f32_e32 v50, v50, v51
	v_mov_b32_e32 v51, v50
	s_nop 1
	v_permlane32_swap_b32 v51, v50
	s_and_saveexec_b64 s[24:25], s[6:7]
	s_cbranch_execz .LBB1_34
	s_lshl_b32 s66, s41, 2
	v_lshl_add_u64 v[52:53], s[20:21], 0, v[66:67]
	s_ashr_i32 s67, s66, 31
	v_lshl_add_u64 v[52:53], s[66:67], 2, v[52:53]
	s_lshl_b32 s74, s40, 2
	v_lshl_add_u64 v[52:53], v[52:53], 0, s[74:75]
	s_waitcnt lgkmcnt(0)
	v_add_f32_e32 v50, v50, v51
	global_store_dword v[52:53], v50, off
.LBB1_34:
	s_or_b64 exec, exec, s[24:25]
	v_add_u32_e32 v50, 0x90, v144
	s_waitcnt lgkmcnt(0)
	v_ashrrev_i32_e32 v51, 31, v50
	v_lshlrev_b64 v[52:53], 10, v[50:51]
	v_lshlrev_b64 v[50:51], 6, v[50:51]
	v_lshl_add_u64 v[56:57], v[52:53], 0, v[142:143]
	v_lshl_add_u64 v[52:53], v[146:147], 0, v[50:51]
	global_load_dwordx4 v[52:55], v[52:53], off
	v_lshlrev_b64 v[56:57], 1, v[56:57]
	v_lshl_add_u64 v[216:217], s[16:17], 0, v[56:57]
	v_lshl_add_u64 v[218:219], s[22:23], 0, v[56:57]
	global_load_dwordx4 v[200:203], v[216:217], off
	global_load_dwordx4 v[204:207], v[218:219], off
	global_load_dwordx4 v[208:211], v[216:217], off offset:256
	global_load_dwordx4 v[212:215], v[218:219], off offset:256
	s_waitcnt vmcnt(0)
	v_mov_b32_e32 v58, v53
	v_mov_b32_e32 v59, v54
	v_mov_b32_e32 v53, v55
	v_pk_add_f32 v[52:53], v[58:59], v[52:53]
	v_lshl_add_u64 v[54:55], s[22:23], 0, v[56:57]
	v_add_f32_e32 v52, v52, v53
	v_mov_b32_e32 v53, v52
	s_nop 1
	v_permlane16_swap_b32 v53, v52
	s_waitcnt lgkmcnt(0)
	v_add_f32_e32 v52, v52, v53
	v_mov_b32_e32 v53, v52
	s_nop 1
	v_permlane32_swap_b32 v53, v52
	s_waitcnt lgkmcnt(0)
	v_add_f32_e32 v52, v52, v53
	v_fmamk_f32 v52, v52, 0x3a800000, v173
	v_cmp_gt_f32_e32 vcc, s64, v52
	v_mul_f32_e32 v53, 0x4b800000, v52
	s_nop 0
	v_cndmask_b32_e32 v52, v52, v53, vcc
	v_rsq_f32_e32 v52, v52
	s_nop 0
	v_mul_f32_e32 v53, 0x45800000, v52
	v_cndmask_b32_e32 v58, v52, v53, vcc
	v_lshl_add_u64 v[52:53], s[16:17], 0, v[56:57]
	v_mov_b32_e32 v60, v200
	v_mov_b32_e32 v61, v201
	v_mov_b32_e32 v62, v202
	v_mov_b32_e32 v63, v203
	v_mul_f32_e32 v46, v46, v58
	v_mul_f32_e32 v46, 0xbfb8aa3b, v46
	v_mul_f32_e32 v42, v42, v58
	v_exp_f32_e32 v46, v46
	v_mul_f32_e32 v42, 0xbfb8aa3b, v42
	v_exp_f32_e32 v42, v42
	v_mul_f32_e32 v38, v38, v58
	v_add_f32_e32 v46, 1.0, v46
	v_rcp_f32_e32 v46, v46
	v_add_f32_e32 v42, 1.0, v42
	v_rcp_f32_e32 v42, v42
	v_mul_f32_e32 v34, v34, v58
	v_mul_f32_e32 v38, 0xbfb8aa3b, v38
	v_mul_f32_e32 v34, 0xbfb8aa3b, v34
	v_exp_f32_e32 v38, v38
	v_exp_f32_e32 v34, v34
	v_add_f32_e32 v38, 1.0, v38
	v_add_f32_e32 v34, 1.0, v34
	v_rcp_f32_e32 v38, v38
	v_rcp_f32_e32 v34, v34
	s_nop 0
	v_lshlrev_b32_e32 v59, 16, v60
	v_and_b32_e32 v64, 0xffff0000, v60
	v_lshlrev_b32_e32 v65, 16, v61
	v_and_b32_e32 v66, 0xffff0000, v61
	v_lshlrev_b32_e32 v67, 16, v62
	v_and_b32_e32 v68, 0xffff0000, v62
	v_lshlrev_b32_e32 v69, 16, v63
	v_and_b32_e32 v70, 0xffff0000, v63
	v_mov_b32_e32 v60, v204
	v_mov_b32_e32 v61, v205
	v_mov_b32_e32 v62, v206
	v_mov_b32_e32 v63, v207
	s_nop 0
	v_lshlrev_b32_e32 v71, 16, v60
	v_lshlrev_b32_e32 v73, 16, v62
	v_fmac_f32_e32 v59, v46, v71
	v_mul_f32_e32 v46, v47, v58
	v_mul_f32_e32 v46, 0xbfb8aa3b, v46
	v_fmac_f32_e32 v67, v42, v73
	v_mul_f32_e32 v42, v43, v58
	v_exp_f32_e32 v46, v46
	v_mul_f32_e32 v42, 0xbfb8aa3b, v42
	v_exp_f32_e32 v42, v42
	v_and_b32_e32 v60, 0xffff0000, v60
	v_add_f32_e32 v46, 1.0, v46
	v_rcp_f32_e32 v46, v46
	v_add_f32_e32 v42, 1.0, v42
	v_rcp_f32_e32 v42, v42
	v_and_b32_e32 v62, 0xffff0000, v62
	v_fmac_f32_e32 v64, v46, v60
	v_mul_f32_e32 v46, v48, v58
	v_mul_f32_e32 v46, 0xbfb8aa3b, v46
	v_fmac_f32_e32 v68, v42, v62
	v_mul_f32_e32 v42, v44, v58
	v_exp_f32_e32 v46, v46
	v_mul_f32_e32 v42, 0xbfb8aa3b, v42
	v_exp_f32_e32 v42, v42
	v_lshlrev_b32_e32 v72, 16, v61
	v_add_f32_e32 v46, 1.0, v46
	v_rcp_f32_e32 v46, v46
	v_add_f32_e32 v42, 1.0, v42
	v_rcp_f32_e32 v42, v42
; __device__ __forceinline__ unsigned cvt_pk_bf16(float lo, float hi) { unsigned r; asm volatile("v_cvt_pk_bf16_f32 %0, %1, %2" : "=v"(r) : "v"(lo), "v"(hi)); return r; }
; __device__ __forceinline__ float bflo(unsigned w) { return __uint_as_float(w << 16); }
; __device__ __forceinline__ float bfhi(unsigned w) { return __uint_as_float(w & 0xffff0000u); }
; __device__ __forceinline__ float fast_sigmoid(float x) { return __builtin_amdgcn_rcpf(1.0f + __builtin_amdgcn_exp2f(-1.44269504089f * x)); }
;     __device__ __forceinline__ void operator()(const f32x4 (&acc)[2][2][4][2], const Unit& u, int wr, int wc, int fr, int fq, LAS unsigned char* lds) const {
;     ...
;                 for (int bj = 0; bj < 2; ++bj) { const size_t o = off + bj * HALF; const u32x4 bw = *(const u32x4*)(base + o);
;                     const float bs[8] = {bflo(bw.x), bfhi(bw.x), bflo(bw.y), bfhi(bw.y), bflo(bw.z), bfhi(bw.z), bflo(bw.w), bfhi(bw.w)};
;                     float hn[8];
;                     if (MODE == 0) {
; #pragma unroll
;                         for (int n = 0; n < 2; ++n)
; #pragma unroll
;                             for (int e = 0; e < 4; ++e) hn[4 * n + e] = bs[4 * n + e] + (acc[ai][bj][m][n][e] + bv[bj][n][e]) * scale;
;                     } else { const u32x4 pw = *(const u32x4*)(pp + o);
;                         const float pv[8] = {bflo(pw.x), bfhi(pw.x), bflo(pw.y), bfhi(pw.y), bflo(pw.z), bfhi(pw.z), bflo(pw.w), bfhi(pw.w)};
; #pragma unroll
;                         for (int n = 0; n < 2; ++n)
; #pragma unroll
;                             for (int e = 0; e < 4; ++e) hn[4 * n + e] = bs[4 * n + e] + fast_sigmoid(acc[ai][bj][m][n][e] * rs) * pv[4 * n + e]; }
;                     u32x4 w; w.x = cvt_pk_bf16(hn[0], hn[1]); w.y = cvt_pk_bf16(hn[2], hn[3]); w.z = cvt_pk_bf16(hn[4], hn[5]); w.w = cvt_pk_bf16(hn[6], hn[7]); *(u32x4*)(hb + o) = w;
;                     const float hr[8] = {bflo(w.x), bfhi(w.x), bflo(w.y), bfhi(w.y), bflo(w.z), bfhi(w.z), bflo(w.w), bfhi(w.w)};
;                     ss += ((hr[0] * hr[0] + hr[1] * hr[1]) + (hr[2] * hr[2] + hr[3] * hr[3])) + ((hr[4] * hr[4] + hr[5] * hr[5]) + (hr[6] * hr[6] + hr[7] * hr[7])); }
;                 ss += __shfl_xor(ss, 16); ss += __shfl_xor(ss, 32);
;                 if (fq == 0) rss_out[(size_t)row * 16 + u.pn * 4 + wc] = ss; }
	v_lshlrev_b32_e32 v74, 16, v63
	v_fmac_f32_e32 v65, v46, v72
	v_mul_f32_e32 v46, v49, v58
	v_mul_f32_e32 v46, 0xbfb8aa3b, v46
	v_fmac_f32_e32 v69, v42, v74
	v_mul_f32_e32 v42, v45, v58
	v_exp_f32_e32 v46, v46
	v_mul_f32_e32 v42, 0xbfb8aa3b, v42
	v_exp_f32_e32 v42, v42
	v_and_b32_e32 v61, 0xffff0000, v61
	v_add_f32_e32 v46, 1.0, v46
	v_rcp_f32_e32 v46, v46
	v_add_f32_e32 v42, 1.0, v42
	v_rcp_f32_e32 v42, v42
	v_and_b32_e32 v63, 0xffff0000, v63
	v_fmac_f32_e32 v66, v46, v61
	v_lshl_add_u64 v[46:47], s[18:19], 0, v[56:57]
	v_fmac_f32_e32 v70, v42, v63
	v_cvt_pk_bf16_f32 v42, v59, v64
	v_cvt_pk_bf16_f32 v43, v65, v66
	v_cvt_pk_bf16_f32 v44, v67, v68
	v_cvt_pk_bf16_f32 v45, v69, v70
	global_store_dwordx4 v[46:47], v[42:45], off
	v_mov_b32_e32 v60, v208
	v_mov_b32_e32 v61, v209
	v_mov_b32_e32 v62, v210
	v_mov_b32_e32 v63, v211
	v_lshlrev_b32_e32 v48, 16, v42
	v_and_b32_e32 v42, 0xffff0000, v42
	v_lshlrev_b32_e32 v49, 16, v43
	v_and_b32_e32 v43, 0xffff0000, v43
	v_mul_f32_e32 v42, v42, v42
	v_mul_f32_e32 v43, v43, v43
	v_lshlrev_b32_e32 v56, 16, v44
	v_and_b32_e32 v44, 0xffff0000, v44
	v_lshlrev_b32_e32 v57, 16, v45
	v_and_b32_e32 v45, 0xffff0000, v45
	v_fmac_f32_e32 v42, v48, v48
	v_fmac_f32_e32 v43, v49, v49
	v_add_f32_e32 v42, v42, v43
	v_mul_f32_e32 v43, v44, v44
	v_mul_f32_e32 v44, v45, v45
	v_fmac_f32_e32 v43, v56, v56
	v_fmac_f32_e32 v44, v57, v57
	v_add_f32_e32 v43, v43, v44
	v_add_f32_e32 v42, v42, v43
	s_nop 0
	v_lshlrev_b32_e32 v43, 16, v60
	v_and_b32_e32 v44, 0xffff0000, v60
	v_lshlrev_b32_e32 v45, 16, v61
	v_and_b32_e32 v48, 0xffff0000, v61
	v_lshlrev_b32_e32 v49, 16, v62
	v_and_b32_e32 v52, 0xffff0000, v62
	v_lshlrev_b32_e32 v53, 16, v63
	v_and_b32_e32 v56, 0xffff0000, v63
	v_mov_b32_e32 v60, v212
	v_mov_b32_e32 v61, v213
	v_mov_b32_e32 v62, v214
	v_mov_b32_e32 v63, v215
	s_nop 0
	v_lshlrev_b32_e32 v54, 16, v60
	v_and_b32_e32 v55, 0xffff0000, v60
	v_lshlrev_b32_e32 v60, 16, v62
	v_fmac_f32_e32 v43, v38, v54
	v_mul_f32_e32 v38, v39, v58
	v_fmac_f32_e32 v49, v34, v60
	v_mul_f32_e32 v34, v35, v58
	v_mul_f32_e32 v38, 0xbfb8aa3b, v38
	v_mul_f32_e32 v34, 0xbfb8aa3b, v34
	v_exp_f32_e32 v38, v38
	v_exp_f32_e32 v34, v34
	v_lshlrev_b32_e32 v57, 16, v61
	v_and_b32_e32 v59, 0xffff0000, v61
	v_add_f32_e32 v38, 1.0, v38
	v_add_f32_e32 v34, 1.0, v34
	v_rcp_f32_e32 v38, v38
	v_rcp_f32_e32 v34, v34
	v_and_b32_e32 v61, 0xffff0000, v62
	v_lshlrev_b32_e32 v62, 16, v63
	v_fmac_f32_e32 v44, v38, v55
	v_mul_f32_e32 v38, v40, v58
	v_fmac_f32_e32 v52, v34, v61
	v_mul_f32_e32 v34, v36, v58
	v_mul_f32_e32 v38, 0xbfb8aa3b, v38
	v_mul_f32_e32 v34, 0xbfb8aa3b, v34
	v_exp_f32_e32 v38, v38
	v_exp_f32_e32 v34, v34
	v_and_b32_e32 v63, 0xffff0000, v63
	v_add_f32_e32 v38, 1.0, v38
	v_add_f32_e32 v34, 1.0, v34
	v_rcp_f32_e32 v38, v38
	v_rcp_f32_e32 v34, v34
	v_fmac_f32_e32 v45, v38, v57
	v_mul_f32_e32 v38, v41, v58
	v_fmac_f32_e32 v53, v34, v62
	v_mul_f32_e32 v34, v37, v58
	v_mul_f32_e32 v38, 0xbfb8aa3b, v38
	v_mul_f32_e32 v34, 0xbfb8aa3b, v34
	v_exp_f32_e32 v38, v38
	v_exp_f32_e32 v34, v34
	v_add_f32_e32 v38, 1.0, v38
	v_add_f32_e32 v34, 1.0, v34
	v_rcp_f32_e32 v38, v38
	v_rcp_f32_e32 v34, v34
	v_fmac_f32_e32 v48, v38, v59
	v_fmac_f32_e32 v56, v34, v63
	v_cvt_pk_bf16_f32 v34, v43, v44
	v_cvt_pk_bf16_f32 v35, v45, v48
	v_cvt_pk_bf16_f32 v36, v49, v52
	v_cvt_pk_bf16_f32 v37, v53, v56
	global_store_dwordx4 v[46:47], v[34:37], off offset:256
	v_lshlrev_b32_e32 v38, 16, v34
	v_lshlrev_b32_e32 v39, 16, v35
	v_and_b32_e32 v34, 0xffff0000, v34
	v_and_b32_e32 v35, 0xffff0000, v35
	v_mul_f32_e32 v34, v34, v34
	v_mul_f32_e32 v35, v35, v35
	v_lshlrev_b32_e32 v40, 16, v36
	v_and_b32_e32 v36, 0xffff0000, v36
	v_lshlrev_b32_e32 v41, 16, v37
	v_and_b32_e32 v37, 0xffff0000, v37
	v_fmac_f32_e32 v34, v38, v38
	v_fmac_f32_e32 v35, v39, v39
	v_add_f32_e32 v34, v34, v35
	v_mul_f32_e32 v35, v36, v36
	v_mul_f32_e32 v36, v37, v37
	v_fmac_f32_e32 v35, v40, v40
	v_fmac_f32_e32 v36, v41, v41
	v_add_f32_e32 v35, v35, v36
	v_add_f32_e32 v34, v34, v35
	v_add_f32_e32 v34, v42, v34
	v_mov_b32_e32 v35, v34
	s_nop 1
	v_permlane16_swap_b32 v35, v34
	s_waitcnt lgkmcnt(0)
	v_add_f32_e32 v34, v34, v35
	v_mov_b32_e32 v35, v34
	s_nop 1
	v_permlane32_swap_b32 v35, v34
	s_and_saveexec_b64 s[24:25], s[6:7]
	s_cbranch_execz .LBB1_36
	s_lshl_b32 s66, s41, 2
	v_lshl_add_u64 v[36:37], s[20:21], 0, v[50:51]
	s_ashr_i32 s67, s66, 31
	v_lshl_add_u64 v[36:37], s[66:67], 2, v[36:37]
	s_lshl_b32 s74, s40, 2
	v_lshl_add_u64 v[36:37], v[36:37], 0, s[74:75]
	s_waitcnt lgkmcnt(0)
	v_add_f32_e32 v34, v34, v35
	global_store_dword v[36:37], v34, off
; __device__ __forceinline__ float rstd_of4(const float* rss, int row, int fq) {
;     const f32x4 a = *(const f32x4*)(rss + (size_t)row * 16 + 4 * fq); float s = (a[0] + a[1]) + (a[2] + a[3]);
;     s += __shfl_xor(s, 16); s += __shfl_xor(s, 32);
;     return rsqrtf(s * (1.0f / 1024.0f) + EPS); }
;     __device__ __forceinline__ void operator()(const f32x4 (&acc)[2][2][4][2], const Unit& u, int wr, int wc, int fr, int fq, LAS unsigned char* lds) const {
;     ...
;             for (int m = 0; m < 4; ++m) { const int row = row0 + ai * HALF + m * 16; const size_t off = (size_t)row * D + col0;
;                 float rs = 1.0f; if (MODE == 1) rs = rstd_of4(rss_in, row, fq);
;                 float ss = 0.f;
; #pragma unroll
;                 for (int bj = 0; bj < 2; ++bj) { const size_t o = off + bj * HALF; const u32x4 bw = *(const u32x4*)(base + o);
;                     const float bs[8] = {bflo(bw.x), bfhi(bw.x), bflo(bw.y), bfhi(bw.y), bflo(bw.z), bfhi(bw.z), bflo(bw.w), bfhi(bw.w)};
;                     float hn[8];
;                     if (MODE == 0) {
; #pragma unroll
;                         for (int n = 0; n < 2; ++n)
; #pragma unroll
;                             for (int e = 0; e < 4; ++e) hn[4 * n + e] = bs[4 * n + e] + (acc[ai][bj][m][n][e] + bv[bj][n][e]) * scale;
;                     } else { const u32x4 pw = *(const u32x4*)(pp + o);
;                         const float pv[8] = {bflo(pw.x), bfhi(pw.x), bflo(pw.y), bfhi(pw.y), bflo(pw.z), bfhi(pw.z), bflo(pw.w), bfhi(pw.w)};
; #pragma unroll
;                         for (int n = 0; n < 2; ++n)
; #pragma unroll
;                             for (int e = 0; e < 4; ++e) hn[4 * n + e] = bs[4 * n + e] + fast_sigmoid(acc[ai][bj][m][n][e] * rs) * pv[4 * n + e]; }
;                     u32x4 w; w.x = cvt_pk_bf16(hn[0], hn[1]); w.y = cvt_pk_bf16(hn[2], hn[3]); w.z = cvt_pk_bf16(hn[4], hn[5]); w.w = cvt_pk_bf16(hn[6], hn[7]); *(u32x4*)(hb + o) = w;
;                     const float hr[8] = {bflo(w.x), bfhi(w.x), bflo(w.y), bfhi(w.y), bflo(w.z), bfhi(w.z), bflo(w.w), bfhi(w.w)};
;                     ss += ((hr[0] * hr[0] + hr[1] * hr[1]) + (hr[2] * hr[2] + hr[3] * hr[3])) + ((hr[4] * hr[4] + hr[5] * hr[5]) + (hr[6] * hr[6] + hr[7] * hr[7])); }
;                 ss += __shfl_xor(ss, 16); ss += __shfl_xor(ss, 32);
;                 if (fq == 0) rss_out[(size_t)row * 16 + u.pn * 4 + wc] = ss; }
.LBB1_36:
	s_or_b64 exec, exec, s[24:25]
	v_add_u32_e32 v34, 0xa0, v144
	s_waitcnt lgkmcnt(0)
	v_ashrrev_i32_e32 v35, 31, v34
	v_lshlrev_b64 v[36:37], 10, v[34:35]
	v_lshlrev_b64 v[34:35], 6, v[34:35]
	v_lshl_add_u64 v[40:41], v[36:37], 0, v[142:143]
	v_lshl_add_u64 v[36:37], v[146:147], 0, v[34:35]
	global_load_dwordx4 v[36:39], v[36:37], off
	v_lshlrev_b64 v[40:41], 1, v[40:41]
	v_lshl_add_u64 v[216:217], s[16:17], 0, v[40:41]
	v_lshl_add_u64 v[218:219], s[22:23], 0, v[40:41]
	global_load_dwordx4 v[200:203], v[216:217], off
	global_load_dwordx4 v[204:207], v[218:219], off
	global_load_dwordx4 v[208:211], v[216:217], off offset:256
	global_load_dwordx4 v[212:215], v[218:219], off offset:256
	s_waitcnt vmcnt(0)
	v_mov_b32_e32 v42, v37
	v_mov_b32_e32 v43, v38
	v_mov_b32_e32 v37, v39
	v_pk_add_f32 v[36:37], v[42:43], v[36:37]
	v_lshl_add_u64 v[38:39], s[22:23], 0, v[40:41]
	v_add_f32_e32 v36, v36, v37
	v_mov_b32_e32 v37, v36
	s_nop 1
	v_permlane16_swap_b32 v37, v36
	s_waitcnt lgkmcnt(0)
	v_add_f32_e32 v36, v36, v37
	v_mov_b32_e32 v37, v36
	s_nop 1
	v_permlane32_swap_b32 v37, v36
	s_waitcnt lgkmcnt(0)
	v_add_f32_e32 v36, v36, v37
	v_fmamk_f32 v36, v36, 0x3a800000, v173
	v_cmp_gt_f32_e32 vcc, s64, v36
	v_mul_f32_e32 v37, 0x4b800000, v36
	s_nop 0
	v_cndmask_b32_e32 v36, v36, v37, vcc
	v_rsq_f32_e32 v36, v36
	s_nop 0
	v_mul_f32_e32 v37, 0x45800000, v36
	v_cndmask_b32_e32 v42, v36, v37, vcc
	v_lshl_add_u64 v[36:37], s[16:17], 0, v[40:41]
	v_mov_b32_e32 v44, v200
	v_mov_b32_e32 v45, v201
	v_mov_b32_e32 v46, v202
	v_mov_b32_e32 v47, v203
	v_mul_f32_e32 v30, v30, v42
	v_mul_f32_e32 v30, 0xbfb8aa3b, v30
	v_mul_f32_e32 v26, v26, v42
	v_exp_f32_e32 v30, v30
	v_mul_f32_e32 v26, 0xbfb8aa3b, v26
	v_exp_f32_e32 v26, v26
	v_mul_f32_e32 v22, v22, v42
	v_add_f32_e32 v30, 1.0, v30
	v_rcp_f32_e32 v30, v30
	v_add_f32_e32 v26, 1.0, v26
	v_rcp_f32_e32 v26, v26
	v_mul_f32_e32 v18, v18, v42
	v_mul_f32_e32 v22, 0xbfb8aa3b, v22
	v_mul_f32_e32 v18, 0xbfb8aa3b, v18
	v_exp_f32_e32 v22, v22
	v_exp_f32_e32 v18, v18
	v_add_f32_e32 v22, 1.0, v22
	v_add_f32_e32 v18, 1.0, v18
	v_rcp_f32_e32 v22, v22
	v_rcp_f32_e32 v18, v18
	s_nop 0
	v_lshlrev_b32_e32 v43, 16, v44
	v_and_b32_e32 v48, 0xffff0000, v44
	v_lshlrev_b32_e32 v49, 16, v45
	v_and_b32_e32 v50, 0xffff0000, v45
	v_lshlrev_b32_e32 v51, 16, v46
	v_and_b32_e32 v52, 0xffff0000, v46
	v_lshlrev_b32_e32 v53, 16, v47
	v_and_b32_e32 v54, 0xffff0000, v47
	v_mov_b32_e32 v44, v204
	v_mov_b32_e32 v45, v205
	v_mov_b32_e32 v46, v206
	v_mov_b32_e32 v47, v207
	s_nop 0
	v_lshlrev_b32_e32 v55, 16, v44
	v_lshlrev_b32_e32 v57, 16, v46
	v_fmac_f32_e32 v43, v30, v55
	v_mul_f32_e32 v30, v31, v42
	v_mul_f32_e32 v30, 0xbfb8aa3b, v30
	v_fmac_f32_e32 v51, v26, v57
	v_mul_f32_e32 v26, v27, v42
	v_exp_f32_e32 v30, v30
	v_mul_f32_e32 v26, 0xbfb8aa3b, v26
	v_exp_f32_e32 v26, v26
	v_and_b32_e32 v44, 0xffff0000, v44
	v_add_f32_e32 v30, 1.0, v30
	v_rcp_f32_e32 v30, v30
	v_add_f32_e32 v26, 1.0, v26
	v_rcp_f32_e32 v26, v26
	v_and_b32_e32 v46, 0xffff0000, v46
	v_fmac_f32_e32 v48, v30, v44
	v_mul_f32_e32 v30, v32, v42
	v_mul_f32_e32 v30, 0xbfb8aa3b, v30
	v_fmac_f32_e32 v52, v26, v46
	v_mul_f32_e32 v26, v28, v42
	v_exp_f32_e32 v30, v30
	v_mul_f32_e32 v26, 0xbfb8aa3b, v26
	v_exp_f32_e32 v26, v26
	v_lshlrev_b32_e32 v56, 16, v45
	v_add_f32_e32 v30, 1.0, v30
	v_rcp_f32_e32 v30, v30
	v_add_f32_e32 v26, 1.0, v26
	v_rcp_f32_e32 v26, v26
	v_lshlrev_b32_e32 v58, 16, v47
	v_fmac_f32_e32 v49, v30, v56
	v_mul_f32_e32 v30, v33, v42
	v_mul_f32_e32 v30, 0xbfb8aa3b, v30
	v_fmac_f32_e32 v53, v26, v58
	v_mul_f32_e32 v26, v29, v42
	v_exp_f32_e32 v30, v30
	v_mul_f32_e32 v26, 0xbfb8aa3b, v26
	v_exp_f32_e32 v26, v26
	v_and_b32_e32 v45, 0xffff0000, v45
	v_add_f32_e32 v30, 1.0, v30
	v_rcp_f32_e32 v30, v30
	v_add_f32_e32 v26, 1.0, v26
	v_rcp_f32_e32 v26, v26
	v_and_b32_e32 v47, 0xffff0000, v47
	v_fmac_f32_e32 v50, v30, v45
	v_lshl_add_u64 v[30:31], s[18:19], 0, v[40:41]
	v_fmac_f32_e32 v54, v26, v47
	v_cvt_pk_bf16_f32 v26, v43, v48
	v_cvt_pk_bf16_f32 v27, v49, v50
	v_cvt_pk_bf16_f32 v28, v51, v52
	v_cvt_pk_bf16_f32 v29, v53, v54
	global_store_dwordx4 v[30:31], v[26:29], off
	v_mov_b32_e32 v44, v208
	v_mov_b32_e32 v45, v209
	v_mov_b32_e32 v46, v210
	v_mov_b32_e32 v47, v211
	v_lshlrev_b32_e32 v32, 16, v26
	v_and_b32_e32 v26, 0xffff0000, v26
	v_lshlrev_b32_e32 v33, 16, v27
	v_and_b32_e32 v27, 0xffff0000, v27
	v_mul_f32_e32 v26, v26, v26
	v_mul_f32_e32 v27, v27, v27
	v_lshlrev_b32_e32 v40, 16, v28
	v_and_b32_e32 v28, 0xffff0000, v28
	v_lshlrev_b32_e32 v41, 16, v29
	v_and_b32_e32 v29, 0xffff0000, v29
	v_fmac_f32_e32 v26, v32, v32
	v_fmac_f32_e32 v27, v33, v33
	v_add_f32_e32 v26, v26, v27
	v_mul_f32_e32 v27, v28, v28
	v_mul_f32_e32 v28, v29, v29
	v_fmac_f32_e32 v27, v40, v40
	v_fmac_f32_e32 v28, v41, v41
	v_add_f32_e32 v27, v27, v28
	v_add_f32_e32 v26, v26, v27
	s_nop 0
	v_lshlrev_b32_e32 v27, 16, v44
	v_and_b32_e32 v28, 0xffff0000, v44
	v_lshlrev_b32_e32 v29, 16, v45
	v_and_b32_e32 v32, 0xffff0000, v45
	v_lshlrev_b32_e32 v33, 16, v46
	v_and_b32_e32 v36, 0xffff0000, v46
	v_lshlrev_b32_e32 v37, 16, v47
	v_and_b32_e32 v40, 0xffff0000, v47
	v_mov_b32_e32 v44, v212
	v_mov_b32_e32 v45, v213
	v_mov_b32_e32 v46, v214
	v_mov_b32_e32 v47, v215
	s_nop 0
	v_lshlrev_b32_e32 v38, 16, v44
	v_and_b32_e32 v39, 0xffff0000, v44
	v_lshlrev_b32_e32 v44, 16, v46
	v_fmac_f32_e32 v27, v22, v38
	v_mul_f32_e32 v22, v23, v42
	v_fmac_f32_e32 v33, v18, v44
	v_mul_f32_e32 v18, v19, v42
	v_mul_f32_e32 v22, 0xbfb8aa3b, v22
	v_mul_f32_e32 v18, 0xbfb8aa3b, v18
	v_exp_f32_e32 v22, v22
	v_exp_f32_e32 v18, v18
	v_lshlrev_b32_e32 v41, 16, v45
	v_and_b32_e32 v43, 0xffff0000, v45
	v_add_f32_e32 v22, 1.0, v22
	v_add_f32_e32 v18, 1.0, v18
; __device__ __forceinline__ float rstd_of4(const float* rss, int row, int fq) {
;     const f32x4 a = *(const f32x4*)(rss + (size_t)row * 16 + 4 * fq); float s = (a[0] + a[1]) + (a[2] + a[3]);
;     s += __shfl_xor(s, 16); s += __shfl_xor(s, 32);
;     return rsqrtf(s * (1.0f / 1024.0f) + EPS); }
;     __device__ __forceinline__ void operator()(const f32x4 (&acc)[2][2][4][2], const Unit& u, int wr, int wc, int fr, int fq, LAS unsigned char* lds) const {
;     ...
;             for (int m = 0; m < 4; ++m) { const int row = row0 + ai * HALF + m * 16; const size_t off = (size_t)row * D + col0;
;                 float rs = 1.0f; if (MODE == 1) rs = rstd_of4(rss_in, row, fq);
;                 float ss = 0.f;
; #pragma unroll
;                 for (int bj = 0; bj < 2; ++bj) { const size_t o = off + bj * HALF; const u32x4 bw = *(const u32x4*)(base + o);
;                     const float bs[8] = {bflo(bw.x), bfhi(bw.x), bflo(bw.y), bfhi(bw.y), bflo(bw.z), bfhi(bw.z), bflo(bw.w), bfhi(bw.w)};
;                     float hn[8];
;                     if (MODE == 0) {
; #pragma unroll
;                         for (int n = 0; n < 2; ++n)
; #pragma unroll
;                             for (int e = 0; e < 4; ++e) hn[4 * n + e] = bs[4 * n + e] + (acc[ai][bj][m][n][e] + bv[bj][n][e]) * scale;
;                     } else { const u32x4 pw = *(const u32x4*)(pp + o);
;                         const float pv[8] = {bflo(pw.x), bfhi(pw.x), bflo(pw.y), bfhi(pw.y), bflo(pw.z), bfhi(pw.z), bflo(pw.w), bfhi(pw.w)};
; #pragma unroll
;                         for (int n = 0; n < 2; ++n)
; #pragma unroll
;                             for (int e = 0; e < 4; ++e) hn[4 * n + e] = bs[4 * n + e] + fast_sigmoid(acc[ai][bj][m][n][e] * rs) * pv[4 * n + e]; }
;                     u32x4 w; w.x = cvt_pk_bf16(hn[0], hn[1]); w.y = cvt_pk_bf16(hn[2], hn[3]); w.z = cvt_pk_bf16(hn[4], hn[5]); w.w = cvt_pk_bf16(hn[6], hn[7]); *(u32x4*)(hb + o) = w;
;                     const float hr[8] = {bflo(w.x), bfhi(w.x), bflo(w.y), bfhi(w.y), bflo(w.z), bfhi(w.z), bflo(w.w), bfhi(w.w)};
;                     ss += ((hr[0] * hr[0] + hr[1] * hr[1]) + (hr[2] * hr[2] + hr[3] * hr[3])) + ((hr[4] * hr[4] + hr[5] * hr[5]) + (hr[6] * hr[6] + hr[7] * hr[7])); }
;                 ss += __shfl_xor(ss, 16); ss += __shfl_xor(ss, 32);
;                 if (fq == 0) rss_out[(size_t)row * 16 + u.pn * 4 + wc] = ss; }
	v_rcp_f32_e32 v22, v22
	v_rcp_f32_e32 v18, v18
	v_and_b32_e32 v45, 0xffff0000, v46
	v_lshlrev_b32_e32 v46, 16, v47
	v_fmac_f32_e32 v28, v22, v39
	v_mul_f32_e32 v22, v24, v42
	v_fmac_f32_e32 v36, v18, v45
	v_mul_f32_e32 v18, v20, v42
	v_mul_f32_e32 v22, 0xbfb8aa3b, v22
	v_mul_f32_e32 v18, 0xbfb8aa3b, v18
	v_exp_f32_e32 v22, v22
	v_exp_f32_e32 v18, v18
	v_and_b32_e32 v47, 0xffff0000, v47
	v_add_f32_e32 v22, 1.0, v22
	v_add_f32_e32 v18, 1.0, v18
	v_rcp_f32_e32 v22, v22
	v_rcp_f32_e32 v18, v18
	v_fmac_f32_e32 v29, v22, v41
	v_mul_f32_e32 v22, v25, v42
	v_fmac_f32_e32 v37, v18, v46
	v_mul_f32_e32 v18, v21, v42
	v_mul_f32_e32 v22, 0xbfb8aa3b, v22
	v_mul_f32_e32 v18, 0xbfb8aa3b, v18
	v_exp_f32_e32 v22, v22
	v_exp_f32_e32 v18, v18
	v_add_f32_e32 v22, 1.0, v22
	v_add_f32_e32 v18, 1.0, v18
	v_rcp_f32_e32 v22, v22
	v_rcp_f32_e32 v18, v18
	v_fmac_f32_e32 v32, v22, v43
	v_fmac_f32_e32 v40, v18, v47
	v_cvt_pk_bf16_f32 v18, v27, v28
	v_cvt_pk_bf16_f32 v19, v29, v32
	v_cvt_pk_bf16_f32 v20, v33, v36
	v_cvt_pk_bf16_f32 v21, v37, v40
	global_store_dwordx4 v[30:31], v[18:21], off offset:256
	v_lshlrev_b32_e32 v22, 16, v18
	v_lshlrev_b32_e32 v23, 16, v19
	v_and_b32_e32 v18, 0xffff0000, v18
	v_and_b32_e32 v19, 0xffff0000, v19
	v_mul_f32_e32 v18, v18, v18
	v_mul_f32_e32 v19, v19, v19
	v_lshlrev_b32_e32 v24, 16, v20
	v_and_b32_e32 v20, 0xffff0000, v20
	v_lshlrev_b32_e32 v25, 16, v21
	v_and_b32_e32 v21, 0xffff0000, v21
	v_fmac_f32_e32 v18, v22, v22
	v_fmac_f32_e32 v19, v23, v23
	v_add_f32_e32 v18, v18, v19
	v_mul_f32_e32 v19, v20, v20
	v_mul_f32_e32 v20, v21, v21
	v_fmac_f32_e32 v19, v24, v24
	v_fmac_f32_e32 v20, v25, v25
	v_add_f32_e32 v19, v19, v20
	v_add_f32_e32 v18, v18, v19
	v_add_f32_e32 v18, v26, v18
	v_mov_b32_e32 v19, v18
	s_nop 1
	v_permlane16_swap_b32 v19, v18
	s_waitcnt lgkmcnt(0)
	v_add_f32_e32 v18, v18, v19
	v_mov_b32_e32 v19, v18
	s_nop 1
	v_permlane32_swap_b32 v19, v18
	s_and_saveexec_b64 s[24:25], s[6:7]
	s_cbranch_execz .LBB1_38
	s_lshl_b32 s66, s41, 2
	v_lshl_add_u64 v[20:21], s[20:21], 0, v[34:35]
	s_ashr_i32 s67, s66, 31
	v_lshl_add_u64 v[20:21], s[66:67], 2, v[20:21]
	s_lshl_b32 s74, s40, 2
	v_lshl_add_u64 v[20:21], v[20:21], 0, s[74:75]
	s_waitcnt lgkmcnt(0)
	v_add_f32_e32 v18, v18, v19
	global_store_dword v[20:21], v18, off
.LBB1_38:
	s_or_b64 exec, exec, s[24:25]
	v_add_u32_e32 v20, 0xb0, v144
	v_ashrrev_i32_e32 v21, 31, v20
	s_waitcnt lgkmcnt(0)
	v_lshlrev_b64 v[18:19], 6, v[20:21]
	v_lshl_add_u64 v[22:23], v[146:147], 0, v[18:19]
	global_load_dwordx4 v[22:25], v[22:23], off
	v_lshlrev_b64 v[20:21], 10, v[20:21]
	v_lshl_add_u64 v[20:21], v[20:21], 0, v[142:143]
	v_lshlrev_b64 v[20:21], 1, v[20:21]
	v_lshl_add_u64 v[34:35], s[16:17], 0, v[20:21]
	v_lshl_add_u64 v[36:37], s[22:23], 0, v[20:21]
	global_load_dwordx4 v[26:29], v[34:35], off
	global_load_dwordx4 v[30:33], v[36:37], off
	v_lshl_add_u64 v[20:21], s[18:19], 0, v[20:21]
	s_waitcnt vmcnt(2)
	v_mov_b32_e32 v38, v23
	v_mov_b32_e32 v39, v24
	v_mov_b32_e32 v23, v25
	v_pk_add_f32 v[22:23], v[38:39], v[22:23]
	s_waitcnt vmcnt(1)
	v_and_b32_e32 v24, 0xffff0000, v26
	v_add_f32_e32 v22, v22, v23
	v_mov_b32_e32 v38, v22
	s_nop 1
	v_permlane16_swap_b32 v38, v22
	v_lshlrev_b32_e32 v23, 16, v26
	v_lshlrev_b32_e32 v25, 16, v27
	v_and_b32_e32 v26, 0xffff0000, v27
	v_lshlrev_b32_e32 v27, 16, v28
	s_waitcnt lgkmcnt(0)
	v_add_f32_e32 v22, v22, v38
	v_mov_b32_e32 v38, v22
	s_nop 1
	v_permlane32_swap_b32 v38, v22
	v_and_b32_e32 v28, 0xffff0000, v28
	v_lshlrev_b32_e32 v39, 16, v29
	v_and_b32_e32 v29, 0xffff0000, v29
	s_waitcnt vmcnt(0)
	v_lshlrev_b32_e32 v40, 16, v30
	s_waitcnt lgkmcnt(0)
; __device__ __forceinline__ float rstd_of4(const float* rss, int row, int fq) {
;     const f32x4 a = *(const f32x4*)(rss + (size_t)row * 16 + 4 * fq); float s = (a[0] + a[1]) + (a[2] + a[3]);
;     s += __shfl_xor(s, 16); s += __shfl_xor(s, 32);
;     return rsqrtf(s * (1.0f / 1024.0f) + EPS); }
;     __device__ __forceinline__ void operator()(const f32x4 (&acc)[2][2][4][2], const Unit& u, int wr, int wc, int fr, int fq, LAS unsigned char* lds) const {
;     ...
;             for (int m = 0; m < 4; ++m) { const int row = row0 + ai * HALF + m * 16; const size_t off = (size_t)row * D + col0;
;                 float rs = 1.0f; if (MODE == 1) rs = rstd_of4(rss_in, row, fq);
;                 float ss = 0.f;
; #pragma unroll
;                 for (int bj = 0; bj < 2; ++bj) { const size_t o = off + bj * HALF; const u32x4 bw = *(const u32x4*)(base + o);
;                     const float bs[8] = {bflo(bw.x), bfhi(bw.x), bflo(bw.y), bfhi(bw.y), bflo(bw.z), bfhi(bw.z), bflo(bw.w), bfhi(bw.w)};
;                     float hn[8];
;                     if (MODE == 0) {
; #pragma unroll
;                         for (int n = 0; n < 2; ++n)
; #pragma unroll
;                             for (int e = 0; e < 4; ++e) hn[4 * n + e] = bs[4 * n + e] + (acc[ai][bj][m][n][e] + bv[bj][n][e]) * scale;
;                     } else { const u32x4 pw = *(const u32x4*)(pp + o);
;                         const float pv[8] = {bflo(pw.x), bfhi(pw.x), bflo(pw.y), bfhi(pw.y), bflo(pw.z), bfhi(pw.z), bflo(pw.w), bfhi(pw.w)};
; #pragma unroll
;                         for (int n = 0; n < 2; ++n)
; #pragma unroll
;                             for (int e = 0; e < 4; ++e) hn[4 * n + e] = bs[4 * n + e] + fast_sigmoid(acc[ai][bj][m][n][e] * rs) * pv[4 * n + e]; }
;                     u32x4 w; w.x = cvt_pk_bf16(hn[0], hn[1]); w.y = cvt_pk_bf16(hn[2], hn[3]); w.z = cvt_pk_bf16(hn[4], hn[5]); w.w = cvt_pk_bf16(hn[6], hn[7]); *(u32x4*)(hb + o) = w;
;                     const float hr[8] = {bflo(w.x), bfhi(w.x), bflo(w.y), bfhi(w.y), bflo(w.z), bfhi(w.z), bflo(w.w), bfhi(w.w)};
;                     ss += ((hr[0] * hr[0] + hr[1] * hr[1]) + (hr[2] * hr[2] + hr[3] * hr[3])) + ((hr[4] * hr[4] + hr[5] * hr[5]) + (hr[6] * hr[6] + hr[7] * hr[7])); }
;                 ss += __shfl_xor(ss, 16); ss += __shfl_xor(ss, 32);
;                 if (fq == 0) rss_out[(size_t)row * 16 + u.pn * 4 + wc] = ss; }
	v_add_f32_e32 v22, v22, v38
	v_fmamk_f32 v22, v22, 0x3a800000, v173
	v_mul_f32_e32 v38, 0x4b800000, v22
	v_cmp_gt_f32_e32 vcc, s64, v22
	v_and_b32_e32 v30, 0xffff0000, v30
	v_lshlrev_b32_e32 v41, 16, v31
	v_cndmask_b32_e32 v22, v22, v38, vcc
	v_rsq_f32_e32 v22, v22
	v_and_b32_e32 v31, 0xffff0000, v31
	v_lshlrev_b32_e32 v42, 16, v32
	v_and_b32_e32 v32, 0xffff0000, v32
	v_mul_f32_e32 v43, 0x45800000, v22
	v_cndmask_b32_e32 v43, v22, v43, vcc
	v_mul_f32_e32 v14, v14, v43
	v_mul_f32_e32 v15, v15, v43
	v_mul_f32_e32 v16, v16, v43
	v_mul_f32_e32 v17, v17, v43
	v_mul_f32_e32 v10, v10, v43
	v_mul_f32_e32 v11, v11, v43
	v_mul_f32_e32 v12, v12, v43
	v_mul_f32_e32 v13, v13, v43
	v_mul_f32_e32 v14, 0xbfb8aa3b, v14
	v_mul_f32_e32 v15, 0xbfb8aa3b, v15
	v_mul_f32_e32 v16, 0xbfb8aa3b, v16
	v_mul_f32_e32 v17, 0xbfb8aa3b, v17
	v_mul_f32_e32 v10, 0xbfb8aa3b, v10
	v_mul_f32_e32 v11, 0xbfb8aa3b, v11
	v_mul_f32_e32 v12, 0xbfb8aa3b, v12
	v_mul_f32_e32 v13, 0xbfb8aa3b, v13
	v_exp_f32_e32 v14, v14
	v_exp_f32_e32 v15, v15
	v_exp_f32_e32 v16, v16
	v_exp_f32_e32 v17, v17
	v_exp_f32_e32 v10, v10
	v_exp_f32_e32 v11, v11
	v_exp_f32_e32 v12, v12
	v_exp_f32_e32 v13, v13
	v_add_f32_e32 v14, 1.0, v14
	v_add_f32_e32 v15, 1.0, v15
	v_add_f32_e32 v16, 1.0, v16
	v_add_f32_e32 v17, 1.0, v17
	v_add_f32_e32 v10, 1.0, v10
	v_add_f32_e32 v11, 1.0, v11
	v_add_f32_e32 v12, 1.0, v12
	v_add_f32_e32 v13, 1.0, v13
	v_rcp_f32_e32 v14, v14
	v_rcp_f32_e32 v15, v15
	v_rcp_f32_e32 v16, v16
	v_rcp_f32_e32 v17, v17
	v_rcp_f32_e32 v10, v10
	v_rcp_f32_e32 v11, v11
	v_rcp_f32_e32 v12, v12
	v_rcp_f32_e32 v13, v13
	v_lshlrev_b32_e32 v38, 16, v33
	v_and_b32_e32 v33, 0xffff0000, v33
	v_fmac_f32_e32 v23, v14, v40
	v_fmac_f32_e32 v24, v15, v30
	v_fmac_f32_e32 v25, v16, v41
	v_fmac_f32_e32 v26, v17, v31
	v_fmac_f32_e32 v27, v10, v42
	v_fmac_f32_e32 v28, v11, v32
	v_fmac_f32_e32 v39, v12, v38
	v_fmac_f32_e32 v29, v13, v33
	v_cvt_pk_bf16_f32 v10, v23, v24
	v_cvt_pk_bf16_f32 v11, v25, v26
	v_cvt_pk_bf16_f32 v12, v27, v28
	v_cvt_pk_bf16_f32 v13, v39, v29
	global_store_dwordx4 v[20:21], v[10:13], off
	global_load_dwordx4 v[14:17], v[34:35], off offset:256
	global_load_dwordx4 v[22:25], v[36:37], off offset:256
	v_mul_f32_e32 v7, v7, v43
	v_mul_f32_e32 v9, v9, v43
	v_mul_f32_e32 v6, v6, v43
	v_mul_f32_e32 v8, v8, v43
	v_mul_f32_e32 v0, v0, v43
	v_mul_f32_e32 v1, v1, v43
	v_mul_f32_e32 v2, v2, v43
	v_mul_f32_e32 v3, v3, v43
	v_mul_f32_e32 v7, 0xbfb8aa3b, v7
	v_mul_f32_e32 v9, 0xbfb8aa3b, v9
	v_mul_f32_e32 v6, 0xbfb8aa3b, v6
	v_mul_f32_e32 v8, 0xbfb8aa3b, v8
	v_mul_f32_e32 v0, 0xbfb8aa3b, v0
	v_mul_f32_e32 v1, 0xbfb8aa3b, v1
	v_mul_f32_e32 v2, 0xbfb8aa3b, v2
	v_mul_f32_e32 v3, 0xbfb8aa3b, v3
	v_exp_f32_e32 v7, v7
	v_exp_f32_e32 v9, v9
	v_exp_f32_e32 v6, v6
	v_exp_f32_e32 v8, v8
	v_exp_f32_e32 v0, v0
	v_exp_f32_e32 v1, v1
	v_exp_f32_e32 v2, v2
	v_exp_f32_e32 v3, v3
	v_add_f32_e32 v7, 1.0, v7
	v_add_f32_e32 v9, 1.0, v9
	v_lshlrev_b32_e32 v26, 16, v10
	v_and_b32_e32 v10, 0xffff0000, v10
	v_lshlrev_b32_e32 v27, 16, v11
	v_and_b32_e32 v11, 0xffff0000, v11
	v_lshlrev_b32_e32 v28, 16, v12
	v_and_b32_e32 v12, 0xffff0000, v12
	v_lshlrev_b32_e32 v29, 16, v13
	v_and_b32_e32 v13, 0xffff0000, v13
	v_add_f32_e32 v6, 1.0, v6
	v_add_f32_e32 v8, 1.0, v8
	v_add_f32_e32 v0, 1.0, v0
	v_add_f32_e32 v1, 1.0, v1
	v_add_f32_e32 v2, 1.0, v2
	v_add_f32_e32 v3, 1.0, v3
	v_rcp_f32_e32 v7, v7
	v_rcp_f32_e32 v9, v9
	v_mul_f32_e32 v10, v10, v10
	v_mul_f32_e32 v11, v11, v11
	v_mul_f32_e32 v12, v12, v12
	v_mul_f32_e32 v13, v13, v13
	v_rcp_f32_e32 v6, v6
	v_rcp_f32_e32 v8, v8
	v_rcp_f32_e32 v0, v0
	v_rcp_f32_e32 v1, v1
	v_rcp_f32_e32 v2, v2
	v_rcp_f32_e32 v3, v3
	v_fmac_f32_e32 v10, v26, v26
	v_fmac_f32_e32 v11, v27, v27
	v_fmac_f32_e32 v12, v28, v28
	v_fmac_f32_e32 v13, v29, v29
	v_add_f32_e32 v10, v10, v11
	v_add_f32_e32 v11, v12, v13
	v_add_f32_e32 v10, v10, v11
	s_waitcnt vmcnt(1)
	v_lshlrev_b32_e32 v11, 16, v14
	v_and_b32_e32 v12, 0xffff0000, v14
	v_and_b32_e32 v14, 0xffff0000, v15
	s_waitcnt vmcnt(0)
	v_lshlrev_b32_e32 v27, 16, v22
	v_and_b32_e32 v22, 0xffff0000, v22
	v_lshlrev_b32_e32 v28, 16, v23
	v_and_b32_e32 v23, 0xffff0000, v23
	v_lshlrev_b32_e32 v13, 16, v15
	v_lshlrev_b32_e32 v15, 16, v16
	v_and_b32_e32 v16, 0xffff0000, v16
	v_lshlrev_b32_e32 v26, 16, v17
	v_and_b32_e32 v17, 0xffff0000, v17
	v_lshlrev_b32_e32 v29, 16, v24
	v_and_b32_e32 v24, 0xffff0000, v24
	v_lshlrev_b32_e32 v30, 16, v25
	v_and_b32_e32 v25, 0xffff0000, v25
	v_fmac_f32_e32 v12, v7, v22
	v_fmac_f32_e32 v14, v9, v23
	v_fmac_f32_e32 v11, v6, v27
	v_fmac_f32_e32 v13, v8, v28
	v_fmac_f32_e32 v15, v0, v29
	v_fmac_f32_e32 v16, v1, v24
	v_fmac_f32_e32 v26, v2, v30
	v_fmac_f32_e32 v17, v3, v25
	v_cvt_pk_bf16_f32 v6, v11, v12
	v_cvt_pk_bf16_f32 v7, v13, v14
	v_cvt_pk_bf16_f32 v8, v15, v16
	v_cvt_pk_bf16_f32 v9, v26, v17
	global_store_dwordx4 v[20:21], v[6:9], off offset:256
	v_and_b32_e32 v1, 0xffff0000, v6
	v_and_b32_e32 v3, 0xffff0000, v7
	v_and_b32_e32 v12, 0xffff0000, v8
	v_and_b32_e32 v14, 0xffff0000, v9
	v_lshlrev_b32_e32 v0, 16, v6
	v_lshlrev_b32_e32 v2, 16, v7
	v_lshlrev_b32_e32 v11, 16, v8
	v_lshlrev_b32_e32 v13, 16, v9
	v_mul_f32_e32 v1, v1, v1
	v_mul_f32_e32 v3, v3, v3
	v_mul_f32_e32 v12, v12, v12
	v_mul_f32_e32 v14, v14, v14
	v_fmac_f32_e32 v1, v0, v0
	v_fmac_f32_e32 v3, v2, v2
	v_fmac_f32_e32 v12, v11, v11
	v_fmac_f32_e32 v14, v13, v13
	v_add_f32_e32 v0, v1, v3
	v_add_f32_e32 v1, v12, v14
	v_add_f32_e32 v0, v0, v1
	v_add_f32_e32 v0, v10, v0
	ds_bpermute_b32 v1, v158, v0
	s_waitcnt lgkmcnt(0)
	v_add_f32_e32 v0, v0, v1
	ds_bpermute_b32 v1, v145, v0
	s_and_saveexec_b64 s[16:17], s[6:7]
	s_cbranch_execz .LBB1_19
	s_lshl_b32 s18, s41, 2
	v_lshl_add_u64 v[2:3], s[20:21], 0, v[18:19]
	s_ashr_i32 s19, s18, 31
	v_lshl_add_u64 v[2:3], s[18:19], 2, v[2:3]
	s_lshl_b32 s74, s40, 2
	v_lshl_add_u64 v[2:3], v[2:3], 0, s[74:75]
	s_waitcnt lgkmcnt(0)
	v_add_f32_e32 v0, v0, v1
	global_store_dword v[2:3], v0, off
	s_branch .LBB1_19

; template <class Epi, int KK, int LDA, int LDB, int NN, bool AGRP>
; __device__ __forceinline__ void gemm_phase(LAS unsigned char* lds, const bf16_t* gA, const bf16_t* gBt, int G_, int bid_, int tid) {
;     ...
;         const bool has_next = S.next(ui + 1, nxt);
;         const char* nA = has_next ? (const char*)g.A + (size_t)nxt.pm * tstepA + PG8_ACOL(nxt.pn) : cA; const char* nB = has_next ? (const char*)g.Bt + (size_t)nxt.pn * tstepB : cB;
;     ...
; #pragma unroll
;         for (int a = 0; a < 2; ++a)
; #pragma unroll
;             for (int b = 0; b < 2; ++b)
; #pragma unroll
;                 for (int m = 0; m < 4; ++m)
; #pragma unroll
;                     for (int n = 0; n < 2; ++n) acc[a][b][m][n] = (f32x4){zr, zr, zr, zr};
;         cur = nxt; cA = nA; cB = nB; ++ui;
.LBB1_71:
	s_ashr_i32 s1, s0, 31
	s_lshl_b64 s[12:13], s[0:1], 17
	s_add_u32 s12, s40, s12
	s_addc_u32 s13, s41, s13
	s_and_b64 s[14:15], s[22:23], exec
	s_cselect_b32 s1, s13, s21
	s_cselect_b32 s7, s12, s20
	s_ashr_i32 s9, s8, 31
	s_lshl_b64 s[14:15], s[8:9], 17
	s_add_u32 s14, s43, s14
	s_addc_u32 s15, s44, s15
	s_and_b64 s[22:23], s[22:23], exec
	s_cselect_b32 s9, s15, s19
	s_cselect_b32 s17, s14, s18
	s_mov_b64 s[26:27], 0
	s_mov_b64 s[22:23], -1
	s_mov_b64 s[24:25], 0
	v_mov_b32_e32 v0, v161
	v_mov_b32_e32 v1, v161
	v_mov_b32_e32 v2, v161
	v_mov_b32_e32 v3, v161
	v_mov_b32_e32 v6, v161
	v_mov_b32_e32 v7, v161
	v_mov_b32_e32 v8, v161
	v_mov_b32_e32 v9, v161
	v_mov_b32_e32 v18, v161
	v_mov_b32_e32 v19, v161
	v_mov_b32_e32 v20, v161
	v_mov_b32_e32 v21, v161
	v_mov_b32_e32 v22, v161
	v_mov_b32_e32 v23, v161
	v_mov_b32_e32 v24, v161
	v_mov_b32_e32 v25, v161
	v_mov_b32_e32 v34, v161
	v_mov_b32_e32 v35, v161
	v_mov_b32_e32 v36, v161
	v_mov_b32_e32 v37, v161
	v_mov_b32_e32 v38, v161
	v_mov_b32_e32 v39, v161
	v_mov_b32_e32 v40, v161
	v_mov_b32_e32 v41, v161
	v_mov_b32_e32 v50, v161
	v_mov_b32_e32 v51, v161
	v_mov_b32_e32 v52, v161
	v_mov_b32_e32 v53, v161
	v_mov_b32_e32 v54, v161
	v_mov_b32_e32 v55, v161
	v_mov_b32_e32 v56, v161
	v_mov_b32_e32 v57, v161
	v_mov_b32_e32 v10, v161
	v_mov_b32_e32 v11, v161
	v_mov_b32_e32 v12, v161
	v_mov_b32_e32 v13, v161
	v_mov_b32_e32 v14, v161
	v_mov_b32_e32 v15, v161
	v_mov_b32_e32 v16, v161
	v_mov_b32_e32 v17, v161
	v_mov_b32_e32 v26, v161
	v_mov_b32_e32 v27, v161
	v_mov_b32_e32 v28, v161
	v_mov_b32_e32 v29, v161
	v_mov_b32_e32 v30, v161
	v_mov_b32_e32 v31, v161
	v_mov_b32_e32 v32, v161
	v_mov_b32_e32 v33, v161
	v_mov_b32_e32 v42, v161
	v_mov_b32_e32 v43, v161
	v_mov_b32_e32 v44, v161
	v_mov_b32_e32 v45, v161
	v_mov_b32_e32 v46, v161
	v_mov_b32_e32 v47, v161
	v_mov_b32_e32 v48, v161
	v_mov_b32_e32 v49, v161
	v_mov_b32_e32 v58, v161
	v_mov_b32_e32 v59, v161
	v_mov_b32_e32 v60, v161
	v_mov_b32_e32 v61, v161
	v_mov_b32_e32 v62, v161
	v_mov_b32_e32 v63, v161
	v_mov_b32_e32 v64, v161
	v_mov_b32_e32 v65, v161
	v_mov_b32_e32 v66, v161
	v_mov_b32_e32 v67, v161
	v_mov_b32_e32 v68, v161
	v_mov_b32_e32 v69, v161
	v_mov_b32_e32 v70, v161
	v_mov_b32_e32 v71, v161
	v_mov_b32_e32 v72, v161
	v_mov_b32_e32 v73, v161
	s_nop 0
	v_mov_b32_e32 v82, v161
	v_mov_b32_e32 v83, v161
	v_mov_b32_e32 v84, v161
	v_mov_b32_e32 v85, v161
	v_mov_b32_e32 v86, v161
	v_mov_b32_e32 v87, v161
	v_mov_b32_e32 v88, v161
	v_mov_b32_e32 v89, v161
	v_mov_b32_e32 v112, v161
	v_mov_b32_e32 v113, v161
	v_mov_b32_e32 v114, v161
	v_mov_b32_e32 v115, v161
	v_mov_b32_e32 v116, v161
	v_mov_b32_e32 v117, v161
	v_mov_b32_e32 v118, v161
	v_mov_b32_e32 v119, v161
	v_mov_b32_e32 v128, v161
	v_mov_b32_e32 v129, v161
	v_mov_b32_e32 v130, v161
	v_mov_b32_e32 v131, v161
	v_mov_b32_e32 v132, v161
	v_mov_b32_e32 v133, v161
	v_mov_b32_e32 v134, v161
	v_mov_b32_e32 v135, v161
	v_mov_b32_e32 v74, v161
	v_mov_b32_e32 v75, v161
	v_mov_b32_e32 v76, v161
	v_mov_b32_e32 v77, v161
	v_mov_b32_e32 v78, v161
	v_mov_b32_e32 v79, v161
	v_mov_b32_e32 v80, v161
	v_mov_b32_e32 v81, v161
	v_mov_b32_e32 v90, v161
	v_mov_b32_e32 v91, v161
	v_mov_b32_e32 v92, v161
	v_mov_b32_e32 v93, v161
	v_mov_b32_e32 v98, v161
	v_mov_b32_e32 v99, v161
	v_mov_b32_e32 v100, v161
	v_mov_b32_e32 v101, v161
	v_mov_b32_e32 v120, v161
	v_mov_b32_e32 v121, v161
	v_mov_b32_e32 v122, v161
	v_mov_b32_e32 v123, v161
	v_mov_b32_e32 v124, v161
	v_mov_b32_e32 v125, v161
	v_mov_b32_e32 v126, v161
	v_mov_b32_e32 v127, v161
	v_mov_b32_e32 v136, v161
	v_mov_b32_e32 v137, v161
	v_mov_b32_e32 v138, v161
	v_mov_b32_e32 v139, v161
	v_mov_b32_e32 v140, v161
	v_mov_b32_e32 v141, v161
	v_mov_b32_e32 v142, v161
	v_mov_b32_e32 v143, v161

; template <class Epi, int KK, int LDA, int LDB, int NN, bool AGRP>
; __device__ __forceinline__ void gemm_phase(LAS unsigned char* lds, const bf16_t* gA, const bf16_t* gBt, int G_, int bid_, int tid) {
;     ...
;         const bool has_next = S.next(ui + 1, nxt);
;         const char* nA = has_next ? (const char*)g.A + (size_t)nxt.pm * tstepA + PG8_ACOL(nxt.pn) : cA; const char* nB = has_next ? (const char*)g.Bt + (size_t)nxt.pn * tstepB : cB;
;     ...
; #pragma unroll
;         for (int a = 0; a < 2; ++a)
; #pragma unroll
;             for (int b = 0; b < 2; ++b)
; #pragma unroll
;                 for (int m = 0; m < 4; ++m)
; #pragma unroll
;                     for (int n = 0; n < 2; ++n) acc[a][b][m][n] = (f32x4){zr, zr, zr, zr};
;         cur = nxt; cA = nA; cB = nB; ++ui;
.LBB1_280:
	s_ashr_i32 s7, s6, 31
	s_lshl_b64 s[12:13], s[6:7], 19
	s_add_u32 s1, s39, s12
	s_addc_u32 s7, s40, s13
	s_lshl_b32 s9, s8, 8
	s_and_b32 s9, s9, 0x600
	s_add_u32 s12, s1, s9
	s_addc_u32 s13, s7, 0
	s_and_b64 s[14:15], s[20:21], exec
	s_cselect_b32 s1, s13, s19
	s_cselect_b32 s7, s12, s18
	s_ashr_i32 s9, s8, 31
	s_lshl_b64 s[14:15], s[8:9], 17
	s_add_u32 s14, s41, s14
	s_addc_u32 s15, s43, s15
	s_and_b64 s[20:21], s[20:21], exec
	s_cselect_b32 s9, s15, s17
	s_cselect_b32 s35, s14, s16
	s_mov_b64 s[24:25], 0
	s_mov_b64 s[20:21], -1
	s_mov_b64 s[22:23], 0
	v_mov_b32_e32 v0, v164
	v_mov_b32_e32 v1, v164
	v_mov_b32_e32 v2, v164
	v_mov_b32_e32 v3, v164
	v_mov_b32_e32 v10, v164
	v_mov_b32_e32 v11, v164
	v_mov_b32_e32 v12, v164
	v_mov_b32_e32 v13, v164
	v_mov_b32_e32 v18, v164
	v_mov_b32_e32 v19, v164
	v_mov_b32_e32 v20, v164
	v_mov_b32_e32 v21, v164
	v_mov_b32_e32 v26, v164
	v_mov_b32_e32 v27, v164
	v_mov_b32_e32 v28, v164
	v_mov_b32_e32 v29, v164
	v_mov_b32_e32 v34, v164
	v_mov_b32_e32 v35, v164
	v_mov_b32_e32 v36, v164
	v_mov_b32_e32 v37, v164
	v_mov_b32_e32 v42, v164
	v_mov_b32_e32 v43, v164
	v_mov_b32_e32 v44, v164
	v_mov_b32_e32 v45, v164
	v_mov_b32_e32 v50, v164
	v_mov_b32_e32 v51, v164
	v_mov_b32_e32 v52, v164
	v_mov_b32_e32 v53, v164
	v_mov_b32_e32 v58, v164
	v_mov_b32_e32 v59, v164
	v_mov_b32_e32 v60, v164
	v_mov_b32_e32 v61, v164
	v_mov_b32_e32 v6, v164
	v_mov_b32_e32 v7, v164
	v_mov_b32_e32 v8, v164
	v_mov_b32_e32 v9, v164
	v_mov_b32_e32 v14, v164
	v_mov_b32_e32 v15, v164
	v_mov_b32_e32 v16, v164
	v_mov_b32_e32 v17, v164
	v_mov_b32_e32 v22, v164
	v_mov_b32_e32 v23, v164
	v_mov_b32_e32 v24, v164
	v_mov_b32_e32 v25, v164
	v_mov_b32_e32 v30, v164
	v_mov_b32_e32 v31, v164
	v_mov_b32_e32 v32, v164
	v_mov_b32_e32 v33, v164
	v_mov_b32_e32 v38, v164
	v_mov_b32_e32 v39, v164
	v_mov_b32_e32 v40, v164
	v_mov_b32_e32 v41, v164
	v_mov_b32_e32 v46, v164
	v_mov_b32_e32 v47, v164
	v_mov_b32_e32 v48, v164
	v_mov_b32_e32 v49, v164
	v_mov_b32_e32 v54, v164
	v_mov_b32_e32 v55, v164
	v_mov_b32_e32 v56, v164
	v_mov_b32_e32 v57, v164
	v_mov_b32_e32 v62, v164
	v_mov_b32_e32 v63, v164
	v_mov_b32_e32 v64, v164
	v_mov_b32_e32 v65, v164
	s_nop 0
	v_mov_b32_e32 v90, v164
	v_mov_b32_e32 v91, v164
	v_mov_b32_e32 v92, v164
	v_mov_b32_e32 v93, v164
	v_mov_b32_e32 v98, v164
	v_mov_b32_e32 v99, v164
	v_mov_b32_e32 v100, v164
	v_mov_b32_e32 v101, v164
	v_mov_b32_e32 v106, v164
	v_mov_b32_e32 v107, v164
	v_mov_b32_e32 v108, v164
	v_mov_b32_e32 v109, v164
	v_mov_b32_e32 v114, v164
	v_mov_b32_e32 v115, v164
	v_mov_b32_e32 v116, v164
	v_mov_b32_e32 v117, v164
	v_mov_b32_e32 v122, v164
	v_mov_b32_e32 v123, v164
	v_mov_b32_e32 v124, v164
	v_mov_b32_e32 v125, v164
	v_mov_b32_e32 v130, v164
	v_mov_b32_e32 v131, v164
	v_mov_b32_e32 v132, v164
	v_mov_b32_e32 v133, v164
	v_mov_b32_e32 v138, v164
	v_mov_b32_e32 v139, v164
	v_mov_b32_e32 v140, v164
	v_mov_b32_e32 v141, v164
	v_mov_b32_e32 v146, v164
	v_mov_b32_e32 v147, v164
	v_mov_b32_e32 v148, v164
	v_mov_b32_e32 v149, v164
	v_mov_b32_e32 v94, v164
	v_mov_b32_e32 v95, v164
	v_mov_b32_e32 v96, v164
	v_mov_b32_e32 v97, v164
	v_mov_b32_e32 v102, v164
	v_mov_b32_e32 v103, v164
	v_mov_b32_e32 v104, v164
	v_mov_b32_e32 v105, v164
	v_mov_b32_e32 v110, v164
	v_mov_b32_e32 v111, v164
	v_mov_b32_e32 v112, v164
	v_mov_b32_e32 v113, v164
	v_mov_b32_e32 v118, v164
	v_mov_b32_e32 v119, v164
	v_mov_b32_e32 v120, v164
	v_mov_b32_e32 v121, v164
	v_mov_b32_e32 v126, v164
	v_mov_b32_e32 v127, v164
	v_mov_b32_e32 v128, v164
	v_mov_b32_e32 v129, v164
	v_mov_b32_e32 v134, v164
	v_mov_b32_e32 v135, v164
	v_mov_b32_e32 v136, v164
	v_mov_b32_e32 v137, v164
	v_mov_b32_e32 v142, v164
	v_mov_b32_e32 v143, v164
	v_mov_b32_e32 v144, v164
	v_mov_b32_e32 v145, v164
	v_mov_b32_e32 v150, v164
	v_mov_b32_e32 v151, v164
	v_mov_b32_e32 v152, v164
	v_mov_b32_e32 v153, v164

; template <class Epi, int KK, int LDA, int LDB, int NN, bool AGRP>
; __device__ __forceinline__ void gemm_phase(LAS unsigned char* lds, const bf16_t* gA, const bf16_t* gBt, int G_, int bid_, int tid) {
;     ...
;         const bool has_next = S.next(ui + 1, nxt);
;         const char* nA = has_next ? (const char*)g.A + (size_t)nxt.pm * tstepA + PG8_ACOL(nxt.pn) : cA; const char* nB = has_next ? (const char*)g.Bt + (size_t)nxt.pn * tstepB : cB;
;     ...
; #pragma unroll
;         for (int a = 0; a < 2; ++a)
; #pragma unroll
;             for (int b = 0; b < 2; ++b)
; #pragma unroll
;                 for (int m = 0; m < 4; ++m)
; #pragma unroll
;                     for (int n = 0; n < 2; ++n) acc[a][b][m][n] = (f32x4){zr, zr, zr, zr};
;         cur = nxt; cA = nA; cB = nB; ++ui;
.LBB1_667:
	s_ashr_i32 s1, s0, 31
	s_lshl_b64 s[12:13], s[0:1], 19
	s_add_u32 s12, s96, s12
	s_addc_u32 s13, s97, s13
	s_and_b64 s[14:15], s[22:23], exec
	s_cselect_b32 s1, s13, s21
	s_cselect_b32 s7, s12, s20
	s_ashr_i32 s9, s8, 31
	s_lshl_b64 s[14:15], s[8:9], 19
	s_add_u32 s14, s24, s14
	s_addc_u32 s15, s25, s15
	s_and_b64 s[22:23], s[22:23], exec
	s_cselect_b32 s9, s15, s19
	s_cselect_b32 s17, s14, s18
	s_add_u32 s34, s18, 0x100
	s_addc_u32 s35, s19, 0
	s_add_u32 s18, s20, 0x40080
	s_addc_u32 s19, s21, 0
	s_mov_b32 s57, -2
	v_mov_b32_e32 v0, v182
	v_mov_b32_e32 v1, v182
	v_mov_b32_e32 v2, v182
	v_mov_b32_e32 v3, v182
	v_mov_b32_e32 v6, v182
	v_mov_b32_e32 v7, v182
	v_mov_b32_e32 v8, v182
	v_mov_b32_e32 v9, v182
	v_mov_b32_e32 v18, v182
	v_mov_b32_e32 v19, v182
	v_mov_b32_e32 v20, v182
	v_mov_b32_e32 v21, v182
	v_mov_b32_e32 v22, v182
	v_mov_b32_e32 v23, v182
	v_mov_b32_e32 v24, v182
	v_mov_b32_e32 v25, v182
	v_mov_b32_e32 v34, v182
	v_mov_b32_e32 v35, v182
	v_mov_b32_e32 v36, v182
	v_mov_b32_e32 v37, v182
	v_mov_b32_e32 v38, v182
	v_mov_b32_e32 v39, v182
	v_mov_b32_e32 v40, v182
	v_mov_b32_e32 v41, v182
	v_mov_b32_e32 v50, v182
	v_mov_b32_e32 v51, v182
	v_mov_b32_e32 v52, v182
	v_mov_b32_e32 v53, v182
	v_mov_b32_e32 v54, v182
	v_mov_b32_e32 v55, v182
	v_mov_b32_e32 v56, v182
	v_mov_b32_e32 v57, v182
	v_mov_b32_e32 v10, v182
	v_mov_b32_e32 v11, v182
	v_mov_b32_e32 v12, v182
	v_mov_b32_e32 v13, v182
	v_mov_b32_e32 v14, v182
	v_mov_b32_e32 v15, v182
	v_mov_b32_e32 v16, v182
	v_mov_b32_e32 v17, v182
	v_mov_b32_e32 v26, v182
	v_mov_b32_e32 v27, v182
	v_mov_b32_e32 v28, v182
	v_mov_b32_e32 v29, v182
	v_mov_b32_e32 v30, v182
	v_mov_b32_e32 v31, v182
	v_mov_b32_e32 v32, v182
	v_mov_b32_e32 v33, v182
	v_mov_b32_e32 v42, v182
	v_mov_b32_e32 v43, v182
	v_mov_b32_e32 v44, v182
	v_mov_b32_e32 v45, v182
	v_mov_b32_e32 v46, v182
	v_mov_b32_e32 v47, v182
	v_mov_b32_e32 v48, v182
	v_mov_b32_e32 v49, v182
	v_mov_b32_e32 v58, v182
	v_mov_b32_e32 v59, v182
	v_mov_b32_e32 v60, v182
	v_mov_b32_e32 v61, v182
	v_mov_b32_e32 v62, v182
	v_mov_b32_e32 v63, v182
	v_mov_b32_e32 v64, v182
	v_mov_b32_e32 v65, v182
	v_mov_b32_e32 v66, v182
	v_mov_b32_e32 v67, v182
	v_mov_b32_e32 v68, v182
	v_mov_b32_e32 v69, v182
	v_mov_b32_e32 v70, v182
	v_mov_b32_e32 v71, v182
	v_mov_b32_e32 v72, v182
	v_mov_b32_e32 v73, v182
	s_nop 0
	v_mov_b32_e32 v82, v182
	v_mov_b32_e32 v83, v182
	v_mov_b32_e32 v84, v182
	v_mov_b32_e32 v85, v182
	v_mov_b32_e32 v86, v182
	v_mov_b32_e32 v87, v182
	v_mov_b32_e32 v88, v182
	v_mov_b32_e32 v89, v182
	v_mov_b32_e32 v112, v182
	v_mov_b32_e32 v113, v182
	v_mov_b32_e32 v114, v182
	v_mov_b32_e32 v115, v182
	v_mov_b32_e32 v116, v182
	v_mov_b32_e32 v117, v182
	v_mov_b32_e32 v118, v182
	v_mov_b32_e32 v119, v182
	v_mov_b32_e32 v128, v182
	v_mov_b32_e32 v129, v182
	v_mov_b32_e32 v130, v182
	v_mov_b32_e32 v131, v182
	v_mov_b32_e32 v132, v182
	v_mov_b32_e32 v133, v182
	v_mov_b32_e32 v134, v182
	v_mov_b32_e32 v135, v182
	v_mov_b32_e32 v74, v182
	v_mov_b32_e32 v75, v182
	v_mov_b32_e32 v76, v182
	v_mov_b32_e32 v77, v182
	v_mov_b32_e32 v78, v182
	v_mov_b32_e32 v79, v182
	v_mov_b32_e32 v80, v182
	v_mov_b32_e32 v81, v182
	v_mov_b32_e32 v104, v182
	v_mov_b32_e32 v105, v182
	v_mov_b32_e32 v106, v182
	v_mov_b32_e32 v107, v182
	v_mov_b32_e32 v108, v182
	v_mov_b32_e32 v109, v182
	v_mov_b32_e32 v110, v182
	v_mov_b32_e32 v111, v182
	v_mov_b32_e32 v120, v182
	v_mov_b32_e32 v121, v182
	v_mov_b32_e32 v122, v182
	v_mov_b32_e32 v123, v182
	v_mov_b32_e32 v124, v182
	v_mov_b32_e32 v125, v182
	v_mov_b32_e32 v126, v182
	v_mov_b32_e32 v127, v182
	v_mov_b32_e32 v136, v182
	v_mov_b32_e32 v137, v182
	v_mov_b32_e32 v138, v182
	v_mov_b32_e32 v139, v182
	v_mov_b32_e32 v140, v182
	v_mov_b32_e32 v141, v182
	v_mov_b32_e32 v142, v182
	v_mov_b32_e32 v143, v182

; __device__ __forceinline__ unsigned cvt_pk_bf16(float lo, float hi) { unsigned r; asm volatile("v_cvt_pk_bf16_f32 %0, %1, %2" : "=v"(r) : "v"(lo), "v"(hi)); return r; }
; __device__ __forceinline__ float rstd_of4(const float* rss, int row, int fq) {
;     const f32x4 a = *(const f32x4*)(rss + (size_t)row * 16 + 4 * fq); float s = (a[0] + a[1]) + (a[2] + a[3]);
;     s += __shfl_xor(s, 16); s += __shfl_xor(s, 32);
;     return rsqrtf(s * (1.0f / 1024.0f) + EPS); }
;     __device__ __forceinline__ void operator()(const f32x4 (&acc)[2][2][4][2], const Unit& u, int wr, int wc, int fr, int fq, LAS unsigned char* lds) const {
;     ...
; #pragma unroll
;         for (int ai = 0; ai < 2; ++ai)
; #pragma unroll
;             for (int m = 0; m < 4; ++m) { const int row = row0 + ai * HALF + m * 16; const float rs = rss ? rstd_of4(rss, row, fq) : 1.0f;
; #pragma unroll
;                 for (int bj = 0; bj < 2; ++bj) { const f32x4 v0 = acc[ai][bj][m][0] * rs + bv[bj][0], v1 = acc[ai][bj][m][1] * rs + bv[bj][1];
;                     u32x4 w; w.x = cvt_pk_bf16(v0[0], v0[1]); w.y = cvt_pk_bf16(v0[2], v0[3]); w.z = cvt_pk_bf16(v1[0], v1[1]); w.w = cvt_pk_bf16(v1[2], v1[3]);
;                     *(u32x4*)(O + (size_t)row * ldc + col0 + bj * HALF) = w; } }
.LBB1_677:
	v_readfirstlane_b32 s1, v160
	v_lshl_add_u32 v160, s16, 8, v183
	s_cmp_lg_u64 s[18:19], 0
	s_cselect_b64 s[16:17], -1, 0
	s_cmp_eq_u64 s[18:19], 0
	v_lshl_add_u64 v[158:159], s[18:19], 0, v[4:5]
	v_ashrrev_i32_e32 v161, 31, v160
	v_mov_b32_e32 v164, 1.0
	v_mov_b32_e32 v166, 1.0
	s_cbranch_scc1 .LBB1_679
	v_lshlrev_b64 v[188:189], 6, v[160:161]
	v_lshl_add_u64 v[188:189], v[158:159], 0, v[188:189]
	global_load_dwordx4 v[188:191], v[188:189], off
	v_or_b32_e32 v228, 16, v160
	v_ashrrev_i32_e32 v229, 31, v228
	v_lshlrev_b64 v[228:229], 6, v[228:229]
	v_lshl_add_u64 v[228:229], v[158:159], 0, v[228:229]
	global_load_dwordx4 v[200:203], v[228:229], off
	v_or_b32_e32 v228, 32, v160
	v_ashrrev_i32_e32 v229, 31, v228
	v_lshlrev_b64 v[228:229], 6, v[228:229]
	v_lshl_add_u64 v[228:229], v[158:159], 0, v[228:229]
	global_load_dwordx4 v[204:207], v[228:229], off
	v_or_b32_e32 v228, 48, v160
	v_ashrrev_i32_e32 v229, 31, v228
	v_lshlrev_b64 v[228:229], 6, v[228:229]
	v_lshl_add_u64 v[228:229], v[158:159], 0, v[228:229]
	global_load_dwordx4 v[208:211], v[228:229], off
	v_add_u32_e32 v228, 0x80, v160
	v_ashrrev_i32_e32 v229, 31, v228
	v_lshlrev_b64 v[228:229], 6, v[228:229]
	v_lshl_add_u64 v[228:229], v[158:159], 0, v[228:229]
	global_load_dwordx4 v[212:215], v[228:229], off
	v_add_u32_e32 v228, 0x90, v160
	v_ashrrev_i32_e32 v229, 31, v228
	v_lshlrev_b64 v[228:229], 6, v[228:229]
	v_lshl_add_u64 v[228:229], v[158:159], 0, v[228:229]
	global_load_dwordx4 v[216:219], v[228:229], off
	v_add_u32_e32 v228, 0xa0, v160
	v_ashrrev_i32_e32 v229, 31, v228
	v_lshlrev_b64 v[228:229], 6, v[228:229]
	v_lshl_add_u64 v[228:229], v[158:159], 0, v[228:229]
	global_load_dwordx4 v[220:223], v[228:229], off
	v_add_u32_e32 v228, 0xb0, v160
	v_ashrrev_i32_e32 v229, 31, v228
	v_lshlrev_b64 v[228:229], 6, v[228:229]
	v_lshl_add_u64 v[228:229], v[158:159], 0, v[228:229]
	global_load_dwordx4 v[224:227], v[228:229], off
	v_and_b32_e32 v187, 64, v171
	v_xor_b32_e32 v166, 16, v171
	v_add_u32_e32 v187, 64, v187
	v_cmp_lt_i32_e32 vcc, v166, v187
	s_waitcnt vmcnt(0)
	v_mov_b32_e32 v194, v189
	v_mov_b32_e32 v195, v190
	v_mov_b32_e32 v189, v191
	v_pk_add_f32 v[188:189], v[194:195], v[188:189]
	v_cndmask_b32_e32 v166, v171, v166, vcc
	v_add_f32_e32 v161, v188, v189
	v_lshlrev_b32_e32 v166, 2, v166
	v_mov_b32_e32 v166, v161
	s_nop 1
	v_permlane16_swap_b32 v166, v161
	s_waitcnt lgkmcnt(0)
	v_add_f32_e32 v161, v161, v166
	v_xor_b32_e32 v166, 32, v171
	v_cmp_lt_i32_e32 vcc, v166, v187
	s_nop 1
	v_cndmask_b32_e32 v166, v171, v166, vcc
	v_lshlrev_b32_e32 v166, 2, v166
	v_mov_b32_e32 v166, v161
	s_nop 1
	v_permlane32_swap_b32 v166, v161
	s_waitcnt lgkmcnt(0)
	v_add_f32_e32 v161, v161, v166
	v_fmamk_f32 v161, v161, 0x3a800000, v173
	v_cmp_gt_f32_e32 vcc, s64, v161
	v_mul_f32_e32 v166, 0x4b800000, v161
	s_nop 0
	v_cndmask_b32_e32 v161, v161, v166, vcc
	v_rsq_f32_e32 v161, v161
	s_nop 0
	v_mul_f32_e32 v166, 0x45800000, v161
	v_cndmask_b32_e32 v166, v161, v166, vcc
.LBB1_679:
	v_mov_b32_e32 v188, s9
	v_mov_b32_e32 v189, s22
	v_lshl_add_u64 v[162:163], v[162:163], 1, v[188:189]
	v_mad_i64_i32 v[188:189], s[6:7], s1, v160, 0
	v_lshl_add_u64 v[188:189], v[188:189], 1, v[162:163]
	v_pk_fma_f32 v[142:143], v[142:143], v[166:167], v[156:157] op_sel_hi:[1,0,1]
	v_pk_fma_f32 v[140:141], v[140:141], v[166:167], v[94:95] op_sel_hi:[1,0,1]
	s_waitcnt vmcnt(0)
	v_pk_fma_f32 v[190:191], v[138:139], v[166:167], v[92:93] op_sel_hi:[1,0,1]
	v_pk_fma_f32 v[138:139], v[136:137], v[166:167], v[90:91] op_sel_hi:[1,0,1]
	v_cvt_pk_bf16_f32 v136, v140, v141
	v_cvt_pk_bf16_f32 v137, v142, v143
	v_pk_fma_f32 v[134:135], v[134:135], v[166:167], v[102:103] op_sel_hi:[1,0,1]
	v_cvt_pk_bf16_f32 v138, v138, v139
	v_cvt_pk_bf16_f32 v139, v190, v191
	global_store_dwordx4 v[188:189], v[136:139], off
	v_pk_fma_f32 v[132:133], v[132:133], v[166:167], v[100:101] op_sel_hi:[1,0,1]
	s_andn2_b64 vcc, exec, s[16:17]
	v_pk_fma_f32 v[136:137], v[130:131], v[166:167], v[98:99] op_sel_hi:[1,0,1]
	v_pk_fma_f32 v[130:131], v[128:129], v[166:167], v[96:97] op_sel_hi:[1,0,1]
	v_cvt_pk_bf16_f32 v128, v132, v133
	v_cvt_pk_bf16_f32 v129, v134, v135
	s_nop 0
	v_cvt_pk_bf16_f32 v130, v130, v131
	v_cvt_pk_bf16_f32 v131, v136, v137
	global_store_dwordx4 v[188:189], v[128:131], off offset:256
	s_nop 1
	v_or_b32_e32 v128, 16, v160
	v_cndmask_b32_e64 v129, 0, 1, s[16:17]
	v_cmp_ne_u32_e64 s[6:7], 1, v129
	v_ashrrev_i32_e32 v129, 31, v128
	s_cbranch_vccnz .LBB1_681
	v_lshlrev_b64 v[130:131], 6, v[128:129]
	v_lshl_add_u64 v[130:131], v[158:159], 0, v[130:131]
	v_mov_b32_e32 v130, v200
	v_mov_b32_e32 v131, v201
	v_mov_b32_e32 v132, v202
	v_mov_b32_e32 v133, v203
	s_nop 0
	v_mov_b32_e32 v134, v131
	v_mov_b32_e32 v135, v132
	v_mov_b32_e32 v131, v133
	v_pk_add_f32 v[130:131], v[134:135], v[130:131]
	s_nop 0
	v_add_f32_e32 v129, v130, v131
	v_and_b32_e32 v131, 64, v171
	v_xor_b32_e32 v130, 16, v171
	v_add_u32_e32 v131, 64, v131
	v_cmp_lt_i32_e32 vcc, v130, v131
	s_nop 1
	v_cndmask_b32_e32 v130, v171, v130, vcc
	v_lshlrev_b32_e32 v130, 2, v130
	v_mov_b32_e32 v130, v129
	s_nop 1
	v_permlane16_swap_b32 v130, v129
	s_waitcnt lgkmcnt(0)
	v_add_f32_e32 v129, v129, v130
	v_xor_b32_e32 v130, 32, v171
	v_cmp_lt_i32_e32 vcc, v130, v131
	s_nop 1
	v_cndmask_b32_e32 v130, v171, v130, vcc
	v_lshlrev_b32_e32 v130, 2, v130
	v_mov_b32_e32 v130, v129
	s_nop 1
	v_permlane32_swap_b32 v130, v129
	s_waitcnt lgkmcnt(0)
	v_add_f32_e32 v129, v129, v130
	v_fmamk_f32 v129, v129, 0x3a800000, v173
	v_cmp_gt_f32_e32 vcc, s64, v129
	v_mul_f32_e32 v130, 0x4b800000, v129
	s_nop 0
	v_cndmask_b32_e32 v129, v129, v130, vcc
	v_rsq_f32_e32 v129, v129
	s_nop 0
	v_mul_f32_e32 v130, 0x45800000, v129
	v_cndmask_b32_e32 v164, v129, v130, vcc
; __device__ __forceinline__ unsigned cvt_pk_bf16(float lo, float hi) { unsigned r; asm volatile("v_cvt_pk_bf16_f32 %0, %1, %2" : "=v"(r) : "v"(lo), "v"(hi)); return r; }
; __device__ __forceinline__ float rstd_of4(const float* rss, int row, int fq) {
;     const f32x4 a = *(const f32x4*)(rss + (size_t)row * 16 + 4 * fq); float s = (a[0] + a[1]) + (a[2] + a[3]);
;     s += __shfl_xor(s, 16); s += __shfl_xor(s, 32);
;     return rsqrtf(s * (1.0f / 1024.0f) + EPS); }
;     __device__ __forceinline__ void operator()(const f32x4 (&acc)[2][2][4][2], const Unit& u, int wr, int wc, int fr, int fq, LAS unsigned char* lds) const {
;     ...
; #pragma unroll
;         for (int ai = 0; ai < 2; ++ai)
; #pragma unroll
;             for (int m = 0; m < 4; ++m) { const int row = row0 + ai * HALF + m * 16; const float rs = rss ? rstd_of4(rss, row, fq) : 1.0f;
; #pragma unroll
;                 for (int bj = 0; bj < 2; ++bj) { const f32x4 v0 = acc[ai][bj][m][0] * rs + bv[bj][0], v1 = acc[ai][bj][m][1] * rs + bv[bj][1];
;                     u32x4 w; w.x = cvt_pk_bf16(v0[0], v0[1]); w.y = cvt_pk_bf16(v0[2], v0[3]); w.z = cvt_pk_bf16(v1[0], v1[1]); w.w = cvt_pk_bf16(v1[2], v1[3]);
;                     *(u32x4*)(O + (size_t)row * ldc + col0 + bj * HALF) = w; } }
.LBB1_681:
	v_mad_i64_i32 v[128:129], s[16:17], s1, v128, 0
	v_lshl_add_u64 v[128:129], v[128:129], 1, v[162:163]
	v_pk_fma_f32 v[126:127], v[126:127], v[164:165], v[156:157] op_sel_hi:[1,0,1]
	v_pk_fma_f32 v[124:125], v[124:125], v[164:165], v[94:95] op_sel_hi:[1,0,1]
	v_pk_fma_f32 v[130:131], v[122:123], v[164:165], v[92:93] op_sel_hi:[1,0,1]
	v_pk_fma_f32 v[122:123], v[120:121], v[164:165], v[90:91] op_sel_hi:[1,0,1]
	v_cvt_pk_bf16_f32 v120, v124, v125
	v_cvt_pk_bf16_f32 v121, v126, v127
	v_pk_fma_f32 v[118:119], v[118:119], v[164:165], v[102:103] op_sel_hi:[1,0,1]
	v_cvt_pk_bf16_f32 v122, v122, v123
	v_cvt_pk_bf16_f32 v123, v130, v131
	global_store_dwordx4 v[128:129], v[120:123], off
	v_pk_fma_f32 v[116:117], v[116:117], v[164:165], v[100:101] op_sel_hi:[1,0,1]
	s_and_b64 vcc, exec, s[6:7]
	v_pk_fma_f32 v[120:121], v[114:115], v[164:165], v[98:99] op_sel_hi:[1,0,1]
	v_pk_fma_f32 v[114:115], v[112:113], v[164:165], v[96:97] op_sel_hi:[1,0,1]
	v_cvt_pk_bf16_f32 v112, v116, v117
	v_cvt_pk_bf16_f32 v113, v118, v119
	v_mov_b32_e32 v116, 1.0
	v_cvt_pk_bf16_f32 v114, v114, v115
	v_cvt_pk_bf16_f32 v115, v120, v121
	global_store_dwordx4 v[128:129], v[112:115], off offset:256
	s_nop 1
	v_or_b32_e32 v114, 32, v160
	v_ashrrev_i32_e32 v115, 31, v114
	v_mov_b32_e32 v112, 1.0
	s_cbranch_vccnz .LBB1_683
	v_lshlrev_b64 v[116:117], 6, v[114:115]
	v_lshl_add_u64 v[116:117], v[158:159], 0, v[116:117]
	v_mov_b32_e32 v116, v204
	v_mov_b32_e32 v117, v205
	v_mov_b32_e32 v118, v206
	v_mov_b32_e32 v119, v207
	v_xor_b32_e32 v115, 16, v171
	s_nop 0
	v_mov_b32_e32 v120, v117
	v_mov_b32_e32 v121, v118
	v_mov_b32_e32 v117, v119
	v_pk_add_f32 v[116:117], v[120:121], v[116:117]
	s_nop 0
	v_add_f32_e32 v113, v116, v117
	v_and_b32_e32 v116, 64, v171
	v_add_u32_e32 v116, 64, v116
	v_cmp_lt_i32_e32 vcc, v115, v116
	s_nop 1
	v_cndmask_b32_e32 v115, v171, v115, vcc
	v_lshlrev_b32_e32 v115, 2, v115
	v_mov_b32_e32 v115, v113
	s_nop 1
	v_permlane16_swap_b32 v115, v113
	s_waitcnt lgkmcnt(0)
	v_add_f32_e32 v113, v113, v115
	v_xor_b32_e32 v115, 32, v171
	v_cmp_lt_i32_e32 vcc, v115, v116
	s_nop 1
	v_cndmask_b32_e32 v115, v171, v115, vcc
	v_lshlrev_b32_e32 v115, 2, v115
	v_mov_b32_e32 v115, v113
	s_nop 1
	v_permlane32_swap_b32 v115, v113
	s_waitcnt lgkmcnt(0)
	v_add_f32_e32 v113, v113, v115
	v_fmamk_f32 v113, v113, 0x3a800000, v173
	v_cmp_gt_f32_e32 vcc, s64, v113
	v_mul_f32_e32 v115, 0x4b800000, v113
	s_nop 0
	v_cndmask_b32_e32 v113, v113, v115, vcc
	v_rsq_f32_e32 v113, v113
	s_nop 0
	v_mul_f32_e32 v115, 0x45800000, v113
	v_cndmask_b32_e32 v116, v113, v115, vcc
.LBB1_683:
	v_mad_i64_i32 v[114:115], s[16:17], s1, v114, 0
	v_lshl_add_u64 v[114:115], v[114:115], 1, v[162:163]
	v_pk_fma_f32 v[110:111], v[110:111], v[116:117], v[156:157] op_sel_hi:[1,0,1]
	v_pk_fma_f32 v[108:109], v[108:109], v[116:117], v[94:95] op_sel_hi:[1,0,1]
	v_pk_fma_f32 v[118:119], v[106:107], v[116:117], v[92:93] op_sel_hi:[1,0,1]
	v_pk_fma_f32 v[106:107], v[104:105], v[116:117], v[90:91] op_sel_hi:[1,0,1]
	v_cvt_pk_bf16_f32 v104, v108, v109
	v_cvt_pk_bf16_f32 v105, v110, v111
	v_pk_fma_f32 v[86:87], v[86:87], v[116:117], v[100:101] op_sel_hi:[1,0,1]
	v_cvt_pk_bf16_f32 v106, v106, v107
	v_cvt_pk_bf16_f32 v107, v118, v119
	global_store_dwordx4 v[114:115], v[104:107], off
	v_pk_fma_f32 v[88:89], v[88:89], v[116:117], v[102:103] op_sel_hi:[1,0,1]
	s_and_b64 vcc, exec, s[6:7]
	v_pk_fma_f32 v[104:105], v[84:85], v[116:117], v[98:99] op_sel_hi:[1,0,1]
	v_pk_fma_f32 v[84:85], v[82:83], v[116:117], v[96:97] op_sel_hi:[1,0,1]
	v_cvt_pk_bf16_f32 v82, v86, v87
	v_cvt_pk_bf16_f32 v83, v88, v89
	s_nop 0
	v_cvt_pk_bf16_f32 v84, v84, v85
	v_cvt_pk_bf16_f32 v85, v104, v105
	global_store_dwordx4 v[114:115], v[82:85], off offset:256
	s_nop 1
	v_or_b32_e32 v82, 48, v160
	v_ashrrev_i32_e32 v83, 31, v82
	s_cbranch_vccnz .LBB1_685
	v_lshlrev_b64 v[84:85], 6, v[82:83]
	v_lshl_add_u64 v[84:85], v[158:159], 0, v[84:85]
	v_mov_b32_e32 v84, v208
	v_mov_b32_e32 v85, v209
	v_mov_b32_e32 v86, v210
	v_mov_b32_e32 v87, v211
	s_nop 0
	v_mov_b32_e32 v88, v85
	v_mov_b32_e32 v89, v86
	v_mov_b32_e32 v85, v87
	v_pk_add_f32 v[84:85], v[88:89], v[84:85]
	s_nop 0
	v_add_f32_e32 v83, v84, v85
	v_and_b32_e32 v85, 64, v171
	v_xor_b32_e32 v84, 16, v171
	v_add_u32_e32 v85, 64, v85
	v_cmp_lt_i32_e32 vcc, v84, v85
	s_nop 1
	v_cndmask_b32_e32 v84, v171, v84, vcc
	v_lshlrev_b32_e32 v84, 2, v84
	v_mov_b32_e32 v84, v83
	s_nop 1
	v_permlane16_swap_b32 v84, v83
	s_waitcnt lgkmcnt(0)
	v_add_f32_e32 v83, v83, v84
	v_xor_b32_e32 v84, 32, v171
	v_cmp_lt_i32_e32 vcc, v84, v85
	s_nop 1
	v_cndmask_b32_e32 v84, v171, v84, vcc
	v_lshlrev_b32_e32 v84, 2, v84
	v_mov_b32_e32 v84, v83
	s_nop 1
	v_permlane32_swap_b32 v84, v83
	s_waitcnt lgkmcnt(0)
	v_add_f32_e32 v83, v83, v84
	v_fmamk_f32 v83, v83, 0x3a800000, v173
	v_cmp_gt_f32_e32 vcc, s64, v83
	v_mul_f32_e32 v84, 0x4b800000, v83
	s_nop 0
	v_cndmask_b32_e32 v83, v83, v84, vcc
	v_rsq_f32_e32 v83, v83
	s_nop 0
	v_mul_f32_e32 v84, 0x45800000, v83
	v_cndmask_b32_e32 v112, v83, v84, vcc
; __device__ __forceinline__ unsigned cvt_pk_bf16(float lo, float hi) { unsigned r; asm volatile("v_cvt_pk_bf16_f32 %0, %1, %2" : "=v"(r) : "v"(lo), "v"(hi)); return r; }
; __device__ __forceinline__ float rstd_of4(const float* rss, int row, int fq) {
;     const f32x4 a = *(const f32x4*)(rss + (size_t)row * 16 + 4 * fq); float s = (a[0] + a[1]) + (a[2] + a[3]);
;     s += __shfl_xor(s, 16); s += __shfl_xor(s, 32);
;     return rsqrtf(s * (1.0f / 1024.0f) + EPS); }
;     __device__ __forceinline__ void operator()(const f32x4 (&acc)[2][2][4][2], const Unit& u, int wr, int wc, int fr, int fq, LAS unsigned char* lds) const {
;     ...
; #pragma unroll
;         for (int ai = 0; ai < 2; ++ai)
; #pragma unroll
;             for (int m = 0; m < 4; ++m) { const int row = row0 + ai * HALF + m * 16; const float rs = rss ? rstd_of4(rss, row, fq) : 1.0f;
; #pragma unroll
;                 for (int bj = 0; bj < 2; ++bj) { const f32x4 v0 = acc[ai][bj][m][0] * rs + bv[bj][0], v1 = acc[ai][bj][m][1] * rs + bv[bj][1];
;                     u32x4 w; w.x = cvt_pk_bf16(v0[0], v0[1]); w.y = cvt_pk_bf16(v0[2], v0[3]); w.z = cvt_pk_bf16(v1[0], v1[1]); w.w = cvt_pk_bf16(v1[2], v1[3]);
;                     *(u32x4*)(O + (size_t)row * ldc + col0 + bj * HALF) = w; } }
.LBB1_685:
	v_mad_i64_i32 v[82:83], s[16:17], s1, v82, 0
	v_lshl_add_u64 v[82:83], v[82:83], 1, v[162:163]
	v_pk_fma_f32 v[80:81], v[80:81], v[112:113], v[156:157] op_sel_hi:[1,0,1]
	v_pk_fma_f32 v[78:79], v[78:79], v[112:113], v[94:95] op_sel_hi:[1,0,1]
	v_pk_fma_f32 v[84:85], v[76:77], v[112:113], v[92:93] op_sel_hi:[1,0,1]
	v_pk_fma_f32 v[76:77], v[74:75], v[112:113], v[90:91] op_sel_hi:[1,0,1]
	v_cvt_pk_bf16_f32 v74, v78, v79
	v_cvt_pk_bf16_f32 v75, v80, v81
	v_pk_fma_f32 v[72:73], v[72:73], v[112:113], v[102:103] op_sel_hi:[1,0,1]
	v_cvt_pk_bf16_f32 v76, v76, v77
	v_cvt_pk_bf16_f32 v77, v84, v85
	global_store_dwordx4 v[82:83], v[74:77], off
	v_pk_fma_f32 v[70:71], v[70:71], v[112:113], v[100:101] op_sel_hi:[1,0,1]
	s_and_b64 vcc, exec, s[6:7]
	v_pk_fma_f32 v[74:75], v[68:69], v[112:113], v[98:99] op_sel_hi:[1,0,1]
	v_pk_fma_f32 v[68:69], v[66:67], v[112:113], v[96:97] op_sel_hi:[1,0,1]
	v_cvt_pk_bf16_f32 v66, v70, v71
	v_cvt_pk_bf16_f32 v67, v72, v73
	v_mov_b32_e32 v70, 1.0
	v_cvt_pk_bf16_f32 v68, v68, v69
	v_cvt_pk_bf16_f32 v69, v74, v75
	global_store_dwordx4 v[82:83], v[66:69], off offset:256
	s_nop 1
	v_add_u32_e32 v68, 0x80, v160
	v_ashrrev_i32_e32 v69, 31, v68
	v_mov_b32_e32 v66, 1.0
	s_cbranch_vccnz .LBB1_687
	v_lshlrev_b64 v[70:71], 6, v[68:69]
	v_lshl_add_u64 v[70:71], v[158:159], 0, v[70:71]
	v_mov_b32_e32 v70, v212
	v_mov_b32_e32 v71, v213
	v_mov_b32_e32 v72, v214
	v_mov_b32_e32 v73, v215
	v_xor_b32_e32 v69, 16, v171
	s_nop 0
	v_mov_b32_e32 v74, v71
	v_mov_b32_e32 v75, v72
	v_mov_b32_e32 v71, v73
	v_pk_add_f32 v[70:71], v[74:75], v[70:71]
	s_nop 0
	v_add_f32_e32 v67, v70, v71
	v_and_b32_e32 v70, 64, v171
	v_add_u32_e32 v70, 64, v70
	v_cmp_lt_i32_e32 vcc, v69, v70
	s_nop 1
	v_cndmask_b32_e32 v69, v171, v69, vcc
	v_lshlrev_b32_e32 v69, 2, v69
	v_mov_b32_e32 v69, v67
	s_nop 1
	v_permlane16_swap_b32 v69, v67
	s_waitcnt lgkmcnt(0)
	v_add_f32_e32 v67, v67, v69
	v_xor_b32_e32 v69, 32, v171
	v_cmp_lt_i32_e32 vcc, v69, v70
	s_nop 1
	v_cndmask_b32_e32 v69, v171, v69, vcc
	v_lshlrev_b32_e32 v69, 2, v69
	v_mov_b32_e32 v69, v67
	s_nop 1
	v_permlane32_swap_b32 v69, v67
	s_waitcnt lgkmcnt(0)
	v_add_f32_e32 v67, v67, v69
	v_fmamk_f32 v67, v67, 0x3a800000, v173
	v_cmp_gt_f32_e32 vcc, s64, v67
	v_mul_f32_e32 v69, 0x4b800000, v67
	s_nop 0
	v_cndmask_b32_e32 v67, v67, v69, vcc
	v_rsq_f32_e32 v67, v67
	s_nop 0
	v_mul_f32_e32 v69, 0x45800000, v67
	v_cndmask_b32_e32 v70, v67, v69, vcc
.LBB1_687:
	v_mad_i64_i32 v[68:69], s[16:17], s1, v68, 0
	v_lshl_add_u64 v[68:69], v[68:69], 1, v[162:163]
	v_pk_fma_f32 v[64:65], v[64:65], v[70:71], v[156:157] op_sel_hi:[1,0,1]
	v_pk_fma_f32 v[62:63], v[62:63], v[70:71], v[94:95] op_sel_hi:[1,0,1]
	v_pk_fma_f32 v[72:73], v[60:61], v[70:71], v[92:93] op_sel_hi:[1,0,1]
	v_pk_fma_f32 v[60:61], v[58:59], v[70:71], v[90:91] op_sel_hi:[1,0,1]
	v_cvt_pk_bf16_f32 v58, v62, v63
	v_cvt_pk_bf16_f32 v59, v64, v65
	v_pk_fma_f32 v[54:55], v[54:55], v[70:71], v[100:101] op_sel_hi:[1,0,1]
	v_cvt_pk_bf16_f32 v60, v60, v61
	v_cvt_pk_bf16_f32 v61, v72, v73
	global_store_dwordx4 v[68:69], v[58:61], off
	v_pk_fma_f32 v[56:57], v[56:57], v[70:71], v[102:103] op_sel_hi:[1,0,1]
	s_and_b64 vcc, exec, s[6:7]
	v_pk_fma_f32 v[58:59], v[52:53], v[70:71], v[98:99] op_sel_hi:[1,0,1]
	v_pk_fma_f32 v[52:53], v[50:51], v[70:71], v[96:97] op_sel_hi:[1,0,1]
	v_cvt_pk_bf16_f32 v50, v54, v55
	v_cvt_pk_bf16_f32 v51, v56, v57
	s_nop 0
	v_cvt_pk_bf16_f32 v52, v52, v53
	v_cvt_pk_bf16_f32 v53, v58, v59
	global_store_dwordx4 v[68:69], v[50:53], off offset:256
	s_nop 1
	v_add_u32_e32 v50, 0x90, v160
	v_ashrrev_i32_e32 v51, 31, v50
	s_cbranch_vccnz .LBB1_689
	v_lshlrev_b64 v[52:53], 6, v[50:51]
	v_lshl_add_u64 v[52:53], v[158:159], 0, v[52:53]
	v_mov_b32_e32 v52, v216
	v_mov_b32_e32 v53, v217
	v_mov_b32_e32 v54, v218
	v_mov_b32_e32 v55, v219
	s_nop 0
	v_mov_b32_e32 v56, v53
	v_mov_b32_e32 v57, v54
	v_mov_b32_e32 v53, v55
	v_pk_add_f32 v[52:53], v[56:57], v[52:53]
	s_nop 0
	v_add_f32_e32 v51, v52, v53
	v_and_b32_e32 v53, 64, v171
	v_xor_b32_e32 v52, 16, v171
	v_add_u32_e32 v53, 64, v53
	v_cmp_lt_i32_e32 vcc, v52, v53
	s_nop 1
	v_cndmask_b32_e32 v52, v171, v52, vcc
	v_lshlrev_b32_e32 v52, 2, v52
	v_mov_b32_e32 v52, v51
	s_nop 1
	v_permlane16_swap_b32 v52, v51
	s_waitcnt lgkmcnt(0)
	v_add_f32_e32 v51, v51, v52
	v_xor_b32_e32 v52, 32, v171
	v_cmp_lt_i32_e32 vcc, v52, v53
	s_nop 1
	v_cndmask_b32_e32 v52, v171, v52, vcc
	v_lshlrev_b32_e32 v52, 2, v52
	v_mov_b32_e32 v52, v51
	s_nop 1
	v_permlane32_swap_b32 v52, v51
	s_waitcnt lgkmcnt(0)
	v_add_f32_e32 v51, v51, v52
	v_fmamk_f32 v51, v51, 0x3a800000, v173
	v_cmp_gt_f32_e32 vcc, s64, v51
	v_mul_f32_e32 v52, 0x4b800000, v51
	s_nop 0
	v_cndmask_b32_e32 v51, v51, v52, vcc
	v_rsq_f32_e32 v51, v51
	s_nop 0
	v_mul_f32_e32 v52, 0x45800000, v51
	v_cndmask_b32_e32 v66, v51, v52, vcc
; __device__ __forceinline__ unsigned cvt_pk_bf16(float lo, float hi) { unsigned r; asm volatile("v_cvt_pk_bf16_f32 %0, %1, %2" : "=v"(r) : "v"(lo), "v"(hi)); return r; }
; __device__ __forceinline__ float rstd_of4(const float* rss, int row, int fq) {
;     const f32x4 a = *(const f32x4*)(rss + (size_t)row * 16 + 4 * fq); float s = (a[0] + a[1]) + (a[2] + a[3]);
;     s += __shfl_xor(s, 16); s += __shfl_xor(s, 32);
;     return rsqrtf(s * (1.0f / 1024.0f) + EPS); }
;     __device__ __forceinline__ void operator()(const f32x4 (&acc)[2][2][4][2], const Unit& u, int wr, int wc, int fr, int fq, LAS unsigned char* lds) const {
;     ...
; #pragma unroll
;         for (int ai = 0; ai < 2; ++ai)
; #pragma unroll
;             for (int m = 0; m < 4; ++m) { const int row = row0 + ai * HALF + m * 16; const float rs = rss ? rstd_of4(rss, row, fq) : 1.0f;
; #pragma unroll
;                 for (int bj = 0; bj < 2; ++bj) { const f32x4 v0 = acc[ai][bj][m][0] * rs + bv[bj][0], v1 = acc[ai][bj][m][1] * rs + bv[bj][1];
;                     u32x4 w; w.x = cvt_pk_bf16(v0[0], v0[1]); w.y = cvt_pk_bf16(v0[2], v0[3]); w.z = cvt_pk_bf16(v1[0], v1[1]); w.w = cvt_pk_bf16(v1[2], v1[3]);
;                     *(u32x4*)(O + (size_t)row * ldc + col0 + bj * HALF) = w; } }
.LBB1_689:
	v_mad_i64_i32 v[50:51], s[16:17], s1, v50, 0
	v_lshl_add_u64 v[50:51], v[50:51], 1, v[162:163]
	v_pk_fma_f32 v[48:49], v[48:49], v[66:67], v[156:157] op_sel_hi:[1,0,1]
	v_pk_fma_f32 v[46:47], v[46:47], v[66:67], v[94:95] op_sel_hi:[1,0,1]
	v_pk_fma_f32 v[52:53], v[44:45], v[66:67], v[92:93] op_sel_hi:[1,0,1]
	v_pk_fma_f32 v[44:45], v[42:43], v[66:67], v[90:91] op_sel_hi:[1,0,1]
	v_cvt_pk_bf16_f32 v42, v46, v47
	v_cvt_pk_bf16_f32 v43, v48, v49
	v_pk_fma_f32 v[40:41], v[40:41], v[66:67], v[102:103] op_sel_hi:[1,0,1]
	v_cvt_pk_bf16_f32 v44, v44, v45
	v_cvt_pk_bf16_f32 v45, v52, v53
	global_store_dwordx4 v[50:51], v[42:45], off
	v_pk_fma_f32 v[38:39], v[38:39], v[66:67], v[100:101] op_sel_hi:[1,0,1]
	s_and_b64 vcc, exec, s[6:7]
	v_pk_fma_f32 v[42:43], v[36:37], v[66:67], v[98:99] op_sel_hi:[1,0,1]
	v_pk_fma_f32 v[36:37], v[34:35], v[66:67], v[96:97] op_sel_hi:[1,0,1]
	v_cvt_pk_bf16_f32 v34, v38, v39
	v_cvt_pk_bf16_f32 v35, v40, v41
	v_mov_b32_e32 v38, 1.0
	v_cvt_pk_bf16_f32 v36, v36, v37
	v_cvt_pk_bf16_f32 v37, v42, v43
	global_store_dwordx4 v[50:51], v[34:37], off offset:256
	s_nop 1
	v_add_u32_e32 v36, 0xa0, v160
	v_ashrrev_i32_e32 v37, 31, v36
	v_mov_b32_e32 v34, 1.0
	s_cbranch_vccnz .LBB1_691
	v_lshlrev_b64 v[38:39], 6, v[36:37]
	v_lshl_add_u64 v[38:39], v[158:159], 0, v[38:39]
	v_mov_b32_e32 v38, v220
	v_mov_b32_e32 v39, v221
	v_mov_b32_e32 v40, v222
	v_mov_b32_e32 v41, v223
	v_xor_b32_e32 v37, 16, v171
	s_nop 0
	v_mov_b32_e32 v42, v39
	v_mov_b32_e32 v43, v40
	v_mov_b32_e32 v39, v41
	v_pk_add_f32 v[38:39], v[42:43], v[38:39]
	s_nop 0
	v_add_f32_e32 v35, v38, v39
	v_and_b32_e32 v38, 64, v171
	v_add_u32_e32 v38, 64, v38
	v_cmp_lt_i32_e32 vcc, v37, v38
	s_nop 1
	v_cndmask_b32_e32 v37, v171, v37, vcc
	v_lshlrev_b32_e32 v37, 2, v37
	v_mov_b32_e32 v37, v35
	s_nop 1
	v_permlane16_swap_b32 v37, v35
	s_waitcnt lgkmcnt(0)
	v_add_f32_e32 v35, v35, v37
	v_xor_b32_e32 v37, 32, v171
	v_cmp_lt_i32_e32 vcc, v37, v38
	s_nop 1
	v_cndmask_b32_e32 v37, v171, v37, vcc
	v_lshlrev_b32_e32 v37, 2, v37
	v_mov_b32_e32 v37, v35
	s_nop 1
	v_permlane32_swap_b32 v37, v35
	s_waitcnt lgkmcnt(0)
	v_add_f32_e32 v35, v35, v37
	v_fmamk_f32 v35, v35, 0x3a800000, v173
	v_cmp_gt_f32_e32 vcc, s64, v35
	v_mul_f32_e32 v37, 0x4b800000, v35
	s_nop 0
	v_cndmask_b32_e32 v35, v35, v37, vcc
	v_rsq_f32_e32 v35, v35
	s_nop 0
	v_mul_f32_e32 v37, 0x45800000, v35
	v_cndmask_b32_e32 v38, v35, v37, vcc
.LBB1_691:
	v_mad_i64_i32 v[36:37], s[16:17], s1, v36, 0
	v_lshl_add_u64 v[36:37], v[36:37], 1, v[162:163]
	v_pk_fma_f32 v[32:33], v[32:33], v[38:39], v[156:157] op_sel_hi:[1,0,1]
	v_pk_fma_f32 v[30:31], v[30:31], v[38:39], v[94:95] op_sel_hi:[1,0,1]
	v_pk_fma_f32 v[40:41], v[28:29], v[38:39], v[92:93] op_sel_hi:[1,0,1]
	v_pk_fma_f32 v[28:29], v[26:27], v[38:39], v[90:91] op_sel_hi:[1,0,1]
	v_cvt_pk_bf16_f32 v26, v30, v31
	v_cvt_pk_bf16_f32 v27, v32, v33
	v_pk_fma_f32 v[22:23], v[22:23], v[38:39], v[100:101] op_sel_hi:[1,0,1]
	v_cvt_pk_bf16_f32 v28, v28, v29
	v_cvt_pk_bf16_f32 v29, v40, v41
	global_store_dwordx4 v[36:37], v[26:29], off
	v_pk_fma_f32 v[24:25], v[24:25], v[38:39], v[102:103] op_sel_hi:[1,0,1]
	s_and_b64 vcc, exec, s[6:7]
	v_pk_fma_f32 v[26:27], v[20:21], v[38:39], v[98:99] op_sel_hi:[1,0,1]
	v_pk_fma_f32 v[20:21], v[18:19], v[38:39], v[96:97] op_sel_hi:[1,0,1]
	v_cvt_pk_bf16_f32 v18, v22, v23
	v_cvt_pk_bf16_f32 v19, v24, v25
	s_nop 0
	v_cvt_pk_bf16_f32 v20, v20, v21
	v_cvt_pk_bf16_f32 v21, v26, v27
	global_store_dwordx4 v[36:37], v[18:21], off offset:256
	s_nop 1
	v_add_u32_e32 v18, 0xb0, v160
	v_ashrrev_i32_e32 v19, 31, v18
	s_cbranch_vccnz .LBB1_664
	v_lshlrev_b64 v[20:21], 6, v[18:19]
	v_lshl_add_u64 v[20:21], v[158:159], 0, v[20:21]
	v_mov_b32_e32 v20, v224
	v_mov_b32_e32 v21, v225
	v_mov_b32_e32 v22, v226
	v_mov_b32_e32 v23, v227
	s_nop 0
	v_mov_b32_e32 v24, v21
	v_mov_b32_e32 v25, v22
	v_mov_b32_e32 v21, v23
	v_pk_add_f32 v[20:21], v[24:25], v[20:21]
	s_nop 0
	v_add_f32_e32 v19, v20, v21
	v_and_b32_e32 v21, 64, v171
	v_xor_b32_e32 v20, 16, v171
	v_add_u32_e32 v21, 64, v21
	v_cmp_lt_i32_e32 vcc, v20, v21
	s_nop 1
	v_cndmask_b32_e32 v20, v171, v20, vcc
	v_lshlrev_b32_e32 v20, 2, v20
	v_mov_b32_e32 v20, v19
	s_nop 1
	v_permlane16_swap_b32 v20, v19
	s_waitcnt lgkmcnt(0)
	v_add_f32_e32 v19, v19, v20
	v_xor_b32_e32 v20, 32, v171
	v_cmp_lt_i32_e32 vcc, v20, v21
	s_nop 1
	v_cndmask_b32_e32 v20, v171, v20, vcc
	v_lshlrev_b32_e32 v20, 2, v20
	v_mov_b32_e32 v20, v19
	s_nop 1
	v_permlane32_swap_b32 v20, v19
	s_waitcnt lgkmcnt(0)
	v_add_f32_e32 v19, v19, v20
	v_fmamk_f32 v19, v19, 0x3a800000, v173
	v_cmp_gt_f32_e32 vcc, s64, v19
	v_mul_f32_e32 v20, 0x4b800000, v19
	s_nop 0
	v_cndmask_b32_e32 v19, v19, v20, vcc
	v_rsq_f32_e32 v19, v19
	s_nop 0
	v_mul_f32_e32 v20, 0x45800000, v19
	v_cndmask_b32_e32 v34, v19, v20, vcc
	s_branch .LBB1_664

; template <class Epi, int KK, int LDA, int LDB, int NN, bool AGRP>
; __device__ __forceinline__ void gemm_phase(LAS unsigned char* lds, const bf16_t* gA, const bf16_t* gBt, int G_, int bid_, int tid) {
;     ...
; #pragma unroll
;         for (int a = 0; a < 2; ++a)
; #pragma unroll
;             for (int b = 0; b < 2; ++b)
; #pragma unroll
;                 for (int m = 0; m < 4; ++m)
; #pragma unroll
;                     for (int n = 0; n < 2; ++n) acc[a][b][m][n] = (f32x4){zr, zr, zr, zr};
;         cur = nxt; cA = nA; cB = nB; ++ui;
.LBB1_763:
	s_add_u32 s20, s14, 0x100
	s_addc_u32 s21, s15, 0
	s_mov_b32 s65, -2
	v_mov_b32_e32 v0, v160
	s_waitcnt lgkmcnt(0)
	v_mov_b32_e32 v1, v160
	v_mov_b32_e32 v2, v160
	v_mov_b32_e32 v3, v160
	v_mov_b32_e32 v6, v160
	v_mov_b32_e32 v7, v160
	v_mov_b32_e32 v8, v160
	v_mov_b32_e32 v9, v160
	v_mov_b32_e32 v18, v160
	v_mov_b32_e32 v19, v160
	v_mov_b32_e32 v20, v160
	v_mov_b32_e32 v21, v160
	v_mov_b32_e32 v22, v160
	v_mov_b32_e32 v23, v160
	v_mov_b32_e32 v24, v160
	v_mov_b32_e32 v25, v160
	v_mov_b32_e32 v34, v160
	v_mov_b32_e32 v35, v160
	v_mov_b32_e32 v36, v160
	v_mov_b32_e32 v37, v160
	v_mov_b32_e32 v38, v160
	v_mov_b32_e32 v39, v160
	v_mov_b32_e32 v40, v160
	v_mov_b32_e32 v41, v160
	v_mov_b32_e32 v50, v160
	v_mov_b32_e32 v51, v160
	v_mov_b32_e32 v52, v160
	v_mov_b32_e32 v53, v160
	v_mov_b32_e32 v54, v160
	v_mov_b32_e32 v55, v160
	v_mov_b32_e32 v56, v160
	v_mov_b32_e32 v57, v160
	v_mov_b32_e32 v10, v160
	v_mov_b32_e32 v11, v160
	v_mov_b32_e32 v12, v160
	v_mov_b32_e32 v13, v160
	v_mov_b32_e32 v14, v160
	v_mov_b32_e32 v15, v160
	v_mov_b32_e32 v16, v160
	v_mov_b32_e32 v17, v160
	v_mov_b32_e32 v26, v160
	v_mov_b32_e32 v27, v160
	v_mov_b32_e32 v28, v160
	v_mov_b32_e32 v29, v160
	v_mov_b32_e32 v30, v160
	v_mov_b32_e32 v31, v160
	v_mov_b32_e32 v32, v160
	v_mov_b32_e32 v33, v160
	v_mov_b32_e32 v42, v160
	v_mov_b32_e32 v43, v160
	v_mov_b32_e32 v44, v160
	v_mov_b32_e32 v45, v160
	v_mov_b32_e32 v46, v160
	v_mov_b32_e32 v47, v160
	v_mov_b32_e32 v48, v160
	v_mov_b32_e32 v49, v160
	v_mov_b32_e32 v58, v160
	v_mov_b32_e32 v59, v160
	v_mov_b32_e32 v60, v160
	v_mov_b32_e32 v61, v160
	v_mov_b32_e32 v62, v160
	v_mov_b32_e32 v63, v160
	v_mov_b32_e32 v64, v160
	v_mov_b32_e32 v65, v160
	v_mov_b32_e32 v74, v160
	v_mov_b32_e32 v75, v160
	v_mov_b32_e32 v76, v160
	v_mov_b32_e32 v77, v160
	s_nop 0
	v_mov_b32_e32 v86, v160
	v_mov_b32_e32 v87, v160
	v_mov_b32_e32 v88, v160
	v_mov_b32_e32 v89, v160
	v_mov_b32_e32 v98, v160
	v_mov_b32_e32 v99, v160
	v_mov_b32_e32 v100, v160
	v_mov_b32_e32 v101, v160
	v_mov_b32_e32 v102, v160
	v_mov_b32_e32 v103, v160
	v_mov_b32_e32 v104, v160
	v_mov_b32_e32 v105, v160
	v_mov_b32_e32 v114, v160
	v_mov_b32_e32 v115, v160
	v_mov_b32_e32 v116, v160
	v_mov_b32_e32 v117, v160
	v_mov_b32_e32 v118, v160
	v_mov_b32_e32 v119, v160
	v_mov_b32_e32 v120, v160
	v_mov_b32_e32 v121, v160
	v_mov_b32_e32 v130, v160
	v_mov_b32_e32 v131, v160
	v_mov_b32_e32 v132, v160
	v_mov_b32_e32 v133, v160
	v_mov_b32_e32 v134, v160
	v_mov_b32_e32 v135, v160
	v_mov_b32_e32 v136, v160
	v_mov_b32_e32 v137, v160
	v_mov_b32_e32 v90, v160
	v_mov_b32_e32 v91, v160
	v_mov_b32_e32 v92, v160
	v_mov_b32_e32 v93, v160
	v_mov_b32_e32 v94, v160
	v_mov_b32_e32 v95, v160
	v_mov_b32_e32 v96, v160
	v_mov_b32_e32 v97, v160
	v_mov_b32_e32 v106, v160
	v_mov_b32_e32 v107, v160
	v_mov_b32_e32 v108, v160
	v_mov_b32_e32 v109, v160
	v_mov_b32_e32 v110, v160
	v_mov_b32_e32 v111, v160
	v_mov_b32_e32 v112, v160
	v_mov_b32_e32 v113, v160
	v_mov_b32_e32 v122, v160
	v_mov_b32_e32 v123, v160
	v_mov_b32_e32 v124, v160
	v_mov_b32_e32 v125, v160
	v_mov_b32_e32 v126, v160
	v_mov_b32_e32 v127, v160
	v_mov_b32_e32 v128, v160
	v_mov_b32_e32 v129, v160
	v_mov_b32_e32 v138, v160
	v_mov_b32_e32 v139, v160
	v_mov_b32_e32 v140, v160
	v_mov_b32_e32 v141, v160
	v_mov_b32_e32 v142, v160
	v_mov_b32_e32 v143, v160
	v_mov_b32_e32 v144, v160
	v_mov_b32_e32 v145, v160

; __device__ __forceinline__ unsigned cvt_pk_bf16(float lo, float hi) { unsigned r; asm volatile("v_cvt_pk_bf16_f32 %0, %1, %2" : "=v"(r) : "v"(lo), "v"(hi)); return r; }
; __device__ __forceinline__ float bflo(unsigned w) { return __uint_as_float(w << 16); }
;     __device__ __forceinline__ void operator()(const f32x4 (&acc)[2][2][4][2], const Unit& u, int wr, int wc, int fr, int fq, LAS unsigned char* lds) const {
;     ...
;             for (int m = 0; m < 4; ++m) { const int row = row0 + ai * HALF + m * 16; const size_t off = (size_t)row * D + col0;
;                 float rs = 1.0f; if (MODE == 1) rs = rstd_of4(rss_in, row, fq);
;                 float ss = 0.f;
; #pragma unroll
;                 for (int bj = 0; bj < 2; ++bj) { const size_t o = off + bj * HALF; const u32x4 bw = *(const u32x4*)(base + o);
;                     const float bs[8] = {bflo(bw.x), bfhi(bw.x), bflo(bw.y), bfhi(bw.y), bflo(bw.z), bfhi(bw.z), bflo(bw.w), bfhi(bw.w)};
;                     float hn[8];
;                     if (MODE == 0) {
; #pragma unroll
;                         for (int n = 0; n < 2; ++n)
; #pragma unroll
;                             for (int e = 0; e < 4; ++e) hn[4 * n + e] = bs[4 * n + e] + (acc[ai][bj][m][n][e] + bv[bj][n][e]) * scale;
;                     } else { const u32x4 pw = *(const u32x4*)(pp + o);
;                         const float pv[8] = {bflo(pw.x), bfhi(pw.x), bflo(pw.y), bfhi(pw.y), bflo(pw.z), bfhi(pw.z), bflo(pw.w), bfhi(pw.w)};
; #pragma unroll
;                         for (int n = 0; n < 2; ++n)
; #pragma unroll
;                             for (int e = 0; e < 4; ++e) hn[4 * n + e] = bs[4 * n + e] + fast_sigmoid(acc[ai][bj][m][n][e] * rs) * pv[4 * n + e]; }
;                     u32x4 w; w.x = cvt_pk_bf16(hn[0], hn[1]); w.y = cvt_pk_bf16(hn[2], hn[3]); w.z = cvt_pk_bf16(hn[4], hn[5]); w.w = cvt_pk_bf16(hn[6], hn[7]); *(u32x4*)(hb + o) = w;
;                     const float hr[8] = {bflo(w.x), bfhi(w.x), bflo(w.y), bfhi(w.y), bflo(w.z), bfhi(w.z), bflo(w.w), bfhi(w.w)};
;                     ss += ((hr[0] * hr[0] + hr[1] * hr[1]) + (hr[2] * hr[2] + hr[3] * hr[3])) + ((hr[4] * hr[4] + hr[5] * hr[5]) + (hr[6] * hr[6] + hr[7] * hr[7])); }
;                 ss += __shfl_xor(ss, 16); ss += __shfl_xor(ss, 32);
;                 if (fq == 0) rss_out[(size_t)row * 16 + u.pn * 4 + wc] = ss; }
.LBB1_773:
	v_lshl_add_u32 v158, s74, 8, v161
	v_ashrrev_i32_e32 v159, 31, v158
	v_lshlrev_b64 v[166:167], 10, v[158:159]
	v_lshl_add_u64 v[166:167], v[166:167], 0, v[156:157]
	v_lshlrev_b64 v[176:177], 1, v[166:167]
	v_lshl_add_u64 v[178:179], s[18:19], 0, v[176:177]
	global_load_dwordx4 v[166:169], v[178:179], off
	global_load_dwordx4 v[184:187], v[178:179], off offset:256
	v_or_b32_e32 v228, 16, v158
	v_ashrrev_i32_e32 v229, 31, v228
	v_lshlrev_b64 v[228:229], 10, v[228:229]
	v_lshl_add_u64 v[228:229], v[228:229], 0, v[156:157]
	v_lshlrev_b64 v[228:229], 1, v[228:229]
	v_lshl_add_u64 v[228:229], s[18:19], 0, v[228:229]
	global_load_dwordx4 v[188:191], v[228:229], off
	global_load_dwordx4 v[200:203], v[228:229], off offset:256
	v_or_b32_e32 v228, 32, v158
	v_ashrrev_i32_e32 v229, 31, v228
	v_lshlrev_b64 v[228:229], 10, v[228:229]
	v_lshl_add_u64 v[228:229], v[228:229], 0, v[156:157]
	v_lshlrev_b64 v[228:229], 1, v[228:229]
	v_lshl_add_u64 v[228:229], s[18:19], 0, v[228:229]
	global_load_dwordx4 v[204:207], v[228:229], off
	global_load_dwordx4 v[208:211], v[228:229], off offset:256
	v_or_b32_e32 v228, 48, v158
	v_ashrrev_i32_e32 v229, 31, v228
	v_lshlrev_b64 v[228:229], 10, v[228:229]
	v_lshl_add_u64 v[228:229], v[228:229], 0, v[156:157]
	v_lshlrev_b64 v[228:229], 1, v[228:229]
	v_lshl_add_u64 v[228:229], s[18:19], 0, v[228:229]
	global_load_dwordx4 v[212:215], v[228:229], off
	global_load_dwordx4 v[216:219], v[228:229], off offset:256
	s_waitcnt vmcnt(0)
	v_add_f32_e32 v142, v142, v82
	v_add_f32_e32 v143, v143, v83
	v_add_f32_e32 v144, v144, v84
	v_add_f32_e32 v145, v145, v85
	v_add_f32_e32 v138, v138, v78
	v_add_f32_e32 v139, v139, v79
	v_add_f32_e32 v140, v140, v80
	v_add_f32_e32 v141, v141, v81
	v_lshl_add_u64 v[176:177], s[16:17], 0, v[176:177]
	v_add_f32_e32 v134, v134, v70
	v_add_f32_e32 v136, v136, v72
	v_add_f32_e32 v130, v130, v66
	v_add_f32_e32 v135, v135, v71
	v_add_f32_e32 v137, v137, v73
	v_add_f32_e32 v131, v131, v67
	v_add_f32_e32 v133, v133, v69
	v_lshlrev_b32_e32 v165, 16, v166
	v_and_b32_e32 v166, 0xffff0000, v166
	v_lshlrev_b32_e32 v175, 16, v167
	v_and_b32_e32 v167, 0xffff0000, v167
	v_lshlrev_b32_e32 v180, 16, v168
	v_and_b32_e32 v168, 0xffff0000, v168
	v_lshlrev_b32_e32 v181, 16, v169
	v_and_b32_e32 v169, 0xffff0000, v169
	v_fmac_f32_e32 v165, s65, v142
	v_fmac_f32_e32 v166, s65, v143
	v_fmac_f32_e32 v175, s65, v144
	v_fmac_f32_e32 v167, s65, v145
	v_fmac_f32_e32 v180, s65, v138
	v_fmac_f32_e32 v168, s65, v139
	v_fmac_f32_e32 v181, s65, v140
	v_fmac_f32_e32 v169, s65, v141
	v_cvt_pk_bf16_f32 v138, v165, v166
	v_cvt_pk_bf16_f32 v139, v175, v167
	v_cvt_pk_bf16_f32 v140, v180, v168
	v_cvt_pk_bf16_f32 v141, v181, v169
	global_store_dwordx4 v[176:177], v[138:141], off
	v_mov_b32_e32 v142, v184
	v_mov_b32_e32 v143, v185
	v_mov_b32_e32 v144, v186
	v_mov_b32_e32 v145, v187
	v_lshlrev_b32_e32 v167, 16, v138
	v_and_b32_e32 v138, 0xffff0000, v138
	v_lshlrev_b32_e32 v168, 16, v139
	v_and_b32_e32 v139, 0xffff0000, v139
	v_lshlrev_b32_e32 v169, 16, v140
	v_and_b32_e32 v140, 0xffff0000, v140
	v_lshlrev_b32_e32 v175, 16, v141
	v_and_b32_e32 v141, 0xffff0000, v141
	v_mul_f32_e32 v138, v138, v138
	v_mul_f32_e32 v139, v139, v139
	v_mul_f32_e32 v140, v140, v140
	v_mul_f32_e32 v141, v141, v141
	v_fmac_f32_e32 v138, v167, v167
	v_fmac_f32_e32 v139, v168, v168
	v_fmac_f32_e32 v140, v169, v169
	v_fmac_f32_e32 v141, v175, v175
	v_add_f32_e32 v138, v138, v139
	v_add_f32_e32 v139, v140, v141
	v_add_f32_e32 v138, v138, v139
	v_add_f32_e32 v165, v132, v68
	v_and_b32_e32 v166, 64, v171
	v_xor_b32_e32 v132, 16, v171
	v_add_u32_e32 v166, 64, v166
	v_cmp_lt_i32_e32 vcc, v132, v166
	s_nop 0
	v_lshlrev_b32_e32 v139, 16, v142
	v_and_b32_e32 v140, 0xffff0000, v142
	v_lshlrev_b32_e32 v141, 16, v143
	v_and_b32_e32 v142, 0xffff0000, v143
	v_lshlrev_b32_e32 v143, 16, v144
	v_and_b32_e32 v144, 0xffff0000, v144
	v_lshlrev_b32_e32 v167, 16, v145
	v_and_b32_e32 v145, 0xffff0000, v145
	v_fmac_f32_e32 v139, s65, v134
	v_fmac_f32_e32 v141, s65, v136
	v_fmac_f32_e32 v143, s65, v130
	v_fmac_f32_e32 v140, s65, v135
	v_fmac_f32_e32 v142, s65, v137
	v_fmac_f32_e32 v144, s65, v131
	v_fmac_f32_e32 v167, s65, v165
	v_fmac_f32_e32 v145, s65, v133
	v_cvt_pk_bf16_f32 v134, v139, v140
	v_cvt_pk_bf16_f32 v135, v141, v142
	v_cvt_pk_bf16_f32 v136, v143, v144
	v_cvt_pk_bf16_f32 v137, v167, v145
	v_cndmask_b32_e32 v132, v171, v132, vcc
	v_and_b32_e32 v131, 0xffff0000, v134
	v_and_b32_e32 v139, 0xffff0000, v135
	v_and_b32_e32 v141, 0xffff0000, v136
	v_and_b32_e32 v143, 0xffff0000, v137
	v_lshlrev_b32_e32 v130, 16, v134
	v_lshlrev_b32_e32 v133, 16, v135
	v_lshlrev_b32_e32 v140, 16, v136
	v_lshlrev_b32_e32 v142, 16, v137
	v_mul_f32_e32 v131, v131, v131
	v_mul_f32_e32 v139, v139, v139
	v_mul_f32_e32 v141, v141, v141
	v_mul_f32_e32 v143, v143, v143
	v_fmac_f32_e32 v131, v130, v130
	v_fmac_f32_e32 v139, v133, v133
	v_fmac_f32_e32 v141, v140, v140
	v_fmac_f32_e32 v143, v142, v142
	v_add_f32_e32 v130, v131, v139
	v_add_f32_e32 v131, v141, v143
	v_add_f32_e32 v130, v130, v131
	v_lshlrev_b32_e32 v132, 2, v132
	v_add_f32_e32 v130, v138, v130
	v_mov_b32_e32 v131, v130
	s_nop 1
	v_permlane16_swap_b32 v131, v130
	v_xor_b32_e32 v133, 32, v171
	v_cmp_lt_i32_e32 vcc, v133, v166
	global_store_dwordx4 v[176:177], v[134:137], off offset:256
	s_waitcnt lgkmcnt(0)
	v_add_f32_e32 v130, v130, v131
	v_cndmask_b32_e32 v133, v171, v133, vcc
	v_lshlrev_b32_e32 v133, 2, v133
	v_mov_b32_e32 v131, v130
	s_nop 1
	v_permlane32_swap_b32 v131, v130
	s_and_saveexec_b64 s[8:9], s[6:7]
	s_cbranch_execz .LBB1_775
	s_waitcnt lgkmcnt(0)
	v_add_f32_e32 v134, v130, v131
	s_lshl_b32 s20, s23, 2
	v_lshlrev_b64 v[130:131], 6, v[158:159]
	s_ashr_i32 s21, s20, 31
	v_lshl_add_u64 v[130:131], s[14:15], 0, v[130:131]
	v_lshl_add_u64 v[130:131], s[20:21], 2, v[130:131]
	s_lshl_b32 s74, s40, 2
	v_lshl_add_u64 v[130:131], v[130:131], 0, s[74:75]
	global_store_dword v[130:131], v134, off
; __device__ __forceinline__ unsigned cvt_pk_bf16(float lo, float hi) { unsigned r; asm volatile("v_cvt_pk_bf16_f32 %0, %1, %2" : "=v"(r) : "v"(lo), "v"(hi)); return r; }
; __device__ __forceinline__ float bflo(unsigned w) { return __uint_as_float(w << 16); }
;     __device__ __forceinline__ void operator()(const f32x4 (&acc)[2][2][4][2], const Unit& u, int wr, int wc, int fr, int fq, LAS unsigned char* lds) const {
;     ...
;             for (int m = 0; m < 4; ++m) { const int row = row0 + ai * HALF + m * 16; const size_t off = (size_t)row * D + col0;
;                 float rs = 1.0f; if (MODE == 1) rs = rstd_of4(rss_in, row, fq);
;                 float ss = 0.f;
; #pragma unroll
;                 for (int bj = 0; bj < 2; ++bj) { const size_t o = off + bj * HALF; const u32x4 bw = *(const u32x4*)(base + o);
;                     const float bs[8] = {bflo(bw.x), bfhi(bw.x), bflo(bw.y), bfhi(bw.y), bflo(bw.z), bfhi(bw.z), bflo(bw.w), bfhi(bw.w)};
;                     float hn[8];
;                     if (MODE == 0) {
; #pragma unroll
;                         for (int n = 0; n < 2; ++n)
; #pragma unroll
;                             for (int e = 0; e < 4; ++e) hn[4 * n + e] = bs[4 * n + e] + (acc[ai][bj][m][n][e] + bv[bj][n][e]) * scale;
;                     } else { const u32x4 pw = *(const u32x4*)(pp + o);
;                         const float pv[8] = {bflo(pw.x), bfhi(pw.x), bflo(pw.y), bfhi(pw.y), bflo(pw.z), bfhi(pw.z), bflo(pw.w), bfhi(pw.w)};
; #pragma unroll
;                         for (int n = 0; n < 2; ++n)
; #pragma unroll
;                             for (int e = 0; e < 4; ++e) hn[4 * n + e] = bs[4 * n + e] + fast_sigmoid(acc[ai][bj][m][n][e] * rs) * pv[4 * n + e]; }
;                     u32x4 w; w.x = cvt_pk_bf16(hn[0], hn[1]); w.y = cvt_pk_bf16(hn[2], hn[3]); w.z = cvt_pk_bf16(hn[4], hn[5]); w.w = cvt_pk_bf16(hn[6], hn[7]); *(u32x4*)(hb + o) = w;
;                     const float hr[8] = {bflo(w.x), bfhi(w.x), bflo(w.y), bfhi(w.y), bflo(w.z), bfhi(w.z), bflo(w.w), bfhi(w.w)};
;                     ss += ((hr[0] * hr[0] + hr[1] * hr[1]) + (hr[2] * hr[2] + hr[3] * hr[3])) + ((hr[4] * hr[4] + hr[5] * hr[5]) + (hr[6] * hr[6] + hr[7] * hr[7])); }
;                 ss += __shfl_xor(ss, 16); ss += __shfl_xor(ss, 32);
;                 if (fq == 0) rss_out[(size_t)row * 16 + u.pn * 4 + wc] = ss; }
.LBB1_775:
	s_or_b64 exec, exec, s[8:9]
	v_or_b32_e32 v130, 16, v158
	s_waitcnt lgkmcnt(0)
	v_ashrrev_i32_e32 v131, 31, v130
	v_lshlrev_b64 v[134:135], 10, v[130:131]
	v_lshl_add_u64 v[134:135], v[134:135], 0, v[156:157]
	v_lshlrev_b64 v[138:139], 1, v[134:135]
	v_lshl_add_u64 v[140:141], s[18:19], 0, v[138:139]
	v_mov_b32_e32 v134, v188
	v_mov_b32_e32 v135, v189
	v_mov_b32_e32 v136, v190
	v_mov_b32_e32 v137, v191
	v_add_f32_e32 v126, v126, v82
	v_add_f32_e32 v127, v127, v83
	v_add_f32_e32 v128, v128, v84
	v_add_f32_e32 v129, v129, v85
	v_add_f32_e32 v122, v122, v78
	v_add_f32_e32 v123, v123, v79
	v_add_f32_e32 v124, v124, v80
	v_add_f32_e32 v125, v125, v81
	v_lshl_add_u64 v[138:139], s[16:17], 0, v[138:139]
	v_add_f32_e32 v119, v119, v71
	v_add_f32_e32 v121, v121, v73
	v_add_f32_e32 v118, v118, v70
	v_add_f32_e32 v120, v120, v72
	v_add_f32_e32 v114, v114, v66
	v_add_f32_e32 v115, v115, v67
	v_add_f32_e32 v116, v116, v68
	v_add_f32_e32 v117, v117, v69
	s_nop 0
	v_lshlrev_b32_e32 v142, 16, v134
	v_and_b32_e32 v134, 0xffff0000, v134
	v_lshlrev_b32_e32 v143, 16, v135
	v_and_b32_e32 v135, 0xffff0000, v135
	v_lshlrev_b32_e32 v144, 16, v136
	v_and_b32_e32 v136, 0xffff0000, v136
	v_lshlrev_b32_e32 v145, 16, v137
	v_and_b32_e32 v137, 0xffff0000, v137
	v_fmac_f32_e32 v142, s65, v126
	v_fmac_f32_e32 v134, s65, v127
	v_fmac_f32_e32 v143, s65, v128
	v_fmac_f32_e32 v135, s65, v129
	v_fmac_f32_e32 v144, s65, v122
	v_fmac_f32_e32 v136, s65, v123
	v_fmac_f32_e32 v145, s65, v124
	v_fmac_f32_e32 v137, s65, v125
	v_cvt_pk_bf16_f32 v122, v142, v134
	v_cvt_pk_bf16_f32 v123, v143, v135
	v_cvt_pk_bf16_f32 v124, v144, v136
	v_cvt_pk_bf16_f32 v125, v145, v137
	global_store_dwordx4 v[138:139], v[122:125], off
	v_mov_b32_e32 v126, v200
	v_mov_b32_e32 v127, v201
	v_mov_b32_e32 v128, v202
	v_mov_b32_e32 v129, v203
	v_lshlrev_b32_e32 v134, 16, v122
	v_and_b32_e32 v122, 0xffff0000, v122
	v_lshlrev_b32_e32 v135, 16, v123
	v_and_b32_e32 v123, 0xffff0000, v123
	v_lshlrev_b32_e32 v136, 16, v124
	v_and_b32_e32 v124, 0xffff0000, v124
	v_lshlrev_b32_e32 v137, 16, v125
	v_and_b32_e32 v125, 0xffff0000, v125
	v_mul_f32_e32 v122, v122, v122
	v_mul_f32_e32 v123, v123, v123
	v_mul_f32_e32 v124, v124, v124
	v_mul_f32_e32 v125, v125, v125
	v_fmac_f32_e32 v122, v134, v134
	v_fmac_f32_e32 v123, v135, v135
	v_fmac_f32_e32 v124, v136, v136
	v_fmac_f32_e32 v125, v137, v137
	v_add_f32_e32 v122, v122, v123
	v_add_f32_e32 v123, v124, v125
	v_add_f32_e32 v122, v122, v123
	s_nop 0
	v_lshlrev_b32_e32 v123, 16, v126
	v_and_b32_e32 v124, 0xffff0000, v126
	v_and_b32_e32 v126, 0xffff0000, v127
	v_lshlrev_b32_e32 v125, 16, v127
	v_lshlrev_b32_e32 v127, 16, v128
	v_and_b32_e32 v128, 0xffff0000, v128
	v_lshlrev_b32_e32 v134, 16, v129
	v_and_b32_e32 v129, 0xffff0000, v129
	v_fmac_f32_e32 v124, s65, v119
	v_fmac_f32_e32 v126, s65, v121
	v_fmac_f32_e32 v123, s65, v118
	v_fmac_f32_e32 v125, s65, v120
	v_fmac_f32_e32 v127, s65, v114
	v_fmac_f32_e32 v128, s65, v115
	v_fmac_f32_e32 v134, s65, v116
	v_fmac_f32_e32 v129, s65, v117
	v_cvt_pk_bf16_f32 v116, v123, v124
	v_cvt_pk_bf16_f32 v117, v125, v126
	v_cvt_pk_bf16_f32 v118, v127, v128
	v_cvt_pk_bf16_f32 v119, v134, v129
	global_store_dwordx4 v[138:139], v[116:119], off offset:256
	v_and_b32_e32 v115, 0xffff0000, v116
	v_and_b32_e32 v121, 0xffff0000, v117
	v_and_b32_e32 v124, 0xffff0000, v118
	v_and_b32_e32 v126, 0xffff0000, v119
	v_lshlrev_b32_e32 v114, 16, v116
	v_lshlrev_b32_e32 v120, 16, v117
	v_lshlrev_b32_e32 v123, 16, v118
	v_lshlrev_b32_e32 v125, 16, v119
	v_mul_f32_e32 v115, v115, v115
	v_mul_f32_e32 v121, v121, v121
	v_mul_f32_e32 v124, v124, v124
	v_mul_f32_e32 v126, v126, v126
	v_fmac_f32_e32 v115, v114, v114
	v_fmac_f32_e32 v121, v120, v120
	v_fmac_f32_e32 v124, v123, v123
	v_fmac_f32_e32 v126, v125, v125
	v_add_f32_e32 v114, v115, v121
	v_add_f32_e32 v115, v124, v126
	v_add_f32_e32 v114, v114, v115
	v_add_f32_e32 v114, v122, v114
	v_mov_b32_e32 v115, v114
	s_nop 1
	v_permlane16_swap_b32 v115, v114
	s_waitcnt lgkmcnt(0)
	v_add_f32_e32 v114, v114, v115
	v_mov_b32_e32 v115, v114
	s_nop 1
	v_permlane32_swap_b32 v115, v114
	s_and_saveexec_b64 s[8:9], s[6:7]
	s_cbranch_execz .LBB1_777
	s_waitcnt lgkmcnt(0)
	v_add_f32_e32 v116, v114, v115
	s_lshl_b32 s20, s23, 2
	v_lshlrev_b64 v[114:115], 6, v[130:131]
	s_ashr_i32 s21, s20, 31
	v_lshl_add_u64 v[114:115], s[14:15], 0, v[114:115]
	v_lshl_add_u64 v[114:115], s[20:21], 2, v[114:115]
	s_lshl_b32 s74, s40, 2
	v_lshl_add_u64 v[114:115], v[114:115], 0, s[74:75]
	global_store_dword v[114:115], v116, off
; __device__ __forceinline__ unsigned cvt_pk_bf16(float lo, float hi) { unsigned r; asm volatile("v_cvt_pk_bf16_f32 %0, %1, %2" : "=v"(r) : "v"(lo), "v"(hi)); return r; }
; __device__ __forceinline__ float bflo(unsigned w) { return __uint_as_float(w << 16); }
;     __device__ __forceinline__ void operator()(const f32x4 (&acc)[2][2][4][2], const Unit& u, int wr, int wc, int fr, int fq, LAS unsigned char* lds) const {
;     ...
;             for (int m = 0; m < 4; ++m) { const int row = row0 + ai * HALF + m * 16; const size_t off = (size_t)row * D + col0;
;                 float rs = 1.0f; if (MODE == 1) rs = rstd_of4(rss_in, row, fq);
;                 float ss = 0.f;
; #pragma unroll
;                 for (int bj = 0; bj < 2; ++bj) { const size_t o = off + bj * HALF; const u32x4 bw = *(const u32x4*)(base + o);
;                     const float bs[8] = {bflo(bw.x), bfhi(bw.x), bflo(bw.y), bfhi(bw.y), bflo(bw.z), bfhi(bw.z), bflo(bw.w), bfhi(bw.w)};
;                     float hn[8];
;                     if (MODE == 0) {
; #pragma unroll
;                         for (int n = 0; n < 2; ++n)
; #pragma unroll
;                             for (int e = 0; e < 4; ++e) hn[4 * n + e] = bs[4 * n + e] + (acc[ai][bj][m][n][e] + bv[bj][n][e]) * scale;
;                     } else { const u32x4 pw = *(const u32x4*)(pp + o);
;                         const float pv[8] = {bflo(pw.x), bfhi(pw.x), bflo(pw.y), bfhi(pw.y), bflo(pw.z), bfhi(pw.z), bflo(pw.w), bfhi(pw.w)};
; #pragma unroll
;                         for (int n = 0; n < 2; ++n)
; #pragma unroll
;                             for (int e = 0; e < 4; ++e) hn[4 * n + e] = bs[4 * n + e] + fast_sigmoid(acc[ai][bj][m][n][e] * rs) * pv[4 * n + e]; }
;                     u32x4 w; w.x = cvt_pk_bf16(hn[0], hn[1]); w.y = cvt_pk_bf16(hn[2], hn[3]); w.z = cvt_pk_bf16(hn[4], hn[5]); w.w = cvt_pk_bf16(hn[6], hn[7]); *(u32x4*)(hb + o) = w;
;                     const float hr[8] = {bflo(w.x), bfhi(w.x), bflo(w.y), bfhi(w.y), bflo(w.z), bfhi(w.z), bflo(w.w), bfhi(w.w)};
;                     ss += ((hr[0] * hr[0] + hr[1] * hr[1]) + (hr[2] * hr[2] + hr[3] * hr[3])) + ((hr[4] * hr[4] + hr[5] * hr[5]) + (hr[6] * hr[6] + hr[7] * hr[7])); }
;                 ss += __shfl_xor(ss, 16); ss += __shfl_xor(ss, 32);
;                 if (fq == 0) rss_out[(size_t)row * 16 + u.pn * 4 + wc] = ss; }
.LBB1_777:
	s_or_b64 exec, exec, s[8:9]
	v_or_b32_e32 v114, 32, v158
	s_waitcnt lgkmcnt(0)
	v_ashrrev_i32_e32 v115, 31, v114
	v_lshlrev_b64 v[116:117], 10, v[114:115]
	v_lshl_add_u64 v[116:117], v[116:117], 0, v[156:157]
	v_lshlrev_b64 v[120:121], 1, v[116:117]
	v_lshl_add_u64 v[122:123], s[18:19], 0, v[120:121]
	v_mov_b32_e32 v116, v204
	v_mov_b32_e32 v117, v205
	v_mov_b32_e32 v118, v206
	v_mov_b32_e32 v119, v207
	v_add_f32_e32 v110, v110, v82
	v_add_f32_e32 v111, v111, v83
	v_add_f32_e32 v112, v112, v84
	v_add_f32_e32 v113, v113, v85
	v_add_f32_e32 v106, v106, v78
	v_add_f32_e32 v107, v107, v79
	v_add_f32_e32 v108, v108, v80
	v_add_f32_e32 v109, v109, v81
	v_lshl_add_u64 v[120:121], s[16:17], 0, v[120:121]
	v_add_f32_e32 v103, v103, v71
	v_add_f32_e32 v105, v105, v73
	v_add_f32_e32 v102, v102, v70
	v_add_f32_e32 v104, v104, v72
	v_add_f32_e32 v98, v98, v66
	v_add_f32_e32 v99, v99, v67
	v_add_f32_e32 v100, v100, v68
	v_add_f32_e32 v101, v101, v69
	s_nop 0
	v_lshlrev_b32_e32 v124, 16, v116
	v_and_b32_e32 v116, 0xffff0000, v116
	v_lshlrev_b32_e32 v125, 16, v117
	v_and_b32_e32 v117, 0xffff0000, v117
	v_lshlrev_b32_e32 v126, 16, v118
	v_and_b32_e32 v118, 0xffff0000, v118
	v_lshlrev_b32_e32 v127, 16, v119
	v_and_b32_e32 v119, 0xffff0000, v119
	v_fmac_f32_e32 v124, s65, v110
	v_fmac_f32_e32 v116, s65, v111
	v_fmac_f32_e32 v125, s65, v112
	v_fmac_f32_e32 v117, s65, v113
	v_fmac_f32_e32 v126, s65, v106
	v_fmac_f32_e32 v118, s65, v107
	v_fmac_f32_e32 v127, s65, v108
	v_fmac_f32_e32 v119, s65, v109
	v_cvt_pk_bf16_f32 v106, v124, v116
	v_cvt_pk_bf16_f32 v107, v125, v117
	v_cvt_pk_bf16_f32 v108, v126, v118
	v_cvt_pk_bf16_f32 v109, v127, v119
	global_store_dwordx4 v[120:121], v[106:109], off
	v_mov_b32_e32 v110, v208
	v_mov_b32_e32 v111, v209
	v_mov_b32_e32 v112, v210
	v_mov_b32_e32 v113, v211
	v_lshlrev_b32_e32 v116, 16, v106
	v_and_b32_e32 v106, 0xffff0000, v106
	v_lshlrev_b32_e32 v117, 16, v107
	v_and_b32_e32 v107, 0xffff0000, v107
	v_lshlrev_b32_e32 v118, 16, v108
	v_and_b32_e32 v108, 0xffff0000, v108
	v_lshlrev_b32_e32 v119, 16, v109
	v_and_b32_e32 v109, 0xffff0000, v109
	v_mul_f32_e32 v106, v106, v106
	v_mul_f32_e32 v107, v107, v107
	v_mul_f32_e32 v108, v108, v108
	v_mul_f32_e32 v109, v109, v109
	v_fmac_f32_e32 v106, v116, v116
	v_fmac_f32_e32 v107, v117, v117
	v_fmac_f32_e32 v108, v118, v118
	v_fmac_f32_e32 v109, v119, v119
	v_add_f32_e32 v106, v106, v107
	v_add_f32_e32 v107, v108, v109
	v_add_f32_e32 v106, v106, v107
	s_nop 0
	v_lshlrev_b32_e32 v107, 16, v110
	v_and_b32_e32 v108, 0xffff0000, v110
	v_and_b32_e32 v110, 0xffff0000, v111
	v_lshlrev_b32_e32 v109, 16, v111
	v_lshlrev_b32_e32 v111, 16, v112
	v_and_b32_e32 v112, 0xffff0000, v112
	v_lshlrev_b32_e32 v116, 16, v113
	v_and_b32_e32 v113, 0xffff0000, v113
	v_fmac_f32_e32 v108, s65, v103
	v_fmac_f32_e32 v110, s65, v105
	v_fmac_f32_e32 v107, s65, v102
	v_fmac_f32_e32 v109, s65, v104
	v_fmac_f32_e32 v111, s65, v98
	v_fmac_f32_e32 v112, s65, v99
	v_fmac_f32_e32 v116, s65, v100
	v_fmac_f32_e32 v113, s65, v101
	v_cvt_pk_bf16_f32 v100, v107, v108
	v_cvt_pk_bf16_f32 v101, v109, v110
	v_cvt_pk_bf16_f32 v102, v111, v112
	v_cvt_pk_bf16_f32 v103, v116, v113
	global_store_dwordx4 v[120:121], v[100:103], off offset:256
	v_and_b32_e32 v99, 0xffff0000, v100
	v_and_b32_e32 v105, 0xffff0000, v101
	v_and_b32_e32 v108, 0xffff0000, v102
	v_and_b32_e32 v110, 0xffff0000, v103
	v_lshlrev_b32_e32 v98, 16, v100
	v_lshlrev_b32_e32 v104, 16, v101
	v_lshlrev_b32_e32 v107, 16, v102
	v_lshlrev_b32_e32 v109, 16, v103
	v_mul_f32_e32 v99, v99, v99
	v_mul_f32_e32 v105, v105, v105
	v_mul_f32_e32 v108, v108, v108
	v_mul_f32_e32 v110, v110, v110
	v_fmac_f32_e32 v99, v98, v98
	v_fmac_f32_e32 v105, v104, v104
	v_fmac_f32_e32 v108, v107, v107
	v_fmac_f32_e32 v110, v109, v109
	v_add_f32_e32 v98, v99, v105
	v_add_f32_e32 v99, v108, v110
	v_add_f32_e32 v98, v98, v99
	v_add_f32_e32 v98, v106, v98
	v_mov_b32_e32 v99, v98
	s_nop 1
	v_permlane16_swap_b32 v99, v98
	s_waitcnt lgkmcnt(0)
	v_add_f32_e32 v98, v98, v99
	v_mov_b32_e32 v99, v98
	s_nop 1
	v_permlane32_swap_b32 v99, v98
	s_and_saveexec_b64 s[8:9], s[6:7]
	s_cbranch_execz .LBB1_779
	s_waitcnt lgkmcnt(0)
	v_add_f32_e32 v100, v98, v99
	s_lshl_b32 s20, s23, 2
	v_lshlrev_b64 v[98:99], 6, v[114:115]
	s_ashr_i32 s21, s20, 31
	v_lshl_add_u64 v[98:99], s[14:15], 0, v[98:99]
	v_lshl_add_u64 v[98:99], s[20:21], 2, v[98:99]
	s_lshl_b32 s74, s40, 2
	v_lshl_add_u64 v[98:99], v[98:99], 0, s[74:75]
	global_store_dword v[98:99], v100, off
; __device__ __forceinline__ unsigned cvt_pk_bf16(float lo, float hi) { unsigned r; asm volatile("v_cvt_pk_bf16_f32 %0, %1, %2" : "=v"(r) : "v"(lo), "v"(hi)); return r; }
; __device__ __forceinline__ float bflo(unsigned w) { return __uint_as_float(w << 16); }
;     __device__ __forceinline__ void operator()(const f32x4 (&acc)[2][2][4][2], const Unit& u, int wr, int wc, int fr, int fq, LAS unsigned char* lds) const {
;     ...
;             for (int m = 0; m < 4; ++m) { const int row = row0 + ai * HALF + m * 16; const size_t off = (size_t)row * D + col0;
;                 float rs = 1.0f; if (MODE == 1) rs = rstd_of4(rss_in, row, fq);
;                 float ss = 0.f;
; #pragma unroll
;                 for (int bj = 0; bj < 2; ++bj) { const size_t o = off + bj * HALF; const u32x4 bw = *(const u32x4*)(base + o);
;                     const float bs[8] = {bflo(bw.x), bfhi(bw.x), bflo(bw.y), bfhi(bw.y), bflo(bw.z), bfhi(bw.z), bflo(bw.w), bfhi(bw.w)};
;                     float hn[8];
;                     if (MODE == 0) {
; #pragma unroll
;                         for (int n = 0; n < 2; ++n)
; #pragma unroll
;                             for (int e = 0; e < 4; ++e) hn[4 * n + e] = bs[4 * n + e] + (acc[ai][bj][m][n][e] + bv[bj][n][e]) * scale;
;                     } else { const u32x4 pw = *(const u32x4*)(pp + o);
;                         const float pv[8] = {bflo(pw.x), bfhi(pw.x), bflo(pw.y), bfhi(pw.y), bflo(pw.z), bfhi(pw.z), bflo(pw.w), bfhi(pw.w)};
; #pragma unroll
;                         for (int n = 0; n < 2; ++n)
; #pragma unroll
;                             for (int e = 0; e < 4; ++e) hn[4 * n + e] = bs[4 * n + e] + fast_sigmoid(acc[ai][bj][m][n][e] * rs) * pv[4 * n + e]; }
;                     u32x4 w; w.x = cvt_pk_bf16(hn[0], hn[1]); w.y = cvt_pk_bf16(hn[2], hn[3]); w.z = cvt_pk_bf16(hn[4], hn[5]); w.w = cvt_pk_bf16(hn[6], hn[7]); *(u32x4*)(hb + o) = w;
;                     const float hr[8] = {bflo(w.x), bfhi(w.x), bflo(w.y), bfhi(w.y), bflo(w.z), bfhi(w.z), bflo(w.w), bfhi(w.w)};
;                     ss += ((hr[0] * hr[0] + hr[1] * hr[1]) + (hr[2] * hr[2] + hr[3] * hr[3])) + ((hr[4] * hr[4] + hr[5] * hr[5]) + (hr[6] * hr[6] + hr[7] * hr[7])); }
;                 ss += __shfl_xor(ss, 16); ss += __shfl_xor(ss, 32);
;                 if (fq == 0) rss_out[(size_t)row * 16 + u.pn * 4 + wc] = ss; }
.LBB1_779:
	s_or_b64 exec, exec, s[8:9]
	v_or_b32_e32 v98, 48, v158
	s_waitcnt lgkmcnt(0)
	v_ashrrev_i32_e32 v99, 31, v98
	v_lshlrev_b64 v[100:101], 10, v[98:99]
	v_lshl_add_u64 v[100:101], v[100:101], 0, v[156:157]
	v_lshlrev_b64 v[104:105], 1, v[100:101]
	v_lshl_add_u64 v[106:107], s[18:19], 0, v[104:105]
	v_mov_b32_e32 v100, v212
	v_mov_b32_e32 v101, v213
	v_mov_b32_e32 v102, v214
	v_mov_b32_e32 v103, v215
	v_add_f32_e32 v94, v94, v82
	v_add_f32_e32 v95, v95, v83
	v_add_f32_e32 v96, v96, v84
	v_add_f32_e32 v97, v97, v85
	v_add_f32_e32 v90, v90, v78
	v_add_f32_e32 v91, v91, v79
	v_add_f32_e32 v92, v92, v80
	v_add_f32_e32 v93, v93, v81
	v_lshl_add_u64 v[104:105], s[16:17], 0, v[104:105]
	v_add_f32_e32 v87, v87, v71
	v_add_f32_e32 v89, v89, v73
	v_add_f32_e32 v86, v86, v70
	v_add_f32_e32 v88, v88, v72
	v_add_f32_e32 v74, v74, v66
	v_add_f32_e32 v75, v75, v67
	v_add_f32_e32 v76, v76, v68
	v_add_f32_e32 v77, v77, v69
	s_nop 0
	v_lshlrev_b32_e32 v108, 16, v100
	v_and_b32_e32 v100, 0xffff0000, v100
	v_lshlrev_b32_e32 v109, 16, v101
	v_and_b32_e32 v101, 0xffff0000, v101
	v_lshlrev_b32_e32 v110, 16, v102
	v_and_b32_e32 v102, 0xffff0000, v102
	v_lshlrev_b32_e32 v111, 16, v103
	v_and_b32_e32 v103, 0xffff0000, v103
	v_fmac_f32_e32 v108, s65, v94
	v_fmac_f32_e32 v100, s65, v95
	v_fmac_f32_e32 v109, s65, v96
	v_fmac_f32_e32 v101, s65, v97
	v_fmac_f32_e32 v110, s65, v90
	v_fmac_f32_e32 v102, s65, v91
	v_fmac_f32_e32 v111, s65, v92
	v_fmac_f32_e32 v103, s65, v93
	v_cvt_pk_bf16_f32 v90, v108, v100
	v_cvt_pk_bf16_f32 v91, v109, v101
	v_cvt_pk_bf16_f32 v92, v110, v102
	v_cvt_pk_bf16_f32 v93, v111, v103
	global_store_dwordx4 v[104:105], v[90:93], off
	v_mov_b32_e32 v94, v216
	v_mov_b32_e32 v95, v217
	v_mov_b32_e32 v96, v218
	v_mov_b32_e32 v97, v219
	v_lshlrev_b32_e32 v100, 16, v90
	v_and_b32_e32 v90, 0xffff0000, v90
	v_lshlrev_b32_e32 v101, 16, v91
	v_and_b32_e32 v91, 0xffff0000, v91
	v_lshlrev_b32_e32 v102, 16, v92
	v_and_b32_e32 v92, 0xffff0000, v92
	v_lshlrev_b32_e32 v103, 16, v93
	v_and_b32_e32 v93, 0xffff0000, v93
	v_mul_f32_e32 v90, v90, v90
	v_mul_f32_e32 v91, v91, v91
	v_mul_f32_e32 v92, v92, v92
	v_mul_f32_e32 v93, v93, v93
	v_fmac_f32_e32 v90, v100, v100
	v_fmac_f32_e32 v91, v101, v101
	v_fmac_f32_e32 v92, v102, v102
	v_fmac_f32_e32 v93, v103, v103
	v_add_f32_e32 v90, v90, v91
	v_add_f32_e32 v91, v92, v93
	v_add_f32_e32 v90, v90, v91
	s_nop 0
	v_lshlrev_b32_e32 v91, 16, v94
	v_and_b32_e32 v92, 0xffff0000, v94
	v_and_b32_e32 v94, 0xffff0000, v95
	v_lshlrev_b32_e32 v93, 16, v95
	v_lshlrev_b32_e32 v95, 16, v96
	v_and_b32_e32 v96, 0xffff0000, v96
	v_lshlrev_b32_e32 v100, 16, v97
	v_and_b32_e32 v97, 0xffff0000, v97
	v_fmac_f32_e32 v92, s65, v87
	v_fmac_f32_e32 v94, s65, v89
	v_fmac_f32_e32 v91, s65, v86
	v_fmac_f32_e32 v93, s65, v88
	v_fmac_f32_e32 v95, s65, v74
	v_fmac_f32_e32 v96, s65, v75
	v_fmac_f32_e32 v100, s65, v76
	v_fmac_f32_e32 v97, s65, v77
	v_cvt_pk_bf16_f32 v86, v91, v92
	v_cvt_pk_bf16_f32 v87, v93, v94
	v_cvt_pk_bf16_f32 v88, v95, v96
	v_cvt_pk_bf16_f32 v89, v100, v97
	global_store_dwordx4 v[104:105], v[86:89], off offset:256
	v_and_b32_e32 v75, 0xffff0000, v86
	v_and_b32_e32 v77, 0xffff0000, v87
	v_and_b32_e32 v92, 0xffff0000, v88
	v_and_b32_e32 v94, 0xffff0000, v89
	v_lshlrev_b32_e32 v74, 16, v86
	v_lshlrev_b32_e32 v76, 16, v87
	v_lshlrev_b32_e32 v91, 16, v88
	v_lshlrev_b32_e32 v93, 16, v89
	v_mul_f32_e32 v75, v75, v75
	v_mul_f32_e32 v77, v77, v77
	v_mul_f32_e32 v92, v92, v92
	v_mul_f32_e32 v94, v94, v94
	v_fmac_f32_e32 v75, v74, v74
	v_fmac_f32_e32 v77, v76, v76
	v_fmac_f32_e32 v92, v91, v91
	v_fmac_f32_e32 v94, v93, v93
	v_add_f32_e32 v74, v75, v77
	v_add_f32_e32 v75, v92, v94
	v_add_f32_e32 v74, v74, v75
	v_add_f32_e32 v74, v90, v74
	v_mov_b32_e32 v75, v74
	s_nop 1
	v_permlane16_swap_b32 v75, v74
	s_waitcnt lgkmcnt(0)
	v_add_f32_e32 v74, v74, v75
	v_mov_b32_e32 v75, v74
	s_nop 1
	v_permlane32_swap_b32 v75, v74
	s_and_saveexec_b64 s[8:9], s[6:7]
	s_cbranch_execz .LBB1_781
	s_waitcnt lgkmcnt(0)
	v_add_f32_e32 v76, v74, v75
	s_lshl_b32 s20, s23, 2
	v_lshlrev_b64 v[74:75], 6, v[98:99]
	s_ashr_i32 s21, s20, 31
	v_lshl_add_u64 v[74:75], s[14:15], 0, v[74:75]
	v_lshl_add_u64 v[74:75], s[20:21], 2, v[74:75]
	s_lshl_b32 s74, s40, 2
	v_lshl_add_u64 v[74:75], v[74:75], 0, s[74:75]
	global_store_dword v[74:75], v76, off
; __device__ __forceinline__ unsigned cvt_pk_bf16(float lo, float hi) { unsigned r; asm volatile("v_cvt_pk_bf16_f32 %0, %1, %2" : "=v"(r) : "v"(lo), "v"(hi)); return r; }
; __device__ __forceinline__ float bflo(unsigned w) { return __uint_as_float(w << 16); }
;     __device__ __forceinline__ void operator()(const f32x4 (&acc)[2][2][4][2], const Unit& u, int wr, int wc, int fr, int fq, LAS unsigned char* lds) const {
;     ...
;             for (int m = 0; m < 4; ++m) { const int row = row0 + ai * HALF + m * 16; const size_t off = (size_t)row * D + col0;
;                 float rs = 1.0f; if (MODE == 1) rs = rstd_of4(rss_in, row, fq);
;                 float ss = 0.f;
; #pragma unroll
;                 for (int bj = 0; bj < 2; ++bj) { const size_t o = off + bj * HALF; const u32x4 bw = *(const u32x4*)(base + o);
;                     const float bs[8] = {bflo(bw.x), bfhi(bw.x), bflo(bw.y), bfhi(bw.y), bflo(bw.z), bfhi(bw.z), bflo(bw.w), bfhi(bw.w)};
;                     float hn[8];
;                     if (MODE == 0) {
; #pragma unroll
;                         for (int n = 0; n < 2; ++n)
; #pragma unroll
;                             for (int e = 0; e < 4; ++e) hn[4 * n + e] = bs[4 * n + e] + (acc[ai][bj][m][n][e] + bv[bj][n][e]) * scale;
;                     } else { const u32x4 pw = *(const u32x4*)(pp + o);
;                         const float pv[8] = {bflo(pw.x), bfhi(pw.x), bflo(pw.y), bfhi(pw.y), bflo(pw.z), bfhi(pw.z), bflo(pw.w), bfhi(pw.w)};
; #pragma unroll
;                         for (int n = 0; n < 2; ++n)
; #pragma unroll
;                             for (int e = 0; e < 4; ++e) hn[4 * n + e] = bs[4 * n + e] + fast_sigmoid(acc[ai][bj][m][n][e] * rs) * pv[4 * n + e]; }
;                     u32x4 w; w.x = cvt_pk_bf16(hn[0], hn[1]); w.y = cvt_pk_bf16(hn[2], hn[3]); w.z = cvt_pk_bf16(hn[4], hn[5]); w.w = cvt_pk_bf16(hn[6], hn[7]); *(u32x4*)(hb + o) = w;
;                     const float hr[8] = {bflo(w.x), bfhi(w.x), bflo(w.y), bfhi(w.y), bflo(w.z), bfhi(w.z), bflo(w.w), bfhi(w.w)};
;                     ss += ((hr[0] * hr[0] + hr[1] * hr[1]) + (hr[2] * hr[2] + hr[3] * hr[3])) + ((hr[4] * hr[4] + hr[5] * hr[5]) + (hr[6] * hr[6] + hr[7] * hr[7])); }
;                 ss += __shfl_xor(ss, 16); ss += __shfl_xor(ss, 32);
;                 if (fq == 0) rss_out[(size_t)row * 16 + u.pn * 4 + wc] = ss; }
.LBB1_781:
	s_or_b64 exec, exec, s[8:9]
	v_add_u32_e32 v74, 0x80, v158
	s_waitcnt lgkmcnt(0)
	v_ashrrev_i32_e32 v75, 31, v74
	v_lshlrev_b64 v[76:77], 10, v[74:75]
	v_lshl_add_u64 v[76:77], v[76:77], 0, v[156:157]
	v_lshlrev_b64 v[76:77], 1, v[76:77]
	v_lshl_add_u64 v[90:91], s[18:19], 0, v[76:77]
	global_load_dwordx4 v[86:89], v[90:91], off
	global_load_dwordx4 v[184:187], v[90:91], off offset:256
	v_add_u32_e32 v228, 0x90, v158
	v_ashrrev_i32_e32 v229, 31, v228
	v_lshlrev_b64 v[228:229], 10, v[228:229]
	v_lshl_add_u64 v[228:229], v[228:229], 0, v[156:157]
	v_lshlrev_b64 v[228:229], 1, v[228:229]
	v_lshl_add_u64 v[228:229], s[18:19], 0, v[228:229]
	global_load_dwordx4 v[188:191], v[228:229], off
	global_load_dwordx4 v[200:203], v[228:229], off offset:256
	v_add_u32_e32 v228, 0xa0, v158
	v_ashrrev_i32_e32 v229, 31, v228
	v_lshlrev_b64 v[228:229], 10, v[228:229]
	v_lshl_add_u64 v[228:229], v[228:229], 0, v[156:157]
	v_lshlrev_b64 v[228:229], 1, v[228:229]
	v_lshl_add_u64 v[228:229], s[18:19], 0, v[228:229]
	global_load_dwordx4 v[204:207], v[228:229], off
	global_load_dwordx4 v[208:211], v[228:229], off offset:256
	v_add_u32_e32 v228, 0xb0, v158
	v_ashrrev_i32_e32 v229, 31, v228
	v_lshlrev_b64 v[228:229], 10, v[228:229]
	v_lshl_add_u64 v[228:229], v[228:229], 0, v[156:157]
	v_lshlrev_b64 v[228:229], 1, v[228:229]
	v_lshl_add_u64 v[228:229], s[18:19], 0, v[228:229]
	global_load_dwordx4 v[212:215], v[228:229], off
	global_load_dwordx4 v[216:219], v[228:229], off offset:256
	v_add_f32_e32 v62, v62, v82
	v_add_f32_e32 v63, v63, v83
	v_add_f32_e32 v64, v64, v84
	v_add_f32_e32 v65, v65, v85
	v_add_f32_e32 v58, v58, v78
	v_add_f32_e32 v59, v59, v79
	v_add_f32_e32 v60, v60, v80
	v_add_f32_e32 v61, v61, v81
	v_lshl_add_u64 v[76:77], s[16:17], 0, v[76:77]
	v_add_f32_e32 v55, v55, v71
	v_add_f32_e32 v57, v57, v73
	v_add_f32_e32 v54, v54, v70
	v_add_f32_e32 v56, v56, v72
	v_add_f32_e32 v50, v50, v66
	v_add_f32_e32 v51, v51, v67
	v_add_f32_e32 v52, v52, v68
	v_add_f32_e32 v53, v53, v69
	s_waitcnt vmcnt(0)
	v_lshlrev_b32_e32 v92, 16, v86
	v_and_b32_e32 v86, 0xffff0000, v86
	v_lshlrev_b32_e32 v93, 16, v87
	v_and_b32_e32 v87, 0xffff0000, v87
	v_lshlrev_b32_e32 v94, 16, v88
	v_and_b32_e32 v88, 0xffff0000, v88
	v_lshlrev_b32_e32 v95, 16, v89
	v_and_b32_e32 v89, 0xffff0000, v89
	v_fmac_f32_e32 v92, s65, v62
	v_fmac_f32_e32 v86, s65, v63
	v_fmac_f32_e32 v93, s65, v64
	v_fmac_f32_e32 v87, s65, v65
	v_fmac_f32_e32 v94, s65, v58
	v_fmac_f32_e32 v88, s65, v59
	v_fmac_f32_e32 v95, s65, v60
	v_fmac_f32_e32 v89, s65, v61
	v_cvt_pk_bf16_f32 v58, v92, v86
	v_cvt_pk_bf16_f32 v59, v93, v87
	v_cvt_pk_bf16_f32 v60, v94, v88
	v_cvt_pk_bf16_f32 v61, v95, v89
	global_store_dwordx4 v[76:77], v[58:61], off
	v_mov_b32_e32 v62, v184
	v_mov_b32_e32 v63, v185
	v_mov_b32_e32 v64, v186
	v_mov_b32_e32 v65, v187
	v_lshlrev_b32_e32 v86, 16, v58
	v_and_b32_e32 v58, 0xffff0000, v58
	v_lshlrev_b32_e32 v87, 16, v59
	v_and_b32_e32 v59, 0xffff0000, v59
	v_lshlrev_b32_e32 v88, 16, v60
	v_and_b32_e32 v60, 0xffff0000, v60
	v_lshlrev_b32_e32 v89, 16, v61
	v_and_b32_e32 v61, 0xffff0000, v61
	v_mul_f32_e32 v58, v58, v58
	v_mul_f32_e32 v59, v59, v59
	v_mul_f32_e32 v60, v60, v60
	v_mul_f32_e32 v61, v61, v61
	v_fmac_f32_e32 v58, v86, v86
	v_fmac_f32_e32 v59, v87, v87
	v_fmac_f32_e32 v60, v88, v88
	v_fmac_f32_e32 v61, v89, v89
	v_add_f32_e32 v58, v58, v59
	v_add_f32_e32 v59, v60, v61
	v_add_f32_e32 v58, v58, v59
	s_nop 0
	v_lshlrev_b32_e32 v59, 16, v62
	v_and_b32_e32 v60, 0xffff0000, v62
	v_and_b32_e32 v62, 0xffff0000, v63
	v_lshlrev_b32_e32 v61, 16, v63
	v_lshlrev_b32_e32 v63, 16, v64
	v_and_b32_e32 v64, 0xffff0000, v64
	v_lshlrev_b32_e32 v86, 16, v65
	v_and_b32_e32 v65, 0xffff0000, v65
	v_fmac_f32_e32 v60, s65, v55
	v_fmac_f32_e32 v62, s65, v57
	v_fmac_f32_e32 v59, s65, v54
	v_fmac_f32_e32 v61, s65, v56
	v_fmac_f32_e32 v63, s65, v50
	v_fmac_f32_e32 v64, s65, v51
	v_fmac_f32_e32 v86, s65, v52
	v_fmac_f32_e32 v65, s65, v53
	v_cvt_pk_bf16_f32 v52, v59, v60
	v_cvt_pk_bf16_f32 v53, v61, v62
	v_cvt_pk_bf16_f32 v54, v63, v64
	v_cvt_pk_bf16_f32 v55, v86, v65
	global_store_dwordx4 v[76:77], v[52:55], off offset:256
	v_and_b32_e32 v51, 0xffff0000, v52
	v_and_b32_e32 v57, 0xffff0000, v53
	v_and_b32_e32 v60, 0xffff0000, v54
	v_and_b32_e32 v62, 0xffff0000, v55
	v_lshlrev_b32_e32 v50, 16, v52
	v_lshlrev_b32_e32 v56, 16, v53
	v_lshlrev_b32_e32 v59, 16, v54
	v_lshlrev_b32_e32 v61, 16, v55
	v_mul_f32_e32 v51, v51, v51
	v_mul_f32_e32 v57, v57, v57
	v_mul_f32_e32 v60, v60, v60
	v_mul_f32_e32 v62, v62, v62
	v_fmac_f32_e32 v51, v50, v50
	v_fmac_f32_e32 v57, v56, v56
	v_fmac_f32_e32 v60, v59, v59
	v_fmac_f32_e32 v62, v61, v61
	v_add_f32_e32 v50, v51, v57
	v_add_f32_e32 v51, v60, v62
	v_add_f32_e32 v50, v50, v51
	v_add_f32_e32 v50, v58, v50
	v_mov_b32_e32 v51, v50
	s_nop 1
	v_permlane16_swap_b32 v51, v50
	s_waitcnt lgkmcnt(0)
	v_add_f32_e32 v50, v50, v51
	v_mov_b32_e32 v51, v50
	s_nop 1
	v_permlane32_swap_b32 v51, v50
	s_and_saveexec_b64 s[8:9], s[6:7]
	s_cbranch_execz .LBB1_783
	s_waitcnt lgkmcnt(0)
	v_add_f32_e32 v52, v50, v51
	s_lshl_b32 s20, s23, 2
	v_lshlrev_b64 v[50:51], 6, v[74:75]
	s_ashr_i32 s21, s20, 31
	v_lshl_add_u64 v[50:51], s[14:15], 0, v[50:51]
	v_lshl_add_u64 v[50:51], s[20:21], 2, v[50:51]
	s_lshl_b32 s74, s40, 2
	v_lshl_add_u64 v[50:51], v[50:51], 0, s[74:75]
	global_store_dword v[50:51], v52, off
; __device__ __forceinline__ unsigned cvt_pk_bf16(float lo, float hi) { unsigned r; asm volatile("v_cvt_pk_bf16_f32 %0, %1, %2" : "=v"(r) : "v"(lo), "v"(hi)); return r; }
; __device__ __forceinline__ float bflo(unsigned w) { return __uint_as_float(w << 16); }
;     __device__ __forceinline__ void operator()(const f32x4 (&acc)[2][2][4][2], const Unit& u, int wr, int wc, int fr, int fq, LAS unsigned char* lds) const {
;     ...
;             for (int m = 0; m < 4; ++m) { const int row = row0 + ai * HALF + m * 16; const size_t off = (size_t)row * D + col0;
;                 float rs = 1.0f; if (MODE == 1) rs = rstd_of4(rss_in, row, fq);
;                 float ss = 0.f;
; #pragma unroll
;                 for (int bj = 0; bj < 2; ++bj) { const size_t o = off + bj * HALF; const u32x4 bw = *(const u32x4*)(base + o);
;                     const float bs[8] = {bflo(bw.x), bfhi(bw.x), bflo(bw.y), bfhi(bw.y), bflo(bw.z), bfhi(bw.z), bflo(bw.w), bfhi(bw.w)};
;                     float hn[8];
;                     if (MODE == 0) {
; #pragma unroll
;                         for (int n = 0; n < 2; ++n)
; #pragma unroll
;                             for (int e = 0; e < 4; ++e) hn[4 * n + e] = bs[4 * n + e] + (acc[ai][bj][m][n][e] + bv[bj][n][e]) * scale;
;                     } else { const u32x4 pw = *(const u32x4*)(pp + o);
;                         const float pv[8] = {bflo(pw.x), bfhi(pw.x), bflo(pw.y), bfhi(pw.y), bflo(pw.z), bfhi(pw.z), bflo(pw.w), bfhi(pw.w)};
; #pragma unroll
;                         for (int n = 0; n < 2; ++n)
; #pragma unroll
;                             for (int e = 0; e < 4; ++e) hn[4 * n + e] = bs[4 * n + e] + fast_sigmoid(acc[ai][bj][m][n][e] * rs) * pv[4 * n + e]; }
;                     u32x4 w; w.x = cvt_pk_bf16(hn[0], hn[1]); w.y = cvt_pk_bf16(hn[2], hn[3]); w.z = cvt_pk_bf16(hn[4], hn[5]); w.w = cvt_pk_bf16(hn[6], hn[7]); *(u32x4*)(hb + o) = w;
;                     const float hr[8] = {bflo(w.x), bfhi(w.x), bflo(w.y), bfhi(w.y), bflo(w.z), bfhi(w.z), bflo(w.w), bfhi(w.w)};
;                     ss += ((hr[0] * hr[0] + hr[1] * hr[1]) + (hr[2] * hr[2] + hr[3] * hr[3])) + ((hr[4] * hr[4] + hr[5] * hr[5]) + (hr[6] * hr[6] + hr[7] * hr[7])); }
;                 ss += __shfl_xor(ss, 16); ss += __shfl_xor(ss, 32);
;                 if (fq == 0) rss_out[(size_t)row * 16 + u.pn * 4 + wc] = ss; }
.LBB1_783:
	s_or_b64 exec, exec, s[8:9]
	v_add_u32_e32 v50, 0x90, v158
	s_waitcnt lgkmcnt(0)
	v_ashrrev_i32_e32 v51, 31, v50
	v_lshlrev_b64 v[52:53], 10, v[50:51]
	v_lshl_add_u64 v[52:53], v[52:53], 0, v[156:157]
	v_lshlrev_b64 v[56:57], 1, v[52:53]
	v_lshl_add_u64 v[58:59], s[18:19], 0, v[56:57]
	v_mov_b32_e32 v52, v188
	v_mov_b32_e32 v53, v189
	v_mov_b32_e32 v54, v190
	v_mov_b32_e32 v55, v191
	v_add_f32_e32 v46, v46, v82
	v_add_f32_e32 v47, v47, v83
	v_add_f32_e32 v48, v48, v84
	v_add_f32_e32 v49, v49, v85
	v_add_f32_e32 v42, v42, v78
	v_add_f32_e32 v43, v43, v79
	v_add_f32_e32 v44, v44, v80
	v_add_f32_e32 v45, v45, v81
	v_lshl_add_u64 v[56:57], s[16:17], 0, v[56:57]
	v_add_f32_e32 v39, v39, v71
	v_add_f32_e32 v41, v41, v73
	v_add_f32_e32 v38, v38, v70
	v_add_f32_e32 v40, v40, v72
	v_add_f32_e32 v34, v34, v66
	v_add_f32_e32 v35, v35, v67
	v_add_f32_e32 v36, v36, v68
	v_add_f32_e32 v37, v37, v69
	s_nop 0
	v_lshlrev_b32_e32 v60, 16, v52
	v_and_b32_e32 v52, 0xffff0000, v52
	v_lshlrev_b32_e32 v61, 16, v53
	v_and_b32_e32 v53, 0xffff0000, v53
	v_lshlrev_b32_e32 v62, 16, v54
	v_and_b32_e32 v54, 0xffff0000, v54
	v_lshlrev_b32_e32 v63, 16, v55
	v_and_b32_e32 v55, 0xffff0000, v55
	v_fmac_f32_e32 v60, s65, v46
	v_fmac_f32_e32 v52, s65, v47
	v_fmac_f32_e32 v61, s65, v48
	v_fmac_f32_e32 v53, s65, v49
	v_fmac_f32_e32 v62, s65, v42
	v_fmac_f32_e32 v54, s65, v43
	v_fmac_f32_e32 v63, s65, v44
	v_fmac_f32_e32 v55, s65, v45
	v_cvt_pk_bf16_f32 v42, v60, v52
	v_cvt_pk_bf16_f32 v43, v61, v53
	v_cvt_pk_bf16_f32 v44, v62, v54
	v_cvt_pk_bf16_f32 v45, v63, v55
	global_store_dwordx4 v[56:57], v[42:45], off
	v_mov_b32_e32 v46, v200
	v_mov_b32_e32 v47, v201
	v_mov_b32_e32 v48, v202
	v_mov_b32_e32 v49, v203
	v_lshlrev_b32_e32 v52, 16, v42
	v_and_b32_e32 v42, 0xffff0000, v42
	v_lshlrev_b32_e32 v53, 16, v43
	v_and_b32_e32 v43, 0xffff0000, v43
	v_lshlrev_b32_e32 v54, 16, v44
	v_and_b32_e32 v44, 0xffff0000, v44
	v_lshlrev_b32_e32 v55, 16, v45
	v_and_b32_e32 v45, 0xffff0000, v45
	v_mul_f32_e32 v42, v42, v42
	v_mul_f32_e32 v43, v43, v43
	v_mul_f32_e32 v44, v44, v44
	v_mul_f32_e32 v45, v45, v45
	v_fmac_f32_e32 v42, v52, v52
	v_fmac_f32_e32 v43, v53, v53
	v_fmac_f32_e32 v44, v54, v54
	v_fmac_f32_e32 v45, v55, v55
	v_add_f32_e32 v42, v42, v43
	v_add_f32_e32 v43, v44, v45
	v_add_f32_e32 v42, v42, v43
	s_nop 0
	v_lshlrev_b32_e32 v43, 16, v46
	v_and_b32_e32 v44, 0xffff0000, v46
	v_and_b32_e32 v46, 0xffff0000, v47
	v_lshlrev_b32_e32 v45, 16, v47
	v_lshlrev_b32_e32 v47, 16, v48
	v_and_b32_e32 v48, 0xffff0000, v48
	v_lshlrev_b32_e32 v52, 16, v49
	v_and_b32_e32 v49, 0xffff0000, v49
	v_fmac_f32_e32 v44, s65, v39
	v_fmac_f32_e32 v46, s65, v41
	v_fmac_f32_e32 v43, s65, v38
	v_fmac_f32_e32 v45, s65, v40
	v_fmac_f32_e32 v47, s65, v34
	v_fmac_f32_e32 v48, s65, v35
	v_fmac_f32_e32 v52, s65, v36
	v_fmac_f32_e32 v49, s65, v37
	v_cvt_pk_bf16_f32 v36, v43, v44
	v_cvt_pk_bf16_f32 v37, v45, v46
	v_cvt_pk_bf16_f32 v38, v47, v48
	v_cvt_pk_bf16_f32 v39, v52, v49
	global_store_dwordx4 v[56:57], v[36:39], off offset:256
	v_and_b32_e32 v35, 0xffff0000, v36
	v_and_b32_e32 v41, 0xffff0000, v37
	v_and_b32_e32 v44, 0xffff0000, v38
	v_and_b32_e32 v46, 0xffff0000, v39
	v_lshlrev_b32_e32 v34, 16, v36
	v_lshlrev_b32_e32 v40, 16, v37
	v_lshlrev_b32_e32 v43, 16, v38
	v_lshlrev_b32_e32 v45, 16, v39
	v_mul_f32_e32 v35, v35, v35
	v_mul_f32_e32 v41, v41, v41
	v_mul_f32_e32 v44, v44, v44
	v_mul_f32_e32 v46, v46, v46
	v_fmac_f32_e32 v35, v34, v34
	v_fmac_f32_e32 v41, v40, v40
	v_fmac_f32_e32 v44, v43, v43
	v_fmac_f32_e32 v46, v45, v45
	v_add_f32_e32 v34, v35, v41
	v_add_f32_e32 v35, v44, v46
	v_add_f32_e32 v34, v34, v35
	v_add_f32_e32 v34, v42, v34
	v_mov_b32_e32 v35, v34
	s_nop 1
	v_permlane16_swap_b32 v35, v34
	s_waitcnt lgkmcnt(0)
	v_add_f32_e32 v34, v34, v35
	v_mov_b32_e32 v35, v34
	s_nop 1
	v_permlane32_swap_b32 v35, v34
	s_and_saveexec_b64 s[8:9], s[6:7]
	s_cbranch_execz .LBB1_785
	s_waitcnt lgkmcnt(0)
	v_add_f32_e32 v36, v34, v35
	s_lshl_b32 s20, s23, 2
	v_lshlrev_b64 v[34:35], 6, v[50:51]
	s_ashr_i32 s21, s20, 31
	v_lshl_add_u64 v[34:35], s[14:15], 0, v[34:35]
	v_lshl_add_u64 v[34:35], s[20:21], 2, v[34:35]
	s_lshl_b32 s74, s40, 2
	v_lshl_add_u64 v[34:35], v[34:35], 0, s[74:75]
	global_store_dword v[34:35], v36, off
.LBB1_785:
	s_or_b64 exec, exec, s[8:9]
	v_add_u32_e32 v34, 0xa0, v158
	s_waitcnt lgkmcnt(0)
; __device__ __forceinline__ unsigned cvt_pk_bf16(float lo, float hi) { unsigned r; asm volatile("v_cvt_pk_bf16_f32 %0, %1, %2" : "=v"(r) : "v"(lo), "v"(hi)); return r; }
; __device__ __forceinline__ float bflo(unsigned w) { return __uint_as_float(w << 16); }
;     __device__ __forceinline__ void operator()(const f32x4 (&acc)[2][2][4][2], const Unit& u, int wr, int wc, int fr, int fq, LAS unsigned char* lds) const {
;     ...
;             for (int m = 0; m < 4; ++m) { const int row = row0 + ai * HALF + m * 16; const size_t off = (size_t)row * D + col0;
;                 float rs = 1.0f; if (MODE == 1) rs = rstd_of4(rss_in, row, fq);
;                 float ss = 0.f;
; #pragma unroll
;                 for (int bj = 0; bj < 2; ++bj) { const size_t o = off + bj * HALF; const u32x4 bw = *(const u32x4*)(base + o);
;                     const float bs[8] = {bflo(bw.x), bfhi(bw.x), bflo(bw.y), bfhi(bw.y), bflo(bw.z), bfhi(bw.z), bflo(bw.w), bfhi(bw.w)};
;                     float hn[8];
;                     if (MODE == 0) {
; #pragma unroll
;                         for (int n = 0; n < 2; ++n)
; #pragma unroll
;                             for (int e = 0; e < 4; ++e) hn[4 * n + e] = bs[4 * n + e] + (acc[ai][bj][m][n][e] + bv[bj][n][e]) * scale;
;                     } else { const u32x4 pw = *(const u32x4*)(pp + o);
;                         const float pv[8] = {bflo(pw.x), bfhi(pw.x), bflo(pw.y), bfhi(pw.y), bflo(pw.z), bfhi(pw.z), bflo(pw.w), bfhi(pw.w)};
; #pragma unroll
;                         for (int n = 0; n < 2; ++n)
; #pragma unroll
;                             for (int e = 0; e < 4; ++e) hn[4 * n + e] = bs[4 * n + e] + fast_sigmoid(acc[ai][bj][m][n][e] * rs) * pv[4 * n + e]; }
;                     u32x4 w; w.x = cvt_pk_bf16(hn[0], hn[1]); w.y = cvt_pk_bf16(hn[2], hn[3]); w.z = cvt_pk_bf16(hn[4], hn[5]); w.w = cvt_pk_bf16(hn[6], hn[7]); *(u32x4*)(hb + o) = w;
;                     const float hr[8] = {bflo(w.x), bfhi(w.x), bflo(w.y), bfhi(w.y), bflo(w.z), bfhi(w.z), bflo(w.w), bfhi(w.w)};
;                     ss += ((hr[0] * hr[0] + hr[1] * hr[1]) + (hr[2] * hr[2] + hr[3] * hr[3])) + ((hr[4] * hr[4] + hr[5] * hr[5]) + (hr[6] * hr[6] + hr[7] * hr[7])); }
;                 ss += __shfl_xor(ss, 16); ss += __shfl_xor(ss, 32);
;                 if (fq == 0) rss_out[(size_t)row * 16 + u.pn * 4 + wc] = ss; }
	v_ashrrev_i32_e32 v35, 31, v34
	v_lshlrev_b64 v[36:37], 10, v[34:35]
	v_lshl_add_u64 v[36:37], v[36:37], 0, v[156:157]
	v_lshlrev_b64 v[40:41], 1, v[36:37]
	v_lshl_add_u64 v[42:43], s[18:19], 0, v[40:41]
	v_mov_b32_e32 v36, v204
	v_mov_b32_e32 v37, v205
	v_mov_b32_e32 v38, v206
	v_mov_b32_e32 v39, v207
	v_add_f32_e32 v30, v30, v82
	v_add_f32_e32 v31, v31, v83
	v_add_f32_e32 v32, v32, v84
	v_add_f32_e32 v33, v33, v85
	v_add_f32_e32 v26, v26, v78
	v_add_f32_e32 v27, v27, v79
	v_add_f32_e32 v28, v28, v80
	v_add_f32_e32 v29, v29, v81
	v_lshl_add_u64 v[40:41], s[16:17], 0, v[40:41]
	v_add_f32_e32 v23, v23, v71
	v_add_f32_e32 v25, v25, v73
	v_add_f32_e32 v22, v22, v70
	v_add_f32_e32 v24, v24, v72
	v_add_f32_e32 v18, v18, v66
	v_add_f32_e32 v19, v19, v67
	v_add_f32_e32 v20, v20, v68
	v_add_f32_e32 v21, v21, v69
	s_nop 0
	v_lshlrev_b32_e32 v44, 16, v36
	v_and_b32_e32 v36, 0xffff0000, v36
	v_lshlrev_b32_e32 v45, 16, v37
	v_and_b32_e32 v37, 0xffff0000, v37
	v_lshlrev_b32_e32 v46, 16, v38
	v_and_b32_e32 v38, 0xffff0000, v38
	v_lshlrev_b32_e32 v47, 16, v39
	v_and_b32_e32 v39, 0xffff0000, v39
	v_fmac_f32_e32 v44, s65, v30
	v_fmac_f32_e32 v36, s65, v31
	v_fmac_f32_e32 v45, s65, v32
	v_fmac_f32_e32 v37, s65, v33
	v_fmac_f32_e32 v46, s65, v26
	v_fmac_f32_e32 v38, s65, v27
	v_fmac_f32_e32 v47, s65, v28
	v_fmac_f32_e32 v39, s65, v29
	v_cvt_pk_bf16_f32 v26, v44, v36
	v_cvt_pk_bf16_f32 v27, v45, v37
	v_cvt_pk_bf16_f32 v28, v46, v38
	v_cvt_pk_bf16_f32 v29, v47, v39
	global_store_dwordx4 v[40:41], v[26:29], off
	v_mov_b32_e32 v30, v208
	v_mov_b32_e32 v31, v209
	v_mov_b32_e32 v32, v210
	v_mov_b32_e32 v33, v211
	v_lshlrev_b32_e32 v36, 16, v26
	v_and_b32_e32 v26, 0xffff0000, v26
	v_lshlrev_b32_e32 v37, 16, v27
	v_and_b32_e32 v27, 0xffff0000, v27
	v_lshlrev_b32_e32 v38, 16, v28
	v_and_b32_e32 v28, 0xffff0000, v28
	v_lshlrev_b32_e32 v39, 16, v29
	v_and_b32_e32 v29, 0xffff0000, v29
	v_mul_f32_e32 v26, v26, v26
	v_mul_f32_e32 v27, v27, v27
	v_mul_f32_e32 v28, v28, v28
	v_mul_f32_e32 v29, v29, v29
	v_fmac_f32_e32 v26, v36, v36
	v_fmac_f32_e32 v27, v37, v37
	v_fmac_f32_e32 v28, v38, v38
	v_fmac_f32_e32 v29, v39, v39
	v_add_f32_e32 v26, v26, v27
	v_add_f32_e32 v27, v28, v29
	v_add_f32_e32 v26, v26, v27
	s_nop 0
	v_lshlrev_b32_e32 v27, 16, v30
	v_and_b32_e32 v28, 0xffff0000, v30
	v_and_b32_e32 v30, 0xffff0000, v31
	v_lshlrev_b32_e32 v29, 16, v31
	v_lshlrev_b32_e32 v31, 16, v32
	v_and_b32_e32 v32, 0xffff0000, v32
	v_lshlrev_b32_e32 v36, 16, v33
	v_and_b32_e32 v33, 0xffff0000, v33
	v_fmac_f32_e32 v28, s65, v23
	v_fmac_f32_e32 v30, s65, v25
	v_fmac_f32_e32 v27, s65, v22
	v_fmac_f32_e32 v29, s65, v24
	v_fmac_f32_e32 v31, s65, v18
	v_fmac_f32_e32 v32, s65, v19
	v_fmac_f32_e32 v36, s65, v20
	v_fmac_f32_e32 v33, s65, v21
	v_cvt_pk_bf16_f32 v20, v27, v28
	v_cvt_pk_bf16_f32 v21, v29, v30
	v_cvt_pk_bf16_f32 v22, v31, v32
	v_cvt_pk_bf16_f32 v23, v36, v33
	global_store_dwordx4 v[40:41], v[20:23], off offset:256
	v_and_b32_e32 v19, 0xffff0000, v20
	v_and_b32_e32 v25, 0xffff0000, v21
	v_and_b32_e32 v28, 0xffff0000, v22
	v_and_b32_e32 v30, 0xffff0000, v23
	v_lshlrev_b32_e32 v18, 16, v20
	v_lshlrev_b32_e32 v24, 16, v21
	v_lshlrev_b32_e32 v27, 16, v22
	v_lshlrev_b32_e32 v29, 16, v23
	v_mul_f32_e32 v19, v19, v19
	v_mul_f32_e32 v25, v25, v25
	v_mul_f32_e32 v28, v28, v28
	v_mul_f32_e32 v30, v30, v30
	v_fmac_f32_e32 v19, v18, v18
	v_fmac_f32_e32 v25, v24, v24
	v_fmac_f32_e32 v28, v27, v27
	v_fmac_f32_e32 v30, v29, v29
	v_add_f32_e32 v18, v19, v25
	v_add_f32_e32 v19, v28, v30
	v_add_f32_e32 v18, v18, v19
	v_add_f32_e32 v18, v26, v18
	v_mov_b32_e32 v19, v18
	s_nop 1
	v_permlane16_swap_b32 v19, v18
	s_waitcnt lgkmcnt(0)
	v_add_f32_e32 v18, v18, v19
	v_mov_b32_e32 v19, v18
	s_nop 1
	v_permlane32_swap_b32 v19, v18
	s_and_saveexec_b64 s[8:9], s[6:7]
	s_cbranch_execz .LBB1_787
	s_waitcnt lgkmcnt(0)
	v_add_f32_e32 v20, v18, v19
	s_lshl_b32 s20, s23, 2
	v_lshlrev_b64 v[18:19], 6, v[34:35]
	s_ashr_i32 s21, s20, 31
	v_lshl_add_u64 v[18:19], s[14:15], 0, v[18:19]
	v_lshl_add_u64 v[18:19], s[20:21], 2, v[18:19]
	s_lshl_b32 s74, s40, 2
	v_lshl_add_u64 v[18:19], v[18:19], 0, s[74:75]
	global_store_dword v[18:19], v20, off
; __device__ __forceinline__ unsigned cvt_pk_bf16(float lo, float hi) { unsigned r; asm volatile("v_cvt_pk_bf16_f32 %0, %1, %2" : "=v"(r) : "v"(lo), "v"(hi)); return r; }
; __device__ __forceinline__ float bflo(unsigned w) { return __uint_as_float(w << 16); }
;     __device__ __forceinline__ void operator()(const f32x4 (&acc)[2][2][4][2], const Unit& u, int wr, int wc, int fr, int fq, LAS unsigned char* lds) const {
;     ...
;             for (int m = 0; m < 4; ++m) { const int row = row0 + ai * HALF + m * 16; const size_t off = (size_t)row * D + col0;
;                 float rs = 1.0f; if (MODE == 1) rs = rstd_of4(rss_in, row, fq);
;                 float ss = 0.f;
; #pragma unroll
;                 for (int bj = 0; bj < 2; ++bj) { const size_t o = off + bj * HALF; const u32x4 bw = *(const u32x4*)(base + o);
;                     const float bs[8] = {bflo(bw.x), bfhi(bw.x), bflo(bw.y), bfhi(bw.y), bflo(bw.z), bfhi(bw.z), bflo(bw.w), bfhi(bw.w)};
;                     float hn[8];
;                     if (MODE == 0) {
; #pragma unroll
;                         for (int n = 0; n < 2; ++n)
; #pragma unroll
;                             for (int e = 0; e < 4; ++e) hn[4 * n + e] = bs[4 * n + e] + (acc[ai][bj][m][n][e] + bv[bj][n][e]) * scale;
;                     } else { const u32x4 pw = *(const u32x4*)(pp + o);
;                         const float pv[8] = {bflo(pw.x), bfhi(pw.x), bflo(pw.y), bfhi(pw.y), bflo(pw.z), bfhi(pw.z), bflo(pw.w), bfhi(pw.w)};
; #pragma unroll
;                         for (int n = 0; n < 2; ++n)
; #pragma unroll
;                             for (int e = 0; e < 4; ++e) hn[4 * n + e] = bs[4 * n + e] + fast_sigmoid(acc[ai][bj][m][n][e] * rs) * pv[4 * n + e]; }
;                     u32x4 w; w.x = cvt_pk_bf16(hn[0], hn[1]); w.y = cvt_pk_bf16(hn[2], hn[3]); w.z = cvt_pk_bf16(hn[4], hn[5]); w.w = cvt_pk_bf16(hn[6], hn[7]); *(u32x4*)(hb + o) = w;
;                     const float hr[8] = {bflo(w.x), bfhi(w.x), bflo(w.y), bfhi(w.y), bflo(w.z), bfhi(w.z), bflo(w.w), bfhi(w.w)};
;                     ss += ((hr[0] * hr[0] + hr[1] * hr[1]) + (hr[2] * hr[2] + hr[3] * hr[3])) + ((hr[4] * hr[4] + hr[5] * hr[5]) + (hr[6] * hr[6] + hr[7] * hr[7])); }
;                 ss += __shfl_xor(ss, 16); ss += __shfl_xor(ss, 32);
;                 if (fq == 0) rss_out[(size_t)row * 16 + u.pn * 4 + wc] = ss; }
.LBB1_787:
	s_or_b64 exec, exec, s[8:9]
	v_add_u32_e32 v18, 0xb0, v158
	s_waitcnt lgkmcnt(0)
	v_ashrrev_i32_e32 v19, 31, v18
	v_lshlrev_b64 v[20:21], 10, v[18:19]
	v_lshl_add_u64 v[20:21], v[20:21], 0, v[156:157]
	v_lshlrev_b64 v[24:25], 1, v[20:21]
	v_lshl_add_u64 v[26:27], s[18:19], 0, v[24:25]
	v_mov_b32_e32 v20, v212
	v_mov_b32_e32 v21, v213
	v_mov_b32_e32 v22, v214
	v_mov_b32_e32 v23, v215
	v_add_f32_e32 v14, v14, v82
	v_add_f32_e32 v15, v15, v83
	v_add_f32_e32 v16, v16, v84
	v_add_f32_e32 v17, v17, v85
	v_add_f32_e32 v10, v10, v78
	v_add_f32_e32 v11, v11, v79
	v_add_f32_e32 v12, v12, v80
	v_add_f32_e32 v13, v13, v81
	v_lshl_add_u64 v[24:25], s[16:17], 0, v[24:25]
	v_add_f32_e32 v7, v7, v71
	v_add_f32_e32 v9, v9, v73
	v_add_f32_e32 v6, v6, v70
	v_add_f32_e32 v8, v8, v72
	v_add_f32_e32 v0, v0, v66
	v_add_f32_e32 v1, v1, v67
	v_add_f32_e32 v2, v2, v68
	v_add_f32_e32 v3, v3, v69
	s_nop 0
	v_lshlrev_b32_e32 v28, 16, v20
	v_and_b32_e32 v20, 0xffff0000, v20
	v_lshlrev_b32_e32 v29, 16, v21
	v_and_b32_e32 v21, 0xffff0000, v21
	v_lshlrev_b32_e32 v30, 16, v22
	v_and_b32_e32 v22, 0xffff0000, v22
	v_lshlrev_b32_e32 v31, 16, v23
	v_and_b32_e32 v23, 0xffff0000, v23
	v_fmac_f32_e32 v28, s65, v14
	v_fmac_f32_e32 v20, s65, v15
	v_fmac_f32_e32 v29, s65, v16
	v_fmac_f32_e32 v21, s65, v17
	v_fmac_f32_e32 v30, s65, v10
	v_fmac_f32_e32 v22, s65, v11
	v_fmac_f32_e32 v31, s65, v12
	v_fmac_f32_e32 v23, s65, v13
	v_cvt_pk_bf16_f32 v10, v28, v20
	v_cvt_pk_bf16_f32 v11, v29, v21
	v_cvt_pk_bf16_f32 v12, v30, v22
	v_cvt_pk_bf16_f32 v13, v31, v23
	global_store_dwordx4 v[24:25], v[10:13], off
	v_mov_b32_e32 v14, v216
	v_mov_b32_e32 v15, v217
	v_mov_b32_e32 v16, v218
	v_mov_b32_e32 v17, v219
	v_lshlrev_b32_e32 v20, 16, v10
	v_and_b32_e32 v10, 0xffff0000, v10
	v_lshlrev_b32_e32 v21, 16, v11
	v_and_b32_e32 v11, 0xffff0000, v11
	v_lshlrev_b32_e32 v22, 16, v12
	v_and_b32_e32 v12, 0xffff0000, v12
	v_lshlrev_b32_e32 v23, 16, v13
	v_and_b32_e32 v13, 0xffff0000, v13
	v_mul_f32_e32 v10, v10, v10
	v_mul_f32_e32 v11, v11, v11
	v_mul_f32_e32 v12, v12, v12
	v_mul_f32_e32 v13, v13, v13
	v_fmac_f32_e32 v10, v20, v20
	v_fmac_f32_e32 v11, v21, v21
	v_fmac_f32_e32 v12, v22, v22
	v_fmac_f32_e32 v13, v23, v23
	v_add_f32_e32 v10, v10, v11
	v_add_f32_e32 v11, v12, v13
	v_add_f32_e32 v10, v10, v11
	s_nop 0
	v_lshlrev_b32_e32 v11, 16, v14
	v_and_b32_e32 v12, 0xffff0000, v14
	v_and_b32_e32 v14, 0xffff0000, v15
	v_lshlrev_b32_e32 v13, 16, v15
	v_lshlrev_b32_e32 v15, 16, v16
	v_and_b32_e32 v16, 0xffff0000, v16
	v_lshlrev_b32_e32 v20, 16, v17
	v_and_b32_e32 v17, 0xffff0000, v17
	v_fmac_f32_e32 v12, s65, v7
	v_fmac_f32_e32 v14, s65, v9
	v_fmac_f32_e32 v11, s65, v6
	v_fmac_f32_e32 v13, s65, v8
	v_fmac_f32_e32 v15, s65, v0
	v_fmac_f32_e32 v16, s65, v1
	v_fmac_f32_e32 v20, s65, v2
	v_fmac_f32_e32 v17, s65, v3
	v_cvt_pk_bf16_f32 v6, v11, v12
	v_cvt_pk_bf16_f32 v7, v13, v14
	v_cvt_pk_bf16_f32 v8, v15, v16
	v_cvt_pk_bf16_f32 v9, v20, v17
	global_store_dwordx4 v[24:25], v[6:9], off offset:256
	v_and_b32_e32 v1, 0xffff0000, v6
	v_and_b32_e32 v3, 0xffff0000, v7
	v_and_b32_e32 v12, 0xffff0000, v8
	v_and_b32_e32 v14, 0xffff0000, v9
	v_lshlrev_b32_e32 v0, 16, v6
	v_lshlrev_b32_e32 v2, 16, v7
	v_lshlrev_b32_e32 v11, 16, v8
	v_lshlrev_b32_e32 v13, 16, v9
	v_mul_f32_e32 v1, v1, v1
	v_mul_f32_e32 v3, v3, v3
	v_mul_f32_e32 v12, v12, v12
	v_mul_f32_e32 v14, v14, v14
	v_fmac_f32_e32 v1, v0, v0
	v_fmac_f32_e32 v3, v2, v2
	v_fmac_f32_e32 v12, v11, v11
	v_fmac_f32_e32 v14, v13, v13
	v_add_f32_e32 v0, v1, v3
	v_add_f32_e32 v1, v12, v14
	v_add_f32_e32 v0, v0, v1
	v_add_f32_e32 v0, v10, v0
	v_mov_b32_e32 v1, v0
	s_nop 1
	v_permlane16_swap_b32 v1, v0
	s_waitcnt lgkmcnt(0)
	v_add_f32_e32 v0, v0, v1
	v_mov_b32_e32 v1, v0
	s_nop 1
	v_permlane32_swap_b32 v1, v0
	s_and_saveexec_b64 s[8:9], s[6:7]
	s_cbranch_execz .LBB1_756
	s_waitcnt lgkmcnt(0)
	v_add_f32_e32 v2, v0, v1
	s_lshl_b32 s16, s23, 2
	v_lshlrev_b64 v[0:1], 6, v[18:19]
	s_ashr_i32 s17, s16, 31
	v_lshl_add_u64 v[0:1], s[14:15], 0, v[0:1]
	v_lshl_add_u64 v[0:1], s[16:17], 2, v[0:1]
	s_lshl_b32 s74, s40, 2
	v_lshl_add_u64 v[0:1], v[0:1], 0, s[74:75]
	global_store_dword v[0:1], v2, off
	s_branch .LBB1_756

; template <class Epi, int KK, int LDA, int LDB, int NN, bool AGRP>
; __device__ __forceinline__ void gemm_phase(LAS unsigned char* lds, const bf16_t* gA, const bf16_t* gBt, int G_, int bid_, int tid) {
;     ...
;         const char* nA = has_next ? (const char*)g.A + (size_t)nxt.pm * tstepA + PG8_ACOL(nxt.pn) : cA; const char* nB = has_next ? (const char*)g.Bt + (size_t)nxt.pn * tstepB : cB;
; #pragma nounroll
;         for (int t = 0; t < nt; t += 2) {
;             const bool last = (t == nt - 2);
;             const char* a1 = cA + (size_t)(t + 1) * kstep;
;             const char* a2 = last ? nA : cA + (size_t)(t + 2) * kstep; const char* b2 = last ? nB : cB + (size_t)(t + 2) * kstep;
;     ...
; #pragma unroll
;         for (int a = 0; a < 2; ++a)
; #pragma unroll
;             for (int b = 0; b < 2; ++b)
; #pragma unroll
;                 for (int m = 0; m < 4; ++m)
; #pragma unroll
;                     for (int n = 0; n < 2; ++n) acc[a][b][m][n] = (f32x4){zr, zr, zr, zr};
;         cur = nxt; cA = nA; cB = nB; ++ui;
.LBB1_803:
	s_ashr_i32 s11, s10, 31
	s_lshl_b64 s[16:17], s[10:11], 19
	s_add_u32 s16, s31, s16
	s_addc_u32 s17, s34, s17
	s_and_b64 s[18:19], s[22:23], exec
	s_cselect_b32 s11, s17, s21
	s_cselect_b32 s24, s16, s20
	s_ashr_i32 s13, s12, 31
	s_lshl_b64 s[18:19], s[12:13], 19
	s_add_u32 s18, s35, s18
	s_addc_u32 s19, s36, s19
	s_and_b64 s[22:23], s[22:23], exec
	s_cselect_b32 s13, s19, s9
	s_cselect_b32 s25, s18, s8
	s_add_u32 s28, s8, 0x100
	s_addc_u32 s29, s9, 0
	s_add_u32 s8, s20, 0x40080
	s_addc_u32 s9, s21, 0
	s_mov_b32 s65, -2
	v_mov_b32_e32 v0, v160
	s_waitcnt lgkmcnt(0)
	v_mov_b32_e32 v1, v160
	v_mov_b32_e32 v2, v160
	v_mov_b32_e32 v3, v160
	v_mov_b32_e32 v6, v160
	v_mov_b32_e32 v7, v160
	v_mov_b32_e32 v8, v160
	v_mov_b32_e32 v9, v160
	v_mov_b32_e32 v18, v160
	v_mov_b32_e32 v19, v160
	v_mov_b32_e32 v20, v160
	v_mov_b32_e32 v21, v160
	v_mov_b32_e32 v22, v160
	v_mov_b32_e32 v23, v160
	v_mov_b32_e32 v24, v160
	v_mov_b32_e32 v25, v160
	v_mov_b32_e32 v34, v160
	v_mov_b32_e32 v35, v160
	v_mov_b32_e32 v36, v160
	v_mov_b32_e32 v37, v160
	v_mov_b32_e32 v38, v160
	v_mov_b32_e32 v39, v160
	v_mov_b32_e32 v40, v160
	v_mov_b32_e32 v41, v160
	v_mov_b32_e32 v50, v160
	v_mov_b32_e32 v51, v160
	v_mov_b32_e32 v52, v160
	v_mov_b32_e32 v53, v160
	v_mov_b32_e32 v54, v160
	v_mov_b32_e32 v55, v160
	v_mov_b32_e32 v56, v160
	v_mov_b32_e32 v57, v160
	v_mov_b32_e32 v10, v160
	v_mov_b32_e32 v11, v160
	v_mov_b32_e32 v12, v160
	v_mov_b32_e32 v13, v160
	v_mov_b32_e32 v14, v160
	v_mov_b32_e32 v15, v160
	v_mov_b32_e32 v16, v160
	v_mov_b32_e32 v17, v160
	v_mov_b32_e32 v26, v160
	v_mov_b32_e32 v27, v160
	v_mov_b32_e32 v28, v160
	v_mov_b32_e32 v29, v160
	v_mov_b32_e32 v30, v160
	v_mov_b32_e32 v31, v160
	v_mov_b32_e32 v32, v160
	v_mov_b32_e32 v33, v160
	v_mov_b32_e32 v42, v160
	v_mov_b32_e32 v43, v160
	v_mov_b32_e32 v44, v160
	v_mov_b32_e32 v45, v160
	v_mov_b32_e32 v46, v160
	v_mov_b32_e32 v47, v160
	v_mov_b32_e32 v48, v160
	v_mov_b32_e32 v49, v160
	v_mov_b32_e32 v58, v160
	v_mov_b32_e32 v59, v160
	v_mov_b32_e32 v60, v160
	v_mov_b32_e32 v61, v160
	v_mov_b32_e32 v62, v160
	v_mov_b32_e32 v63, v160
	v_mov_b32_e32 v64, v160
	v_mov_b32_e32 v65, v160
	v_mov_b32_e32 v74, v160
	v_mov_b32_e32 v75, v160
	v_mov_b32_e32 v76, v160
	v_mov_b32_e32 v77, v160
	s_nop 0
	v_mov_b32_e32 v82, v160
	v_mov_b32_e32 v83, v160
	v_mov_b32_e32 v84, v160
	v_mov_b32_e32 v85, v160
	v_mov_b32_e32 v98, v160
	v_mov_b32_e32 v99, v160
	v_mov_b32_e32 v100, v160
	v_mov_b32_e32 v101, v160
	v_mov_b32_e32 v102, v160
	v_mov_b32_e32 v103, v160
	v_mov_b32_e32 v104, v160
	v_mov_b32_e32 v105, v160
	v_mov_b32_e32 v114, v160
	v_mov_b32_e32 v115, v160
	v_mov_b32_e32 v116, v160
	v_mov_b32_e32 v117, v160
	v_mov_b32_e32 v118, v160
	v_mov_b32_e32 v119, v160
	v_mov_b32_e32 v120, v160
	v_mov_b32_e32 v121, v160
	v_mov_b32_e32 v130, v160
	v_mov_b32_e32 v131, v160
	v_mov_b32_e32 v132, v160
	v_mov_b32_e32 v133, v160
	v_mov_b32_e32 v134, v160
	v_mov_b32_e32 v135, v160
	v_mov_b32_e32 v136, v160
	v_mov_b32_e32 v137, v160
	v_mov_b32_e32 v90, v160
	v_mov_b32_e32 v91, v160
	v_mov_b32_e32 v92, v160
	v_mov_b32_e32 v93, v160
	v_mov_b32_e32 v94, v160
	v_mov_b32_e32 v95, v160
	v_mov_b32_e32 v96, v160
	v_mov_b32_e32 v97, v160
	v_mov_b32_e32 v106, v160
	v_mov_b32_e32 v107, v160
	v_mov_b32_e32 v108, v160
	v_mov_b32_e32 v109, v160
	v_mov_b32_e32 v110, v160
	v_mov_b32_e32 v111, v160
	v_mov_b32_e32 v112, v160
	v_mov_b32_e32 v113, v160
	v_mov_b32_e32 v122, v160
	v_mov_b32_e32 v123, v160
	v_mov_b32_e32 v124, v160
	v_mov_b32_e32 v125, v160
	v_mov_b32_e32 v126, v160
	v_mov_b32_e32 v127, v160
	v_mov_b32_e32 v128, v160
	v_mov_b32_e32 v129, v160
	v_mov_b32_e32 v138, v160
	v_mov_b32_e32 v139, v160
	v_mov_b32_e32 v140, v160
	v_mov_b32_e32 v141, v160
	v_mov_b32_e32 v142, v160
	v_mov_b32_e32 v143, v160
	v_mov_b32_e32 v144, v160
	v_mov_b32_e32 v145, v160

; __device__ __forceinline__ unsigned cvt_pk_bf16(float lo, float hi) { unsigned r; asm volatile("v_cvt_pk_bf16_f32 %0, %1, %2" : "=v"(r) : "v"(lo), "v"(hi)); return r; }
; __device__ __forceinline__ float bflo(unsigned w) { return __uint_as_float(w << 16); }
;     __device__ __forceinline__ void operator()(const f32x4 (&acc)[2][2][4][2], const Unit& u, int wr, int wc, int fr, int fq, LAS unsigned char* lds) const {
;     ...
;             for (int m = 0; m < 4; ++m) { const int row = row0 + ai * HALF + m * 16; const size_t off = (size_t)row * D + col0;
;                 float rs = 1.0f; if (MODE == 1) rs = rstd_of4(rss_in, row, fq);
;                 float ss = 0.f;
; #pragma unroll
;                 for (int bj = 0; bj < 2; ++bj) { const size_t o = off + bj * HALF; const u32x4 bw = *(const u32x4*)(base + o);
;                     const float bs[8] = {bflo(bw.x), bfhi(bw.x), bflo(bw.y), bfhi(bw.y), bflo(bw.z), bfhi(bw.z), bflo(bw.w), bfhi(bw.w)};
;                     float hn[8];
;                     if (MODE == 0) {
; #pragma unroll
;                         for (int n = 0; n < 2; ++n)
; #pragma unroll
;                             for (int e = 0; e < 4; ++e) hn[4 * n + e] = bs[4 * n + e] + (acc[ai][bj][m][n][e] + bv[bj][n][e]) * scale;
;                     } else { const u32x4 pw = *(const u32x4*)(pp + o);
;                         const float pv[8] = {bflo(pw.x), bfhi(pw.x), bflo(pw.y), bfhi(pw.y), bflo(pw.z), bfhi(pw.z), bflo(pw.w), bfhi(pw.w)};
; #pragma unroll
;                         for (int n = 0; n < 2; ++n)
; #pragma unroll
;                             for (int e = 0; e < 4; ++e) hn[4 * n + e] = bs[4 * n + e] + fast_sigmoid(acc[ai][bj][m][n][e] * rs) * pv[4 * n + e]; }
;                     u32x4 w; w.x = cvt_pk_bf16(hn[0], hn[1]); w.y = cvt_pk_bf16(hn[2], hn[3]); w.z = cvt_pk_bf16(hn[4], hn[5]); w.w = cvt_pk_bf16(hn[6], hn[7]); *(u32x4*)(hb + o) = w;
;                     const float hr[8] = {bflo(w.x), bfhi(w.x), bflo(w.y), bfhi(w.y), bflo(w.z), bfhi(w.z), bflo(w.w), bfhi(w.w)};
;                     ss += ((hr[0] * hr[0] + hr[1] * hr[1]) + (hr[2] * hr[2] + hr[3] * hr[3])) + ((hr[4] * hr[4] + hr[5] * hr[5]) + (hr[6] * hr[6] + hr[7] * hr[7])); }
;                 ss += __shfl_xor(ss, 16); ss += __shfl_xor(ss, 32);
;                 if (fq == 0) rss_out[(size_t)row * 16 + u.pn * 4 + wc] = ss; }
.LBB1_813:
	v_lshl_add_u32 v158, s26, 8, v161
	v_ashrrev_i32_e32 v159, 31, v158
	v_lshlrev_b64 v[166:167], 10, v[158:159]
	v_lshl_add_u64 v[166:167], v[166:167], 0, v[156:157]
	v_lshlrev_b64 v[176:177], 1, v[166:167]
	v_lshl_add_u64 v[178:179], s[24:25], 0, v[176:177]
	global_load_dwordx4 v[166:169], v[178:179], off
	global_load_dwordx4 v[184:187], v[178:179], off offset:256
	v_or_b32_e32 v228, 16, v158
	v_ashrrev_i32_e32 v229, 31, v228
	v_lshlrev_b64 v[228:229], 10, v[228:229]
	v_lshl_add_u64 v[228:229], v[228:229], 0, v[156:157]
	v_lshlrev_b64 v[228:229], 1, v[228:229]
	v_lshl_add_u64 v[228:229], s[24:25], 0, v[228:229]
	global_load_dwordx4 v[188:191], v[228:229], off
	global_load_dwordx4 v[200:203], v[228:229], off offset:256
	v_or_b32_e32 v228, 32, v158
	v_ashrrev_i32_e32 v229, 31, v228
	v_lshlrev_b64 v[228:229], 10, v[228:229]
	v_lshl_add_u64 v[228:229], v[228:229], 0, v[156:157]
	v_lshlrev_b64 v[228:229], 1, v[228:229]
	v_lshl_add_u64 v[228:229], s[24:25], 0, v[228:229]
	global_load_dwordx4 v[204:207], v[228:229], off
	global_load_dwordx4 v[208:211], v[228:229], off offset:256
	v_or_b32_e32 v228, 48, v158
	v_ashrrev_i32_e32 v229, 31, v228
	v_lshlrev_b64 v[228:229], 10, v[228:229]
	v_lshl_add_u64 v[228:229], v[228:229], 0, v[156:157]
	v_lshlrev_b64 v[228:229], 1, v[228:229]
	v_lshl_add_u64 v[228:229], s[24:25], 0, v[228:229]
	global_load_dwordx4 v[212:215], v[228:229], off
	global_load_dwordx4 v[216:219], v[228:229], off offset:256
	s_waitcnt vmcnt(0)
	v_add_f32_e32 v142, v142, v86
	v_add_f32_e32 v143, v143, v87
	v_add_f32_e32 v144, v144, v88
	v_add_f32_e32 v145, v145, v89
	v_add_f32_e32 v138, v138, v78
	v_add_f32_e32 v139, v139, v79
	v_add_f32_e32 v140, v140, v80
	v_add_f32_e32 v141, v141, v81
	v_lshl_add_u64 v[176:177], s[22:23], 0, v[176:177]
	v_add_f32_e32 v134, v134, v70
	v_add_f32_e32 v136, v136, v72
	v_add_f32_e32 v130, v130, v66
	v_add_f32_e32 v135, v135, v71
	v_add_f32_e32 v137, v137, v73
	v_add_f32_e32 v131, v131, v67
	v_add_f32_e32 v133, v133, v69
	v_lshlrev_b32_e32 v165, 16, v166
	v_and_b32_e32 v166, 0xffff0000, v166
	v_lshlrev_b32_e32 v175, 16, v167
	v_and_b32_e32 v167, 0xffff0000, v167
	v_lshlrev_b32_e32 v180, 16, v168
	v_and_b32_e32 v168, 0xffff0000, v168
	v_lshlrev_b32_e32 v181, 16, v169
	v_and_b32_e32 v169, 0xffff0000, v169
	v_fmac_f32_e32 v165, s11, v142
	v_fmac_f32_e32 v166, s11, v143
	v_fmac_f32_e32 v175, s11, v144
	v_fmac_f32_e32 v167, s11, v145
	v_fmac_f32_e32 v180, s11, v138
	v_fmac_f32_e32 v168, s11, v139
	v_fmac_f32_e32 v181, s11, v140
	v_fmac_f32_e32 v169, s11, v141
	v_cvt_pk_bf16_f32 v138, v165, v166
	v_cvt_pk_bf16_f32 v139, v175, v167
	v_cvt_pk_bf16_f32 v140, v180, v168
	v_cvt_pk_bf16_f32 v141, v181, v169
	global_store_dwordx4 v[176:177], v[138:141], off
	v_mov_b32_e32 v142, v184
	v_mov_b32_e32 v143, v185
	v_mov_b32_e32 v144, v186
	v_mov_b32_e32 v145, v187
	v_lshlrev_b32_e32 v167, 16, v138
	v_and_b32_e32 v138, 0xffff0000, v138
	v_lshlrev_b32_e32 v168, 16, v139
	v_and_b32_e32 v139, 0xffff0000, v139
	v_lshlrev_b32_e32 v169, 16, v140
	v_and_b32_e32 v140, 0xffff0000, v140
	v_lshlrev_b32_e32 v175, 16, v141
	v_and_b32_e32 v141, 0xffff0000, v141
	v_mul_f32_e32 v138, v138, v138
	v_mul_f32_e32 v139, v139, v139
	v_mul_f32_e32 v140, v140, v140
	v_mul_f32_e32 v141, v141, v141
	v_fmac_f32_e32 v138, v167, v167
	v_fmac_f32_e32 v139, v168, v168
	v_fmac_f32_e32 v140, v169, v169
	v_fmac_f32_e32 v141, v175, v175
	v_add_f32_e32 v138, v138, v139
	v_add_f32_e32 v139, v140, v141
	v_add_f32_e32 v138, v138, v139
	v_add_f32_e32 v165, v132, v68
	v_and_b32_e32 v166, 64, v171
	v_xor_b32_e32 v132, 16, v171
	v_add_u32_e32 v166, 64, v166
	v_cmp_lt_i32_e32 vcc, v132, v166
	s_nop 0
	v_lshlrev_b32_e32 v139, 16, v142
	v_and_b32_e32 v140, 0xffff0000, v142
	v_lshlrev_b32_e32 v141, 16, v143
	v_and_b32_e32 v142, 0xffff0000, v143
	v_lshlrev_b32_e32 v143, 16, v144
	v_and_b32_e32 v144, 0xffff0000, v144
	v_lshlrev_b32_e32 v167, 16, v145
	v_and_b32_e32 v145, 0xffff0000, v145
	v_fmac_f32_e32 v139, s11, v134
	v_fmac_f32_e32 v141, s11, v136
	v_fmac_f32_e32 v143, s11, v130
	v_fmac_f32_e32 v140, s11, v135
	v_fmac_f32_e32 v142, s11, v137
	v_fmac_f32_e32 v144, s11, v131
	v_fmac_f32_e32 v167, s11, v165
	v_fmac_f32_e32 v145, s11, v133
	v_cvt_pk_bf16_f32 v134, v139, v140
	v_cvt_pk_bf16_f32 v135, v141, v142
	v_cvt_pk_bf16_f32 v136, v143, v144
	v_cvt_pk_bf16_f32 v137, v167, v145
	v_cndmask_b32_e32 v132, v171, v132, vcc
	v_and_b32_e32 v131, 0xffff0000, v134
	v_and_b32_e32 v139, 0xffff0000, v135
	v_and_b32_e32 v141, 0xffff0000, v136
	v_and_b32_e32 v143, 0xffff0000, v137
	v_lshlrev_b32_e32 v130, 16, v134
	v_lshlrev_b32_e32 v133, 16, v135
	v_lshlrev_b32_e32 v140, 16, v136
	v_lshlrev_b32_e32 v142, 16, v137
	v_mul_f32_e32 v131, v131, v131
	v_mul_f32_e32 v139, v139, v139
	v_mul_f32_e32 v141, v141, v141
	v_mul_f32_e32 v143, v143, v143
	v_fmac_f32_e32 v131, v130, v130
	v_fmac_f32_e32 v139, v133, v133
	v_fmac_f32_e32 v141, v140, v140
	v_fmac_f32_e32 v143, v142, v142
	v_add_f32_e32 v130, v131, v139
	v_add_f32_e32 v131, v141, v143
	v_add_f32_e32 v130, v130, v131
	v_lshlrev_b32_e32 v132, 2, v132
	v_add_f32_e32 v130, v138, v130
	v_mov_b32_e32 v131, v130
	s_nop 1
	v_permlane16_swap_b32 v131, v130
	v_xor_b32_e32 v133, 32, v171
	v_cmp_lt_i32_e32 vcc, v133, v166
	global_store_dwordx4 v[176:177], v[134:137], off offset:256
	s_waitcnt lgkmcnt(0)
	v_add_f32_e32 v130, v130, v131
	v_cndmask_b32_e32 v133, v171, v133, vcc
	v_lshlrev_b32_e32 v133, 2, v133
	v_mov_b32_e32 v131, v130
	s_nop 1
	v_permlane32_swap_b32 v131, v130
	s_and_saveexec_b64 s[8:9], s[6:7]
	s_cbranch_execz .LBB1_815
	s_waitcnt lgkmcnt(0)
	v_add_f32_e32 v134, v130, v131
	s_lshl_b32 s28, s0, 2
	v_lshlrev_b64 v[130:131], 6, v[158:159]
	s_ashr_i32 s29, s28, 31
	v_lshl_add_u64 v[130:131], s[20:21], 0, v[130:131]
	v_lshl_add_u64 v[130:131], s[28:29], 2, v[130:131]
	s_lshl_b32 s74, s45, 2
	v_lshl_add_u64 v[130:131], v[130:131], 0, s[74:75]
	global_store_dword v[130:131], v134, off
; __device__ __forceinline__ unsigned cvt_pk_bf16(float lo, float hi) { unsigned r; asm volatile("v_cvt_pk_bf16_f32 %0, %1, %2" : "=v"(r) : "v"(lo), "v"(hi)); return r; }
; __device__ __forceinline__ float bflo(unsigned w) { return __uint_as_float(w << 16); }
;     __device__ __forceinline__ void operator()(const f32x4 (&acc)[2][2][4][2], const Unit& u, int wr, int wc, int fr, int fq, LAS unsigned char* lds) const {
;     ...
;             for (int m = 0; m < 4; ++m) { const int row = row0 + ai * HALF + m * 16; const size_t off = (size_t)row * D + col0;
;                 float rs = 1.0f; if (MODE == 1) rs = rstd_of4(rss_in, row, fq);
;                 float ss = 0.f;
; #pragma unroll
;                 for (int bj = 0; bj < 2; ++bj) { const size_t o = off + bj * HALF; const u32x4 bw = *(const u32x4*)(base + o);
;                     const float bs[8] = {bflo(bw.x), bfhi(bw.x), bflo(bw.y), bfhi(bw.y), bflo(bw.z), bfhi(bw.z), bflo(bw.w), bfhi(bw.w)};
;                     float hn[8];
;                     if (MODE == 0) {
; #pragma unroll
;                         for (int n = 0; n < 2; ++n)
; #pragma unroll
;                             for (int e = 0; e < 4; ++e) hn[4 * n + e] = bs[4 * n + e] + (acc[ai][bj][m][n][e] + bv[bj][n][e]) * scale;
;                     } else { const u32x4 pw = *(const u32x4*)(pp + o);
;                         const float pv[8] = {bflo(pw.x), bfhi(pw.x), bflo(pw.y), bfhi(pw.y), bflo(pw.z), bfhi(pw.z), bflo(pw.w), bfhi(pw.w)};
; #pragma unroll
;                         for (int n = 0; n < 2; ++n)
; #pragma unroll
;                             for (int e = 0; e < 4; ++e) hn[4 * n + e] = bs[4 * n + e] + fast_sigmoid(acc[ai][bj][m][n][e] * rs) * pv[4 * n + e]; }
;                     u32x4 w; w.x = cvt_pk_bf16(hn[0], hn[1]); w.y = cvt_pk_bf16(hn[2], hn[3]); w.z = cvt_pk_bf16(hn[4], hn[5]); w.w = cvt_pk_bf16(hn[6], hn[7]); *(u32x4*)(hb + o) = w;
;                     const float hr[8] = {bflo(w.x), bfhi(w.x), bflo(w.y), bfhi(w.y), bflo(w.z), bfhi(w.z), bflo(w.w), bfhi(w.w)};
;                     ss += ((hr[0] * hr[0] + hr[1] * hr[1]) + (hr[2] * hr[2] + hr[3] * hr[3])) + ((hr[4] * hr[4] + hr[5] * hr[5]) + (hr[6] * hr[6] + hr[7] * hr[7])); }
;                 ss += __shfl_xor(ss, 16); ss += __shfl_xor(ss, 32);
;                 if (fq == 0) rss_out[(size_t)row * 16 + u.pn * 4 + wc] = ss; }
.LBB1_815:
	s_or_b64 exec, exec, s[8:9]
	v_or_b32_e32 v130, 16, v158
	s_waitcnt lgkmcnt(0)
	v_ashrrev_i32_e32 v131, 31, v130
	v_lshlrev_b64 v[134:135], 10, v[130:131]
	v_lshl_add_u64 v[134:135], v[134:135], 0, v[156:157]
	v_lshlrev_b64 v[138:139], 1, v[134:135]
	v_lshl_add_u64 v[140:141], s[24:25], 0, v[138:139]
	v_mov_b32_e32 v134, v188
	v_mov_b32_e32 v135, v189
	v_mov_b32_e32 v136, v190
	v_mov_b32_e32 v137, v191
	v_add_f32_e32 v126, v126, v86
	v_add_f32_e32 v127, v127, v87
	v_add_f32_e32 v128, v128, v88
	v_add_f32_e32 v129, v129, v89
	v_add_f32_e32 v122, v122, v78
	v_add_f32_e32 v123, v123, v79
	v_add_f32_e32 v124, v124, v80
	v_add_f32_e32 v125, v125, v81
	v_lshl_add_u64 v[138:139], s[22:23], 0, v[138:139]
	v_add_f32_e32 v119, v119, v71
	v_add_f32_e32 v121, v121, v73
	v_add_f32_e32 v118, v118, v70
	v_add_f32_e32 v120, v120, v72
	v_add_f32_e32 v114, v114, v66
	v_add_f32_e32 v115, v115, v67
	v_add_f32_e32 v116, v116, v68
	v_add_f32_e32 v117, v117, v69
	s_nop 0
	v_lshlrev_b32_e32 v142, 16, v134
	v_and_b32_e32 v134, 0xffff0000, v134
	v_lshlrev_b32_e32 v143, 16, v135
	v_and_b32_e32 v135, 0xffff0000, v135
	v_lshlrev_b32_e32 v144, 16, v136
	v_and_b32_e32 v136, 0xffff0000, v136
	v_lshlrev_b32_e32 v145, 16, v137
	v_and_b32_e32 v137, 0xffff0000, v137
	v_fmac_f32_e32 v142, s11, v126
	v_fmac_f32_e32 v134, s11, v127
	v_fmac_f32_e32 v143, s11, v128
	v_fmac_f32_e32 v135, s11, v129
	v_fmac_f32_e32 v144, s11, v122
	v_fmac_f32_e32 v136, s11, v123
	v_fmac_f32_e32 v145, s11, v124
	v_fmac_f32_e32 v137, s11, v125
	v_cvt_pk_bf16_f32 v122, v142, v134
	v_cvt_pk_bf16_f32 v123, v143, v135
	v_cvt_pk_bf16_f32 v124, v144, v136
	v_cvt_pk_bf16_f32 v125, v145, v137
	global_store_dwordx4 v[138:139], v[122:125], off
	v_mov_b32_e32 v126, v200
	v_mov_b32_e32 v127, v201
	v_mov_b32_e32 v128, v202
	v_mov_b32_e32 v129, v203
	v_lshlrev_b32_e32 v134, 16, v122
	v_and_b32_e32 v122, 0xffff0000, v122
	v_lshlrev_b32_e32 v135, 16, v123
	v_and_b32_e32 v123, 0xffff0000, v123
	v_lshlrev_b32_e32 v136, 16, v124
	v_and_b32_e32 v124, 0xffff0000, v124
	v_lshlrev_b32_e32 v137, 16, v125
	v_and_b32_e32 v125, 0xffff0000, v125
	v_mul_f32_e32 v122, v122, v122
	v_mul_f32_e32 v123, v123, v123
	v_mul_f32_e32 v124, v124, v124
	v_mul_f32_e32 v125, v125, v125
	v_fmac_f32_e32 v122, v134, v134
	v_fmac_f32_e32 v123, v135, v135
	v_fmac_f32_e32 v124, v136, v136
	v_fmac_f32_e32 v125, v137, v137
	v_add_f32_e32 v122, v122, v123
	v_add_f32_e32 v123, v124, v125
	v_add_f32_e32 v122, v122, v123
	s_nop 0
	v_lshlrev_b32_e32 v123, 16, v126
	v_and_b32_e32 v124, 0xffff0000, v126
	v_and_b32_e32 v126, 0xffff0000, v127
	v_lshlrev_b32_e32 v125, 16, v127
	v_lshlrev_b32_e32 v127, 16, v128
	v_and_b32_e32 v128, 0xffff0000, v128
	v_lshlrev_b32_e32 v134, 16, v129
	v_and_b32_e32 v129, 0xffff0000, v129
	v_fmac_f32_e32 v124, s11, v119
	v_fmac_f32_e32 v126, s11, v121
	v_fmac_f32_e32 v123, s11, v118
	v_fmac_f32_e32 v125, s11, v120
	v_fmac_f32_e32 v127, s11, v114
	v_fmac_f32_e32 v128, s11, v115
	v_fmac_f32_e32 v134, s11, v116
	v_fmac_f32_e32 v129, s11, v117
	v_cvt_pk_bf16_f32 v116, v123, v124
	v_cvt_pk_bf16_f32 v117, v125, v126
	v_cvt_pk_bf16_f32 v118, v127, v128
	v_cvt_pk_bf16_f32 v119, v134, v129
	global_store_dwordx4 v[138:139], v[116:119], off offset:256
	v_and_b32_e32 v115, 0xffff0000, v116
	v_and_b32_e32 v121, 0xffff0000, v117
	v_and_b32_e32 v124, 0xffff0000, v118
	v_and_b32_e32 v126, 0xffff0000, v119
	v_lshlrev_b32_e32 v114, 16, v116
	v_lshlrev_b32_e32 v120, 16, v117
	v_lshlrev_b32_e32 v123, 16, v118
	v_lshlrev_b32_e32 v125, 16, v119
	v_mul_f32_e32 v115, v115, v115
	v_mul_f32_e32 v121, v121, v121
	v_mul_f32_e32 v124, v124, v124
	v_mul_f32_e32 v126, v126, v126
	v_fmac_f32_e32 v115, v114, v114
	v_fmac_f32_e32 v121, v120, v120
	v_fmac_f32_e32 v124, v123, v123
	v_fmac_f32_e32 v126, v125, v125
	v_add_f32_e32 v114, v115, v121
	v_add_f32_e32 v115, v124, v126
	v_add_f32_e32 v114, v114, v115
	v_add_f32_e32 v114, v122, v114
	v_mov_b32_e32 v115, v114
	s_nop 1
	v_permlane16_swap_b32 v115, v114
	s_waitcnt lgkmcnt(0)
	v_add_f32_e32 v114, v114, v115
	v_mov_b32_e32 v115, v114
	s_nop 1
	v_permlane32_swap_b32 v115, v114
	s_and_saveexec_b64 s[8:9], s[6:7]
	s_cbranch_execz .LBB1_817
	s_waitcnt lgkmcnt(0)
	v_add_f32_e32 v116, v114, v115
	s_lshl_b32 s28, s0, 2
	v_lshlrev_b64 v[114:115], 6, v[130:131]
	s_ashr_i32 s29, s28, 31
	v_lshl_add_u64 v[114:115], s[20:21], 0, v[114:115]
	v_lshl_add_u64 v[114:115], s[28:29], 2, v[114:115]
	s_lshl_b32 s74, s45, 2
	v_lshl_add_u64 v[114:115], v[114:115], 0, s[74:75]
	global_store_dword v[114:115], v116, off
; __device__ __forceinline__ unsigned cvt_pk_bf16(float lo, float hi) { unsigned r; asm volatile("v_cvt_pk_bf16_f32 %0, %1, %2" : "=v"(r) : "v"(lo), "v"(hi)); return r; }
; __device__ __forceinline__ float bflo(unsigned w) { return __uint_as_float(w << 16); }
;     __device__ __forceinline__ void operator()(const f32x4 (&acc)[2][2][4][2], const Unit& u, int wr, int wc, int fr, int fq, LAS unsigned char* lds) const {
;     ...
;             for (int m = 0; m < 4; ++m) { const int row = row0 + ai * HALF + m * 16; const size_t off = (size_t)row * D + col0;
;                 float rs = 1.0f; if (MODE == 1) rs = rstd_of4(rss_in, row, fq);
;                 float ss = 0.f;
; #pragma unroll
;                 for (int bj = 0; bj < 2; ++bj) { const size_t o = off + bj * HALF; const u32x4 bw = *(const u32x4*)(base + o);
;                     const float bs[8] = {bflo(bw.x), bfhi(bw.x), bflo(bw.y), bfhi(bw.y), bflo(bw.z), bfhi(bw.z), bflo(bw.w), bfhi(bw.w)};
;                     float hn[8];
;                     if (MODE == 0) {
; #pragma unroll
;                         for (int n = 0; n < 2; ++n)
; #pragma unroll
;                             for (int e = 0; e < 4; ++e) hn[4 * n + e] = bs[4 * n + e] + (acc[ai][bj][m][n][e] + bv[bj][n][e]) * scale;
;                     } else { const u32x4 pw = *(const u32x4*)(pp + o);
;                         const float pv[8] = {bflo(pw.x), bfhi(pw.x), bflo(pw.y), bfhi(pw.y), bflo(pw.z), bfhi(pw.z), bflo(pw.w), bfhi(pw.w)};
; #pragma unroll
;                         for (int n = 0; n < 2; ++n)
; #pragma unroll
;                             for (int e = 0; e < 4; ++e) hn[4 * n + e] = bs[4 * n + e] + fast_sigmoid(acc[ai][bj][m][n][e] * rs) * pv[4 * n + e]; }
;                     u32x4 w; w.x = cvt_pk_bf16(hn[0], hn[1]); w.y = cvt_pk_bf16(hn[2], hn[3]); w.z = cvt_pk_bf16(hn[4], hn[5]); w.w = cvt_pk_bf16(hn[6], hn[7]); *(u32x4*)(hb + o) = w;
;                     const float hr[8] = {bflo(w.x), bfhi(w.x), bflo(w.y), bfhi(w.y), bflo(w.z), bfhi(w.z), bflo(w.w), bfhi(w.w)};
;                     ss += ((hr[0] * hr[0] + hr[1] * hr[1]) + (hr[2] * hr[2] + hr[3] * hr[3])) + ((hr[4] * hr[4] + hr[5] * hr[5]) + (hr[6] * hr[6] + hr[7] * hr[7])); }
;                 ss += __shfl_xor(ss, 16); ss += __shfl_xor(ss, 32);
;                 if (fq == 0) rss_out[(size_t)row * 16 + u.pn * 4 + wc] = ss; }
.LBB1_817:
	s_or_b64 exec, exec, s[8:9]
	v_or_b32_e32 v114, 32, v158
	s_waitcnt lgkmcnt(0)
	v_ashrrev_i32_e32 v115, 31, v114
	v_lshlrev_b64 v[116:117], 10, v[114:115]
	v_lshl_add_u64 v[116:117], v[116:117], 0, v[156:157]
	v_lshlrev_b64 v[120:121], 1, v[116:117]
	v_lshl_add_u64 v[122:123], s[24:25], 0, v[120:121]
	v_mov_b32_e32 v116, v204
	v_mov_b32_e32 v117, v205
	v_mov_b32_e32 v118, v206
	v_mov_b32_e32 v119, v207
	v_add_f32_e32 v110, v110, v86
	v_add_f32_e32 v111, v111, v87
	v_add_f32_e32 v112, v112, v88
	v_add_f32_e32 v113, v113, v89
	v_add_f32_e32 v106, v106, v78
	v_add_f32_e32 v107, v107, v79
	v_add_f32_e32 v108, v108, v80
	v_add_f32_e32 v109, v109, v81
	v_lshl_add_u64 v[120:121], s[22:23], 0, v[120:121]
	v_add_f32_e32 v103, v103, v71
	v_add_f32_e32 v105, v105, v73
	v_add_f32_e32 v102, v102, v70
	v_add_f32_e32 v104, v104, v72
	v_add_f32_e32 v98, v98, v66
	v_add_f32_e32 v99, v99, v67
	v_add_f32_e32 v100, v100, v68
	v_add_f32_e32 v101, v101, v69
	s_nop 0
	v_lshlrev_b32_e32 v124, 16, v116
	v_and_b32_e32 v116, 0xffff0000, v116
	v_lshlrev_b32_e32 v125, 16, v117
	v_and_b32_e32 v117, 0xffff0000, v117
	v_lshlrev_b32_e32 v126, 16, v118
	v_and_b32_e32 v118, 0xffff0000, v118
	v_lshlrev_b32_e32 v127, 16, v119
	v_and_b32_e32 v119, 0xffff0000, v119
	v_fmac_f32_e32 v124, s11, v110
	v_fmac_f32_e32 v116, s11, v111
	v_fmac_f32_e32 v125, s11, v112
	v_fmac_f32_e32 v117, s11, v113
	v_fmac_f32_e32 v126, s11, v106
	v_fmac_f32_e32 v118, s11, v107
	v_fmac_f32_e32 v127, s11, v108
	v_fmac_f32_e32 v119, s11, v109
	v_cvt_pk_bf16_f32 v106, v124, v116
	v_cvt_pk_bf16_f32 v107, v125, v117
	v_cvt_pk_bf16_f32 v108, v126, v118
	v_cvt_pk_bf16_f32 v109, v127, v119
	global_store_dwordx4 v[120:121], v[106:109], off
	v_mov_b32_e32 v110, v208
	v_mov_b32_e32 v111, v209
	v_mov_b32_e32 v112, v210
	v_mov_b32_e32 v113, v211
	v_lshlrev_b32_e32 v116, 16, v106
	v_and_b32_e32 v106, 0xffff0000, v106
	v_lshlrev_b32_e32 v117, 16, v107
	v_and_b32_e32 v107, 0xffff0000, v107
	v_lshlrev_b32_e32 v118, 16, v108
	v_and_b32_e32 v108, 0xffff0000, v108
	v_lshlrev_b32_e32 v119, 16, v109
	v_and_b32_e32 v109, 0xffff0000, v109
	v_mul_f32_e32 v106, v106, v106
	v_mul_f32_e32 v107, v107, v107
	v_mul_f32_e32 v108, v108, v108
	v_mul_f32_e32 v109, v109, v109
	v_fmac_f32_e32 v106, v116, v116
	v_fmac_f32_e32 v107, v117, v117
	v_fmac_f32_e32 v108, v118, v118
	v_fmac_f32_e32 v109, v119, v119
	v_add_f32_e32 v106, v106, v107
	v_add_f32_e32 v107, v108, v109
	v_add_f32_e32 v106, v106, v107
	s_nop 0
	v_lshlrev_b32_e32 v107, 16, v110
	v_and_b32_e32 v108, 0xffff0000, v110
	v_and_b32_e32 v110, 0xffff0000, v111
	v_lshlrev_b32_e32 v109, 16, v111
	v_lshlrev_b32_e32 v111, 16, v112
	v_and_b32_e32 v112, 0xffff0000, v112
	v_lshlrev_b32_e32 v116, 16, v113
	v_and_b32_e32 v113, 0xffff0000, v113
	v_fmac_f32_e32 v108, s11, v103
	v_fmac_f32_e32 v110, s11, v105
	v_fmac_f32_e32 v107, s11, v102
	v_fmac_f32_e32 v109, s11, v104
	v_fmac_f32_e32 v111, s11, v98
	v_fmac_f32_e32 v112, s11, v99
	v_fmac_f32_e32 v116, s11, v100
	v_fmac_f32_e32 v113, s11, v101
	v_cvt_pk_bf16_f32 v100, v107, v108
	v_cvt_pk_bf16_f32 v101, v109, v110
	v_cvt_pk_bf16_f32 v102, v111, v112
	v_cvt_pk_bf16_f32 v103, v116, v113
	global_store_dwordx4 v[120:121], v[100:103], off offset:256
	v_and_b32_e32 v99, 0xffff0000, v100
	v_and_b32_e32 v105, 0xffff0000, v101
	v_and_b32_e32 v108, 0xffff0000, v102
	v_and_b32_e32 v110, 0xffff0000, v103
	v_lshlrev_b32_e32 v98, 16, v100
	v_lshlrev_b32_e32 v104, 16, v101
	v_lshlrev_b32_e32 v107, 16, v102
	v_lshlrev_b32_e32 v109, 16, v103
	v_mul_f32_e32 v99, v99, v99
	v_mul_f32_e32 v105, v105, v105
	v_mul_f32_e32 v108, v108, v108
	v_mul_f32_e32 v110, v110, v110
	v_fmac_f32_e32 v99, v98, v98
	v_fmac_f32_e32 v105, v104, v104
	v_fmac_f32_e32 v108, v107, v107
	v_fmac_f32_e32 v110, v109, v109
	v_add_f32_e32 v98, v99, v105
	v_add_f32_e32 v99, v108, v110
	v_add_f32_e32 v98, v98, v99
	v_add_f32_e32 v98, v106, v98
	v_mov_b32_e32 v99, v98
	s_nop 1
	v_permlane16_swap_b32 v99, v98
	s_waitcnt lgkmcnt(0)
	v_add_f32_e32 v98, v98, v99
	v_mov_b32_e32 v99, v98
	s_nop 1
	v_permlane32_swap_b32 v99, v98
	s_and_saveexec_b64 s[8:9], s[6:7]
	s_cbranch_execz .LBB1_819
	s_waitcnt lgkmcnt(0)
	v_add_f32_e32 v100, v98, v99
	s_lshl_b32 s28, s0, 2
	v_lshlrev_b64 v[98:99], 6, v[114:115]
	s_ashr_i32 s29, s28, 31
	v_lshl_add_u64 v[98:99], s[20:21], 0, v[98:99]
	v_lshl_add_u64 v[98:99], s[28:29], 2, v[98:99]
	s_lshl_b32 s74, s45, 2
	v_lshl_add_u64 v[98:99], v[98:99], 0, s[74:75]
	global_store_dword v[98:99], v100, off
; __device__ __forceinline__ unsigned cvt_pk_bf16(float lo, float hi) { unsigned r; asm volatile("v_cvt_pk_bf16_f32 %0, %1, %2" : "=v"(r) : "v"(lo), "v"(hi)); return r; }
; __device__ __forceinline__ float bflo(unsigned w) { return __uint_as_float(w << 16); }
;     __device__ __forceinline__ void operator()(const f32x4 (&acc)[2][2][4][2], const Unit& u, int wr, int wc, int fr, int fq, LAS unsigned char* lds) const {
;     ...
;             for (int m = 0; m < 4; ++m) { const int row = row0 + ai * HALF + m * 16; const size_t off = (size_t)row * D + col0;
;                 float rs = 1.0f; if (MODE == 1) rs = rstd_of4(rss_in, row, fq);
;                 float ss = 0.f;
; #pragma unroll
;                 for (int bj = 0; bj < 2; ++bj) { const size_t o = off + bj * HALF; const u32x4 bw = *(const u32x4*)(base + o);
;                     const float bs[8] = {bflo(bw.x), bfhi(bw.x), bflo(bw.y), bfhi(bw.y), bflo(bw.z), bfhi(bw.z), bflo(bw.w), bfhi(bw.w)};
;                     float hn[8];
;                     if (MODE == 0) {
; #pragma unroll
;                         for (int n = 0; n < 2; ++n)
; #pragma unroll
;                             for (int e = 0; e < 4; ++e) hn[4 * n + e] = bs[4 * n + e] + (acc[ai][bj][m][n][e] + bv[bj][n][e]) * scale;
;                     } else { const u32x4 pw = *(const u32x4*)(pp + o);
;                         const float pv[8] = {bflo(pw.x), bfhi(pw.x), bflo(pw.y), bfhi(pw.y), bflo(pw.z), bfhi(pw.z), bflo(pw.w), bfhi(pw.w)};
; #pragma unroll
;                         for (int n = 0; n < 2; ++n)
; #pragma unroll
;                             for (int e = 0; e < 4; ++e) hn[4 * n + e] = bs[4 * n + e] + fast_sigmoid(acc[ai][bj][m][n][e] * rs) * pv[4 * n + e]; }
;                     u32x4 w; w.x = cvt_pk_bf16(hn[0], hn[1]); w.y = cvt_pk_bf16(hn[2], hn[3]); w.z = cvt_pk_bf16(hn[4], hn[5]); w.w = cvt_pk_bf16(hn[6], hn[7]); *(u32x4*)(hb + o) = w;
;                     const float hr[8] = {bflo(w.x), bfhi(w.x), bflo(w.y), bfhi(w.y), bflo(w.z), bfhi(w.z), bflo(w.w), bfhi(w.w)};
;                     ss += ((hr[0] * hr[0] + hr[1] * hr[1]) + (hr[2] * hr[2] + hr[3] * hr[3])) + ((hr[4] * hr[4] + hr[5] * hr[5]) + (hr[6] * hr[6] + hr[7] * hr[7])); }
;                 ss += __shfl_xor(ss, 16); ss += __shfl_xor(ss, 32);
;                 if (fq == 0) rss_out[(size_t)row * 16 + u.pn * 4 + wc] = ss; }
.LBB1_819:
	s_or_b64 exec, exec, s[8:9]
	v_or_b32_e32 v98, 48, v158
	s_waitcnt lgkmcnt(0)
	v_ashrrev_i32_e32 v99, 31, v98
	v_lshlrev_b64 v[100:101], 10, v[98:99]
	v_lshl_add_u64 v[100:101], v[100:101], 0, v[156:157]
	v_lshlrev_b64 v[104:105], 1, v[100:101]
	v_lshl_add_u64 v[106:107], s[24:25], 0, v[104:105]
	v_mov_b32_e32 v100, v212
	v_mov_b32_e32 v101, v213
	v_mov_b32_e32 v102, v214
	v_mov_b32_e32 v103, v215
	v_add_f32_e32 v94, v94, v86
	v_add_f32_e32 v95, v95, v87
	v_add_f32_e32 v96, v96, v88
	v_add_f32_e32 v97, v97, v89
	v_add_f32_e32 v90, v90, v78
	v_add_f32_e32 v91, v91, v79
	v_add_f32_e32 v92, v92, v80
	v_add_f32_e32 v93, v93, v81
	v_lshl_add_u64 v[104:105], s[22:23], 0, v[104:105]
	v_add_f32_e32 v83, v83, v71
	v_add_f32_e32 v85, v85, v73
	v_add_f32_e32 v82, v82, v70
	v_add_f32_e32 v84, v84, v72
	v_add_f32_e32 v74, v74, v66
	v_add_f32_e32 v75, v75, v67
	v_add_f32_e32 v76, v76, v68
	v_add_f32_e32 v77, v77, v69
	s_nop 0
	v_lshlrev_b32_e32 v108, 16, v100
	v_and_b32_e32 v100, 0xffff0000, v100
	v_lshlrev_b32_e32 v109, 16, v101
	v_and_b32_e32 v101, 0xffff0000, v101
	v_lshlrev_b32_e32 v110, 16, v102
	v_and_b32_e32 v102, 0xffff0000, v102
	v_lshlrev_b32_e32 v111, 16, v103
	v_and_b32_e32 v103, 0xffff0000, v103
	v_fmac_f32_e32 v108, s11, v94
	v_fmac_f32_e32 v100, s11, v95
	v_fmac_f32_e32 v109, s11, v96
	v_fmac_f32_e32 v101, s11, v97
	v_fmac_f32_e32 v110, s11, v90
	v_fmac_f32_e32 v102, s11, v91
	v_fmac_f32_e32 v111, s11, v92
	v_fmac_f32_e32 v103, s11, v93
	v_cvt_pk_bf16_f32 v90, v108, v100
	v_cvt_pk_bf16_f32 v91, v109, v101
	v_cvt_pk_bf16_f32 v92, v110, v102
	v_cvt_pk_bf16_f32 v93, v111, v103
	global_store_dwordx4 v[104:105], v[90:93], off
	v_mov_b32_e32 v94, v216
	v_mov_b32_e32 v95, v217
	v_mov_b32_e32 v96, v218
	v_mov_b32_e32 v97, v219
	v_lshlrev_b32_e32 v100, 16, v90
	v_and_b32_e32 v90, 0xffff0000, v90
	v_lshlrev_b32_e32 v101, 16, v91
	v_and_b32_e32 v91, 0xffff0000, v91
	v_lshlrev_b32_e32 v102, 16, v92
	v_and_b32_e32 v92, 0xffff0000, v92
	v_lshlrev_b32_e32 v103, 16, v93
	v_and_b32_e32 v93, 0xffff0000, v93
	v_mul_f32_e32 v90, v90, v90
	v_mul_f32_e32 v91, v91, v91
	v_mul_f32_e32 v92, v92, v92
	v_mul_f32_e32 v93, v93, v93
	v_fmac_f32_e32 v90, v100, v100
	v_fmac_f32_e32 v91, v101, v101
	v_fmac_f32_e32 v92, v102, v102
	v_fmac_f32_e32 v93, v103, v103
	v_add_f32_e32 v90, v90, v91
	v_add_f32_e32 v91, v92, v93
	v_add_f32_e32 v90, v90, v91
	s_nop 0
	v_lshlrev_b32_e32 v91, 16, v94
	v_and_b32_e32 v92, 0xffff0000, v94
	v_and_b32_e32 v94, 0xffff0000, v95
	v_lshlrev_b32_e32 v93, 16, v95
	v_lshlrev_b32_e32 v95, 16, v96
	v_and_b32_e32 v96, 0xffff0000, v96
	v_lshlrev_b32_e32 v100, 16, v97
	v_and_b32_e32 v97, 0xffff0000, v97
	v_fmac_f32_e32 v92, s11, v83
	v_fmac_f32_e32 v94, s11, v85
	v_fmac_f32_e32 v91, s11, v82
	v_fmac_f32_e32 v93, s11, v84
	v_fmac_f32_e32 v95, s11, v74
	v_fmac_f32_e32 v96, s11, v75
	v_fmac_f32_e32 v100, s11, v76
	v_fmac_f32_e32 v97, s11, v77
	v_cvt_pk_bf16_f32 v82, v91, v92
	v_cvt_pk_bf16_f32 v83, v93, v94
	v_cvt_pk_bf16_f32 v84, v95, v96
	v_cvt_pk_bf16_f32 v85, v100, v97
	global_store_dwordx4 v[104:105], v[82:85], off offset:256
	v_and_b32_e32 v75, 0xffff0000, v82
	v_and_b32_e32 v77, 0xffff0000, v83
	v_and_b32_e32 v92, 0xffff0000, v84
	v_and_b32_e32 v94, 0xffff0000, v85
	v_lshlrev_b32_e32 v74, 16, v82
	v_lshlrev_b32_e32 v76, 16, v83
	v_lshlrev_b32_e32 v91, 16, v84
	v_lshlrev_b32_e32 v93, 16, v85
	v_mul_f32_e32 v75, v75, v75
	v_mul_f32_e32 v77, v77, v77
	v_mul_f32_e32 v92, v92, v92
	v_mul_f32_e32 v94, v94, v94
	v_fmac_f32_e32 v75, v74, v74
	v_fmac_f32_e32 v77, v76, v76
	v_fmac_f32_e32 v92, v91, v91
	v_fmac_f32_e32 v94, v93, v93
	v_add_f32_e32 v74, v75, v77
	v_add_f32_e32 v75, v92, v94
	v_add_f32_e32 v74, v74, v75
	v_add_f32_e32 v74, v90, v74
	v_mov_b32_e32 v75, v74
	s_nop 1
	v_permlane16_swap_b32 v75, v74
	s_waitcnt lgkmcnt(0)
	v_add_f32_e32 v74, v74, v75
	v_mov_b32_e32 v75, v74
	s_nop 1
	v_permlane32_swap_b32 v75, v74
	s_and_saveexec_b64 s[8:9], s[6:7]
	s_cbranch_execz .LBB1_821
	s_waitcnt lgkmcnt(0)
	v_add_f32_e32 v76, v74, v75
	s_lshl_b32 s28, s0, 2
	v_lshlrev_b64 v[74:75], 6, v[98:99]
	s_ashr_i32 s29, s28, 31
	v_lshl_add_u64 v[74:75], s[20:21], 0, v[74:75]
	v_lshl_add_u64 v[74:75], s[28:29], 2, v[74:75]
	s_lshl_b32 s74, s45, 2
	v_lshl_add_u64 v[74:75], v[74:75], 0, s[74:75]
	global_store_dword v[74:75], v76, off
; __device__ __forceinline__ unsigned cvt_pk_bf16(float lo, float hi) { unsigned r; asm volatile("v_cvt_pk_bf16_f32 %0, %1, %2" : "=v"(r) : "v"(lo), "v"(hi)); return r; }
; __device__ __forceinline__ float bflo(unsigned w) { return __uint_as_float(w << 16); }
;     __device__ __forceinline__ void operator()(const f32x4 (&acc)[2][2][4][2], const Unit& u, int wr, int wc, int fr, int fq, LAS unsigned char* lds) const {
;     ...
;             for (int m = 0; m < 4; ++m) { const int row = row0 + ai * HALF + m * 16; const size_t off = (size_t)row * D + col0;
;                 float rs = 1.0f; if (MODE == 1) rs = rstd_of4(rss_in, row, fq);
;                 float ss = 0.f;
; #pragma unroll
;                 for (int bj = 0; bj < 2; ++bj) { const size_t o = off + bj * HALF; const u32x4 bw = *(const u32x4*)(base + o);
;                     const float bs[8] = {bflo(bw.x), bfhi(bw.x), bflo(bw.y), bfhi(bw.y), bflo(bw.z), bfhi(bw.z), bflo(bw.w), bfhi(bw.w)};
;                     float hn[8];
;                     if (MODE == 0) {
; #pragma unroll
;                         for (int n = 0; n < 2; ++n)
; #pragma unroll
;                             for (int e = 0; e < 4; ++e) hn[4 * n + e] = bs[4 * n + e] + (acc[ai][bj][m][n][e] + bv[bj][n][e]) * scale;
;                     } else { const u32x4 pw = *(const u32x4*)(pp + o);
;                         const float pv[8] = {bflo(pw.x), bfhi(pw.x), bflo(pw.y), bfhi(pw.y), bflo(pw.z), bfhi(pw.z), bflo(pw.w), bfhi(pw.w)};
; #pragma unroll
;                         for (int n = 0; n < 2; ++n)
; #pragma unroll
;                             for (int e = 0; e < 4; ++e) hn[4 * n + e] = bs[4 * n + e] + fast_sigmoid(acc[ai][bj][m][n][e] * rs) * pv[4 * n + e]; }
;                     u32x4 w; w.x = cvt_pk_bf16(hn[0], hn[1]); w.y = cvt_pk_bf16(hn[2], hn[3]); w.z = cvt_pk_bf16(hn[4], hn[5]); w.w = cvt_pk_bf16(hn[6], hn[7]); *(u32x4*)(hb + o) = w;
;                     const float hr[8] = {bflo(w.x), bfhi(w.x), bflo(w.y), bfhi(w.y), bflo(w.z), bfhi(w.z), bflo(w.w), bfhi(w.w)};
;                     ss += ((hr[0] * hr[0] + hr[1] * hr[1]) + (hr[2] * hr[2] + hr[3] * hr[3])) + ((hr[4] * hr[4] + hr[5] * hr[5]) + (hr[6] * hr[6] + hr[7] * hr[7])); }
;                 ss += __shfl_xor(ss, 16); ss += __shfl_xor(ss, 32);
;                 if (fq == 0) rss_out[(size_t)row * 16 + u.pn * 4 + wc] = ss; }
.LBB1_821:
	s_or_b64 exec, exec, s[8:9]
	v_add_u32_e32 v74, 0x80, v158
	s_waitcnt lgkmcnt(0)
	v_ashrrev_i32_e32 v75, 31, v74
	v_lshlrev_b64 v[76:77], 10, v[74:75]
	v_lshl_add_u64 v[76:77], v[76:77], 0, v[156:157]
	v_lshlrev_b64 v[76:77], 1, v[76:77]
	v_lshl_add_u64 v[90:91], s[24:25], 0, v[76:77]
	global_load_dwordx4 v[82:85], v[90:91], off
	global_load_dwordx4 v[184:187], v[90:91], off offset:256
	v_add_u32_e32 v228, 0x90, v158
	v_ashrrev_i32_e32 v229, 31, v228
	v_lshlrev_b64 v[228:229], 10, v[228:229]
	v_lshl_add_u64 v[228:229], v[228:229], 0, v[156:157]
	v_lshlrev_b64 v[228:229], 1, v[228:229]
	v_lshl_add_u64 v[228:229], s[24:25], 0, v[228:229]
	global_load_dwordx4 v[188:191], v[228:229], off
	global_load_dwordx4 v[200:203], v[228:229], off offset:256
	v_add_u32_e32 v228, 0xa0, v158
	v_ashrrev_i32_e32 v229, 31, v228
	v_lshlrev_b64 v[228:229], 10, v[228:229]
	v_lshl_add_u64 v[228:229], v[228:229], 0, v[156:157]
	v_lshlrev_b64 v[228:229], 1, v[228:229]
	v_lshl_add_u64 v[228:229], s[24:25], 0, v[228:229]
	global_load_dwordx4 v[204:207], v[228:229], off
	global_load_dwordx4 v[208:211], v[228:229], off offset:256
	v_add_u32_e32 v228, 0xb0, v158
	v_ashrrev_i32_e32 v229, 31, v228
	v_lshlrev_b64 v[228:229], 10, v[228:229]
	v_lshl_add_u64 v[228:229], v[228:229], 0, v[156:157]
	v_lshlrev_b64 v[228:229], 1, v[228:229]
	v_lshl_add_u64 v[228:229], s[24:25], 0, v[228:229]
	global_load_dwordx4 v[212:215], v[228:229], off
	global_load_dwordx4 v[216:219], v[228:229], off offset:256
	v_add_f32_e32 v62, v62, v86
	v_add_f32_e32 v63, v63, v87
	v_add_f32_e32 v64, v64, v88
	v_add_f32_e32 v65, v65, v89
	v_add_f32_e32 v58, v58, v78
	v_add_f32_e32 v59, v59, v79
	v_add_f32_e32 v60, v60, v80
	v_add_f32_e32 v61, v61, v81
	v_lshl_add_u64 v[76:77], s[22:23], 0, v[76:77]
	v_add_f32_e32 v55, v55, v71
	v_add_f32_e32 v57, v57, v73
	v_add_f32_e32 v54, v54, v70
	v_add_f32_e32 v56, v56, v72
	v_add_f32_e32 v50, v50, v66
	v_add_f32_e32 v51, v51, v67
	v_add_f32_e32 v52, v52, v68
	v_add_f32_e32 v53, v53, v69
	s_waitcnt vmcnt(0)
	v_lshlrev_b32_e32 v92, 16, v82
	v_and_b32_e32 v82, 0xffff0000, v82
	v_lshlrev_b32_e32 v93, 16, v83
	v_and_b32_e32 v83, 0xffff0000, v83
	v_lshlrev_b32_e32 v94, 16, v84
	v_and_b32_e32 v84, 0xffff0000, v84
	v_lshlrev_b32_e32 v95, 16, v85
	v_and_b32_e32 v85, 0xffff0000, v85
	v_fmac_f32_e32 v92, s11, v62
	v_fmac_f32_e32 v82, s11, v63
	v_fmac_f32_e32 v93, s11, v64
	v_fmac_f32_e32 v83, s11, v65
	v_fmac_f32_e32 v94, s11, v58
	v_fmac_f32_e32 v84, s11, v59
	v_fmac_f32_e32 v95, s11, v60
	v_fmac_f32_e32 v85, s11, v61
	v_cvt_pk_bf16_f32 v58, v92, v82
	v_cvt_pk_bf16_f32 v59, v93, v83
	v_cvt_pk_bf16_f32 v60, v94, v84
	v_cvt_pk_bf16_f32 v61, v95, v85
	global_store_dwordx4 v[76:77], v[58:61], off
	v_mov_b32_e32 v62, v184
	v_mov_b32_e32 v63, v185
	v_mov_b32_e32 v64, v186
	v_mov_b32_e32 v65, v187
	v_lshlrev_b32_e32 v82, 16, v58
	v_and_b32_e32 v58, 0xffff0000, v58
	v_lshlrev_b32_e32 v83, 16, v59
	v_and_b32_e32 v59, 0xffff0000, v59
	v_lshlrev_b32_e32 v84, 16, v60
	v_and_b32_e32 v60, 0xffff0000, v60
	v_lshlrev_b32_e32 v85, 16, v61
	v_and_b32_e32 v61, 0xffff0000, v61
	v_mul_f32_e32 v58, v58, v58
	v_mul_f32_e32 v59, v59, v59
	v_mul_f32_e32 v60, v60, v60
	v_mul_f32_e32 v61, v61, v61
	v_fmac_f32_e32 v58, v82, v82
	v_fmac_f32_e32 v59, v83, v83
	v_fmac_f32_e32 v60, v84, v84
	v_fmac_f32_e32 v61, v85, v85
	v_add_f32_e32 v58, v58, v59
	v_add_f32_e32 v59, v60, v61
	v_add_f32_e32 v58, v58, v59
	s_nop 0
	v_lshlrev_b32_e32 v59, 16, v62
	v_and_b32_e32 v60, 0xffff0000, v62
	v_and_b32_e32 v62, 0xffff0000, v63
	v_lshlrev_b32_e32 v61, 16, v63
	v_lshlrev_b32_e32 v63, 16, v64
	v_and_b32_e32 v64, 0xffff0000, v64
	v_lshlrev_b32_e32 v82, 16, v65
	v_and_b32_e32 v65, 0xffff0000, v65
	v_fmac_f32_e32 v60, s11, v55
	v_fmac_f32_e32 v62, s11, v57
	v_fmac_f32_e32 v59, s11, v54
	v_fmac_f32_e32 v61, s11, v56
	v_fmac_f32_e32 v63, s11, v50
	v_fmac_f32_e32 v64, s11, v51
	v_fmac_f32_e32 v82, s11, v52
	v_fmac_f32_e32 v65, s11, v53
	v_cvt_pk_bf16_f32 v52, v59, v60
	v_cvt_pk_bf16_f32 v53, v61, v62
	v_cvt_pk_bf16_f32 v54, v63, v64
	v_cvt_pk_bf16_f32 v55, v82, v65
	global_store_dwordx4 v[76:77], v[52:55], off offset:256
	v_and_b32_e32 v51, 0xffff0000, v52
	v_and_b32_e32 v57, 0xffff0000, v53
	v_and_b32_e32 v60, 0xffff0000, v54
	v_and_b32_e32 v62, 0xffff0000, v55
	v_lshlrev_b32_e32 v50, 16, v52
	v_lshlrev_b32_e32 v56, 16, v53
	v_lshlrev_b32_e32 v59, 16, v54
	v_lshlrev_b32_e32 v61, 16, v55
	v_mul_f32_e32 v51, v51, v51
	v_mul_f32_e32 v57, v57, v57
	v_mul_f32_e32 v60, v60, v60
	v_mul_f32_e32 v62, v62, v62
	v_fmac_f32_e32 v51, v50, v50
	v_fmac_f32_e32 v57, v56, v56
	v_fmac_f32_e32 v60, v59, v59
	v_fmac_f32_e32 v62, v61, v61
	v_add_f32_e32 v50, v51, v57
	v_add_f32_e32 v51, v60, v62
	v_add_f32_e32 v50, v50, v51
	v_add_f32_e32 v50, v58, v50
	v_mov_b32_e32 v51, v50
	s_nop 1
	v_permlane16_swap_b32 v51, v50
	s_waitcnt lgkmcnt(0)
	v_add_f32_e32 v50, v50, v51
	v_mov_b32_e32 v51, v50
	s_nop 1
	v_permlane32_swap_b32 v51, v50
	s_and_saveexec_b64 s[8:9], s[6:7]
	s_cbranch_execz .LBB1_823
	s_waitcnt lgkmcnt(0)
	v_add_f32_e32 v52, v50, v51
	s_lshl_b32 s28, s0, 2
	v_lshlrev_b64 v[50:51], 6, v[74:75]
	s_ashr_i32 s29, s28, 31
	v_lshl_add_u64 v[50:51], s[20:21], 0, v[50:51]
	v_lshl_add_u64 v[50:51], s[28:29], 2, v[50:51]
	s_lshl_b32 s74, s45, 2
	v_lshl_add_u64 v[50:51], v[50:51], 0, s[74:75]
	global_store_dword v[50:51], v52, off
; __device__ __forceinline__ unsigned cvt_pk_bf16(float lo, float hi) { unsigned r; asm volatile("v_cvt_pk_bf16_f32 %0, %1, %2" : "=v"(r) : "v"(lo), "v"(hi)); return r; }
; __device__ __forceinline__ float bflo(unsigned w) { return __uint_as_float(w << 16); }
;     __device__ __forceinline__ void operator()(const f32x4 (&acc)[2][2][4][2], const Unit& u, int wr, int wc, int fr, int fq, LAS unsigned char* lds) const {
;     ...
;             for (int m = 0; m < 4; ++m) { const int row = row0 + ai * HALF + m * 16; const size_t off = (size_t)row * D + col0;
;                 float rs = 1.0f; if (MODE == 1) rs = rstd_of4(rss_in, row, fq);
;                 float ss = 0.f;
; #pragma unroll
;                 for (int bj = 0; bj < 2; ++bj) { const size_t o = off + bj * HALF; const u32x4 bw = *(const u32x4*)(base + o);
;                     const float bs[8] = {bflo(bw.x), bfhi(bw.x), bflo(bw.y), bfhi(bw.y), bflo(bw.z), bfhi(bw.z), bflo(bw.w), bfhi(bw.w)};
;                     float hn[8];
;                     if (MODE == 0) {
; #pragma unroll
;                         for (int n = 0; n < 2; ++n)
; #pragma unroll
;                             for (int e = 0; e < 4; ++e) hn[4 * n + e] = bs[4 * n + e] + (acc[ai][bj][m][n][e] + bv[bj][n][e]) * scale;
;                     } else { const u32x4 pw = *(const u32x4*)(pp + o);
;                         const float pv[8] = {bflo(pw.x), bfhi(pw.x), bflo(pw.y), bfhi(pw.y), bflo(pw.z), bfhi(pw.z), bflo(pw.w), bfhi(pw.w)};
; #pragma unroll
;                         for (int n = 0; n < 2; ++n)
; #pragma unroll
;                             for (int e = 0; e < 4; ++e) hn[4 * n + e] = bs[4 * n + e] + fast_sigmoid(acc[ai][bj][m][n][e] * rs) * pv[4 * n + e]; }
;                     u32x4 w; w.x = cvt_pk_bf16(hn[0], hn[1]); w.y = cvt_pk_bf16(hn[2], hn[3]); w.z = cvt_pk_bf16(hn[4], hn[5]); w.w = cvt_pk_bf16(hn[6], hn[7]); *(u32x4*)(hb + o) = w;
;                     const float hr[8] = {bflo(w.x), bfhi(w.x), bflo(w.y), bfhi(w.y), bflo(w.z), bfhi(w.z), bflo(w.w), bfhi(w.w)};
;                     ss += ((hr[0] * hr[0] + hr[1] * hr[1]) + (hr[2] * hr[2] + hr[3] * hr[3])) + ((hr[4] * hr[4] + hr[5] * hr[5]) + (hr[6] * hr[6] + hr[7] * hr[7])); }
;                 ss += __shfl_xor(ss, 16); ss += __shfl_xor(ss, 32);
;                 if (fq == 0) rss_out[(size_t)row * 16 + u.pn * 4 + wc] = ss; }
.LBB1_823:
	s_or_b64 exec, exec, s[8:9]
	v_add_u32_e32 v50, 0x90, v158
	s_waitcnt lgkmcnt(0)
	v_ashrrev_i32_e32 v51, 31, v50
	v_lshlrev_b64 v[52:53], 10, v[50:51]
	v_lshl_add_u64 v[52:53], v[52:53], 0, v[156:157]
	v_lshlrev_b64 v[56:57], 1, v[52:53]
	v_lshl_add_u64 v[58:59], s[24:25], 0, v[56:57]
	v_mov_b32_e32 v52, v188
	v_mov_b32_e32 v53, v189
	v_mov_b32_e32 v54, v190
	v_mov_b32_e32 v55, v191
	v_add_f32_e32 v46, v46, v86
	v_add_f32_e32 v47, v47, v87
	v_add_f32_e32 v48, v48, v88
	v_add_f32_e32 v49, v49, v89
	v_add_f32_e32 v42, v42, v78
	v_add_f32_e32 v43, v43, v79
	v_add_f32_e32 v44, v44, v80
	v_add_f32_e32 v45, v45, v81
	v_lshl_add_u64 v[56:57], s[22:23], 0, v[56:57]
	v_add_f32_e32 v39, v39, v71
	v_add_f32_e32 v41, v41, v73
	v_add_f32_e32 v38, v38, v70
	v_add_f32_e32 v40, v40, v72
	v_add_f32_e32 v34, v34, v66
	v_add_f32_e32 v35, v35, v67
	v_add_f32_e32 v36, v36, v68
	v_add_f32_e32 v37, v37, v69
	s_nop 0
	v_lshlrev_b32_e32 v60, 16, v52
	v_and_b32_e32 v52, 0xffff0000, v52
	v_lshlrev_b32_e32 v61, 16, v53
	v_and_b32_e32 v53, 0xffff0000, v53
	v_lshlrev_b32_e32 v62, 16, v54
	v_and_b32_e32 v54, 0xffff0000, v54
	v_lshlrev_b32_e32 v63, 16, v55
	v_and_b32_e32 v55, 0xffff0000, v55
	v_fmac_f32_e32 v60, s11, v46
	v_fmac_f32_e32 v52, s11, v47
	v_fmac_f32_e32 v61, s11, v48
	v_fmac_f32_e32 v53, s11, v49
	v_fmac_f32_e32 v62, s11, v42
	v_fmac_f32_e32 v54, s11, v43
	v_fmac_f32_e32 v63, s11, v44
	v_fmac_f32_e32 v55, s11, v45
	v_cvt_pk_bf16_f32 v42, v60, v52
	v_cvt_pk_bf16_f32 v43, v61, v53
	v_cvt_pk_bf16_f32 v44, v62, v54
	v_cvt_pk_bf16_f32 v45, v63, v55
	global_store_dwordx4 v[56:57], v[42:45], off
	v_mov_b32_e32 v46, v200
	v_mov_b32_e32 v47, v201
	v_mov_b32_e32 v48, v202
	v_mov_b32_e32 v49, v203
	v_lshlrev_b32_e32 v52, 16, v42
	v_and_b32_e32 v42, 0xffff0000, v42
	v_lshlrev_b32_e32 v53, 16, v43
	v_and_b32_e32 v43, 0xffff0000, v43
	v_lshlrev_b32_e32 v54, 16, v44
	v_and_b32_e32 v44, 0xffff0000, v44
	v_lshlrev_b32_e32 v55, 16, v45
	v_and_b32_e32 v45, 0xffff0000, v45
	v_mul_f32_e32 v42, v42, v42
	v_mul_f32_e32 v43, v43, v43
	v_mul_f32_e32 v44, v44, v44
	v_mul_f32_e32 v45, v45, v45
	v_fmac_f32_e32 v42, v52, v52
	v_fmac_f32_e32 v43, v53, v53
	v_fmac_f32_e32 v44, v54, v54
	v_fmac_f32_e32 v45, v55, v55
	v_add_f32_e32 v42, v42, v43
	v_add_f32_e32 v43, v44, v45
	v_add_f32_e32 v42, v42, v43
	s_nop 0
	v_lshlrev_b32_e32 v43, 16, v46
	v_and_b32_e32 v44, 0xffff0000, v46
	v_and_b32_e32 v46, 0xffff0000, v47
	v_lshlrev_b32_e32 v45, 16, v47
	v_lshlrev_b32_e32 v47, 16, v48
	v_and_b32_e32 v48, 0xffff0000, v48
	v_lshlrev_b32_e32 v52, 16, v49
	v_and_b32_e32 v49, 0xffff0000, v49
	v_fmac_f32_e32 v44, s11, v39
	v_fmac_f32_e32 v46, s11, v41
	v_fmac_f32_e32 v43, s11, v38
	v_fmac_f32_e32 v45, s11, v40
	v_fmac_f32_e32 v47, s11, v34
	v_fmac_f32_e32 v48, s11, v35
	v_fmac_f32_e32 v52, s11, v36
	v_fmac_f32_e32 v49, s11, v37
	v_cvt_pk_bf16_f32 v36, v43, v44
	v_cvt_pk_bf16_f32 v37, v45, v46
	v_cvt_pk_bf16_f32 v38, v47, v48
	v_cvt_pk_bf16_f32 v39, v52, v49
	global_store_dwordx4 v[56:57], v[36:39], off offset:256
	v_and_b32_e32 v35, 0xffff0000, v36
	v_and_b32_e32 v41, 0xffff0000, v37
	v_and_b32_e32 v44, 0xffff0000, v38
	v_and_b32_e32 v46, 0xffff0000, v39
	v_lshlrev_b32_e32 v34, 16, v36
	v_lshlrev_b32_e32 v40, 16, v37
	v_lshlrev_b32_e32 v43, 16, v38
	v_lshlrev_b32_e32 v45, 16, v39
	v_mul_f32_e32 v35, v35, v35
	v_mul_f32_e32 v41, v41, v41
	v_mul_f32_e32 v44, v44, v44
	v_mul_f32_e32 v46, v46, v46
	v_fmac_f32_e32 v35, v34, v34
	v_fmac_f32_e32 v41, v40, v40
	v_fmac_f32_e32 v44, v43, v43
	v_fmac_f32_e32 v46, v45, v45
	v_add_f32_e32 v34, v35, v41
	v_add_f32_e32 v35, v44, v46
	v_add_f32_e32 v34, v34, v35
	v_add_f32_e32 v34, v42, v34
	v_mov_b32_e32 v35, v34
	s_nop 1
	v_permlane16_swap_b32 v35, v34
	s_waitcnt lgkmcnt(0)
	v_add_f32_e32 v34, v34, v35
	v_mov_b32_e32 v35, v34
	s_nop 1
	v_permlane32_swap_b32 v35, v34
	s_and_saveexec_b64 s[8:9], s[6:7]
	s_cbranch_execz .LBB1_825
	s_waitcnt lgkmcnt(0)
	v_add_f32_e32 v36, v34, v35
	s_lshl_b32 s28, s0, 2
	v_lshlrev_b64 v[34:35], 6, v[50:51]
	s_ashr_i32 s29, s28, 31
	v_lshl_add_u64 v[34:35], s[20:21], 0, v[34:35]
	v_lshl_add_u64 v[34:35], s[28:29], 2, v[34:35]
	s_lshl_b32 s74, s45, 2
	v_lshl_add_u64 v[34:35], v[34:35], 0, s[74:75]
	global_store_dword v[34:35], v36, off
.LBB1_825:
	s_or_b64 exec, exec, s[8:9]
	v_add_u32_e32 v34, 0xa0, v158
	s_waitcnt lgkmcnt(0)
; __device__ __forceinline__ unsigned cvt_pk_bf16(float lo, float hi) { unsigned r; asm volatile("v_cvt_pk_bf16_f32 %0, %1, %2" : "=v"(r) : "v"(lo), "v"(hi)); return r; }
; __device__ __forceinline__ float bflo(unsigned w) { return __uint_as_float(w << 16); }
;     __device__ __forceinline__ void operator()(const f32x4 (&acc)[2][2][4][2], const Unit& u, int wr, int wc, int fr, int fq, LAS unsigned char* lds) const {
;     ...
;             for (int m = 0; m < 4; ++m) { const int row = row0 + ai * HALF + m * 16; const size_t off = (size_t)row * D + col0;
;                 float rs = 1.0f; if (MODE == 1) rs = rstd_of4(rss_in, row, fq);
;                 float ss = 0.f;
; #pragma unroll
;                 for (int bj = 0; bj < 2; ++bj) { const size_t o = off + bj * HALF; const u32x4 bw = *(const u32x4*)(base + o);
;                     const float bs[8] = {bflo(bw.x), bfhi(bw.x), bflo(bw.y), bfhi(bw.y), bflo(bw.z), bfhi(bw.z), bflo(bw.w), bfhi(bw.w)};
;                     float hn[8];
;                     if (MODE == 0) {
; #pragma unroll
;                         for (int n = 0; n < 2; ++n)
; #pragma unroll
;                             for (int e = 0; e < 4; ++e) hn[4 * n + e] = bs[4 * n + e] + (acc[ai][bj][m][n][e] + bv[bj][n][e]) * scale;
;                     } else { const u32x4 pw = *(const u32x4*)(pp + o);
;                         const float pv[8] = {bflo(pw.x), bfhi(pw.x), bflo(pw.y), bfhi(pw.y), bflo(pw.z), bfhi(pw.z), bflo(pw.w), bfhi(pw.w)};
; #pragma unroll
;                         for (int n = 0; n < 2; ++n)
; #pragma unroll
;                             for (int e = 0; e < 4; ++e) hn[4 * n + e] = bs[4 * n + e] + fast_sigmoid(acc[ai][bj][m][n][e] * rs) * pv[4 * n + e]; }
;                     u32x4 w; w.x = cvt_pk_bf16(hn[0], hn[1]); w.y = cvt_pk_bf16(hn[2], hn[3]); w.z = cvt_pk_bf16(hn[4], hn[5]); w.w = cvt_pk_bf16(hn[6], hn[7]); *(u32x4*)(hb + o) = w;
;                     const float hr[8] = {bflo(w.x), bfhi(w.x), bflo(w.y), bfhi(w.y), bflo(w.z), bfhi(w.z), bflo(w.w), bfhi(w.w)};
;                     ss += ((hr[0] * hr[0] + hr[1] * hr[1]) + (hr[2] * hr[2] + hr[3] * hr[3])) + ((hr[4] * hr[4] + hr[5] * hr[5]) + (hr[6] * hr[6] + hr[7] * hr[7])); }
;                 ss += __shfl_xor(ss, 16); ss += __shfl_xor(ss, 32);
;                 if (fq == 0) rss_out[(size_t)row * 16 + u.pn * 4 + wc] = ss; }
	v_ashrrev_i32_e32 v35, 31, v34
	v_lshlrev_b64 v[36:37], 10, v[34:35]
	v_lshl_add_u64 v[36:37], v[36:37], 0, v[156:157]
	v_lshlrev_b64 v[40:41], 1, v[36:37]
	v_lshl_add_u64 v[42:43], s[24:25], 0, v[40:41]
	v_mov_b32_e32 v36, v204
	v_mov_b32_e32 v37, v205
	v_mov_b32_e32 v38, v206
	v_mov_b32_e32 v39, v207
	v_add_f32_e32 v30, v30, v86
	v_add_f32_e32 v31, v31, v87
	v_add_f32_e32 v32, v32, v88
	v_add_f32_e32 v33, v33, v89
	v_add_f32_e32 v26, v26, v78
	v_add_f32_e32 v27, v27, v79
	v_add_f32_e32 v28, v28, v80
	v_add_f32_e32 v29, v29, v81
	v_lshl_add_u64 v[40:41], s[22:23], 0, v[40:41]
	v_add_f32_e32 v23, v23, v71
	v_add_f32_e32 v25, v25, v73
	v_add_f32_e32 v22, v22, v70
	v_add_f32_e32 v24, v24, v72
	v_add_f32_e32 v18, v18, v66
	v_add_f32_e32 v19, v19, v67
	v_add_f32_e32 v20, v20, v68
	v_add_f32_e32 v21, v21, v69
	s_nop 0
	v_lshlrev_b32_e32 v44, 16, v36
	v_and_b32_e32 v36, 0xffff0000, v36
	v_lshlrev_b32_e32 v45, 16, v37
	v_and_b32_e32 v37, 0xffff0000, v37
	v_lshlrev_b32_e32 v46, 16, v38
	v_and_b32_e32 v38, 0xffff0000, v38
	v_lshlrev_b32_e32 v47, 16, v39
	v_and_b32_e32 v39, 0xffff0000, v39
	v_fmac_f32_e32 v44, s11, v30
	v_fmac_f32_e32 v36, s11, v31
	v_fmac_f32_e32 v45, s11, v32
	v_fmac_f32_e32 v37, s11, v33
	v_fmac_f32_e32 v46, s11, v26
	v_fmac_f32_e32 v38, s11, v27
	v_fmac_f32_e32 v47, s11, v28
	v_fmac_f32_e32 v39, s11, v29
	v_cvt_pk_bf16_f32 v26, v44, v36
	v_cvt_pk_bf16_f32 v27, v45, v37
	v_cvt_pk_bf16_f32 v28, v46, v38
	v_cvt_pk_bf16_f32 v29, v47, v39
	global_store_dwordx4 v[40:41], v[26:29], off
	v_mov_b32_e32 v30, v208
	v_mov_b32_e32 v31, v209
	v_mov_b32_e32 v32, v210
	v_mov_b32_e32 v33, v211
	v_lshlrev_b32_e32 v36, 16, v26
	v_and_b32_e32 v26, 0xffff0000, v26
	v_lshlrev_b32_e32 v37, 16, v27
	v_and_b32_e32 v27, 0xffff0000, v27
	v_lshlrev_b32_e32 v38, 16, v28
	v_and_b32_e32 v28, 0xffff0000, v28
	v_lshlrev_b32_e32 v39, 16, v29
	v_and_b32_e32 v29, 0xffff0000, v29
	v_mul_f32_e32 v26, v26, v26
	v_mul_f32_e32 v27, v27, v27
	v_mul_f32_e32 v28, v28, v28
	v_mul_f32_e32 v29, v29, v29
	v_fmac_f32_e32 v26, v36, v36
	v_fmac_f32_e32 v27, v37, v37
	v_fmac_f32_e32 v28, v38, v38
	v_fmac_f32_e32 v29, v39, v39
	v_add_f32_e32 v26, v26, v27
	v_add_f32_e32 v27, v28, v29
	v_add_f32_e32 v26, v26, v27
	s_nop 0
	v_lshlrev_b32_e32 v27, 16, v30
	v_and_b32_e32 v28, 0xffff0000, v30
	v_and_b32_e32 v30, 0xffff0000, v31
	v_lshlrev_b32_e32 v29, 16, v31
	v_lshlrev_b32_e32 v31, 16, v32
	v_and_b32_e32 v32, 0xffff0000, v32
	v_lshlrev_b32_e32 v36, 16, v33
	v_and_b32_e32 v33, 0xffff0000, v33
	v_fmac_f32_e32 v28, s11, v23
	v_fmac_f32_e32 v30, s11, v25
	v_fmac_f32_e32 v27, s11, v22
	v_fmac_f32_e32 v29, s11, v24
	v_fmac_f32_e32 v31, s11, v18
	v_fmac_f32_e32 v32, s11, v19
	v_fmac_f32_e32 v36, s11, v20
	v_fmac_f32_e32 v33, s11, v21
	v_cvt_pk_bf16_f32 v20, v27, v28
	v_cvt_pk_bf16_f32 v21, v29, v30
	v_cvt_pk_bf16_f32 v22, v31, v32
	v_cvt_pk_bf16_f32 v23, v36, v33
	global_store_dwordx4 v[40:41], v[20:23], off offset:256
	v_and_b32_e32 v19, 0xffff0000, v20
	v_and_b32_e32 v25, 0xffff0000, v21
	v_and_b32_e32 v28, 0xffff0000, v22
	v_and_b32_e32 v30, 0xffff0000, v23
	v_lshlrev_b32_e32 v18, 16, v20
	v_lshlrev_b32_e32 v24, 16, v21
	v_lshlrev_b32_e32 v27, 16, v22
	v_lshlrev_b32_e32 v29, 16, v23
	v_mul_f32_e32 v19, v19, v19
	v_mul_f32_e32 v25, v25, v25
	v_mul_f32_e32 v28, v28, v28
	v_mul_f32_e32 v30, v30, v30
	v_fmac_f32_e32 v19, v18, v18
	v_fmac_f32_e32 v25, v24, v24
	v_fmac_f32_e32 v28, v27, v27
	v_fmac_f32_e32 v30, v29, v29
	v_add_f32_e32 v18, v19, v25
	v_add_f32_e32 v19, v28, v30
	v_add_f32_e32 v18, v18, v19
	v_add_f32_e32 v18, v26, v18
	v_mov_b32_e32 v19, v18
	s_nop 1
	v_permlane16_swap_b32 v19, v18
	s_waitcnt lgkmcnt(0)
	v_add_f32_e32 v18, v18, v19
	v_mov_b32_e32 v19, v18
	s_nop 1
	v_permlane32_swap_b32 v19, v18
	s_and_saveexec_b64 s[8:9], s[6:7]
	s_cbranch_execz .LBB1_827
	s_waitcnt lgkmcnt(0)
	v_add_f32_e32 v20, v18, v19
	s_lshl_b32 s28, s0, 2
	v_lshlrev_b64 v[18:19], 6, v[34:35]
	s_ashr_i32 s29, s28, 31
	v_lshl_add_u64 v[18:19], s[20:21], 0, v[18:19]
	v_lshl_add_u64 v[18:19], s[28:29], 2, v[18:19]
	s_lshl_b32 s74, s45, 2
	v_lshl_add_u64 v[18:19], v[18:19], 0, s[74:75]
	global_store_dword v[18:19], v20, off
; __device__ __forceinline__ unsigned cvt_pk_bf16(float lo, float hi) { unsigned r; asm volatile("v_cvt_pk_bf16_f32 %0, %1, %2" : "=v"(r) : "v"(lo), "v"(hi)); return r; }
; __device__ __forceinline__ float bflo(unsigned w) { return __uint_as_float(w << 16); }
;     __device__ __forceinline__ void operator()(const f32x4 (&acc)[2][2][4][2], const Unit& u, int wr, int wc, int fr, int fq, LAS unsigned char* lds) const {
;     ...
;             for (int m = 0; m < 4; ++m) { const int row = row0 + ai * HALF + m * 16; const size_t off = (size_t)row * D + col0;
;                 float rs = 1.0f; if (MODE == 1) rs = rstd_of4(rss_in, row, fq);
;                 float ss = 0.f;
; #pragma unroll
;                 for (int bj = 0; bj < 2; ++bj) { const size_t o = off + bj * HALF; const u32x4 bw = *(const u32x4*)(base + o);
;                     const float bs[8] = {bflo(bw.x), bfhi(bw.x), bflo(bw.y), bfhi(bw.y), bflo(bw.z), bfhi(bw.z), bflo(bw.w), bfhi(bw.w)};
;                     float hn[8];
;                     if (MODE == 0) {
; #pragma unroll
;                         for (int n = 0; n < 2; ++n)
; #pragma unroll
;                             for (int e = 0; e < 4; ++e) hn[4 * n + e] = bs[4 * n + e] + (acc[ai][bj][m][n][e] + bv[bj][n][e]) * scale;
;                     } else { const u32x4 pw = *(const u32x4*)(pp + o);
;                         const float pv[8] = {bflo(pw.x), bfhi(pw.x), bflo(pw.y), bfhi(pw.y), bflo(pw.z), bfhi(pw.z), bflo(pw.w), bfhi(pw.w)};
; #pragma unroll
;                         for (int n = 0; n < 2; ++n)
; #pragma unroll
;                             for (int e = 0; e < 4; ++e) hn[4 * n + e] = bs[4 * n + e] + fast_sigmoid(acc[ai][bj][m][n][e] * rs) * pv[4 * n + e]; }
;                     u32x4 w; w.x = cvt_pk_bf16(hn[0], hn[1]); w.y = cvt_pk_bf16(hn[2], hn[3]); w.z = cvt_pk_bf16(hn[4], hn[5]); w.w = cvt_pk_bf16(hn[6], hn[7]); *(u32x4*)(hb + o) = w;
;                     const float hr[8] = {bflo(w.x), bfhi(w.x), bflo(w.y), bfhi(w.y), bflo(w.z), bfhi(w.z), bflo(w.w), bfhi(w.w)};
;                     ss += ((hr[0] * hr[0] + hr[1] * hr[1]) + (hr[2] * hr[2] + hr[3] * hr[3])) + ((hr[4] * hr[4] + hr[5] * hr[5]) + (hr[6] * hr[6] + hr[7] * hr[7])); }
;                 ss += __shfl_xor(ss, 16); ss += __shfl_xor(ss, 32);
;                 if (fq == 0) rss_out[(size_t)row * 16 + u.pn * 4 + wc] = ss; }
.LBB1_827:
	s_or_b64 exec, exec, s[8:9]
	v_add_u32_e32 v18, 0xb0, v158
	s_waitcnt lgkmcnt(0)
	v_ashrrev_i32_e32 v19, 31, v18
	v_lshlrev_b64 v[20:21], 10, v[18:19]
	v_lshl_add_u64 v[20:21], v[20:21], 0, v[156:157]
	v_lshlrev_b64 v[24:25], 1, v[20:21]
	v_lshl_add_u64 v[26:27], s[24:25], 0, v[24:25]
	v_mov_b32_e32 v20, v212
	v_mov_b32_e32 v21, v213
	v_mov_b32_e32 v22, v214
	v_mov_b32_e32 v23, v215
	v_add_f32_e32 v14, v14, v86
	v_add_f32_e32 v15, v15, v87
	v_add_f32_e32 v16, v16, v88
	v_add_f32_e32 v17, v17, v89
	v_add_f32_e32 v10, v10, v78
	v_add_f32_e32 v11, v11, v79
	v_add_f32_e32 v12, v12, v80
	v_add_f32_e32 v13, v13, v81
	v_lshl_add_u64 v[24:25], s[22:23], 0, v[24:25]
	v_add_f32_e32 v7, v7, v71
	v_add_f32_e32 v9, v9, v73
	v_add_f32_e32 v6, v6, v70
	v_add_f32_e32 v8, v8, v72
	v_add_f32_e32 v0, v0, v66
	v_add_f32_e32 v1, v1, v67
	v_add_f32_e32 v2, v2, v68
	v_add_f32_e32 v3, v3, v69
	s_nop 0
	v_lshlrev_b32_e32 v28, 16, v20
	v_and_b32_e32 v20, 0xffff0000, v20
	v_lshlrev_b32_e32 v29, 16, v21
	v_and_b32_e32 v21, 0xffff0000, v21
	v_lshlrev_b32_e32 v30, 16, v22
	v_and_b32_e32 v22, 0xffff0000, v22
	v_lshlrev_b32_e32 v31, 16, v23
	v_and_b32_e32 v23, 0xffff0000, v23
	v_fmac_f32_e32 v28, s11, v14
	v_fmac_f32_e32 v20, s11, v15
	v_fmac_f32_e32 v29, s11, v16
	v_fmac_f32_e32 v21, s11, v17
	v_fmac_f32_e32 v30, s11, v10
	v_fmac_f32_e32 v22, s11, v11
	v_fmac_f32_e32 v31, s11, v12
	v_fmac_f32_e32 v23, s11, v13
	v_cvt_pk_bf16_f32 v10, v28, v20
	v_cvt_pk_bf16_f32 v11, v29, v21
	v_cvt_pk_bf16_f32 v12, v30, v22
	v_cvt_pk_bf16_f32 v13, v31, v23
	global_store_dwordx4 v[24:25], v[10:13], off
	v_mov_b32_e32 v14, v216
	v_mov_b32_e32 v15, v217
	v_mov_b32_e32 v16, v218
	v_mov_b32_e32 v17, v219
	v_lshlrev_b32_e32 v20, 16, v10
	v_and_b32_e32 v10, 0xffff0000, v10
	v_lshlrev_b32_e32 v21, 16, v11
	v_and_b32_e32 v11, 0xffff0000, v11
	v_lshlrev_b32_e32 v22, 16, v12
	v_and_b32_e32 v12, 0xffff0000, v12
	v_lshlrev_b32_e32 v23, 16, v13
	v_and_b32_e32 v13, 0xffff0000, v13
	v_mul_f32_e32 v10, v10, v10
	v_mul_f32_e32 v11, v11, v11
	v_mul_f32_e32 v12, v12, v12
	v_mul_f32_e32 v13, v13, v13
	v_fmac_f32_e32 v10, v20, v20
	v_fmac_f32_e32 v11, v21, v21
	v_fmac_f32_e32 v12, v22, v22
	v_fmac_f32_e32 v13, v23, v23
	v_add_f32_e32 v10, v10, v11
	v_add_f32_e32 v11, v12, v13
	v_add_f32_e32 v10, v10, v11
	s_nop 0
	v_lshlrev_b32_e32 v11, 16, v14
	v_and_b32_e32 v12, 0xffff0000, v14
	v_and_b32_e32 v14, 0xffff0000, v15
	v_lshlrev_b32_e32 v13, 16, v15
	v_lshlrev_b32_e32 v15, 16, v16
	v_and_b32_e32 v16, 0xffff0000, v16
	v_lshlrev_b32_e32 v20, 16, v17
	v_and_b32_e32 v17, 0xffff0000, v17
	v_fmac_f32_e32 v12, s11, v7
	v_fmac_f32_e32 v14, s11, v9
	v_fmac_f32_e32 v11, s11, v6
	v_fmac_f32_e32 v13, s11, v8
	v_fmac_f32_e32 v15, s11, v0
	v_fmac_f32_e32 v16, s11, v1
	v_fmac_f32_e32 v20, s11, v2
	v_fmac_f32_e32 v17, s11, v3
	v_cvt_pk_bf16_f32 v6, v11, v12
	v_cvt_pk_bf16_f32 v7, v13, v14
	v_cvt_pk_bf16_f32 v8, v15, v16
	v_cvt_pk_bf16_f32 v9, v20, v17
	global_store_dwordx4 v[24:25], v[6:9], off offset:256
	v_and_b32_e32 v1, 0xffff0000, v6
	v_and_b32_e32 v3, 0xffff0000, v7
	v_and_b32_e32 v12, 0xffff0000, v8
	v_and_b32_e32 v14, 0xffff0000, v9
	v_lshlrev_b32_e32 v0, 16, v6
	v_lshlrev_b32_e32 v2, 16, v7
	v_lshlrev_b32_e32 v11, 16, v8
	v_lshlrev_b32_e32 v13, 16, v9
	v_mul_f32_e32 v1, v1, v1
	v_mul_f32_e32 v3, v3, v3
	v_mul_f32_e32 v12, v12, v12
	v_mul_f32_e32 v14, v14, v14
	v_fmac_f32_e32 v1, v0, v0
	v_fmac_f32_e32 v3, v2, v2
	v_fmac_f32_e32 v12, v11, v11
	v_fmac_f32_e32 v14, v13, v13
	v_add_f32_e32 v0, v1, v3
	v_add_f32_e32 v1, v12, v14
	v_add_f32_e32 v0, v0, v1
	v_add_f32_e32 v0, v10, v0
	v_mov_b32_e32 v1, v0
	s_nop 1
	v_permlane16_swap_b32 v1, v0
	s_waitcnt lgkmcnt(0)
	v_add_f32_e32 v0, v0, v1
	v_mov_b32_e32 v1, v0
	s_nop 1
	v_permlane32_swap_b32 v1, v0
	s_and_saveexec_b64 s[8:9], s[6:7]
	s_cbranch_execz .LBB1_800
	s_waitcnt lgkmcnt(0)
	v_add_f32_e32 v2, v0, v1
	s_lshl_b32 s22, s0, 2
	v_lshlrev_b64 v[0:1], 6, v[18:19]
	s_ashr_i32 s23, s22, 31
	v_lshl_add_u64 v[0:1], s[20:21], 0, v[0:1]
	v_lshl_add_u64 v[0:1], s[22:23], 2, v[0:1]
	s_lshl_b32 s74, s45, 2
	v_lshl_add_u64 v[0:1], v[0:1], 0, s[74:75]
	global_store_dword v[0:1], v2, off
	s_branch .LBB1_800

; #define PG8_STAGE(bufoff, gbase, voff) do { _Pragma("unroll") for (int _i = 0; _i < 2; ++_i) \
;         __builtin_amdgcn_global_load_lds((const unsigned*)((const char*)(gbase) + (voff)[_i]), (LAS unsigned*)(lds + (bufoff) + ldsw + _i * 8192), 16, 0, 0); } while (0)
; #define PG8_LDA(dst, b, h) do { _Pragma("unroll") for (int m = 0; m < 4; ++m) _Pragma("unroll") for (int k = 0; k < 2; ++k) dst[m][k] = *(const LAS bf16x8*)(lds + PG8_SA(b, h) + aoff + m * 2048 + k * 1024); } while (0)
; #define PG8_LDB(dst, b, h) do { _Pragma("unroll") for (int n = 0; n < 2; ++n) _Pragma("unroll") for (int k = 0; k < 2; ++k) dst[n][k] = *(const LAS bf16x8*)(lds + PG8_SB(b, h) + boff + n * 2048 + k * 1024); } while (0)
; #define PG8_MMA(ai, bj, At, Bt) do { __builtin_amdgcn_s_setprio(1); _Pragma("unroll") for (int m = 0; m < 4; ++m) _Pragma("unroll") for (int n = 0; n < 2; ++n) _Pragma("unroll") for (int k = 0; k < 2; ++k) \
;         acc[ai][bj][m][n] = __builtin_amdgcn_mfma_f32_16x16x32_bf16(Bt[n][k], At[m][k], acc[ai][bj][m][n], 0, 0, 0); __builtin_amdgcn_s_setprio(0); } while (0)
; #define PG8_WAIT_L(n) asm volatile("s_waitcnt lgkmcnt(" #n ")" ::: "memory")
; #define PG8_BAR __builtin_amdgcn_s_barrier()
; #define PG8_SCHED __builtin_amdgcn_sched_barrier(0)
; template <class Epi, int KK, int LDA, int LDB, int NN, bool AGRP>
; __device__ __forceinline__ void gemm_phase(LAS unsigned char* lds, const bf16_t* gA, const bf16_t* gBt, int G_, int bid_, int tid) {
;     ...
;             const bool last = (t == nt - 2);
;             const char* a1 = cA + (size_t)(t + 1) * kstep;
;             const char* a2 = last ? nA : cA + (size_t)(t + 2) * kstep; const char* b2 = last ? nB : cB + (size_t)(t + 2) * kstep;
;             const char* a3 = a2 + kstep; const char* b3 = b2 + kstep;
;             PG8_LDB(B0, 0, 0); PG8_SCHED; PG8_LDA(At, 0, 0); PG8_STAGE(PG8_SA(1, 1), a1 + hstepA, voffA);
;             PG8_WAIT_L(8); PG8_BAR; PG8_WAIT_L(0); PG8_MMA(0, 0, At, B0); PG8_BAR; PG8_SCHED;
;     ...
; #pragma unroll
;         for (int a = 0; a < 2; ++a)
; #pragma unroll
;             for (int b = 0; b < 2; ++b)
; #pragma unroll
;                 for (int m = 0; m < 4; ++m)
; #pragma unroll
;                     for (int n = 0; n < 2; ++n) acc[a][b][m][n] = (f32x4){zr, zr, zr, zr};
;         cur = nxt; cA = nA; cB = nB; ++ui;
.LBB1_842:
	s_ashr_i32 s7, s6, 31
	s_lshl_b64 s[12:13], s[6:7], 19
	s_add_u32 s12, s26, s12
	s_addc_u32 s13, s25, s13
	s_and_b64 s[14:15], s[22:23], exec
	s_cselect_b32 s7, s13, s21
	s_cselect_b32 s53, s12, s20
	s_ashr_i32 s9, s8, 31
	s_lshl_b64 s[14:15], s[8:9], 19
	s_add_u32 s14, s27, s14
	s_addc_u32 s15, s28, s15
	s_and_b64 s[22:23], s[22:23], exec
	s_cselect_b32 s9, s15, s19
	s_cselect_b32 s54, s14, s18
	s_add_u32 s55, s18, 0x100
	s_addc_u32 s56, s19, 0
	s_add_u32 s18, s20, 0x40080
	s_addc_u32 s19, s21, 0
	s_mov_b32 s57, -2
	v_mov_b32_e32 v0, v149
	v_mov_b32_e32 v1, v149
	v_mov_b32_e32 v2, v149
	v_mov_b32_e32 v3, v149
	v_mov_b32_e32 v10, v149
	v_mov_b32_e32 v11, v149
	v_mov_b32_e32 v12, v149
	v_mov_b32_e32 v13, v149
	v_mov_b32_e32 v18, v149
	v_mov_b32_e32 v19, v149
	v_mov_b32_e32 v20, v149
	v_mov_b32_e32 v21, v149
	v_mov_b32_e32 v26, v149
	v_mov_b32_e32 v27, v149
	v_mov_b32_e32 v28, v149
	v_mov_b32_e32 v29, v149
	v_mov_b32_e32 v34, v149
	v_mov_b32_e32 v35, v149
	v_mov_b32_e32 v36, v149
	v_mov_b32_e32 v37, v149
	v_mov_b32_e32 v42, v149
	v_mov_b32_e32 v43, v149
	v_mov_b32_e32 v44, v149
	v_mov_b32_e32 v45, v149
	v_mov_b32_e32 v50, v149
	v_mov_b32_e32 v51, v149
	v_mov_b32_e32 v52, v149
	v_mov_b32_e32 v53, v149
	v_mov_b32_e32 v58, v149
	v_mov_b32_e32 v59, v149
	v_mov_b32_e32 v60, v149
	v_mov_b32_e32 v61, v149
	v_mov_b32_e32 v6, v149
	v_mov_b32_e32 v7, v149
	v_mov_b32_e32 v8, v149
	v_mov_b32_e32 v9, v149
	v_mov_b32_e32 v14, v149
	v_mov_b32_e32 v15, v149
	v_mov_b32_e32 v16, v149
	v_mov_b32_e32 v17, v149
	v_mov_b32_e32 v22, v149
	v_mov_b32_e32 v23, v149
	v_mov_b32_e32 v24, v149
	v_mov_b32_e32 v25, v149
	v_mov_b32_e32 v30, v149
	v_mov_b32_e32 v31, v149
	v_mov_b32_e32 v32, v149
	v_mov_b32_e32 v33, v149
	v_mov_b32_e32 v38, v149
	v_mov_b32_e32 v39, v149
	v_mov_b32_e32 v40, v149
	v_mov_b32_e32 v41, v149
	v_mov_b32_e32 v46, v149
	v_mov_b32_e32 v47, v149
	v_mov_b32_e32 v48, v149
	v_mov_b32_e32 v49, v149
	v_mov_b32_e32 v54, v149
	v_mov_b32_e32 v55, v149
	v_mov_b32_e32 v56, v149
	v_mov_b32_e32 v57, v149
	v_mov_b32_e32 v62, v149
	v_mov_b32_e32 v63, v149
	v_mov_b32_e32 v64, v149
	v_mov_b32_e32 v65, v149
	v_mov_b32_e32 v66, v149
	v_mov_b32_e32 v67, v149
	v_mov_b32_e32 v68, v149
	v_mov_b32_e32 v69, v149
	v_mov_b32_e32 v74, v149
	v_mov_b32_e32 v75, v149
	v_mov_b32_e32 v76, v149
	v_mov_b32_e32 v77, v149
	s_nop 0
	v_mov_b32_e32 v82, v149
	v_mov_b32_e32 v83, v149
	v_mov_b32_e32 v84, v149
	v_mov_b32_e32 v85, v149
	v_mov_b32_e32 v90, v149
	v_mov_b32_e32 v91, v149
	v_mov_b32_e32 v92, v149
	v_mov_b32_e32 v93, v149
	v_mov_b32_e32 v98, v149
	v_mov_b32_e32 v99, v149
	v_mov_b32_e32 v100, v149
	v_mov_b32_e32 v101, v149
	v_mov_b32_e32 v106, v149
	v_mov_b32_e32 v107, v149
	v_mov_b32_e32 v108, v149
	v_mov_b32_e32 v109, v149
	v_mov_b32_e32 v114, v149
	v_mov_b32_e32 v115, v149
	v_mov_b32_e32 v116, v149
	v_mov_b32_e32 v117, v149
	v_mov_b32_e32 v122, v149
	v_mov_b32_e32 v123, v149
	v_mov_b32_e32 v124, v149
	v_mov_b32_e32 v125, v149
	v_mov_b32_e32 v70, v149
	v_mov_b32_e32 v71, v149
	v_mov_b32_e32 v72, v149
	v_mov_b32_e32 v73, v149
	v_mov_b32_e32 v78, v149
	v_mov_b32_e32 v79, v149
	v_mov_b32_e32 v80, v149
	v_mov_b32_e32 v81, v149
	v_mov_b32_e32 v86, v149
	v_mov_b32_e32 v87, v149
	v_mov_b32_e32 v88, v149
	v_mov_b32_e32 v89, v149
	v_mov_b32_e32 v94, v149
	v_mov_b32_e32 v95, v149
	v_mov_b32_e32 v96, v149
	v_mov_b32_e32 v97, v149
	v_mov_b32_e32 v102, v149
	v_mov_b32_e32 v103, v149
	v_mov_b32_e32 v104, v149
	v_mov_b32_e32 v105, v149
	v_mov_b32_e32 v110, v149
	v_mov_b32_e32 v111, v149
	v_mov_b32_e32 v112, v149
	v_mov_b32_e32 v113, v149
	v_mov_b32_e32 v118, v149
	v_mov_b32_e32 v119, v149
	v_mov_b32_e32 v120, v149
	v_mov_b32_e32 v121, v149
	v_mov_b32_e32 v126, v149
	v_mov_b32_e32 v127, v149
	v_mov_b32_e32 v128, v149
	v_mov_b32_e32 v129, v149
.LBB1_843:
	v_add_u32_e32 v146, s17, v151
	ds_read_b128 v[142:145], v146
	ds_read_b128 v[154:157], v146 offset:1024
	ds_read_b128 v[158:161], v146 offset:2048
	ds_read_b128 v[162:165], v146 offset:3072
	s_add_u32 s20, s18, 0xfffc0080
	s_addc_u32 s21, s19, -1
	s_cmp_eq_u32 s57, 12
	s_cselect_b32 s23, s7, s21
	s_cselect_b32 s22, s53, s20
	s_cselect_b32 s21, s9, s56
	s_cselect_b32 s20, s54, s55
	ds_read_b128 v[166:169], v153
	ds_read_b128 v[176:179], v153 offset:1024
	ds_read_b128 v[180:183], v153 offset:2048
	ds_read_b128 v[184:187], v153 offset:3072
	ds_read_b128 v[188:191], v153 offset:4096
	ds_read_b128 v[200:203], v153 offset:5120
	ds_read_b128 v[204:207], v153 offset:6144
	ds_read_b128 v[208:211], v153 offset:7168
	s_waitcnt lgkmcnt(8)
	s_barrier
	s_waitcnt lgkmcnt(0)
	s_setprio 1
	s_waitcnt lgkmcnt(0)
	v_mfma_f32_16x16x32_bf16 v[126:129], v[142:145], v[166:169], v[126:129]
	v_mfma_f32_16x16x32_bf16 v[118:121], v[158:161], v[166:169], v[118:121]
	v_lshl_add_u64 v[146:147], s[18:19], 0, v[140:141]
	s_add_i32 m0, s31, 0xc000
	v_mfma_f32_16x16x32_bf16 v[110:113], v[142:145], v[180:183], v[110:113]
	v_mfma_f32_16x16x32_bf16 v[102:105], v[158:161], v[180:183], v[102:105]
	global_load_lds_dwordx4 v[146:147], off
	v_mfma_f32_16x16x32_bf16 v[94:97], v[142:145], v[188:191], v[94:97]
	v_mfma_f32_16x16x32_bf16 v[86:89], v[158:161], v[188:191], v[86:89]
	v_mfma_f32_16x16x32_bf16 v[78:81], v[142:145], v[204:207], v[78:81]
	v_mfma_f32_16x16x32_bf16 v[70:73], v[158:161], v[204:207], v[70:73]
	v_lshl_add_u64 v[146:147], s[18:19], 0, v[138:139]
	s_add_i32 m0, s31, 0xe000
	v_mfma_f32_16x16x32_bf16 v[126:129], v[154:157], v[176:179], v[126:129]
	v_mfma_f32_16x16x32_bf16 v[118:121], v[162:165], v[176:179], v[118:121]
	global_load_lds_dwordx4 v[146:147], off
	v_mfma_f32_16x16x32_bf16 v[110:113], v[154:157], v[184:187], v[110:113]
	v_mfma_f32_16x16x32_bf16 v[102:105], v[162:165], v[184:187], v[102:105]
	v_mfma_f32_16x16x32_bf16 v[94:97], v[154:157], v[200:203], v[94:97]
	v_mfma_f32_16x16x32_bf16 v[86:89], v[162:165], v[200:203], v[86:89]
	v_mfma_f32_16x16x32_bf16 v[78:81], v[154:157], v[208:211], v[78:81]
	v_mfma_f32_16x16x32_bf16 v[70:73], v[162:165], v[208:211], v[70:73]
	s_setprio 0
	s_barrier
; #define PG8_STAGE(bufoff, gbase, voff) do { _Pragma("unroll") for (int _i = 0; _i < 2; ++_i) \
;         __builtin_amdgcn_global_load_lds((const unsigned*)((const char*)(gbase) + (voff)[_i]), (LAS unsigned*)(lds + (bufoff) + ldsw + _i * 8192), 16, 0, 0); } while (0)
; #define PG8_LDA(dst, b, h) do { _Pragma("unroll") for (int m = 0; m < 4; ++m) _Pragma("unroll") for (int k = 0; k < 2; ++k) dst[m][k] = *(const LAS bf16x8*)(lds + PG8_SA(b, h) + aoff + m * 2048 + k * 1024); } while (0)
; #define PG8_LDB(dst, b, h) do { _Pragma("unroll") for (int n = 0; n < 2; ++n) _Pragma("unroll") for (int k = 0; k < 2; ++k) dst[n][k] = *(const LAS bf16x8*)(lds + PG8_SB(b, h) + boff + n * 2048 + k * 1024); } while (0)
; #define PG8_MMA(ai, bj, At, Bt) do { __builtin_amdgcn_s_setprio(1); _Pragma("unroll") for (int m = 0; m < 4; ++m) _Pragma("unroll") for (int n = 0; n < 2; ++n) _Pragma("unroll") for (int k = 0; k < 2; ++k) \
;         acc[ai][bj][m][n] = __builtin_amdgcn_mfma_f32_16x16x32_bf16(Bt[n][k], At[m][k], acc[ai][bj][m][n], 0, 0, 0); __builtin_amdgcn_s_setprio(0); } while (0)
; #define PG8_WAIT_V(n) asm volatile("s_waitcnt vmcnt(" #n ")" ::: "memory")
; #define PG8_WAIT_L(n) asm volatile("s_waitcnt lgkmcnt(" #n ")" ::: "memory")
; #define PG8_BAR __builtin_amdgcn_s_barrier()
; #define PG8_SCHED __builtin_amdgcn_sched_barrier(0)
; template <class Epi, int KK, int LDA, int LDB, int NN, bool AGRP>
; __device__ __forceinline__ void gemm_phase(LAS unsigned char* lds, const bf16_t* gA, const bf16_t* gBt, int G_, int bid_, int tid) {
;     ...
;             PG8_LDB(B1, 0, 1); PG8_STAGE(PG8_SB(0, 0), b2, voffB);
;             PG8_BAR; PG8_WAIT_L(0); PG8_MMA(0, 1, At, B1); PG8_BAR;
;             PG8_LDA(At, 0, 1); PG8_STAGE(PG8_SA(0, 0), a2, voffA);
;             PG8_BAR; PG8_WAIT_L(0); PG8_MMA(1, 0, At, B0); PG8_BAR; PG8_SCHED;
;             PG8_STAGE(PG8_SB(0, 1), b2 + hstepB, voffB);
;             PG8_WAIT_V(6); PG8_BAR; PG8_MMA(1, 1, At, B1); PG8_BAR;
;             PG8_LDB(B0, 1, 0); PG8_SCHED; PG8_LDA(At, 1, 0); PG8_STAGE(PG8_SA(0, 1), a2 + hstepA, voffA);
;             PG8_WAIT_L(8); PG8_BAR; PG8_WAIT_L(0); PG8_MMA(0, 0, At, B0); PG8_BAR; PG8_SCHED;
	v_add_u32_e32 v146, s35, v151
	ds_read_b128 v[212:215], v146
	ds_read_b128 v[216:219], v146 offset:1024
	ds_read_b128 v[220:223], v146 offset:2048
	ds_read_b128 v[224:227], v146 offset:3072
	s_barrier
	s_waitcnt lgkmcnt(0)
	s_setprio 1
	s_waitcnt lgkmcnt(0)
	v_mfma_f32_16x16x32_bf16 v[122:125], v[212:215], v[166:169], v[122:125]
	v_mfma_f32_16x16x32_bf16 v[114:117], v[220:223], v[166:169], v[114:117]
	s_mov_b32 m0, s29
	v_lshl_add_u64 v[146:147], s[20:21], 0, v[134:135]
	v_mfma_f32_16x16x32_bf16 v[106:109], v[212:215], v[180:183], v[106:109]
	v_mfma_f32_16x16x32_bf16 v[98:101], v[220:223], v[180:183], v[98:101]
	global_load_lds_dwordx4 v[146:147], off
	v_mfma_f32_16x16x32_bf16 v[90:93], v[212:215], v[188:191], v[90:93]
	v_mfma_f32_16x16x32_bf16 v[82:85], v[220:223], v[188:191], v[82:85]
	v_mfma_f32_16x16x32_bf16 v[74:77], v[212:215], v[204:207], v[74:77]
	v_mfma_f32_16x16x32_bf16 v[66:69], v[220:223], v[204:207], v[66:69]
	v_lshl_add_u64 v[194:195], s[20:21], 0, v[130:131]
	s_mov_b32 m0, s30
	v_mfma_f32_16x16x32_bf16 v[122:125], v[216:219], v[176:179], v[122:125]
	v_mfma_f32_16x16x32_bf16 v[114:117], v[224:227], v[176:179], v[114:117]
	global_load_lds_dwordx4 v[194:195], off
	v_mfma_f32_16x16x32_bf16 v[106:109], v[216:219], v[184:187], v[106:109]
	v_mfma_f32_16x16x32_bf16 v[98:101], v[224:227], v[184:187], v[98:101]
	v_mfma_f32_16x16x32_bf16 v[90:93], v[216:219], v[200:203], v[90:93]
	v_mfma_f32_16x16x32_bf16 v[82:85], v[224:227], v[200:203], v[82:85]
	v_mfma_f32_16x16x32_bf16 v[74:77], v[216:219], v[208:211], v[74:77]
	v_mfma_f32_16x16x32_bf16 v[66:69], v[224:227], v[208:211], v[66:69]
	s_setprio 0
	s_barrier
	ds_read_b128 v[166:169], v153 offset:16384
	ds_read_b128 v[176:179], v153 offset:17408
	ds_read_b128 v[180:183], v153 offset:18432
	ds_read_b128 v[184:187], v153 offset:19456
	ds_read_b128 v[188:191], v153 offset:20480
	ds_read_b128 v[200:203], v153 offset:21504
	ds_read_b128 v[204:207], v153 offset:22528
	ds_read_b128 v[208:211], v153 offset:23552
	s_barrier
	s_waitcnt lgkmcnt(0)
	s_setprio 1
	s_waitcnt lgkmcnt(0)
	v_mfma_f32_16x16x32_bf16 v[62:65], v[142:145], v[166:169], v[62:65]
	v_mfma_f32_16x16x32_bf16 v[54:57], v[158:161], v[166:169], v[54:57]
	s_mov_b32 m0, s31
	v_lshl_add_u64 v[196:197], s[22:23], 0, v[136:137]
	v_mfma_f32_16x16x32_bf16 v[46:49], v[142:145], v[180:183], v[46:49]
	v_mfma_f32_16x16x32_bf16 v[38:41], v[158:161], v[180:183], v[38:41]
	global_load_lds_dwordx4 v[196:197], off
	v_mfma_f32_16x16x32_bf16 v[30:33], v[142:145], v[188:191], v[30:33]
	v_mfma_f32_16x16x32_bf16 v[22:25], v[158:161], v[188:191], v[22:25]
	v_mfma_f32_16x16x32_bf16 v[14:17], v[142:145], v[204:207], v[14:17]
	v_mfma_f32_16x16x32_bf16 v[6:9], v[158:161], v[204:207], v[6:9]
	v_lshl_add_u64 v[228:229], s[22:23], 0, v[132:133]
	s_mov_b32 m0, s34
	v_mfma_f32_16x16x32_bf16 v[62:65], v[154:157], v[176:179], v[62:65]
	v_mfma_f32_16x16x32_bf16 v[54:57], v[162:165], v[176:179], v[54:57]
	global_load_lds_dwordx4 v[228:229], off
	v_mfma_f32_16x16x32_bf16 v[46:49], v[154:157], v[184:187], v[46:49]
	v_mfma_f32_16x16x32_bf16 v[38:41], v[162:165], v[184:187], v[38:41]
	v_mfma_f32_16x16x32_bf16 v[30:33], v[154:157], v[200:203], v[30:33]
	v_mfma_f32_16x16x32_bf16 v[22:25], v[162:165], v[200:203], v[22:25]
	v_mfma_f32_16x16x32_bf16 v[14:17], v[154:157], v[208:211], v[14:17]
	v_mfma_f32_16x16x32_bf16 v[6:9], v[162:165], v[208:211], v[6:9]
	s_setprio 0
	s_barrier
	s_add_u32 s58, s20, 0x40000
	s_addc_u32 s59, s21, 0
	s_waitcnt vmcnt(4)
	s_barrier
	s_setprio 1
	v_mfma_f32_16x16x32_bf16 v[58:61], v[212:215], v[166:169], v[58:61]
	v_mfma_f32_16x16x32_bf16 v[50:53], v[220:223], v[166:169], v[50:53]
	s_mov_b32 m0, s36
	v_lshl_add_u64 v[142:143], s[58:59], 0, v[134:135]
	v_mfma_f32_16x16x32_bf16 v[42:45], v[212:215], v[180:183], v[42:45]
	v_mfma_f32_16x16x32_bf16 v[34:37], v[220:223], v[180:183], v[34:37]
	global_load_lds_dwordx4 v[142:143], off
	v_mfma_f32_16x16x32_bf16 v[26:29], v[212:215], v[188:191], v[26:29]
	v_mfma_f32_16x16x32_bf16 v[18:21], v[220:223], v[188:191], v[18:21]
	v_mfma_f32_16x16x32_bf16 v[10:13], v[212:215], v[204:207], v[10:13]
	v_mfma_f32_16x16x32_bf16 v[0:3], v[220:223], v[204:207], v[0:3]
	v_lshl_add_u64 v[142:143], s[58:59], 0, v[130:131]
	s_mov_b32 m0, s37
	v_mfma_f32_16x16x32_bf16 v[58:61], v[216:219], v[176:179], v[58:61]
	v_mfma_f32_16x16x32_bf16 v[50:53], v[224:227], v[176:179], v[50:53]
	global_load_lds_dwordx4 v[142:143], off
	v_mfma_f32_16x16x32_bf16 v[42:45], v[216:219], v[184:187], v[42:45]
	v_mfma_f32_16x16x32_bf16 v[34:37], v[224:227], v[184:187], v[34:37]
	v_mfma_f32_16x16x32_bf16 v[26:29], v[216:219], v[200:203], v[26:29]
	v_mfma_f32_16x16x32_bf16 v[18:21], v[224:227], v[200:203], v[18:21]
	v_mfma_f32_16x16x32_bf16 v[10:13], v[216:219], v[208:211], v[10:13]
	v_mfma_f32_16x16x32_bf16 v[0:3], v[224:227], v[208:211], v[0:3]
	s_setprio 0
	v_add_u32_e32 v148, s40, v151
	s_barrier
	ds_read_b128 v[142:145], v148
	ds_read_b128 v[154:157], v148 offset:1024
	ds_read_b128 v[158:161], v148 offset:2048
	ds_read_b128 v[162:165], v148 offset:3072
	s_add_u32 s22, s22, 0x40000
	s_addc_u32 s23, s23, 0
	ds_read_b128 v[166:169], v153 offset:32768
	ds_read_b128 v[176:179], v153 offset:33792
	ds_read_b128 v[180:183], v153 offset:34816
	ds_read_b128 v[184:187], v153 offset:35840
	ds_read_b128 v[188:191], v153 offset:36864
	ds_read_b128 v[200:203], v153 offset:37888
	ds_read_b128 v[204:207], v153 offset:38912
	ds_read_b128 v[208:211], v153 offset:39936
	s_waitcnt lgkmcnt(8)
	s_barrier
; #define PG8_STAGE(bufoff, gbase, voff) do { _Pragma("unroll") for (int _i = 0; _i < 2; ++_i) \
;         __builtin_amdgcn_global_load_lds((const unsigned*)((const char*)(gbase) + (voff)[_i]), (LAS unsigned*)(lds + (bufoff) + ldsw + _i * 8192), 16, 0, 0); } while (0)
; #define PG8_LDA(dst, b, h) do { _Pragma("unroll") for (int m = 0; m < 4; ++m) _Pragma("unroll") for (int k = 0; k < 2; ++k) dst[m][k] = *(const LAS bf16x8*)(lds + PG8_SA(b, h) + aoff + m * 2048 + k * 1024); } while (0)
; #define PG8_LDB(dst, b, h) do { _Pragma("unroll") for (int n = 0; n < 2; ++n) _Pragma("unroll") for (int k = 0; k < 2; ++k) dst[n][k] = *(const LAS bf16x8*)(lds + PG8_SB(b, h) + boff + n * 2048 + k * 1024); } while (0)
; #define PG8_MMA(ai, bj, At, Bt) do { __builtin_amdgcn_s_setprio(1); _Pragma("unroll") for (int m = 0; m < 4; ++m) _Pragma("unroll") for (int n = 0; n < 2; ++n) _Pragma("unroll") for (int k = 0; k < 2; ++k) \
;         acc[ai][bj][m][n] = __builtin_amdgcn_mfma_f32_16x16x32_bf16(Bt[n][k], At[m][k], acc[ai][bj][m][n], 0, 0, 0); __builtin_amdgcn_s_setprio(0); } while (0)
; #define PG8_WAIT_V(n) asm volatile("s_waitcnt vmcnt(" #n ")" ::: "memory")
; #define PG8_WAIT_L(n) asm volatile("s_waitcnt lgkmcnt(" #n ")" ::: "memory")
; #define PG8_BAR __builtin_amdgcn_s_barrier()
; #define PG8_SCHED __builtin_amdgcn_sched_barrier(0)
; template <class Epi, int KK, int LDA, int LDB, int NN, bool AGRP>
; __device__ __forceinline__ void gemm_phase(LAS unsigned char* lds, const bf16_t* gA, const bf16_t* gBt, int G_, int bid_, int tid) {
;     ...
;             PG8_WAIT_L(8); PG8_BAR; PG8_WAIT_L(0); PG8_MMA(0, 0, At, B0); PG8_BAR; PG8_SCHED;
;             PG8_LDB(B1, 1, 1); PG8_STAGE(PG8_SB(1, 0), b3, voffB);
;             PG8_BAR; PG8_WAIT_L(0); PG8_MMA(0, 1, At, B1); PG8_BAR;
;             PG8_LDA(At, 1, 1); PG8_STAGE(PG8_SA(1, 0), a3, voffA);
;             PG8_BAR; PG8_WAIT_L(0); PG8_MMA(1, 0, At, B0); PG8_BAR; PG8_SCHED;
;             PG8_STAGE(PG8_SB(1, 1), b3 + hstepB, voffB);
;             PG8_WAIT_V(6); PG8_BAR; PG8_MMA(1, 1, At, B1); PG8_BAR;
	s_waitcnt lgkmcnt(0)
	s_setprio 1
	s_waitcnt lgkmcnt(0)
	v_mfma_f32_16x16x32_bf16 v[126:129], v[142:145], v[166:169], v[126:129]
	v_mfma_f32_16x16x32_bf16 v[118:121], v[158:161], v[166:169], v[118:121]
	s_mov_b32 m0, s38
	v_lshl_add_u64 v[212:213], s[22:23], 0, v[136:137]
	v_mfma_f32_16x16x32_bf16 v[110:113], v[142:145], v[180:183], v[110:113]
	v_mfma_f32_16x16x32_bf16 v[102:105], v[158:161], v[180:183], v[102:105]
	global_load_lds_dwordx4 v[212:213], off
	v_mfma_f32_16x16x32_bf16 v[94:97], v[142:145], v[188:191], v[94:97]
	v_mfma_f32_16x16x32_bf16 v[86:89], v[158:161], v[188:191], v[86:89]
	v_mfma_f32_16x16x32_bf16 v[78:81], v[142:145], v[204:207], v[78:81]
	v_mfma_f32_16x16x32_bf16 v[70:73], v[158:161], v[204:207], v[70:73]
	v_lshl_add_u64 v[212:213], s[22:23], 0, v[132:133]
	s_mov_b32 m0, s39
	v_mfma_f32_16x16x32_bf16 v[126:129], v[154:157], v[176:179], v[126:129]
	v_mfma_f32_16x16x32_bf16 v[118:121], v[162:165], v[176:179], v[118:121]
	global_load_lds_dwordx4 v[212:213], off
	v_mfma_f32_16x16x32_bf16 v[110:113], v[154:157], v[184:187], v[110:113]
	v_mfma_f32_16x16x32_bf16 v[102:105], v[162:165], v[184:187], v[102:105]
	v_mfma_f32_16x16x32_bf16 v[94:97], v[154:157], v[200:203], v[94:97]
	v_mfma_f32_16x16x32_bf16 v[86:89], v[162:165], v[200:203], v[86:89]
	v_mfma_f32_16x16x32_bf16 v[78:81], v[154:157], v[208:211], v[78:81]
	v_mfma_f32_16x16x32_bf16 v[70:73], v[162:165], v[208:211], v[70:73]
	s_setprio 0
	s_barrier
	v_add_u32_e32 v148, s45, v151
	ds_read_b128 v[212:215], v148
	ds_read_b128 v[216:219], v148 offset:1024
	ds_read_b128 v[220:223], v148 offset:2048
	ds_read_b128 v[224:227], v148 offset:3072
	s_barrier
	s_waitcnt lgkmcnt(0)
	s_setprio 1
	s_waitcnt lgkmcnt(0)
	v_mfma_f32_16x16x32_bf16 v[122:125], v[212:215], v[166:169], v[122:125]
	v_mfma_f32_16x16x32_bf16 v[114:117], v[220:223], v[166:169], v[114:117]
	s_mov_b32 m0, s41
	v_lshl_add_u64 v[146:147], v[146:147], 0, s[76:77]
	v_mfma_f32_16x16x32_bf16 v[106:109], v[212:215], v[180:183], v[106:109]
	v_mfma_f32_16x16x32_bf16 v[98:101], v[220:223], v[180:183], v[98:101]
	global_load_lds_dwordx4 v[146:147], off
	v_mfma_f32_16x16x32_bf16 v[90:93], v[212:215], v[188:191], v[90:93]
	v_mfma_f32_16x16x32_bf16 v[82:85], v[220:223], v[188:191], v[82:85]
	v_mfma_f32_16x16x32_bf16 v[74:77], v[212:215], v[204:207], v[74:77]
	v_mfma_f32_16x16x32_bf16 v[66:69], v[220:223], v[204:207], v[66:69]
	v_lshl_add_u64 v[146:147], v[194:195], 0, s[76:77]
	s_mov_b32 m0, s42
	v_mfma_f32_16x16x32_bf16 v[122:125], v[216:219], v[176:179], v[122:125]
	v_mfma_f32_16x16x32_bf16 v[114:117], v[224:227], v[176:179], v[114:117]
	global_load_lds_dwordx4 v[146:147], off
	v_mfma_f32_16x16x32_bf16 v[106:109], v[216:219], v[184:187], v[106:109]
	v_mfma_f32_16x16x32_bf16 v[98:101], v[224:227], v[184:187], v[98:101]
	v_mfma_f32_16x16x32_bf16 v[90:93], v[216:219], v[200:203], v[90:93]
	v_mfma_f32_16x16x32_bf16 v[82:85], v[224:227], v[200:203], v[82:85]
	v_mfma_f32_16x16x32_bf16 v[74:77], v[216:219], v[208:211], v[74:77]
	v_mfma_f32_16x16x32_bf16 v[66:69], v[224:227], v[208:211], v[66:69]
	s_setprio 0
	s_barrier
	ds_read_b128 v[166:169], v153 offset:49152
	ds_read_b128 v[176:179], v153 offset:50176
	ds_read_b128 v[180:183], v153 offset:51200
	ds_read_b128 v[184:187], v153 offset:52224
	ds_read_b128 v[188:191], v153 offset:53248
	ds_read_b128 v[200:203], v153 offset:54272
	ds_read_b128 v[204:207], v153 offset:55296
	ds_read_b128 v[208:211], v153 offset:56320
	s_barrier
	s_waitcnt lgkmcnt(0)
	s_setprio 1
	s_waitcnt lgkmcnt(0)
	v_mfma_f32_16x16x32_bf16 v[62:65], v[142:145], v[166:169], v[62:65]
	v_mfma_f32_16x16x32_bf16 v[54:57], v[158:161], v[166:169], v[54:57]
	s_mov_b32 m0, s43
	v_lshl_add_u64 v[146:147], v[196:197], 0, s[76:77]
	v_mfma_f32_16x16x32_bf16 v[46:49], v[142:145], v[180:183], v[46:49]
	v_mfma_f32_16x16x32_bf16 v[38:41], v[158:161], v[180:183], v[38:41]
	global_load_lds_dwordx4 v[146:147], off
	v_mfma_f32_16x16x32_bf16 v[30:33], v[142:145], v[188:191], v[30:33]
	v_mfma_f32_16x16x32_bf16 v[22:25], v[158:161], v[188:191], v[22:25]
	v_mfma_f32_16x16x32_bf16 v[14:17], v[142:145], v[204:207], v[14:17]
	v_mfma_f32_16x16x32_bf16 v[6:9], v[158:161], v[204:207], v[6:9]
	v_lshl_add_u64 v[146:147], v[228:229], 0, s[76:77]
	s_mov_b32 m0, s44
	v_mfma_f32_16x16x32_bf16 v[62:65], v[154:157], v[176:179], v[62:65]
	v_mfma_f32_16x16x32_bf16 v[54:57], v[162:165], v[176:179], v[54:57]
	global_load_lds_dwordx4 v[146:147], off
	v_mfma_f32_16x16x32_bf16 v[46:49], v[154:157], v[184:187], v[46:49]
	v_mfma_f32_16x16x32_bf16 v[38:41], v[162:165], v[184:187], v[38:41]
	v_mfma_f32_16x16x32_bf16 v[30:33], v[154:157], v[200:203], v[30:33]
	v_mfma_f32_16x16x32_bf16 v[22:25], v[162:165], v[200:203], v[22:25]
	v_mfma_f32_16x16x32_bf16 v[14:17], v[154:157], v[208:211], v[14:17]
	v_mfma_f32_16x16x32_bf16 v[6:9], v[162:165], v[208:211], v[6:9]
	s_setprio 0
	s_barrier
	s_add_u32 s20, s20, 0x40080
	s_addc_u32 s21, s21, 0
	s_waitcnt vmcnt(4)
	s_barrier
; #define PG8_MMA(ai, bj, At, Bt) do { __builtin_amdgcn_s_setprio(1); _Pragma("unroll") for (int m = 0; m < 4; ++m) _Pragma("unroll") for (int n = 0; n < 2; ++n) _Pragma("unroll") for (int k = 0; k < 2; ++k) \
;         acc[ai][bj][m][n] = __builtin_amdgcn_mfma_f32_16x16x32_bf16(Bt[n][k], At[m][k], acc[ai][bj][m][n], 0, 0, 0); __builtin_amdgcn_s_setprio(0); } while (0)
; #define PG8_WAIT_V(n) asm volatile("s_waitcnt vmcnt(" #n ")" ::: "memory")
; #define PG8_BAR __builtin_amdgcn_s_barrier()
; #define EPP(T_, k) ((T_)(__attribute__((address_space(1))) char*)ep64(lds, (k)))
; template <class Epi, int KK, int LDA, int LDB, int NN, bool AGRP>
; __device__ __forceinline__ void gemm_phase(LAS unsigned char* lds, const bf16_t* gA, const bf16_t* gBt, int G_, int bid_, int tid) {
;     ...
;             PG8_WAIT_V(6); PG8_BAR; PG8_MMA(1, 1, At, B1); PG8_BAR;
;         }
;     __device__ __forceinline__ void operator()(const f32x4 (&acc)[2][2][4][2], const Unit& u, int wr, int wc, int fr, int fq, LAS unsigned char* lds) const {
;         bf16_t* O = EPP(bf16_t*, 0); const float* rss = EPP(const float*, 1);
;         const int row0 = u.pm * BM + wr * 64 + fr, j0 = u.pn * 128 + wc * 32 + 8 * fq;
; #pragma unroll
;         for (int ai = 0; ai < 2; ++ai)
; #pragma unroll
;             for (int m = 0; m < 4; ++m) { const int row = row0 + ai * HALF + m * 16; const float rs = rstd_of4(rss, row, fq);
	s_setprio 1
	v_mfma_f32_16x16x32_bf16 v[58:61], v[212:215], v[166:169], v[58:61]
	v_mfma_f32_16x16x32_bf16 v[50:53], v[220:223], v[166:169], v[50:53]
	s_mov_b32 m0, s46
	v_lshl_add_u64 v[142:143], s[20:21], 0, v[134:135]
	v_mfma_f32_16x16x32_bf16 v[42:45], v[212:215], v[180:183], v[42:45]
	v_mfma_f32_16x16x32_bf16 v[34:37], v[220:223], v[180:183], v[34:37]
	global_load_lds_dwordx4 v[142:143], off
	v_mfma_f32_16x16x32_bf16 v[26:29], v[212:215], v[188:191], v[26:29]
	v_mfma_f32_16x16x32_bf16 v[18:21], v[220:223], v[188:191], v[18:21]
	v_mfma_f32_16x16x32_bf16 v[10:13], v[212:215], v[204:207], v[10:13]
	v_mfma_f32_16x16x32_bf16 v[0:3], v[220:223], v[204:207], v[0:3]
	v_lshl_add_u64 v[142:143], s[20:21], 0, v[130:131]
	s_mov_b32 m0, s47
	v_mfma_f32_16x16x32_bf16 v[58:61], v[216:219], v[176:179], v[58:61]
	v_mfma_f32_16x16x32_bf16 v[50:53], v[224:227], v[176:179], v[50:53]
	global_load_lds_dwordx4 v[142:143], off
	v_mfma_f32_16x16x32_bf16 v[42:45], v[216:219], v[184:187], v[42:45]
	v_mfma_f32_16x16x32_bf16 v[34:37], v[224:227], v[184:187], v[34:37]
	v_mfma_f32_16x16x32_bf16 v[26:29], v[216:219], v[200:203], v[26:29]
	v_mfma_f32_16x16x32_bf16 v[18:21], v[224:227], v[200:203], v[18:21]
	v_mfma_f32_16x16x32_bf16 v[10:13], v[216:219], v[208:211], v[10:13]
	v_mfma_f32_16x16x32_bf16 v[0:3], v[224:227], v[208:211], v[0:3]
	s_setprio 0
	s_add_i32 s57, s57, 2
	s_add_u32 s55, s55, 0x100
	s_addc_u32 s56, s56, 0
	s_add_u32 s18, s18, 0x100
	s_addc_u32 s19, s19, 0
	s_cmp_gt_u32 s57, 13
	s_barrier
	s_cbranch_scc0 .LBB1_843
	v_mov_b32_e32 v142, s66
	v_mov_b32_e32 v143, s48
	v_and_b32_e32 v148, 64, v171
	ds_read_b32 v142, v142
	ds_read_b32 v143, v143
	v_mov_b32_e32 v144, s49
	v_mov_b32_e32 v145, s50
	v_xor_b32_e32 v147, 16, v171
	v_add_u32_e32 v148, 64, v148
	ds_read_b32 v144, v144
	ds_read_b32 v145, v145
	v_cmp_lt_i32_e32 vcc, v147, v148
	s_waitcnt lgkmcnt(0)
	v_readfirstlane_b32 s7, v142
	v_readfirstlane_b32 s9, v143
	v_cndmask_b32_e32 v147, v171, v147, vcc
	v_lshlrev_b32_e32 v154, 2, v147
	v_xor_b32_e32 v147, 32, v171
	v_cmp_lt_i32_e32 vcc, v147, v148
	v_lshl_or_b32 v156, s52, 7, v152
	v_lshl_add_u32 v146, s16, 8, v150
	v_cndmask_b32_e32 v147, v171, v147, vcc
	v_mov_b32_e32 v142, s7
	v_mov_b32_e32 v143, s9
	v_readfirstlane_b32 s18, v144
	v_readfirstlane_b32 s19, v145
	v_lshlrev_b32_e32 v155, 2, v147
	v_ashrrev_i32_e32 v157, 31, v156
	v_ashrrev_i32_e32 v147, 31, v146
	v_lshl_add_u64 v[144:145], s[18:19], 0, v[4:5]
	v_lshl_add_u64 v[142:143], v[156:157], 1, v[142:143]
	v_lshlrev_b64 v[156:157], 6, v[146:147]
	v_lshl_add_u64 v[156:157], v[144:145], 0, v[156:157]
	global_load_dwordx4 v[156:159], v[156:157], off
	v_or_b32_e32 v162, 16, v146
	v_ashrrev_i32_e32 v163, 31, v162
	v_lshlrev_b64 v[162:163], 6, v[162:163]
	v_lshl_add_u64 v[162:163], v[144:145], 0, v[162:163]
	global_load_dwordx4 v[200:203], v[162:163], off
	v_or_b32_e32 v162, 32, v146
	v_ashrrev_i32_e32 v163, 31, v162
	v_lshlrev_b64 v[162:163], 6, v[162:163]
	v_lshl_add_u64 v[162:163], v[144:145], 0, v[162:163]
	global_load_dwordx4 v[204:207], v[162:163], off
	v_or_b32_e32 v162, 48, v146
	v_ashrrev_i32_e32 v163, 31, v162
	v_lshlrev_b64 v[162:163], 6, v[162:163]
	v_lshl_add_u64 v[162:163], v[144:145], 0, v[162:163]
	global_load_dwordx4 v[208:211], v[162:163], off
	v_add_u32_e32 v162, 0x80, v146
	v_ashrrev_i32_e32 v163, 31, v162
	v_lshlrev_b64 v[162:163], 6, v[162:163]
	v_lshl_add_u64 v[162:163], v[144:145], 0, v[162:163]
	global_load_dwordx4 v[212:215], v[162:163], off
	v_add_u32_e32 v162, 0x90, v146
	v_ashrrev_i32_e32 v163, 31, v162
	v_lshlrev_b64 v[162:163], 6, v[162:163]
	v_lshl_add_u64 v[162:163], v[144:145], 0, v[162:163]
	global_load_dwordx4 v[216:219], v[162:163], off
	v_add_u32_e32 v162, 0xa0, v146
	v_ashrrev_i32_e32 v163, 31, v162
	v_lshlrev_b64 v[162:163], 6, v[162:163]
	v_lshl_add_u64 v[162:163], v[144:145], 0, v[162:163]
	global_load_dwordx4 v[220:223], v[162:163], off
	v_add_u32_e32 v162, 0xb0, v146
	v_ashrrev_i32_e32 v163, 31, v162
	v_lshlrev_b64 v[162:163], 6, v[162:163]
	v_lshl_add_u64 v[162:163], v[144:145], 0, v[162:163]
	global_load_dwordx4 v[224:227], v[162:163], off
	s_mov_b32 s52, s8
	s_mov_b32 s16, s6
	s_mov_b64 s[20:21], s[12:13]
	s_waitcnt vmcnt(0)
	v_mov_b32_e32 v160, v157
	v_mov_b32_e32 v161, v158
	v_mov_b32_e32 v157, v159
	v_pk_add_f32 v[156:157], v[160:161], v[156:157]
	s_nop 0
	v_add_f32_e32 v147, v156, v157
	v_mov_b32_e32 v148, v147
	s_nop 1
	v_permlane16_swap_b32 v148, v147
	v_mov_b32_e32 v156, v122
	v_mov_b32_e32 v157, v126
	v_mov_b32_e32 v126, v123
	s_waitcnt lgkmcnt(0)
	v_add_f32_e32 v147, v147, v148
	v_mov_b32_e32 v148, v147
	s_nop 1
	v_permlane32_swap_b32 v148, v147
	s_waitcnt lgkmcnt(0)
; __device__ __forceinline__ unsigned cvt_pk_bf16(float lo, float hi) { unsigned r; asm volatile("v_cvt_pk_bf16_f32 %0, %1, %2" : "=v"(r) : "v"(lo), "v"(hi)); return r; }
; __device__ __forceinline__ float fast_sigmoid(float x) { return __builtin_amdgcn_rcpf(1.0f + __builtin_amdgcn_exp2f(-1.44269504089f * x)); }
; __device__ __forceinline__ float rstd_of4(const float* rss, int row, int fq) {
;     const f32x4 a = *(const f32x4*)(rss + (size_t)row * 16 + 4 * fq); float s = (a[0] + a[1]) + (a[2] + a[3]);
;     s += __shfl_xor(s, 16); s += __shfl_xor(s, 32);
;     return rsqrtf(s * (1.0f / 1024.0f) + EPS); }
;     __device__ __forceinline__ void operator()(const f32x4 (&acc)[2][2][4][2], const Unit& u, int wr, int wc, int fr, int fq, LAS unsigned char* lds) const {
;     ...
;             for (int m = 0; m < 4; ++m) { const int row = row0 + ai * HALF + m * 16; const float rs = rstd_of4(rss, row, fq);
;                 float h[8];
; #pragma unroll
;                 for (int n = 0; n < 2; ++n)
; #pragma unroll
;                     for (int e = 0; e < 4; ++e) { const float gt = acc[ai][0][m][n][e] * rs, up = acc[ai][1][m][n][e] * rs; h[n * 4 + e] = gt * fast_sigmoid(gt) * up; }
;                 u32x4 w; w.x = cvt_pk_bf16(h[0], h[1]); w.y = cvt_pk_bf16(h[2], h[3]); w.z = cvt_pk_bf16(h[4], h[5]); w.w = cvt_pk_bf16(h[6], h[7]);
;                 *(u32x4*)(O + (size_t)row * DFF + j0) = w; }
	v_add_f32_e32 v147, v147, v148
	v_fmamk_f32 v147, v147, 0x3a800000, v173
	v_cmp_gt_f32_e32 vcc, s64, v147
	v_mul_f32_e32 v148, 0x4b800000, v147
	s_nop 0
	v_cndmask_b32_e32 v147, v147, v148, vcc
	v_rsq_f32_e32 v147, v147
	s_nop 0
	v_mul_f32_e32 v148, 0x45800000, v147
	v_cndmask_b32_e32 v148, v147, v148, vcc
	v_pk_mul_f32 v[156:157], v[156:157], v[148:149] op_sel_hi:[1,0]
	s_nop 0
	v_mul_f32_e32 v122, 0xbfb8aa3b, v157
	v_exp_f32_e32 v122, v122
	s_nop 0
	v_add_f32_e32 v122, 1.0, v122
	v_rcp_f32_e32 v122, v122
	s_nop 0
	v_mul_f32_e32 v122, v157, v122
	v_mul_f32_e32 v147, v156, v122
	v_pk_mul_f32 v[122:123], v[126:127], v[148:149] op_sel_hi:[1,0]
	s_nop 0
	v_mul_f32_e32 v126, 0xbfb8aa3b, v123
	v_exp_f32_e32 v126, v126
	s_nop 0
	v_add_f32_e32 v126, 1.0, v126
	v_rcp_f32_e32 v126, v126
	s_nop 0
	v_mul_f32_e32 v123, v123, v126
	v_mul_f32_e32 v126, v122, v123
	v_mov_b32_e32 v122, v124
	v_mov_b32_e32 v123, v128
	v_pk_mul_f32 v[122:123], v[122:123], v[148:149] op_sel_hi:[1,0]
	v_mov_b32_e32 v128, v125
	v_mul_f32_e32 v124, 0xbfb8aa3b, v123
	v_exp_f32_e32 v124, v124
	s_nop 0
	v_add_f32_e32 v124, 1.0, v124
	v_rcp_f32_e32 v124, v124
	s_nop 0
	v_mul_f32_e32 v123, v123, v124
	v_mul_f32_e32 v124, v122, v123
	v_pk_mul_f32 v[122:123], v[128:129], v[148:149] op_sel_hi:[1,0]
	s_nop 0
	v_mul_f32_e32 v125, 0xbfb8aa3b, v123
	v_exp_f32_e32 v125, v125
	s_nop 0
	v_add_f32_e32 v125, 1.0, v125
	v_rcp_f32_e32 v125, v125
	s_nop 0
	v_mul_f32_e32 v123, v123, v125
	v_mul_f32_e32 v125, v122, v123
	v_mov_b32_e32 v122, v114
	v_mov_b32_e32 v123, v118
	v_pk_mul_f32 v[122:123], v[122:123], v[148:149] op_sel_hi:[1,0]
	v_mov_b32_e32 v118, v115
	v_mul_f32_e32 v114, 0xbfb8aa3b, v123
	v_exp_f32_e32 v114, v114
	s_nop 0
	v_add_f32_e32 v114, 1.0, v114
	v_rcp_f32_e32 v114, v114
	s_nop 0
	v_mul_f32_e32 v114, v123, v114
	v_mul_f32_e32 v122, v122, v114
	v_pk_mul_f32 v[114:115], v[118:119], v[148:149] op_sel_hi:[1,0]
	s_nop 0
	v_mul_f32_e32 v118, 0xbfb8aa3b, v115
	v_exp_f32_e32 v118, v118
	s_nop 0
	v_add_f32_e32 v118, 1.0, v118
	v_rcp_f32_e32 v118, v118
	s_nop 0
	v_mul_f32_e32 v115, v115, v118
	v_mul_f32_e32 v118, v114, v115
	v_mov_b32_e32 v114, v116
	v_mov_b32_e32 v115, v120
	v_pk_mul_f32 v[114:115], v[114:115], v[148:149] op_sel_hi:[1,0]
	v_mov_b32_e32 v120, v117
	v_mul_f32_e32 v116, 0xbfb8aa3b, v115
	v_exp_f32_e32 v116, v116
	s_nop 0
	v_add_f32_e32 v116, 1.0, v116
	v_rcp_f32_e32 v116, v116
	s_nop 0
	v_mul_f32_e32 v115, v115, v116
	v_mul_f32_e32 v119, v114, v115
	v_pk_mul_f32 v[114:115], v[120:121], v[148:149] op_sel_hi:[1,0]
	s_nop 0
	v_mul_f32_e32 v116, 0xbfb8aa3b, v115
	v_exp_f32_e32 v116, v116
	s_nop 0
	v_add_f32_e32 v116, 1.0, v116
	v_rcp_f32_e32 v116, v116
	s_nop 0
	v_mul_f32_e32 v115, v115, v116
	v_mul_f32_e32 v117, v114, v115
	v_cvt_pk_bf16_f32 v114, v147, v126
	v_cvt_pk_bf16_f32 v115, v124, v125
	v_cvt_pk_bf16_f32 v116, v122, v118
	v_cvt_pk_bf16_f32 v117, v119, v117
	v_mad_i64_i32 v[118:119], s[18:19], v146, s88, v[142:143]
	global_store_dwordx4 v[118:119], v[114:117], off
	s_nop 1
	v_or_b32_e32 v114, 16, v146
	v_ashrrev_i32_e32 v115, 31, v114
	v_lshlrev_b64 v[116:117], 6, v[114:115]
	v_lshl_add_u64 v[116:117], v[144:145], 0, v[116:117]
	v_mov_b32_e32 v116, v200
	v_mov_b32_e32 v117, v201
	v_mov_b32_e32 v118, v202
	v_mov_b32_e32 v119, v203
	s_nop 0
	v_mov_b32_e32 v120, v117
	v_mov_b32_e32 v121, v118
	v_mov_b32_e32 v117, v119
	v_pk_add_f32 v[116:117], v[120:121], v[116:117]
	v_mov_b32_e32 v118, v106
	v_add_f32_e32 v115, v116, v117
	v_mov_b32_e32 v116, v115
	s_nop 1
	v_permlane16_swap_b32 v116, v115
	v_mov_b32_e32 v119, v110
	v_mov_b32_e32 v110, v107
	s_waitcnt lgkmcnt(0)
	v_add_f32_e32 v115, v115, v116
	v_mov_b32_e32 v116, v115
	s_nop 1
	v_permlane32_swap_b32 v116, v115
	s_waitcnt lgkmcnt(0)
	v_add_f32_e32 v115, v115, v116
	v_fmamk_f32 v115, v115, 0x3a800000, v173
	v_cmp_gt_f32_e32 vcc, s64, v115
	v_mul_f32_e32 v116, 0x4b800000, v115
	s_nop 0
	v_cndmask_b32_e32 v115, v115, v116, vcc
	v_rsq_f32_e32 v115, v115
	s_nop 0
	v_mul_f32_e32 v116, 0x45800000, v115
	v_cndmask_b32_e32 v116, v115, v116, vcc
	v_pk_mul_f32 v[118:119], v[118:119], v[116:117] op_sel_hi:[1,0]
	s_nop 0
	v_mul_f32_e32 v106, 0xbfb8aa3b, v119
	v_exp_f32_e32 v106, v106
	s_nop 0
	v_add_f32_e32 v106, 1.0, v106
	v_rcp_f32_e32 v106, v106
	s_nop 0
	v_mul_f32_e32 v106, v119, v106
	v_mul_f32_e32 v115, v118, v106
	v_pk_mul_f32 v[106:107], v[110:111], v[116:117] op_sel_hi:[1,0]
	s_nop 0
	v_mul_f32_e32 v110, 0xbfb8aa3b, v107
	v_exp_f32_e32 v110, v110
	s_nop 0
	v_add_f32_e32 v110, 1.0, v110
	v_rcp_f32_e32 v110, v110
	s_nop 0
	v_mul_f32_e32 v107, v107, v110
	v_mul_f32_e32 v110, v106, v107
	v_mov_b32_e32 v106, v108
	v_mov_b32_e32 v107, v112
	v_pk_mul_f32 v[106:107], v[106:107], v[116:117] op_sel_hi:[1,0]
	v_mov_b32_e32 v112, v109
	v_mul_f32_e32 v108, 0xbfb8aa3b, v107
	v_exp_f32_e32 v108, v108
	s_nop 0
	v_add_f32_e32 v108, 1.0, v108
	v_rcp_f32_e32 v108, v108
	s_nop 0
	v_mul_f32_e32 v107, v107, v108
	v_mul_f32_e32 v108, v106, v107
	v_pk_mul_f32 v[106:107], v[112:113], v[116:117] op_sel_hi:[1,0]
	s_nop 0
	v_mul_f32_e32 v109, 0xbfb8aa3b, v107
	v_exp_f32_e32 v109, v109
	s_nop 0
	v_add_f32_e32 v109, 1.0, v109
	v_rcp_f32_e32 v109, v109
	s_nop 0
	v_mul_f32_e32 v107, v107, v109
	v_mul_f32_e32 v109, v106, v107
	v_mov_b32_e32 v106, v98
	v_mov_b32_e32 v107, v102
	v_pk_mul_f32 v[106:107], v[106:107], v[116:117] op_sel_hi:[1,0]
	v_mov_b32_e32 v102, v99
	v_mul_f32_e32 v98, 0xbfb8aa3b, v107
	v_exp_f32_e32 v98, v98
	s_nop 0
	v_add_f32_e32 v98, 1.0, v98
	v_rcp_f32_e32 v98, v98
	s_nop 0
	v_mul_f32_e32 v98, v107, v98
	v_mul_f32_e32 v106, v106, v98
	v_pk_mul_f32 v[98:99], v[102:103], v[116:117] op_sel_hi:[1,0]
	s_nop 0
	v_mul_f32_e32 v102, 0xbfb8aa3b, v99
; __device__ __forceinline__ unsigned cvt_pk_bf16(float lo, float hi) { unsigned r; asm volatile("v_cvt_pk_bf16_f32 %0, %1, %2" : "=v"(r) : "v"(lo), "v"(hi)); return r; }
; __device__ __forceinline__ float fast_sigmoid(float x) { return __builtin_amdgcn_rcpf(1.0f + __builtin_amdgcn_exp2f(-1.44269504089f * x)); }
; __device__ __forceinline__ float rstd_of4(const float* rss, int row, int fq) {
;     const f32x4 a = *(const f32x4*)(rss + (size_t)row * 16 + 4 * fq); float s = (a[0] + a[1]) + (a[2] + a[3]);
;     s += __shfl_xor(s, 16); s += __shfl_xor(s, 32);
;     return rsqrtf(s * (1.0f / 1024.0f) + EPS); }
;     __device__ __forceinline__ void operator()(const f32x4 (&acc)[2][2][4][2], const Unit& u, int wr, int wc, int fr, int fq, LAS unsigned char* lds) const {
;     ...
;             for (int m = 0; m < 4; ++m) { const int row = row0 + ai * HALF + m * 16; const float rs = rstd_of4(rss, row, fq);
;                 float h[8];
; #pragma unroll
;                 for (int n = 0; n < 2; ++n)
; #pragma unroll
;                     for (int e = 0; e < 4; ++e) { const float gt = acc[ai][0][m][n][e] * rs, up = acc[ai][1][m][n][e] * rs; h[n * 4 + e] = gt * fast_sigmoid(gt) * up; }
;                 u32x4 w; w.x = cvt_pk_bf16(h[0], h[1]); w.y = cvt_pk_bf16(h[2], h[3]); w.z = cvt_pk_bf16(h[4], h[5]); w.w = cvt_pk_bf16(h[6], h[7]);
;                 *(u32x4*)(O + (size_t)row * DFF + j0) = w; }
	v_exp_f32_e32 v102, v102
	s_nop 0
	v_add_f32_e32 v102, 1.0, v102
	v_rcp_f32_e32 v102, v102
	s_nop 0
	v_mul_f32_e32 v99, v99, v102
	v_mul_f32_e32 v102, v98, v99
	v_mov_b32_e32 v98, v100
	v_mov_b32_e32 v99, v104
	v_pk_mul_f32 v[98:99], v[98:99], v[116:117] op_sel_hi:[1,0]
	v_mov_b32_e32 v104, v101
	v_mul_f32_e32 v100, 0xbfb8aa3b, v99
	v_exp_f32_e32 v100, v100
	s_nop 0
	v_add_f32_e32 v100, 1.0, v100
	v_rcp_f32_e32 v100, v100
	s_nop 0
	v_mul_f32_e32 v99, v99, v100
	v_mul_f32_e32 v103, v98, v99
	v_pk_mul_f32 v[98:99], v[104:105], v[116:117] op_sel_hi:[1,0]
	s_nop 0
	v_mul_f32_e32 v100, 0xbfb8aa3b, v99
	v_exp_f32_e32 v100, v100
	s_nop 0
	v_add_f32_e32 v100, 1.0, v100
	v_rcp_f32_e32 v100, v100
	s_nop 0
	v_mul_f32_e32 v99, v99, v100
	v_mul_f32_e32 v101, v98, v99
	v_cvt_pk_bf16_f32 v98, v115, v110
	v_cvt_pk_bf16_f32 v99, v108, v109
	v_cvt_pk_bf16_f32 v100, v106, v102
	v_cvt_pk_bf16_f32 v101, v103, v101
	v_mad_i64_i32 v[102:103], s[18:19], v114, s88, v[142:143]
	global_store_dwordx4 v[102:103], v[98:101], off
	s_nop 1
	v_or_b32_e32 v98, 32, v146
	v_ashrrev_i32_e32 v99, 31, v98
	v_lshlrev_b64 v[100:101], 6, v[98:99]
	v_lshl_add_u64 v[100:101], v[144:145], 0, v[100:101]
	v_mov_b32_e32 v100, v204
	v_mov_b32_e32 v101, v205
	v_mov_b32_e32 v102, v206
	v_mov_b32_e32 v103, v207
	s_nop 0
	v_mov_b32_e32 v104, v101
	v_mov_b32_e32 v105, v102
	v_mov_b32_e32 v101, v103
	v_pk_add_f32 v[100:101], v[104:105], v[100:101]
	v_mov_b32_e32 v102, v90
	v_add_f32_e32 v99, v100, v101
	v_mov_b32_e32 v100, v99
	s_nop 1
	v_permlane16_swap_b32 v100, v99
	v_mov_b32_e32 v103, v94
	v_mov_b32_e32 v94, v91
	s_waitcnt lgkmcnt(0)
	v_add_f32_e32 v99, v99, v100
	v_mov_b32_e32 v100, v99
	s_nop 1
	v_permlane32_swap_b32 v100, v99
	s_waitcnt lgkmcnt(0)
	v_add_f32_e32 v99, v99, v100
	v_fmamk_f32 v99, v99, 0x3a800000, v173
	v_cmp_gt_f32_e32 vcc, s64, v99
	v_mul_f32_e32 v100, 0x4b800000, v99
	s_nop 0
	v_cndmask_b32_e32 v99, v99, v100, vcc
	v_rsq_f32_e32 v99, v99
	s_nop 0
	v_mul_f32_e32 v100, 0x45800000, v99
	v_cndmask_b32_e32 v100, v99, v100, vcc
	v_pk_mul_f32 v[102:103], v[102:103], v[100:101] op_sel_hi:[1,0]
	s_nop 0
	v_mul_f32_e32 v90, 0xbfb8aa3b, v103
	v_exp_f32_e32 v90, v90
	s_nop 0
	v_add_f32_e32 v90, 1.0, v90
	v_rcp_f32_e32 v90, v90
	s_nop 0
	v_mul_f32_e32 v90, v103, v90
	v_mul_f32_e32 v99, v102, v90
	v_pk_mul_f32 v[90:91], v[94:95], v[100:101] op_sel_hi:[1,0]
	s_nop 0
	v_mul_f32_e32 v94, 0xbfb8aa3b, v91
	v_exp_f32_e32 v94, v94
	s_nop 0
	v_add_f32_e32 v94, 1.0, v94
	v_rcp_f32_e32 v94, v94
	s_nop 0
	v_mul_f32_e32 v91, v91, v94
	v_mul_f32_e32 v94, v90, v91
	v_mov_b32_e32 v90, v92
	v_mov_b32_e32 v91, v96
	v_pk_mul_f32 v[90:91], v[90:91], v[100:101] op_sel_hi:[1,0]
	v_mov_b32_e32 v96, v93
	v_mul_f32_e32 v92, 0xbfb8aa3b, v91
	v_exp_f32_e32 v92, v92
	s_nop 0
	v_add_f32_e32 v92, 1.0, v92
	v_rcp_f32_e32 v92, v92
	s_nop 0
	v_mul_f32_e32 v91, v91, v92
	v_mul_f32_e32 v92, v90, v91
	v_pk_mul_f32 v[90:91], v[96:97], v[100:101] op_sel_hi:[1,0]
	s_nop 0
	v_mul_f32_e32 v93, 0xbfb8aa3b, v91
	v_exp_f32_e32 v93, v93
	s_nop 0
	v_add_f32_e32 v93, 1.0, v93
	v_rcp_f32_e32 v93, v93
	s_nop 0
	v_mul_f32_e32 v91, v91, v93
	v_mul_f32_e32 v93, v90, v91
	v_mov_b32_e32 v90, v82
	v_mov_b32_e32 v91, v86
	v_pk_mul_f32 v[90:91], v[90:91], v[100:101] op_sel_hi:[1,0]
	v_mov_b32_e32 v86, v83
	v_mul_f32_e32 v82, 0xbfb8aa3b, v91
	v_exp_f32_e32 v82, v82
	s_nop 0
	v_add_f32_e32 v82, 1.0, v82
	v_rcp_f32_e32 v82, v82
	s_nop 0
	v_mul_f32_e32 v82, v91, v82
	v_mul_f32_e32 v90, v90, v82
	v_pk_mul_f32 v[82:83], v[86:87], v[100:101] op_sel_hi:[1,0]
	s_nop 0
	v_mul_f32_e32 v86, 0xbfb8aa3b, v83
	v_exp_f32_e32 v86, v86
	s_nop 0
	v_add_f32_e32 v86, 1.0, v86
	v_rcp_f32_e32 v86, v86
	s_nop 0
	v_mul_f32_e32 v83, v83, v86
	v_mul_f32_e32 v86, v82, v83
	v_mov_b32_e32 v82, v84
	v_mov_b32_e32 v83, v88
	v_pk_mul_f32 v[82:83], v[82:83], v[100:101] op_sel_hi:[1,0]
	v_mov_b32_e32 v88, v85
	v_mul_f32_e32 v84, 0xbfb8aa3b, v83
	v_exp_f32_e32 v84, v84
	s_nop 0
	v_add_f32_e32 v84, 1.0, v84
	v_rcp_f32_e32 v84, v84
	s_nop 0
	v_mul_f32_e32 v83, v83, v84
	v_mul_f32_e32 v87, v82, v83
	v_pk_mul_f32 v[82:83], v[88:89], v[100:101] op_sel_hi:[1,0]
	s_nop 0
	v_mul_f32_e32 v84, 0xbfb8aa3b, v83
	v_exp_f32_e32 v84, v84
	s_nop 0
	v_add_f32_e32 v84, 1.0, v84
	v_rcp_f32_e32 v84, v84
	s_nop 0
	v_mul_f32_e32 v83, v83, v84
	v_mul_f32_e32 v85, v82, v83
	v_cvt_pk_bf16_f32 v82, v99, v94
	v_cvt_pk_bf16_f32 v83, v92, v93
	v_cvt_pk_bf16_f32 v84, v90, v86
	v_cvt_pk_bf16_f32 v85, v87, v85
	v_mad_i64_i32 v[86:87], s[18:19], v98, s88, v[142:143]
	global_store_dwordx4 v[86:87], v[82:85], off
	s_nop 1
	v_or_b32_e32 v82, 48, v146
	v_ashrrev_i32_e32 v83, 31, v82
	v_lshlrev_b64 v[84:85], 6, v[82:83]
	v_lshl_add_u64 v[84:85], v[144:145], 0, v[84:85]
	v_mov_b32_e32 v84, v208
	v_mov_b32_e32 v85, v209
	v_mov_b32_e32 v86, v210
	v_mov_b32_e32 v87, v211
	s_nop 0
	v_mov_b32_e32 v88, v85
	v_mov_b32_e32 v89, v86
	v_mov_b32_e32 v85, v87
	v_pk_add_f32 v[84:85], v[88:89], v[84:85]
	v_mov_b32_e32 v86, v74
	v_add_f32_e32 v83, v84, v85
	v_mov_b32_e32 v84, v83
	s_nop 1
	v_permlane16_swap_b32 v84, v83
	v_mov_b32_e32 v87, v78
	v_mov_b32_e32 v78, v75
	s_waitcnt lgkmcnt(0)
	v_add_f32_e32 v83, v83, v84
	v_mov_b32_e32 v84, v83
	s_nop 1
	v_permlane32_swap_b32 v84, v83
	s_waitcnt lgkmcnt(0)
; __device__ __forceinline__ unsigned cvt_pk_bf16(float lo, float hi) { unsigned r; asm volatile("v_cvt_pk_bf16_f32 %0, %1, %2" : "=v"(r) : "v"(lo), "v"(hi)); return r; }
; __device__ __forceinline__ float fast_sigmoid(float x) { return __builtin_amdgcn_rcpf(1.0f + __builtin_amdgcn_exp2f(-1.44269504089f * x)); }
; __device__ __forceinline__ float rstd_of4(const float* rss, int row, int fq) {
;     const f32x4 a = *(const f32x4*)(rss + (size_t)row * 16 + 4 * fq); float s = (a[0] + a[1]) + (a[2] + a[3]);
;     s += __shfl_xor(s, 16); s += __shfl_xor(s, 32);
;     return rsqrtf(s * (1.0f / 1024.0f) + EPS); }
;     __device__ __forceinline__ void operator()(const f32x4 (&acc)[2][2][4][2], const Unit& u, int wr, int wc, int fr, int fq, LAS unsigned char* lds) const {
;     ...
;             for (int m = 0; m < 4; ++m) { const int row = row0 + ai * HALF + m * 16; const float rs = rstd_of4(rss, row, fq);
;                 float h[8];
; #pragma unroll
;                 for (int n = 0; n < 2; ++n)
; #pragma unroll
;                     for (int e = 0; e < 4; ++e) { const float gt = acc[ai][0][m][n][e] * rs, up = acc[ai][1][m][n][e] * rs; h[n * 4 + e] = gt * fast_sigmoid(gt) * up; }
;                 u32x4 w; w.x = cvt_pk_bf16(h[0], h[1]); w.y = cvt_pk_bf16(h[2], h[3]); w.z = cvt_pk_bf16(h[4], h[5]); w.w = cvt_pk_bf16(h[6], h[7]);
;                 *(u32x4*)(O + (size_t)row * DFF + j0) = w; }
	v_add_f32_e32 v83, v83, v84
	v_fmamk_f32 v83, v83, 0x3a800000, v173
	v_cmp_gt_f32_e32 vcc, s64, v83
	v_mul_f32_e32 v84, 0x4b800000, v83
	s_nop 0
	v_cndmask_b32_e32 v83, v83, v84, vcc
	v_rsq_f32_e32 v83, v83
	s_nop 0
	v_mul_f32_e32 v84, 0x45800000, v83
	v_cndmask_b32_e32 v84, v83, v84, vcc
	v_pk_mul_f32 v[86:87], v[86:87], v[84:85] op_sel_hi:[1,0]
	s_nop 0
	v_mul_f32_e32 v74, 0xbfb8aa3b, v87
	v_exp_f32_e32 v74, v74
	s_nop 0
	v_add_f32_e32 v74, 1.0, v74
	v_rcp_f32_e32 v74, v74
	s_nop 0
	v_mul_f32_e32 v74, v87, v74
	v_mul_f32_e32 v83, v86, v74
	v_pk_mul_f32 v[74:75], v[78:79], v[84:85] op_sel_hi:[1,0]
	s_nop 0
	v_mul_f32_e32 v78, 0xbfb8aa3b, v75
	v_exp_f32_e32 v78, v78
	s_nop 0
	v_add_f32_e32 v78, 1.0, v78
	v_rcp_f32_e32 v78, v78
	s_nop 0
	v_mul_f32_e32 v75, v75, v78
	v_mul_f32_e32 v78, v74, v75
	v_mov_b32_e32 v74, v76
	v_mov_b32_e32 v75, v80
	v_pk_mul_f32 v[74:75], v[74:75], v[84:85] op_sel_hi:[1,0]
	v_mov_b32_e32 v80, v77
	v_mul_f32_e32 v76, 0xbfb8aa3b, v75
	v_exp_f32_e32 v76, v76
	s_nop 0
	v_add_f32_e32 v76, 1.0, v76
	v_rcp_f32_e32 v76, v76
	s_nop 0
	v_mul_f32_e32 v75, v75, v76
	v_mul_f32_e32 v76, v74, v75
	v_pk_mul_f32 v[74:75], v[80:81], v[84:85] op_sel_hi:[1,0]
	s_nop 0
	v_mul_f32_e32 v77, 0xbfb8aa3b, v75
	v_exp_f32_e32 v77, v77
	s_nop 0
	v_add_f32_e32 v77, 1.0, v77
	v_rcp_f32_e32 v77, v77
	s_nop 0
	v_mul_f32_e32 v75, v75, v77
	v_mul_f32_e32 v77, v74, v75
	v_mov_b32_e32 v74, v66
	v_mov_b32_e32 v75, v70
	v_pk_mul_f32 v[74:75], v[74:75], v[84:85] op_sel_hi:[1,0]
	v_mov_b32_e32 v70, v67
	v_mul_f32_e32 v66, 0xbfb8aa3b, v75
	v_exp_f32_e32 v66, v66
	s_nop 0
	v_add_f32_e32 v66, 1.0, v66
	v_rcp_f32_e32 v66, v66
	s_nop 0
	v_mul_f32_e32 v66, v75, v66
	v_mul_f32_e32 v74, v74, v66
	v_pk_mul_f32 v[66:67], v[70:71], v[84:85] op_sel_hi:[1,0]
	s_nop 0
	v_mul_f32_e32 v70, 0xbfb8aa3b, v67
	v_exp_f32_e32 v70, v70
	s_nop 0
	v_add_f32_e32 v70, 1.0, v70
	v_rcp_f32_e32 v70, v70
	s_nop 0
	v_mul_f32_e32 v67, v67, v70
	v_mul_f32_e32 v70, v66, v67
	v_mov_b32_e32 v66, v68
	v_mov_b32_e32 v67, v72
	v_pk_mul_f32 v[66:67], v[66:67], v[84:85] op_sel_hi:[1,0]
	v_mov_b32_e32 v72, v69
	v_mul_f32_e32 v68, 0xbfb8aa3b, v67
	v_exp_f32_e32 v68, v68
	s_nop 0
	v_add_f32_e32 v68, 1.0, v68
	v_rcp_f32_e32 v68, v68
	s_nop 0
	v_mul_f32_e32 v67, v67, v68
	v_mul_f32_e32 v71, v66, v67
	v_pk_mul_f32 v[66:67], v[72:73], v[84:85] op_sel_hi:[1,0]
	s_nop 0
	v_mul_f32_e32 v68, 0xbfb8aa3b, v67
	v_exp_f32_e32 v68, v68
	s_nop 0
	v_add_f32_e32 v68, 1.0, v68
	v_rcp_f32_e32 v68, v68
	s_nop 0
	v_mul_f32_e32 v67, v67, v68
	v_mul_f32_e32 v69, v66, v67
	v_cvt_pk_bf16_f32 v66, v83, v78
	v_cvt_pk_bf16_f32 v67, v76, v77
	v_cvt_pk_bf16_f32 v68, v74, v70
	v_cvt_pk_bf16_f32 v69, v71, v69
	v_mad_i64_i32 v[70:71], s[18:19], v82, s88, v[142:143]
	global_store_dwordx4 v[70:71], v[66:69], off
	s_nop 1
	v_add_u32_e32 v66, 0x80, v146
	v_ashrrev_i32_e32 v67, 31, v66
	v_lshlrev_b64 v[68:69], 6, v[66:67]
	v_lshl_add_u64 v[68:69], v[144:145], 0, v[68:69]
	v_mov_b32_e32 v68, v212
	v_mov_b32_e32 v69, v213
	v_mov_b32_e32 v70, v214
	v_mov_b32_e32 v71, v215
	s_nop 0
	v_mov_b32_e32 v72, v69
	v_mov_b32_e32 v73, v70
	v_mov_b32_e32 v69, v71
	v_pk_add_f32 v[68:69], v[72:73], v[68:69]
	v_mov_b32_e32 v70, v58
	v_add_f32_e32 v67, v68, v69
	v_mov_b32_e32 v68, v67
	s_nop 1
	v_permlane16_swap_b32 v68, v67
	v_mov_b32_e32 v71, v62
	v_mov_b32_e32 v62, v59
	s_waitcnt lgkmcnt(0)
	v_add_f32_e32 v67, v67, v68
	v_mov_b32_e32 v68, v67
	s_nop 1
	v_permlane32_swap_b32 v68, v67
	s_waitcnt lgkmcnt(0)
	v_add_f32_e32 v67, v67, v68
	v_fmamk_f32 v67, v67, 0x3a800000, v173
	v_cmp_gt_f32_e32 vcc, s64, v67
	v_mul_f32_e32 v68, 0x4b800000, v67
	s_nop 0
	v_cndmask_b32_e32 v67, v67, v68, vcc
	v_rsq_f32_e32 v67, v67
	s_nop 0
	v_mul_f32_e32 v68, 0x45800000, v67
	v_cndmask_b32_e32 v68, v67, v68, vcc
	v_pk_mul_f32 v[70:71], v[70:71], v[68:69] op_sel_hi:[1,0]
	s_nop 0
	v_mul_f32_e32 v58, 0xbfb8aa3b, v71
	v_exp_f32_e32 v58, v58
	s_nop 0
	v_add_f32_e32 v58, 1.0, v58
	v_rcp_f32_e32 v58, v58
	s_nop 0
	v_mul_f32_e32 v58, v71, v58
	v_mul_f32_e32 v67, v70, v58
	v_pk_mul_f32 v[58:59], v[62:63], v[68:69] op_sel_hi:[1,0]
	s_nop 0
	v_mul_f32_e32 v62, 0xbfb8aa3b, v59
	v_exp_f32_e32 v62, v62
	s_nop 0
	v_add_f32_e32 v62, 1.0, v62
	v_rcp_f32_e32 v62, v62
	s_nop 0
	v_mul_f32_e32 v59, v59, v62
	v_mul_f32_e32 v62, v58, v59
	v_mov_b32_e32 v58, v60
	v_mov_b32_e32 v59, v64
	v_pk_mul_f32 v[58:59], v[58:59], v[68:69] op_sel_hi:[1,0]
	v_mov_b32_e32 v64, v61
	v_mul_f32_e32 v60, 0xbfb8aa3b, v59
	v_exp_f32_e32 v60, v60
	s_nop 0
	v_add_f32_e32 v60, 1.0, v60
	v_rcp_f32_e32 v60, v60
	s_nop 0
	v_mul_f32_e32 v59, v59, v60
	v_mul_f32_e32 v60, v58, v59
	v_pk_mul_f32 v[58:59], v[64:65], v[68:69] op_sel_hi:[1,0]
	s_nop 0
	v_mul_f32_e32 v61, 0xbfb8aa3b, v59
	v_exp_f32_e32 v61, v61
	s_nop 0
	v_add_f32_e32 v61, 1.0, v61
	v_rcp_f32_e32 v61, v61
	s_nop 0
	v_mul_f32_e32 v59, v59, v61
	v_mul_f32_e32 v61, v58, v59
	v_mov_b32_e32 v58, v50
	v_mov_b32_e32 v59, v54
	v_pk_mul_f32 v[58:59], v[58:59], v[68:69] op_sel_hi:[1,0]
	v_mov_b32_e32 v54, v51
	v_mul_f32_e32 v50, 0xbfb8aa3b, v59
	v_exp_f32_e32 v50, v50
	s_nop 0
	v_add_f32_e32 v50, 1.0, v50
	v_rcp_f32_e32 v50, v50
	s_nop 0
	v_mul_f32_e32 v50, v59, v50
	v_mul_f32_e32 v58, v58, v50
	v_pk_mul_f32 v[50:51], v[54:55], v[68:69] op_sel_hi:[1,0]
	s_nop 0
	v_mul_f32_e32 v54, 0xbfb8aa3b, v51
	v_exp_f32_e32 v54, v54
	s_nop 0
	v_add_f32_e32 v54, 1.0, v54
	v_rcp_f32_e32 v54, v54
	s_nop 0
	v_mul_f32_e32 v51, v51, v54
	v_mul_f32_e32 v54, v50, v51
	v_mov_b32_e32 v50, v52
	v_mov_b32_e32 v51, v56
	v_pk_mul_f32 v[50:51], v[50:51], v[68:69] op_sel_hi:[1,0]
	v_mov_b32_e32 v56, v53
	v_mul_f32_e32 v52, 0xbfb8aa3b, v51
	v_exp_f32_e32 v52, v52
	s_nop 0
	v_add_f32_e32 v52, 1.0, v52
	v_rcp_f32_e32 v52, v52
	s_nop 0
	v_mul_f32_e32 v51, v51, v52
	v_mul_f32_e32 v55, v50, v51
	v_pk_mul_f32 v[50:51], v[56:57], v[68:69] op_sel_hi:[1,0]
	s_nop 0
	v_mul_f32_e32 v52, 0xbfb8aa3b, v51
	v_exp_f32_e32 v52, v52
	s_nop 0
	v_add_f32_e32 v52, 1.0, v52
	v_rcp_f32_e32 v52, v52
	s_nop 0
	v_mul_f32_e32 v51, v51, v52
	v_mul_f32_e32 v53, v50, v51
	v_cvt_pk_bf16_f32 v50, v67, v62
	v_cvt_pk_bf16_f32 v51, v60, v61
	v_cvt_pk_bf16_f32 v52, v58, v54
	v_cvt_pk_bf16_f32 v53, v55, v53
	v_mad_i64_i32 v[54:55], s[18:19], v66, s88, v[142:143]
	global_store_dwordx4 v[54:55], v[50:53], off
	s_nop 1
	v_add_u32_e32 v50, 0x90, v146
	v_ashrrev_i32_e32 v51, 31, v50
	v_lshlrev_b64 v[52:53], 6, v[50:51]
	v_lshl_add_u64 v[52:53], v[144:145], 0, v[52:53]
	v_mov_b32_e32 v52, v216
	v_mov_b32_e32 v53, v217
	v_mov_b32_e32 v54, v218
	v_mov_b32_e32 v55, v219
	s_nop 0
	v_mov_b32_e32 v56, v53
	v_mov_b32_e32 v57, v54
	v_mov_b32_e32 v53, v55
	v_pk_add_f32 v[52:53], v[56:57], v[52:53]
	v_mov_b32_e32 v54, v42
	v_add_f32_e32 v51, v52, v53
	v_mov_b32_e32 v52, v51
	s_nop 1
	v_permlane16_swap_b32 v52, v51
	v_mov_b32_e32 v55, v46
	v_mov_b32_e32 v46, v43
	s_waitcnt lgkmcnt(0)
; __device__ __forceinline__ unsigned cvt_pk_bf16(float lo, float hi) { unsigned r; asm volatile("v_cvt_pk_bf16_f32 %0, %1, %2" : "=v"(r) : "v"(lo), "v"(hi)); return r; }
; __device__ __forceinline__ float fast_sigmoid(float x) { return __builtin_amdgcn_rcpf(1.0f + __builtin_amdgcn_exp2f(-1.44269504089f * x)); }
; __device__ __forceinline__ float rstd_of4(const float* rss, int row, int fq) {
;     const f32x4 a = *(const f32x4*)(rss + (size_t)row * 16 + 4 * fq); float s = (a[0] + a[1]) + (a[2] + a[3]);
;     s += __shfl_xor(s, 16); s += __shfl_xor(s, 32);
;     return rsqrtf(s * (1.0f / 1024.0f) + EPS); }
;     __device__ __forceinline__ void operator()(const f32x4 (&acc)[2][2][4][2], const Unit& u, int wr, int wc, int fr, int fq, LAS unsigned char* lds) const {
;     ...
;             for (int m = 0; m < 4; ++m) { const int row = row0 + ai * HALF + m * 16; const float rs = rstd_of4(rss, row, fq);
;                 float h[8];
; #pragma unroll
;                 for (int n = 0; n < 2; ++n)
; #pragma unroll
;                     for (int e = 0; e < 4; ++e) { const float gt = acc[ai][0][m][n][e] * rs, up = acc[ai][1][m][n][e] * rs; h[n * 4 + e] = gt * fast_sigmoid(gt) * up; }
;                 u32x4 w; w.x = cvt_pk_bf16(h[0], h[1]); w.y = cvt_pk_bf16(h[2], h[3]); w.z = cvt_pk_bf16(h[4], h[5]); w.w = cvt_pk_bf16(h[6], h[7]);
;                 *(u32x4*)(O + (size_t)row * DFF + j0) = w; }
	v_add_f32_e32 v51, v51, v52
	v_mov_b32_e32 v52, v51
	s_nop 1
	v_permlane32_swap_b32 v52, v51
	s_waitcnt lgkmcnt(0)
	v_add_f32_e32 v51, v51, v52
	v_fmamk_f32 v51, v51, 0x3a800000, v173
	v_cmp_gt_f32_e32 vcc, s64, v51
	v_mul_f32_e32 v52, 0x4b800000, v51
	s_nop 0
	v_cndmask_b32_e32 v51, v51, v52, vcc
	v_rsq_f32_e32 v51, v51
	s_nop 0
	v_mul_f32_e32 v52, 0x45800000, v51
	v_cndmask_b32_e32 v52, v51, v52, vcc
	v_pk_mul_f32 v[54:55], v[54:55], v[52:53] op_sel_hi:[1,0]
	s_nop 0
	v_mul_f32_e32 v42, 0xbfb8aa3b, v55
	v_exp_f32_e32 v42, v42
	s_nop 0
	v_add_f32_e32 v42, 1.0, v42
	v_rcp_f32_e32 v42, v42
	s_nop 0
	v_mul_f32_e32 v42, v55, v42
	v_mul_f32_e32 v51, v54, v42
	v_pk_mul_f32 v[42:43], v[46:47], v[52:53] op_sel_hi:[1,0]
	s_nop 0
	v_mul_f32_e32 v46, 0xbfb8aa3b, v43
	v_exp_f32_e32 v46, v46
	s_nop 0
	v_add_f32_e32 v46, 1.0, v46
	v_rcp_f32_e32 v46, v46
	s_nop 0
	v_mul_f32_e32 v43, v43, v46
	v_mul_f32_e32 v46, v42, v43
	v_mov_b32_e32 v42, v44
	v_mov_b32_e32 v43, v48
	v_pk_mul_f32 v[42:43], v[42:43], v[52:53] op_sel_hi:[1,0]
	v_mov_b32_e32 v48, v45
	v_mul_f32_e32 v44, 0xbfb8aa3b, v43
	v_exp_f32_e32 v44, v44
	s_nop 0
	v_add_f32_e32 v44, 1.0, v44
	v_rcp_f32_e32 v44, v44
	s_nop 0
	v_mul_f32_e32 v43, v43, v44
	v_mul_f32_e32 v44, v42, v43
	v_pk_mul_f32 v[42:43], v[48:49], v[52:53] op_sel_hi:[1,0]
	s_nop 0
	v_mul_f32_e32 v45, 0xbfb8aa3b, v43
	v_exp_f32_e32 v45, v45
	s_nop 0
	v_add_f32_e32 v45, 1.0, v45
	v_rcp_f32_e32 v45, v45
	s_nop 0
	v_mul_f32_e32 v43, v43, v45
	v_mul_f32_e32 v45, v42, v43
	v_mov_b32_e32 v42, v34
	v_mov_b32_e32 v43, v38
	v_pk_mul_f32 v[42:43], v[42:43], v[52:53] op_sel_hi:[1,0]
	v_mov_b32_e32 v38, v35
	v_mul_f32_e32 v34, 0xbfb8aa3b, v43
	v_exp_f32_e32 v34, v34
	s_nop 0
	v_add_f32_e32 v34, 1.0, v34
	v_rcp_f32_e32 v34, v34
	s_nop 0
	v_mul_f32_e32 v34, v43, v34
	v_mul_f32_e32 v42, v42, v34
	v_pk_mul_f32 v[34:35], v[38:39], v[52:53] op_sel_hi:[1,0]
	s_nop 0
	v_mul_f32_e32 v38, 0xbfb8aa3b, v35
	v_exp_f32_e32 v38, v38
	s_nop 0
	v_add_f32_e32 v38, 1.0, v38
	v_rcp_f32_e32 v38, v38
	s_nop 0
	v_mul_f32_e32 v35, v35, v38
	v_mul_f32_e32 v38, v34, v35
	v_mov_b32_e32 v34, v36
	v_mov_b32_e32 v35, v40
	v_pk_mul_f32 v[34:35], v[34:35], v[52:53] op_sel_hi:[1,0]
	v_mov_b32_e32 v40, v37
	v_mul_f32_e32 v36, 0xbfb8aa3b, v35
	v_exp_f32_e32 v36, v36
	s_nop 0
	v_add_f32_e32 v36, 1.0, v36
	v_rcp_f32_e32 v36, v36
	s_nop 0
	v_mul_f32_e32 v35, v35, v36
	v_mul_f32_e32 v39, v34, v35
	v_pk_mul_f32 v[34:35], v[40:41], v[52:53] op_sel_hi:[1,0]
	s_nop 0
	v_mul_f32_e32 v36, 0xbfb8aa3b, v35
	v_exp_f32_e32 v36, v36
	s_nop 0
	v_add_f32_e32 v36, 1.0, v36
	v_rcp_f32_e32 v36, v36
	s_nop 0
	v_mul_f32_e32 v35, v35, v36
	v_mul_f32_e32 v37, v34, v35
	v_cvt_pk_bf16_f32 v34, v51, v46
	v_cvt_pk_bf16_f32 v35, v44, v45
	v_cvt_pk_bf16_f32 v36, v42, v38
	v_cvt_pk_bf16_f32 v37, v39, v37
	v_mad_i64_i32 v[38:39], s[18:19], v50, s88, v[142:143]
	global_store_dwordx4 v[38:39], v[34:37], off
	s_nop 1
	v_add_u32_e32 v34, 0xa0, v146
	v_ashrrev_i32_e32 v35, 31, v34
	v_lshlrev_b64 v[36:37], 6, v[34:35]
	v_lshl_add_u64 v[36:37], v[144:145], 0, v[36:37]
	v_mov_b32_e32 v36, v220
	v_mov_b32_e32 v37, v221
	v_mov_b32_e32 v38, v222
	v_mov_b32_e32 v39, v223
	s_nop 0
	v_mov_b32_e32 v40, v37
	v_mov_b32_e32 v41, v38
	v_mov_b32_e32 v37, v39
	v_pk_add_f32 v[36:37], v[40:41], v[36:37]
	v_mov_b32_e32 v38, v26
	v_add_f32_e32 v35, v36, v37
	v_mov_b32_e32 v36, v35
	s_nop 1
	v_permlane16_swap_b32 v36, v35
	v_mov_b32_e32 v39, v30
	v_mov_b32_e32 v30, v27
	s_waitcnt lgkmcnt(0)
	v_add_f32_e32 v35, v35, v36
	v_mov_b32_e32 v36, v35
	s_nop 1
	v_permlane32_swap_b32 v36, v35
	s_waitcnt lgkmcnt(0)
; __device__ __forceinline__ unsigned cvt_pk_bf16(float lo, float hi) { unsigned r; asm volatile("v_cvt_pk_bf16_f32 %0, %1, %2" : "=v"(r) : "v"(lo), "v"(hi)); return r; }
; __device__ __forceinline__ float fast_sigmoid(float x) { return __builtin_amdgcn_rcpf(1.0f + __builtin_amdgcn_exp2f(-1.44269504089f * x)); }
; #define PG8_WAIT_V(n) asm volatile("s_waitcnt vmcnt(" #n ")" ::: "memory")
; #define PG8_BAR __builtin_amdgcn_s_barrier()
; template <class Epi, int KK, int LDA, int LDB, int NN, bool AGRP>
; __device__ __forceinline__ void gemm_phase(LAS unsigned char* lds, const bf16_t* gA, const bf16_t* gBt, int G_, int bid_, int tid) {
;     ...
;     PG8_WAIT_V(0);
;     if (wr == 0) PG8_BAR;
;     PG8_BAR;
;     __device__ __forceinline__ void operator()(const f32x4 (&acc)[2][2][4][2], const Unit& u, int wr, int wc, int fr, int fq, LAS unsigned char* lds) const {
;     ...
;             for (int m = 0; m < 4; ++m) { const int row = row0 + ai * HALF + m * 16; const float rs = rstd_of4(rss, row, fq);
;                 float h[8];
; #pragma unroll
;                 for (int n = 0; n < 2; ++n)
; #pragma unroll
;                     for (int e = 0; e < 4; ++e) { const float gt = acc[ai][0][m][n][e] * rs, up = acc[ai][1][m][n][e] * rs; h[n * 4 + e] = gt * fast_sigmoid(gt) * up; }
;                 u32x4 w; w.x = cvt_pk_bf16(h[0], h[1]); w.y = cvt_pk_bf16(h[2], h[3]); w.z = cvt_pk_bf16(h[4], h[5]); w.w = cvt_pk_bf16(h[6], h[7]);
;                 *(u32x4*)(O + (size_t)row * DFF + j0) = w; }
	v_add_f32_e32 v35, v35, v36
	v_fmamk_f32 v35, v35, 0x3a800000, v173
	v_cmp_gt_f32_e32 vcc, s64, v35
	v_mul_f32_e32 v36, 0x4b800000, v35
	s_nop 0
	v_cndmask_b32_e32 v35, v35, v36, vcc
	v_rsq_f32_e32 v35, v35
	s_nop 0
	v_mul_f32_e32 v36, 0x45800000, v35
	v_cndmask_b32_e32 v36, v35, v36, vcc
	v_pk_mul_f32 v[38:39], v[38:39], v[36:37] op_sel_hi:[1,0]
	s_nop 0
	v_mul_f32_e32 v26, 0xbfb8aa3b, v39
	v_exp_f32_e32 v26, v26
	s_nop 0
	v_add_f32_e32 v26, 1.0, v26
	v_rcp_f32_e32 v26, v26
	s_nop 0
	v_mul_f32_e32 v26, v39, v26
	v_mul_f32_e32 v35, v38, v26
	v_pk_mul_f32 v[26:27], v[30:31], v[36:37] op_sel_hi:[1,0]
	s_nop 0
	v_mul_f32_e32 v30, 0xbfb8aa3b, v27
	v_exp_f32_e32 v30, v30
	s_nop 0
	v_add_f32_e32 v30, 1.0, v30
	v_rcp_f32_e32 v30, v30
	s_nop 0
	v_mul_f32_e32 v27, v27, v30
	v_mul_f32_e32 v30, v26, v27
	v_mov_b32_e32 v26, v28
	v_mov_b32_e32 v27, v32
	v_pk_mul_f32 v[26:27], v[26:27], v[36:37] op_sel_hi:[1,0]
	v_mov_b32_e32 v32, v29
	v_mul_f32_e32 v28, 0xbfb8aa3b, v27
	v_exp_f32_e32 v28, v28
	s_nop 0
	v_add_f32_e32 v28, 1.0, v28
	v_rcp_f32_e32 v28, v28
	s_nop 0
	v_mul_f32_e32 v27, v27, v28
	v_mul_f32_e32 v28, v26, v27
	v_pk_mul_f32 v[26:27], v[32:33], v[36:37] op_sel_hi:[1,0]
	s_nop 0
	v_mul_f32_e32 v29, 0xbfb8aa3b, v27
	v_exp_f32_e32 v29, v29
	s_nop 0
	v_add_f32_e32 v29, 1.0, v29
	v_rcp_f32_e32 v29, v29
	s_nop 0
	v_mul_f32_e32 v27, v27, v29
	v_mul_f32_e32 v29, v26, v27
	v_mov_b32_e32 v26, v18
	v_mov_b32_e32 v27, v22
	v_pk_mul_f32 v[26:27], v[26:27], v[36:37] op_sel_hi:[1,0]
	v_mov_b32_e32 v22, v19
	v_mul_f32_e32 v18, 0xbfb8aa3b, v27
	v_exp_f32_e32 v18, v18
	s_nop 0
	v_add_f32_e32 v18, 1.0, v18
	v_rcp_f32_e32 v18, v18
	s_nop 0
	v_mul_f32_e32 v18, v27, v18
	v_mul_f32_e32 v26, v26, v18
	v_pk_mul_f32 v[18:19], v[22:23], v[36:37] op_sel_hi:[1,0]
	s_nop 0
	v_mul_f32_e32 v22, 0xbfb8aa3b, v19
	v_exp_f32_e32 v22, v22
	s_nop 0
	v_add_f32_e32 v22, 1.0, v22
	v_rcp_f32_e32 v22, v22
	s_nop 0
	v_mul_f32_e32 v19, v19, v22
	v_mul_f32_e32 v22, v18, v19
	v_mov_b32_e32 v18, v20
	v_mov_b32_e32 v19, v24
	v_pk_mul_f32 v[18:19], v[18:19], v[36:37] op_sel_hi:[1,0]
	v_mov_b32_e32 v24, v21
	v_mul_f32_e32 v20, 0xbfb8aa3b, v19
	v_exp_f32_e32 v20, v20
	s_nop 0
	v_add_f32_e32 v20, 1.0, v20
	v_rcp_f32_e32 v20, v20
	s_nop 0
	v_mul_f32_e32 v19, v19, v20
	v_mul_f32_e32 v23, v18, v19
	v_pk_mul_f32 v[18:19], v[24:25], v[36:37] op_sel_hi:[1,0]
	s_nop 0
	v_mul_f32_e32 v20, 0xbfb8aa3b, v19
	v_exp_f32_e32 v20, v20
	s_nop 0
	v_add_f32_e32 v20, 1.0, v20
	v_rcp_f32_e32 v20, v20
	s_nop 0
	v_mul_f32_e32 v19, v19, v20
	v_mul_f32_e32 v21, v18, v19
	v_cvt_pk_bf16_f32 v18, v35, v30
	v_cvt_pk_bf16_f32 v19, v28, v29
	v_cvt_pk_bf16_f32 v20, v26, v22
	v_cvt_pk_bf16_f32 v21, v23, v21
	v_mad_i64_i32 v[22:23], s[18:19], v34, s88, v[142:143]
	global_store_dwordx4 v[22:23], v[18:21], off
	s_nop 1
	v_add_u32_e32 v18, 0xb0, v146
	v_ashrrev_i32_e32 v19, 31, v18
	v_lshlrev_b64 v[20:21], 6, v[18:19]
	v_lshl_add_u64 v[20:21], v[144:145], 0, v[20:21]
	v_mov_b32_e32 v20, v224
	v_mov_b32_e32 v21, v225
	v_mov_b32_e32 v22, v226
	v_mov_b32_e32 v23, v227
	s_nop 0
	v_mov_b32_e32 v24, v21
	v_mov_b32_e32 v25, v22
	v_mov_b32_e32 v21, v23
	v_pk_add_f32 v[20:21], v[24:25], v[20:21]
	v_mov_b32_e32 v22, v10
	v_add_f32_e32 v19, v20, v21
	v_mov_b32_e32 v20, v19
	s_nop 1
	v_permlane16_swap_b32 v20, v19
	v_mov_b32_e32 v23, v14
	v_mov_b32_e32 v14, v11
	s_waitcnt lgkmcnt(0)
	v_add_f32_e32 v19, v19, v20
	v_mov_b32_e32 v20, v19
	s_nop 1
	v_permlane32_swap_b32 v20, v19
	s_waitcnt lgkmcnt(0)
	v_add_f32_e32 v19, v19, v20
	v_fmamk_f32 v19, v19, 0x3a800000, v173
	v_cmp_gt_f32_e32 vcc, s64, v19
	v_mul_f32_e32 v20, 0x4b800000, v19
	s_nop 0
	v_cndmask_b32_e32 v19, v19, v20, vcc
	v_rsq_f32_e32 v19, v19
	s_nop 0
	v_mul_f32_e32 v20, 0x45800000, v19
	v_cndmask_b32_e32 v20, v19, v20, vcc
	v_pk_mul_f32 v[22:23], v[22:23], v[20:21] op_sel_hi:[1,0]
	s_and_b64 vcc, exec, s[10:11]
	v_mul_f32_e32 v10, 0xbfb8aa3b, v23
	v_exp_f32_e32 v10, v10
	s_nop 0
	v_add_f32_e32 v10, 1.0, v10
	v_rcp_f32_e32 v10, v10
	s_nop 0
	v_mul_f32_e32 v10, v23, v10
	v_mul_f32_e32 v19, v22, v10
	v_pk_mul_f32 v[10:11], v[14:15], v[20:21] op_sel_hi:[1,0]
	s_nop 0
	v_mul_f32_e32 v14, 0xbfb8aa3b, v11
	v_exp_f32_e32 v14, v14
	s_nop 0
	v_add_f32_e32 v14, 1.0, v14
	v_rcp_f32_e32 v14, v14
	s_nop 0
	v_mul_f32_e32 v11, v11, v14
	v_mul_f32_e32 v14, v10, v11
	v_mov_b32_e32 v10, v12
	v_mov_b32_e32 v11, v16
	v_pk_mul_f32 v[10:11], v[10:11], v[20:21] op_sel_hi:[1,0]
	v_mov_b32_e32 v16, v13
	v_mul_f32_e32 v12, 0xbfb8aa3b, v11
	v_exp_f32_e32 v12, v12
	s_nop 0
	v_add_f32_e32 v12, 1.0, v12
	v_rcp_f32_e32 v12, v12
	s_nop 0
	v_mul_f32_e32 v11, v11, v12
	v_mul_f32_e32 v12, v10, v11
	v_pk_mul_f32 v[10:11], v[16:17], v[20:21] op_sel_hi:[1,0]
	s_nop 0
	v_mul_f32_e32 v13, 0xbfb8aa3b, v11
	v_exp_f32_e32 v13, v13
	s_nop 0
	v_add_f32_e32 v13, 1.0, v13
	v_rcp_f32_e32 v13, v13
	s_nop 0
	v_mul_f32_e32 v11, v11, v13
	v_mul_f32_e32 v13, v10, v11
	v_mov_b32_e32 v10, v0
	v_mov_b32_e32 v11, v6
	v_pk_mul_f32 v[10:11], v[10:11], v[20:21] op_sel_hi:[1,0]
	v_mov_b32_e32 v6, v1
	v_mul_f32_e32 v0, 0xbfb8aa3b, v11
	v_exp_f32_e32 v0, v0
	s_nop 0
	v_add_f32_e32 v0, 1.0, v0
	v_rcp_f32_e32 v0, v0
	s_nop 0
	v_mul_f32_e32 v0, v11, v0
	v_mul_f32_e32 v10, v10, v0
	v_pk_mul_f32 v[0:1], v[6:7], v[20:21] op_sel_hi:[1,0]
	s_nop 0
	v_mul_f32_e32 v6, 0xbfb8aa3b, v1
	v_exp_f32_e32 v6, v6
	s_nop 0
	v_add_f32_e32 v6, 1.0, v6
	v_rcp_f32_e32 v6, v6
	s_nop 0
	v_mul_f32_e32 v1, v1, v6
	v_mul_f32_e32 v6, v0, v1
	v_mov_b32_e32 v0, v2
	v_mov_b32_e32 v1, v8
	v_pk_mul_f32 v[0:1], v[0:1], v[20:21] op_sel_hi:[1,0]
	v_mov_b32_e32 v8, v3
	v_mul_f32_e32 v2, 0xbfb8aa3b, v1
	v_exp_f32_e32 v2, v2
	s_nop 0
	v_add_f32_e32 v2, 1.0, v2
	v_rcp_f32_e32 v2, v2
	s_nop 0
	v_mul_f32_e32 v1, v1, v2
	v_mul_f32_e32 v7, v0, v1
	v_pk_mul_f32 v[0:1], v[8:9], v[20:21] op_sel_hi:[1,0]
	s_nop 0
	v_mul_f32_e32 v2, 0xbfb8aa3b, v1
	v_exp_f32_e32 v2, v2
	s_nop 0
	v_add_f32_e32 v2, 1.0, v2
	v_rcp_f32_e32 v2, v2
	s_nop 0
	v_mul_f32_e32 v1, v1, v2
	v_mul_f32_e32 v3, v0, v1
	v_cvt_pk_bf16_f32 v0, v19, v14
	v_cvt_pk_bf16_f32 v1, v12, v13
	v_cvt_pk_bf16_f32 v2, v10, v6
	v_cvt_pk_bf16_f32 v3, v7, v3
	v_mad_i64_i32 v[6:7], s[18:19], v18, s88, v[142:143]
	s_mov_b64 s[18:19], s[14:15]
	global_store_dwordx4 v[6:7], v[0:3], off
	s_cbranch_vccz .LBB1_840
	s_waitcnt vmcnt(0)
	s_cmpk_gt_u32 s24, 0xff
	s_cbranch_scc1 .LBB1_847
	s_barrier
